# K-loops: one static s_setprio 1 for waves 4-7 before each main loop, per-MFMA-block priority toggles removed (strategy 4)
# baseline (speedup 1.0000x reference)
; #define PG8_STAGE(bufoff, gbase, voff) do { _Pragma("unroll") for (int _i = 0; _i < 2; ++_i) \
;         __builtin_amdgcn_global_load_lds((const unsigned*)((const char*)(gbase) + (voff)[_i]), (PG8_LAS unsigned*)(lds + (bufoff) + ldsw + _i * 8192), 16, 0, 0); } while (0)
; #define PG8_LDA(dst, b, h) do { _Pragma("unroll") for (int m = 0; m < 4; ++m) _Pragma("unroll") for (int k = 0; k < 2; ++k) dst[m][k] = *(const PG8_LAS bf16x8*)(lds + PG8_SA(b, h) + aoff + m * 2048 + k * 1024); } while (0)
; #define PG8_LDB(dst, b, h) do { _Pragma("unroll") for (int n = 0; n < 2; ++n) _Pragma("unroll") for (int k = 0; k < 2; ++k) dst[n][k] = *(const PG8_LAS bf16x8*)(lds + PG8_SB(b, h) + boff + n * 2048 + k * 1024); } while (0)
; #define PG8_WAIT_V(n) asm volatile("s_waitcnt vmcnt(" #n ")" ::: "memory")
; #define PG8_WAIT_L(n) asm volatile("s_waitcnt lgkmcnt(" #n ")" ::: "memory")
; template <class Epi, class Sched, bool ALIGN_EPI = false, bool SP2 = false>
; __device__ __forceinline__ void gemm_phase(PG8_LAS unsigned char* lds, const Gemm g, const Sched S, const Epi E, const int tid) {
;     ...
;         const bool has_next = S.next(ui + 1, nxt);
;         const char* nA = has_next ? (const char*)g.A + (size_t)nxt.pm * tstepA + (size_t)nxt.pn * apn : cA; const char* nB = has_next ? (const char*)g.Bt + (size_t)nxt.pn * bpn : cB;
;         for (int t = 0; t < nt; t += 2) {
;             const bool last = (t == nt - 2);
;             const char* a1 = cA + (size_t)(t + 1) * kstep;
;             const char* a2 = last ? nA : cA + (size_t)(t + 2) * kstep; const char* b2 = last ? nB : cB + (size_t)(t + 2) * kstep;
;             const char* a3 = a2 + kstep; const char* b3 = b2 + kstep;
;             if (last && has_next) S.a_ready(nxt);
;             if constexpr (SP2) {
;             PG8_LDB(B0, 0, 0); PG8_LDB(B1, 0, 1); PG8_SCHED; PG8_LDA(At, 0, 0); PG8_STAGE(PG8_SA(1, 1), a1 + hstepA, voffA);
;             PG8_WAIT_V(8); PG8_WAIT_L(0); PG8_BAR; PG8_MMA(0, 0, At, B0); PG8_MMA(0, 1, At, B1); PG8_BAR; PG8_SCHED;
;     ...
;         else {
; #pragma unroll
;         for (int a = 0; a < 2; ++a)
; #pragma unroll
;             for (int b = 0; b < 2; ++b)
; #pragma unroll
;                 for (int m = 0; m < 4; ++m)
; #pragma unroll
;                     for (int n = 0; n < 2; ++n) acc[a][b][m][n] = (f32x4){0.f, 0.f, 0.f, 0.f};
;         }
;         cur = nxt; cA = nA; cB = nB; ++ui;
.LBB0_156:
	s_ashr_i32 s23, s22, 31
	s_lshl_b64 s[24:25], s[22:23], 19
	s_add_u32 s24, s38, s24
	s_addc_u32 s25, s39, s25
	s_and_b64 s[26:27], s[2:3], exec
	s_cselect_b32 s23, s25, s31
	s_cselect_b32 s61, s24, s30
	s_ashr_i32 s15, s14, 31
	s_lshl_b64 s[26:27], s[14:15], 19
	s_add_u32 s26, s40, s26
	s_addc_u32 s27, s41, s27
	s_and_b64 s[36:37], s[2:3], exec
	s_cselect_b32 s15, s27, s35
	s_cselect_b32 s62, s26, s34
	s_add_u32 s30, s30, 0x40080
	s_addc_u32 s31, s31, 0
	s_add_u32 s63, s34, 0x100
	v_mov_b32_e32 v0, 0
	s_addc_u32 s64, s35, 0
	s_mov_b32 s65, -2
	v_mov_b32_e32 v1, v0
	v_mov_b32_e32 v2, v0
	v_mov_b32_e32 v3, v0
	v_mov_b32_e32 v4, v0
	v_mov_b32_e32 v5, v0
	v_mov_b32_e32 v6, v0
	v_mov_b32_e32 v7, v0
	v_mov_b32_e32 v16, v0
	v_mov_b32_e32 v17, v0
	v_mov_b32_e32 v18, v0
	v_mov_b32_e32 v19, v0
	v_mov_b32_e32 v20, v0
	v_mov_b32_e32 v21, v0
	v_mov_b32_e32 v22, v0
	v_mov_b32_e32 v23, v0
	v_mov_b32_e32 v32, v0
	v_mov_b32_e32 v33, v0
	v_mov_b32_e32 v34, v0
	v_mov_b32_e32 v35, v0
	v_mov_b32_e32 v36, v0
	v_mov_b32_e32 v37, v0
	v_mov_b32_e32 v38, v0
	v_mov_b32_e32 v39, v0
	v_mov_b32_e32 v48, v0
	v_mov_b32_e32 v49, v0
	v_mov_b32_e32 v50, v0
	v_mov_b32_e32 v51, v0
	v_mov_b32_e32 v52, v0
	v_mov_b32_e32 v53, v0
	v_mov_b32_e32 v54, v0
	v_mov_b32_e32 v55, v0
	v_mov_b32_e32 v8, v0
	v_mov_b32_e32 v9, v0
	v_mov_b32_e32 v10, v0
	v_mov_b32_e32 v11, v0
	v_mov_b32_e32 v12, v0
	v_mov_b32_e32 v13, v0
	v_mov_b32_e32 v14, v0
	v_mov_b32_e32 v15, v0
	v_mov_b32_e32 v24, v0
	v_mov_b32_e32 v25, v0
	v_mov_b32_e32 v26, v0
	v_mov_b32_e32 v27, v0
	v_mov_b32_e32 v28, v0
	v_mov_b32_e32 v29, v0
	v_mov_b32_e32 v30, v0
	v_mov_b32_e32 v31, v0
	v_mov_b32_e32 v40, v0
	v_mov_b32_e32 v41, v0
	v_mov_b32_e32 v42, v0
	v_mov_b32_e32 v43, v0
	v_mov_b32_e32 v44, v0
	v_mov_b32_e32 v45, v0
	v_mov_b32_e32 v46, v0
	v_mov_b32_e32 v47, v0
	v_mov_b32_e32 v56, v0
	v_mov_b32_e32 v57, v0
	v_mov_b32_e32 v58, v0
	v_mov_b32_e32 v59, v0
	v_mov_b32_e32 v60, v0
	v_mov_b32_e32 v61, v0
	v_mov_b32_e32 v62, v0
	v_mov_b32_e32 v63, v0
	v_mov_b32_e32 v64, v0
	v_mov_b32_e32 v65, v0
	v_mov_b32_e32 v66, v0
	v_mov_b32_e32 v67, v0
	v_mov_b32_e32 v68, v0
	v_mov_b32_e32 v69, v0
	v_mov_b32_e32 v70, v0
	v_mov_b32_e32 v71, v0
	v_mov_b32_e32 v80, v0
	v_mov_b32_e32 v81, v0
	v_mov_b32_e32 v82, v0
	v_mov_b32_e32 v83, v0
	v_mov_b32_e32 v84, v0
	v_mov_b32_e32 v85, v0
	v_mov_b32_e32 v86, v0
	v_mov_b32_e32 v87, v0
	v_mov_b32_e32 v96, v0
	v_mov_b32_e32 v97, v0
	v_mov_b32_e32 v98, v0
	v_mov_b32_e32 v99, v0
	v_mov_b32_e32 v100, v0
	v_mov_b32_e32 v101, v0
	v_mov_b32_e32 v102, v0
	v_mov_b32_e32 v103, v0
	v_mov_b32_e32 v112, v0
	v_mov_b32_e32 v113, v0
	v_mov_b32_e32 v114, v0
	v_mov_b32_e32 v115, v0
	v_mov_b32_e32 v116, v0
	v_mov_b32_e32 v117, v0
	v_mov_b32_e32 v118, v0
	v_mov_b32_e32 v119, v0
	v_mov_b32_e32 v72, v0
	v_mov_b32_e32 v73, v0
	v_mov_b32_e32 v74, v0
	v_mov_b32_e32 v75, v0
	v_mov_b32_e32 v76, v0
	v_mov_b32_e32 v77, v0
	v_mov_b32_e32 v78, v0
	v_mov_b32_e32 v79, v0
	v_mov_b32_e32 v88, v0
	v_mov_b32_e32 v89, v0
	v_mov_b32_e32 v90, v0
	v_mov_b32_e32 v91, v0
	v_mov_b32_e32 v92, v0
	v_mov_b32_e32 v93, v0
	v_mov_b32_e32 v94, v0
	v_mov_b32_e32 v95, v0
	v_mov_b32_e32 v104, v0
	v_mov_b32_e32 v105, v0
	v_mov_b32_e32 v106, v0
	v_mov_b32_e32 v107, v0
	v_mov_b32_e32 v108, v0
	v_mov_b32_e32 v109, v0
	v_mov_b32_e32 v110, v0
	v_mov_b32_e32 v111, v0
	v_mov_b32_e32 v120, v0
	v_mov_b32_e32 v121, v0
	v_mov_b32_e32 v122, v0
	v_mov_b32_e32 v123, v0
	v_mov_b32_e32 v124, v0
	v_mov_b32_e32 v125, v0
	v_mov_b32_e32 v126, v0
	v_mov_b32_e32 v127, v0
	v_readfirstlane_b32 s98, v186
	s_lshr_b32 s98, s98, 8
	s_cmp_eq_u32 s98, 0
	s_cbranch_scc1 .Lprio_skip_0
	s_setprio 1
.Lprio_skip_0:
.LBB0_157:
	ds_read_b128 v[146:149], v169
	ds_read_b128 v[150:153], v169 offset:1024
	ds_read_b128 v[172:175], v169 offset:2048
	ds_read_b128 v[176:179], v169 offset:3072
	ds_read_b128 v[180:183], v170
	ds_read_b128 v[188:191], v170 offset:1024
	ds_read_b128 v[192:195], v170 offset:2048
	ds_read_b128 v[196:199], v170 offset:3072
	s_add_u32 s34, s30, 0xfffc0080
	s_addc_u32 s35, s31, -1
	s_cmp_eq_u32 s65, 12
	s_cselect_b32 s37, s23, s35
	s_cselect_b32 s36, s61, s34
	s_cselect_b32 s35, s15, s64
	s_cselect_b32 s34, s62, s63
	s_add_i32 m0, s29, 0xc000
	ds_read_b128 v[200:203], v171
	ds_read_b128 v[204:207], v171 offset:1024
	ds_read_b128 v[208:211], v171 offset:2048
	ds_read_b128 v[212:215], v171 offset:3072
	ds_read_b128 v[216:219], v171 offset:4096
	ds_read_b128 v[220:223], v171 offset:5120
	ds_read_b128 v[224:227], v171 offset:6144
	ds_read_b128 v[228:231], v171 offset:7168
	global_load_lds_dwordx4 v138, s[30:31]
	s_add_i32 m0, s29, 0xe000
	s_nop 0
	global_load_lds_dwordx4 v140, s[30:31]
	s_waitcnt vmcnt(8)
	s_waitcnt lgkmcnt(0)
	s_barrier
; #define PG8_STAGE(bufoff, gbase, voff) do { _Pragma("unroll") for (int _i = 0; _i < 2; ++_i) \
;         __builtin_amdgcn_global_load_lds((const unsigned*)((const char*)(gbase) + (voff)[_i]), (PG8_LAS unsigned*)(lds + (bufoff) + ldsw + _i * 8192), 16, 0, 0); } while (0)
; #define PG8_LDA(dst, b, h) do { _Pragma("unroll") for (int m = 0; m < 4; ++m) _Pragma("unroll") for (int k = 0; k < 2; ++k) dst[m][k] = *(const PG8_LAS bf16x8*)(lds + PG8_SA(b, h) + aoff + m * 2048 + k * 1024); } while (0)
; #define PG8_MMA(ai, bj, At, Bt) do { __builtin_amdgcn_s_setprio(1); _Pragma("unroll") for (int m = 0; m < 4; ++m) _Pragma("unroll") for (int n = 0; n < 2; ++n) _Pragma("unroll") for (int k = 0; k < 2; ++k) \
;         acc[ai][bj][m][n] = __builtin_amdgcn_mfma_f32_16x16x32_bf16(Bt[n][k], At[m][k], acc[ai][bj][m][n], 0, 0, 0); __builtin_amdgcn_s_setprio(0); } while (0)
; #define PG8_WAIT_V(n) asm volatile("s_waitcnt vmcnt(" #n ")" ::: "memory")
; #define PG8_WAIT_L(n) asm volatile("s_waitcnt lgkmcnt(" #n ")" ::: "memory")
; #define PG8_BAR __builtin_amdgcn_s_barrier()
; #define PG8_SCHED __builtin_amdgcn_sched_barrier(0)
; template <class Epi, class Sched, bool ALIGN_EPI = false, bool SP2 = false>
; __device__ __forceinline__ void gemm_phase(PG8_LAS unsigned char* lds, const Gemm g, const Sched S, const Epi E, const int tid) {
;     ...
;             PG8_WAIT_V(8); PG8_WAIT_L(0); PG8_BAR; PG8_MMA(0, 0, At, B0); PG8_MMA(0, 1, At, B1); PG8_BAR; PG8_SCHED;
;             PG8_LDA(At, 0, 1); PG8_STAGE(PG8_SB(0, 0), b2, voffB); PG8_STAGE(PG8_SB(0, 1), b2 + hstepB, voffB); PG8_STAGE(PG8_SA(0, 0), a2, voffA);
;             PG8_WAIT_V(8); PG8_WAIT_L(0); PG8_BAR; PG8_MMA(1, 0, At, B0); PG8_MMA(1, 1, At, B1); PG8_BAR; PG8_SCHED;
	s_waitcnt lgkmcnt(0)
	v_mfma_f32_16x16x32_bf16 v[124:127], v[146:149], v[200:203], v[124:127]
	v_mfma_f32_16x16x32_bf16 v[120:123], v[172:175], v[200:203], v[120:123]
	v_mfma_f32_16x16x32_bf16 v[108:111], v[146:149], v[208:211], v[108:111]
	v_mfma_f32_16x16x32_bf16 v[104:107], v[172:175], v[208:211], v[104:107]
	v_mfma_f32_16x16x32_bf16 v[92:95], v[146:149], v[216:219], v[92:95]
	v_mfma_f32_16x16x32_bf16 v[88:91], v[172:175], v[216:219], v[88:91]
	v_mfma_f32_16x16x32_bf16 v[76:79], v[146:149], v[224:227], v[76:79]
	v_mfma_f32_16x16x32_bf16 v[72:75], v[172:175], v[224:227], v[72:75]
	v_mfma_f32_16x16x32_bf16 v[124:127], v[150:153], v[204:207], v[124:127]
	v_mfma_f32_16x16x32_bf16 v[120:123], v[176:179], v[204:207], v[120:123]
	v_mfma_f32_16x16x32_bf16 v[108:111], v[150:153], v[212:215], v[108:111]
	v_mfma_f32_16x16x32_bf16 v[104:107], v[176:179], v[212:215], v[104:107]
	v_mfma_f32_16x16x32_bf16 v[92:95], v[150:153], v[220:223], v[92:95]
	v_mfma_f32_16x16x32_bf16 v[88:91], v[176:179], v[220:223], v[88:91]
	v_mfma_f32_16x16x32_bf16 v[76:79], v[150:153], v[228:231], v[76:79]
	v_mfma_f32_16x16x32_bf16 v[72:75], v[176:179], v[228:231], v[72:75]
	v_mfma_f32_16x16x32_bf16 v[116:119], v[180:183], v[200:203], v[116:119]
	v_mfma_f32_16x16x32_bf16 v[112:115], v[192:195], v[200:203], v[112:115]
	v_mfma_f32_16x16x32_bf16 v[100:103], v[180:183], v[208:211], v[100:103]
	v_mfma_f32_16x16x32_bf16 v[96:99], v[192:195], v[208:211], v[96:99]
	v_mfma_f32_16x16x32_bf16 v[84:87], v[180:183], v[216:219], v[84:87]
	v_mfma_f32_16x16x32_bf16 v[80:83], v[192:195], v[216:219], v[80:83]
	v_mfma_f32_16x16x32_bf16 v[68:71], v[180:183], v[224:227], v[68:71]
	v_mfma_f32_16x16x32_bf16 v[64:67], v[192:195], v[224:227], v[64:67]
	v_mfma_f32_16x16x32_bf16 v[116:119], v[188:191], v[204:207], v[116:119]
	v_mfma_f32_16x16x32_bf16 v[112:115], v[196:199], v[204:207], v[112:115]
	v_mfma_f32_16x16x32_bf16 v[100:103], v[188:191], v[212:215], v[100:103]
	v_mfma_f32_16x16x32_bf16 v[96:99], v[196:199], v[212:215], v[96:99]
	v_mfma_f32_16x16x32_bf16 v[84:87], v[188:191], v[220:223], v[84:87]
	v_mfma_f32_16x16x32_bf16 v[80:83], v[196:199], v[220:223], v[80:83]
	v_mfma_f32_16x16x32_bf16 v[68:71], v[188:191], v[228:231], v[68:71]
	v_mfma_f32_16x16x32_bf16 v[64:67], v[196:199], v[228:231], v[64:67]
	s_barrier
	s_add_u32 s98, s34, 0x80
	s_addc_u32 s99, s35, 0
	s_add_u32 s100, s36, 0x80
	s_addc_u32 s101, s37, 0
	s_add_i32 s66, s52, s13
	s_mov_b32 m0, s66
	ds_read_b128 v[200:203], v171 offset:16384
	ds_read_b128 v[204:207], v171 offset:17408
	ds_read_b128 v[208:211], v171 offset:18432
	ds_read_b128 v[212:215], v171 offset:19456
	ds_read_b128 v[216:219], v171 offset:20480
	ds_read_b128 v[220:223], v171 offset:21504
	ds_read_b128 v[224:227], v171 offset:22528
	ds_read_b128 v[228:231], v171 offset:23552
	global_load_lds_dwordx4 v130, s[34:35]
	s_add_i32 m0, s66, 0x2000
	s_add_u32 s66, s34, 0x40000
	s_addc_u32 s67, s35, 0
	s_add_i32 s69, s53, s13
	global_load_lds_dwordx4 v134, s[34:35]
	s_mov_b32 m0, s69
	s_nop 0
	global_load_lds_dwordx4 v130, s[66:67]
	s_add_i32 m0, s69, 0x2000
	s_nop 0
	global_load_lds_dwordx4 v134, s[66:67]
	s_mov_b32 m0, s29
	s_nop 0
	global_load_lds_dwordx4 v128, s[36:37]
	s_mov_b32 m0, s47
	s_nop 0
	global_load_lds_dwordx4 v132, s[36:37]
	s_waitcnt vmcnt(8)
	s_waitcnt lgkmcnt(0)
	s_barrier
	s_waitcnt lgkmcnt(0)
	v_mfma_f32_16x16x32_bf16 v[60:63], v[146:149], v[200:203], v[60:63]
	v_mfma_f32_16x16x32_bf16 v[56:59], v[172:175], v[200:203], v[56:59]
	v_mfma_f32_16x16x32_bf16 v[44:47], v[146:149], v[208:211], v[44:47]
	v_mfma_f32_16x16x32_bf16 v[40:43], v[172:175], v[208:211], v[40:43]
	v_mfma_f32_16x16x32_bf16 v[28:31], v[146:149], v[216:219], v[28:31]
	v_mfma_f32_16x16x32_bf16 v[24:27], v[172:175], v[216:219], v[24:27]
	v_mfma_f32_16x16x32_bf16 v[12:15], v[146:149], v[224:227], v[12:15]
	v_mfma_f32_16x16x32_bf16 v[8:11], v[172:175], v[224:227], v[8:11]
	v_mfma_f32_16x16x32_bf16 v[60:63], v[150:153], v[204:207], v[60:63]
	v_mfma_f32_16x16x32_bf16 v[56:59], v[176:179], v[204:207], v[56:59]
	v_mfma_f32_16x16x32_bf16 v[44:47], v[150:153], v[212:215], v[44:47]
	v_mfma_f32_16x16x32_bf16 v[40:43], v[176:179], v[212:215], v[40:43]
	v_mfma_f32_16x16x32_bf16 v[28:31], v[150:153], v[220:223], v[28:31]
	v_mfma_f32_16x16x32_bf16 v[24:27], v[176:179], v[220:223], v[24:27]
	v_mfma_f32_16x16x32_bf16 v[12:15], v[150:153], v[228:231], v[12:15]
	v_mfma_f32_16x16x32_bf16 v[8:11], v[176:179], v[228:231], v[8:11]
	v_mfma_f32_16x16x32_bf16 v[52:55], v[180:183], v[200:203], v[52:55]
	v_mfma_f32_16x16x32_bf16 v[48:51], v[192:195], v[200:203], v[48:51]
	v_mfma_f32_16x16x32_bf16 v[36:39], v[180:183], v[208:211], v[36:39]
	v_mfma_f32_16x16x32_bf16 v[32:35], v[192:195], v[208:211], v[32:35]
	v_mfma_f32_16x16x32_bf16 v[20:23], v[180:183], v[216:219], v[20:23]
	v_mfma_f32_16x16x32_bf16 v[16:19], v[192:195], v[216:219], v[16:19]
	v_mfma_f32_16x16x32_bf16 v[4:7], v[180:183], v[224:227], v[4:7]
	v_mfma_f32_16x16x32_bf16 v[0:3], v[192:195], v[224:227], v[0:3]
	v_mfma_f32_16x16x32_bf16 v[52:55], v[188:191], v[204:207], v[52:55]
	v_mfma_f32_16x16x32_bf16 v[48:51], v[196:199], v[204:207], v[48:51]
	v_mfma_f32_16x16x32_bf16 v[36:39], v[188:191], v[212:215], v[36:39]
	v_mfma_f32_16x16x32_bf16 v[32:35], v[196:199], v[212:215], v[32:35]
	v_mfma_f32_16x16x32_bf16 v[20:23], v[188:191], v[220:223], v[20:23]
	v_mfma_f32_16x16x32_bf16 v[16:19], v[196:199], v[220:223], v[16:19]
	v_mfma_f32_16x16x32_bf16 v[4:7], v[188:191], v[228:231], v[4:7]
	v_mfma_f32_16x16x32_bf16 v[0:3], v[196:199], v[228:231], v[0:3]
	s_barrier
; #define PG8_STAGE(bufoff, gbase, voff) do { _Pragma("unroll") for (int _i = 0; _i < 2; ++_i) \
;         __builtin_amdgcn_global_load_lds((const unsigned*)((const char*)(gbase) + (voff)[_i]), (PG8_LAS unsigned*)(lds + (bufoff) + ldsw + _i * 8192), 16, 0, 0); } while (0)
; #define PG8_LDA(dst, b, h) do { _Pragma("unroll") for (int m = 0; m < 4; ++m) _Pragma("unroll") for (int k = 0; k < 2; ++k) dst[m][k] = *(const PG8_LAS bf16x8*)(lds + PG8_SA(b, h) + aoff + m * 2048 + k * 1024); } while (0)
; #define PG8_LDB(dst, b, h) do { _Pragma("unroll") for (int n = 0; n < 2; ++n) _Pragma("unroll") for (int k = 0; k < 2; ++k) dst[n][k] = *(const PG8_LAS bf16x8*)(lds + PG8_SB(b, h) + boff + n * 2048 + k * 1024); } while (0)
; #define PG8_MMA(ai, bj, At, Bt) do { __builtin_amdgcn_s_setprio(1); _Pragma("unroll") for (int m = 0; m < 4; ++m) _Pragma("unroll") for (int n = 0; n < 2; ++n) _Pragma("unroll") for (int k = 0; k < 2; ++k) \
;         acc[ai][bj][m][n] = __builtin_amdgcn_mfma_f32_16x16x32_bf16(Bt[n][k], At[m][k], acc[ai][bj][m][n], 0, 0, 0); __builtin_amdgcn_s_setprio(0); } while (0)
; #define PG8_WAIT_V(n) asm volatile("s_waitcnt vmcnt(" #n ")" ::: "memory")
; #define PG8_WAIT_L(n) asm volatile("s_waitcnt lgkmcnt(" #n ")" ::: "memory")
; template <class Epi, class Sched, bool ALIGN_EPI = false, bool SP2 = false>
; __device__ __forceinline__ void gemm_phase(PG8_LAS unsigned char* lds, const Gemm g, const Sched S, const Epi E, const int tid) {
;     ...
;         for (int t = 0; t < nt; t += 2) {
;             const bool last = (t == nt - 2);
;             const char* a1 = cA + (size_t)(t + 1) * kstep;
;             const char* a2 = last ? nA : cA + (size_t)(t + 2) * kstep; const char* b2 = last ? nB : cB + (size_t)(t + 2) * kstep;
;             const char* a3 = a2 + kstep; const char* b3 = b2 + kstep;
;             if (last && has_next) S.a_ready(nxt);
;     ...
;             PG8_LDB(B0, 1, 0); PG8_LDB(B1, 1, 1); PG8_SCHED; PG8_LDA(At, 1, 0); PG8_STAGE(PG8_SA(0, 1), a2 + hstepA, voffA);
;             PG8_WAIT_V(8); PG8_WAIT_L(0); PG8_BAR; PG8_MMA(0, 0, At, B0); PG8_MMA(0, 1, At, B1); PG8_BAR; PG8_SCHED;
;             PG8_LDA(At, 1, 1); PG8_STAGE(PG8_SB(1, 0), b3, voffB); PG8_STAGE(PG8_SB(1, 1), b3 + hstepB, voffB); PG8_STAGE(PG8_SA(1, 0), a3, voffA);
;             PG8_WAIT_V(8); PG8_WAIT_L(0); PG8_BAR; PG8_MMA(1, 0, At, B0); PG8_MMA(1, 1, At, B1); PG8_BAR; PG8_SCHED;
	s_add_i32 s66, 0, 0x18000
	s_add_i32 s67, 0, 0x1c000
	v_add_u32_e32 v176, s66, v166
	v_add_u32_e32 v187, s67, v166
	ds_read_b128 v[146:149], v176
	ds_read_b128 v[150:153], v176 offset:1024
	ds_read_b128 v[172:175], v176 offset:2048
	ds_read_b128 v[176:179], v176 offset:3072
	ds_read_b128 v[180:183], v187
	ds_read_b128 v[188:191], v187 offset:1024
	ds_read_b128 v[192:195], v187 offset:2048
	ds_read_b128 v[196:199], v187 offset:3072
	s_add_u32 s36, s36, 0x40000
	s_addc_u32 s37, s37, 0
	s_mov_b32 m0, s48
	ds_read_b128 v[200:203], v171 offset:32768
	ds_read_b128 v[204:207], v171 offset:33792
	ds_read_b128 v[208:211], v171 offset:34816
	ds_read_b128 v[212:215], v171 offset:35840
	ds_read_b128 v[216:219], v171 offset:36864
	ds_read_b128 v[220:223], v171 offset:37888
	ds_read_b128 v[224:227], v171 offset:38912
	ds_read_b128 v[228:231], v171 offset:39936
	global_load_lds_dwordx4 v128, s[36:37]
	s_mov_b32 m0, s49
	s_nop 0
	global_load_lds_dwordx4 v132, s[36:37]
	s_waitcnt vmcnt(8)
	s_waitcnt lgkmcnt(0)
	s_barrier
	s_waitcnt lgkmcnt(0)
	v_mfma_f32_16x16x32_bf16 v[124:127], v[146:149], v[200:203], v[124:127]
	v_mfma_f32_16x16x32_bf16 v[120:123], v[172:175], v[200:203], v[120:123]
	v_mfma_f32_16x16x32_bf16 v[108:111], v[146:149], v[208:211], v[108:111]
	v_mfma_f32_16x16x32_bf16 v[104:107], v[172:175], v[208:211], v[104:107]
	v_mfma_f32_16x16x32_bf16 v[92:95], v[146:149], v[216:219], v[92:95]
	v_mfma_f32_16x16x32_bf16 v[88:91], v[172:175], v[216:219], v[88:91]
	v_mfma_f32_16x16x32_bf16 v[76:79], v[146:149], v[224:227], v[76:79]
	v_mfma_f32_16x16x32_bf16 v[72:75], v[172:175], v[224:227], v[72:75]
	v_mfma_f32_16x16x32_bf16 v[124:127], v[150:153], v[204:207], v[124:127]
	v_mfma_f32_16x16x32_bf16 v[120:123], v[176:179], v[204:207], v[120:123]
	v_mfma_f32_16x16x32_bf16 v[108:111], v[150:153], v[212:215], v[108:111]
	v_mfma_f32_16x16x32_bf16 v[104:107], v[176:179], v[212:215], v[104:107]
	v_mfma_f32_16x16x32_bf16 v[92:95], v[150:153], v[220:223], v[92:95]
	v_mfma_f32_16x16x32_bf16 v[88:91], v[176:179], v[220:223], v[88:91]
	v_mfma_f32_16x16x32_bf16 v[76:79], v[150:153], v[228:231], v[76:79]
	v_mfma_f32_16x16x32_bf16 v[72:75], v[176:179], v[228:231], v[72:75]
	v_mfma_f32_16x16x32_bf16 v[116:119], v[180:183], v[200:203], v[116:119]
	v_mfma_f32_16x16x32_bf16 v[112:115], v[192:195], v[200:203], v[112:115]
	v_mfma_f32_16x16x32_bf16 v[100:103], v[180:183], v[208:211], v[100:103]
	v_mfma_f32_16x16x32_bf16 v[96:99], v[192:195], v[208:211], v[96:99]
	v_mfma_f32_16x16x32_bf16 v[84:87], v[180:183], v[216:219], v[84:87]
	v_mfma_f32_16x16x32_bf16 v[80:83], v[192:195], v[216:219], v[80:83]
	v_mfma_f32_16x16x32_bf16 v[68:71], v[180:183], v[224:227], v[68:71]
	v_mfma_f32_16x16x32_bf16 v[64:67], v[192:195], v[224:227], v[64:67]
	v_mfma_f32_16x16x32_bf16 v[116:119], v[188:191], v[204:207], v[116:119]
	v_mfma_f32_16x16x32_bf16 v[112:115], v[196:199], v[204:207], v[112:115]
	v_mfma_f32_16x16x32_bf16 v[100:103], v[188:191], v[212:215], v[100:103]
	v_mfma_f32_16x16x32_bf16 v[96:99], v[196:199], v[212:215], v[96:99]
	v_mfma_f32_16x16x32_bf16 v[84:87], v[188:191], v[220:223], v[84:87]
	v_mfma_f32_16x16x32_bf16 v[80:83], v[196:199], v[220:223], v[80:83]
	v_mfma_f32_16x16x32_bf16 v[68:71], v[188:191], v[228:231], v[68:71]
	v_mfma_f32_16x16x32_bf16 v[64:67], v[196:199], v[228:231], v[64:67]
	s_barrier
	s_add_i32 s36, s66, s13
	s_mov_b32 m0, s36
	ds_read_b128 v[200:203], v171 offset:49152
	ds_read_b128 v[204:207], v171 offset:50176
	ds_read_b128 v[208:211], v171 offset:51200
	ds_read_b128 v[212:215], v171 offset:52224
	ds_read_b128 v[216:219], v171 offset:53248
	ds_read_b128 v[220:223], v171 offset:54272
	ds_read_b128 v[224:227], v171 offset:55296
	ds_read_b128 v[228:231], v171 offset:56320
	global_load_lds_dwordx4 v130, s[98:99]
	s_add_i32 m0, s36, 0x2000
	s_add_u32 s34, s34, 0x40080
	s_addc_u32 s35, s35, 0
	s_add_i32 s36, s67, s13
	global_load_lds_dwordx4 v134, s[98:99]
	s_mov_b32 m0, s36
	s_nop 0
	global_load_lds_dwordx4 v130, s[34:35]
	s_add_i32 m0, s36, 0x2000
	s_nop 0
	global_load_lds_dwordx4 v134, s[34:35]
	s_mov_b32 m0, s50
	s_nop 0
	global_load_lds_dwordx4 v128, s[100:101]
	s_mov_b32 m0, s51
	s_nop 0
	global_load_lds_dwordx4 v132, s[100:101]
	s_waitcnt vmcnt(8)
	s_waitcnt lgkmcnt(0)
	s_barrier
	s_waitcnt lgkmcnt(0)
	v_mfma_f32_16x16x32_bf16 v[60:63], v[146:149], v[200:203], v[60:63]
	v_mfma_f32_16x16x32_bf16 v[56:59], v[172:175], v[200:203], v[56:59]
	v_mfma_f32_16x16x32_bf16 v[44:47], v[146:149], v[208:211], v[44:47]
	v_mfma_f32_16x16x32_bf16 v[40:43], v[172:175], v[208:211], v[40:43]
	v_mfma_f32_16x16x32_bf16 v[28:31], v[146:149], v[216:219], v[28:31]
	v_mfma_f32_16x16x32_bf16 v[24:27], v[172:175], v[216:219], v[24:27]
	v_mfma_f32_16x16x32_bf16 v[12:15], v[146:149], v[224:227], v[12:15]
	v_mfma_f32_16x16x32_bf16 v[8:11], v[172:175], v[224:227], v[8:11]
	v_mfma_f32_16x16x32_bf16 v[60:63], v[150:153], v[204:207], v[60:63]
	v_mfma_f32_16x16x32_bf16 v[56:59], v[176:179], v[204:207], v[56:59]
	v_mfma_f32_16x16x32_bf16 v[44:47], v[150:153], v[212:215], v[44:47]
	v_mfma_f32_16x16x32_bf16 v[40:43], v[176:179], v[212:215], v[40:43]
	v_mfma_f32_16x16x32_bf16 v[28:31], v[150:153], v[220:223], v[28:31]
	v_mfma_f32_16x16x32_bf16 v[24:27], v[176:179], v[220:223], v[24:27]
	v_mfma_f32_16x16x32_bf16 v[12:15], v[150:153], v[228:231], v[12:15]
	v_mfma_f32_16x16x32_bf16 v[8:11], v[176:179], v[228:231], v[8:11]
	v_mfma_f32_16x16x32_bf16 v[52:55], v[180:183], v[200:203], v[52:55]
	v_mfma_f32_16x16x32_bf16 v[48:51], v[192:195], v[200:203], v[48:51]
	v_mfma_f32_16x16x32_bf16 v[36:39], v[180:183], v[208:211], v[36:39]
	v_mfma_f32_16x16x32_bf16 v[32:35], v[192:195], v[208:211], v[32:35]
	v_mfma_f32_16x16x32_bf16 v[20:23], v[180:183], v[216:219], v[20:23]
	v_mfma_f32_16x16x32_bf16 v[16:19], v[192:195], v[216:219], v[16:19]
	v_mfma_f32_16x16x32_bf16 v[4:7], v[180:183], v[224:227], v[4:7]
	v_mfma_f32_16x16x32_bf16 v[0:3], v[192:195], v[224:227], v[0:3]
	v_mfma_f32_16x16x32_bf16 v[52:55], v[188:191], v[204:207], v[52:55]
	v_mfma_f32_16x16x32_bf16 v[48:51], v[196:199], v[204:207], v[48:51]
	v_mfma_f32_16x16x32_bf16 v[36:39], v[188:191], v[212:215], v[36:39]
	v_mfma_f32_16x16x32_bf16 v[32:35], v[196:199], v[212:215], v[32:35]
	v_mfma_f32_16x16x32_bf16 v[20:23], v[188:191], v[220:223], v[20:23]
	v_mfma_f32_16x16x32_bf16 v[16:19], v[196:199], v[220:223], v[16:19]
	v_mfma_f32_16x16x32_bf16 v[4:7], v[188:191], v[228:231], v[4:7]
	v_mfma_f32_16x16x32_bf16 v[0:3], v[196:199], v[228:231], v[0:3]
	s_barrier
	s_add_i32 s65, s65, 2
	s_add_u32 s30, s30, 0x100
	s_addc_u32 s31, s31, 0
	s_add_u32 s63, s63, 0x100
	s_addc_u32 s64, s64, 0
	s_cmp_gt_u32 s65, 13
	s_cbranch_scc0 .LBB0_157
	s_setprio 0
	s_and_b64 vcc, exec, s[10:11]
	s_cbranch_vccz .LBB0_160
	s_barrier

; #define PG8_STAGE(bufoff, gbase, voff) do { _Pragma("unroll") for (int _i = 0; _i < 2; ++_i) \
;         __builtin_amdgcn_global_load_lds((const unsigned*)((const char*)(gbase) + (voff)[_i]), (PG8_LAS unsigned*)(lds + (bufoff) + ldsw + _i * 8192), 16, 0, 0); } while (0)
; #define PG8_LDA(dst, b, h) do { _Pragma("unroll") for (int m = 0; m < 4; ++m) _Pragma("unroll") for (int k = 0; k < 2; ++k) dst[m][k] = *(const PG8_LAS bf16x8*)(lds + PG8_SA(b, h) + aoff + m * 2048 + k * 1024); } while (0)
; #define PG8_LDB(dst, b, h) do { _Pragma("unroll") for (int n = 0; n < 2; ++n) _Pragma("unroll") for (int k = 0; k < 2; ++k) dst[n][k] = *(const PG8_LAS bf16x8*)(lds + PG8_SB(b, h) + boff + n * 2048 + k * 1024); } while (0)
; #define PG8_WAIT_V(n) asm volatile("s_waitcnt vmcnt(" #n ")" ::: "memory")
; #define PG8_WAIT_L(n) asm volatile("s_waitcnt lgkmcnt(" #n ")" ::: "memory")
; #define PG8_BAR __builtin_amdgcn_s_barrier()
; template <class Epi, class Sched, bool ALIGN_EPI = false, bool SP2 = false>
; __device__ __forceinline__ void gemm_phase(PG8_LAS unsigned char* lds, const Gemm g, const Sched S, const Epi E, const int tid) {
;     ...
;         const char* nA = has_next ? (const char*)g.A + (size_t)nxt.pm * tstepA + (size_t)nxt.pn * apn : cA; const char* nB = has_next ? (const char*)g.Bt + (size_t)nxt.pn * bpn : cB;
;         for (int t = 0; t < nt; t += 2) {
;             const bool last = (t == nt - 2);
;             const char* a1 = cA + (size_t)(t + 1) * kstep;
;             const char* a2 = last ? nA : cA + (size_t)(t + 2) * kstep; const char* b2 = last ? nB : cB + (size_t)(t + 2) * kstep;
;             const char* a3 = a2 + kstep; const char* b3 = b2 + kstep;
;             if (last && has_next) S.a_ready(nxt);
;             if constexpr (SP2) {
;             PG8_LDB(B0, 0, 0); PG8_LDB(B1, 0, 1); PG8_SCHED; PG8_LDA(At, 0, 0); PG8_STAGE(PG8_SA(1, 1), a1 + hstepA, voffA);
;             PG8_WAIT_V(8); PG8_WAIT_L(0); PG8_BAR; PG8_MMA(0, 0, At, B0); PG8_MMA(0, 1, At, B1); PG8_BAR; PG8_SCHED;
;     ...
; #pragma unroll
;         for (int a = 0; a < 2; ++a)
; #pragma unroll
;             for (int b = 0; b < 2; ++b)
; #pragma unroll
;                 for (int m = 0; m < 4; ++m)
; #pragma unroll
;                     for (int n = 0; n < 2; ++n) acc[a][b][m][n] = (f32x4){0.f, 0.f, 0.f, 0.f};
;         }
;         cur = nxt; cA = nA; cB = nB; ++ui;
.LBB0_203:
	s_ashr_i32 s37, s36, 31
	s_lshl_b64 s[40:41], s[36:37], 19
	s_add_u32 s40, s18, s40
	s_addc_u32 s41, s19, s41
	s_and_b64 s[46:47], s[38:39], exec
	s_cselect_b32 s37, s41, s51
	s_cselect_b32 s76, s40, s50
	s_ashr_i32 s35, s34, 31
	s_lshl_b64 s[46:47], s[34:35], 19
	s_add_u32 s46, s62, s46
	s_addc_u32 s47, s63, s47
	s_and_b64 s[54:55], s[38:39], exec
	s_cselect_b32 s35, s47, s53
	s_cselect_b32 s77, s46, s52
	s_add_u32 s50, s50, 0x40080
	s_addc_u32 s51, s51, 0
	s_add_u32 s78, s52, 0x100
	v_mov_b32_e32 v0, 0
	s_addc_u32 s79, s53, 0
	s_mov_b32 s80, -2
	v_mov_b32_e32 v1, v0
	v_mov_b32_e32 v2, v0
	v_mov_b32_e32 v3, v0
	v_mov_b32_e32 v4, v0
	v_mov_b32_e32 v5, v0
	v_mov_b32_e32 v6, v0
	v_mov_b32_e32 v7, v0
	v_mov_b32_e32 v8, v0
	v_mov_b32_e32 v9, v0
	v_mov_b32_e32 v10, v0
	v_mov_b32_e32 v11, v0
	v_mov_b32_e32 v16, v0
	v_mov_b32_e32 v17, v0
	v_mov_b32_e32 v18, v0
	v_mov_b32_e32 v19, v0
	v_mov_b32_e32 v24, v0
	v_mov_b32_e32 v25, v0
	v_mov_b32_e32 v26, v0
	v_mov_b32_e32 v27, v0
	v_mov_b32_e32 v32, v0
	v_mov_b32_e32 v33, v0
	v_mov_b32_e32 v34, v0
	v_mov_b32_e32 v35, v0
	v_mov_b32_e32 v40, v0
	v_mov_b32_e32 v41, v0
	v_mov_b32_e32 v42, v0
	v_mov_b32_e32 v43, v0
	v_mov_b32_e32 v48, v0
	v_mov_b32_e32 v49, v0
	v_mov_b32_e32 v50, v0
	v_mov_b32_e32 v51, v0
	v_mov_b32_e32 v12, v0
	v_mov_b32_e32 v13, v0
	v_mov_b32_e32 v14, v0
	v_mov_b32_e32 v15, v0
	v_mov_b32_e32 v20, v0
	v_mov_b32_e32 v21, v0
	v_mov_b32_e32 v22, v0
	v_mov_b32_e32 v23, v0
	v_mov_b32_e32 v28, v0
	v_mov_b32_e32 v29, v0
	v_mov_b32_e32 v30, v0
	v_mov_b32_e32 v31, v0
	v_mov_b32_e32 v36, v0
	v_mov_b32_e32 v37, v0
	v_mov_b32_e32 v38, v0
	v_mov_b32_e32 v39, v0
	v_mov_b32_e32 v44, v0
	v_mov_b32_e32 v45, v0
	v_mov_b32_e32 v46, v0
	v_mov_b32_e32 v47, v0
	v_mov_b32_e32 v52, v0
	v_mov_b32_e32 v53, v0
	v_mov_b32_e32 v54, v0
	v_mov_b32_e32 v55, v0
	v_mov_b32_e32 v56, v0
	v_mov_b32_e32 v57, v0
	v_mov_b32_e32 v58, v0
	v_mov_b32_e32 v59, v0
	v_mov_b32_e32 v60, v0
	v_mov_b32_e32 v61, v0
	v_mov_b32_e32 v62, v0
	v_mov_b32_e32 v63, v0
	v_mov_b32_e32 v64, v0
	v_mov_b32_e32 v65, v0
	v_mov_b32_e32 v66, v0
	v_mov_b32_e32 v67, v0
	v_mov_b32_e32 v68, v0
	v_mov_b32_e32 v69, v0
	v_mov_b32_e32 v70, v0
	v_mov_b32_e32 v71, v0
	v_mov_b32_e32 v76, v0
	v_mov_b32_e32 v77, v0
	v_mov_b32_e32 v78, v0
	v_mov_b32_e32 v79, v0
	v_mov_b32_e32 v84, v0
	v_mov_b32_e32 v85, v0
	v_mov_b32_e32 v86, v0
	v_mov_b32_e32 v87, v0
	v_mov_b32_e32 v92, v0
	v_mov_b32_e32 v93, v0
	v_mov_b32_e32 v94, v0
	v_mov_b32_e32 v95, v0
	v_mov_b32_e32 v100, v0
	v_mov_b32_e32 v101, v0
	v_mov_b32_e32 v102, v0
	v_mov_b32_e32 v103, v0
	v_mov_b32_e32 v108, v0
	v_mov_b32_e32 v109, v0
	v_mov_b32_e32 v110, v0
	v_mov_b32_e32 v111, v0
	v_mov_b32_e32 v116, v0
	v_mov_b32_e32 v117, v0
	v_mov_b32_e32 v118, v0
	v_mov_b32_e32 v119, v0
	v_mov_b32_e32 v72, v0
	v_mov_b32_e32 v73, v0
	v_mov_b32_e32 v74, v0
	v_mov_b32_e32 v75, v0
	v_mov_b32_e32 v80, v0
	v_mov_b32_e32 v81, v0
	v_mov_b32_e32 v82, v0
	v_mov_b32_e32 v83, v0
	v_mov_b32_e32 v88, v0
	v_mov_b32_e32 v89, v0
	v_mov_b32_e32 v90, v0
	v_mov_b32_e32 v91, v0
	v_mov_b32_e32 v96, v0
	v_mov_b32_e32 v97, v0
	v_mov_b32_e32 v98, v0
	v_mov_b32_e32 v99, v0
	v_mov_b32_e32 v104, v0
	v_mov_b32_e32 v105, v0
	v_mov_b32_e32 v106, v0
	v_mov_b32_e32 v107, v0
	v_mov_b32_e32 v112, v0
	v_mov_b32_e32 v113, v0
	v_mov_b32_e32 v114, v0
	v_mov_b32_e32 v115, v0
	v_mov_b32_e32 v120, v0
	v_mov_b32_e32 v121, v0
	v_mov_b32_e32 v122, v0
	v_mov_b32_e32 v123, v0
	v_mov_b32_e32 v124, v0
	v_mov_b32_e32 v125, v0
	v_mov_b32_e32 v126, v0
	v_mov_b32_e32 v127, v0
	v_readfirstlane_b32 s98, v186
	s_lshr_b32 s98, s98, 8
	s_cmp_eq_u32 s98, 0
	s_cbranch_scc1 .Lprio_skip_1
	s_setprio 1
.Lprio_skip_1:
.LBB0_204:
	ds_read_b128 v[150:153], v147
	ds_read_b128 v[166:169], v147 offset:1024
	ds_read_b128 v[170:173], v147 offset:2048
	ds_read_b128 v[174:177], v147 offset:3072
	ds_read_b128 v[178:181], v148
	ds_read_b128 v[182:185], v148 offset:1024
	ds_read_b128 v[188:191], v148 offset:2048
	ds_read_b128 v[192:195], v148 offset:3072
	s_add_u32 s52, s50, 0xfffc0080
	s_addc_u32 s53, s51, -1
	s_cmp_eq_u32 s80, 12
	s_cselect_b32 s55, s37, s53
	s_cselect_b32 s54, s76, s52
	s_cselect_b32 s53, s35, s79
	s_cselect_b32 s52, s77, s78
	s_add_i32 m0, s49, 0xc000
	ds_read_b128 v[196:199], v149
	ds_read_b128 v[200:203], v149 offset:1024
	ds_read_b128 v[204:207], v149 offset:2048
	ds_read_b128 v[208:211], v149 offset:3072
	ds_read_b128 v[212:215], v149 offset:4096
	ds_read_b128 v[216:219], v149 offset:5120
	ds_read_b128 v[220:223], v149 offset:6144
	ds_read_b128 v[224:227], v149 offset:7168
	global_load_lds_dwordx4 v138, s[50:51]
	s_add_i32 m0, s49, 0xe000
	s_nop 0
	global_load_lds_dwordx4 v140, s[50:51]
	s_waitcnt vmcnt(8)
	s_waitcnt lgkmcnt(0)
	s_barrier
; #define PG8_STAGE(bufoff, gbase, voff) do { _Pragma("unroll") for (int _i = 0; _i < 2; ++_i) \
;         __builtin_amdgcn_global_load_lds((const unsigned*)((const char*)(gbase) + (voff)[_i]), (PG8_LAS unsigned*)(lds + (bufoff) + ldsw + _i * 8192), 16, 0, 0); } while (0)
; #define PG8_LDA(dst, b, h) do { _Pragma("unroll") for (int m = 0; m < 4; ++m) _Pragma("unroll") for (int k = 0; k < 2; ++k) dst[m][k] = *(const PG8_LAS bf16x8*)(lds + PG8_SA(b, h) + aoff + m * 2048 + k * 1024); } while (0)
; #define PG8_MMA(ai, bj, At, Bt) do { __builtin_amdgcn_s_setprio(1); _Pragma("unroll") for (int m = 0; m < 4; ++m) _Pragma("unroll") for (int n = 0; n < 2; ++n) _Pragma("unroll") for (int k = 0; k < 2; ++k) \
;         acc[ai][bj][m][n] = __builtin_amdgcn_mfma_f32_16x16x32_bf16(Bt[n][k], At[m][k], acc[ai][bj][m][n], 0, 0, 0); __builtin_amdgcn_s_setprio(0); } while (0)
; #define PG8_WAIT_V(n) asm volatile("s_waitcnt vmcnt(" #n ")" ::: "memory")
; #define PG8_WAIT_L(n) asm volatile("s_waitcnt lgkmcnt(" #n ")" ::: "memory")
; #define PG8_BAR __builtin_amdgcn_s_barrier()
; #define PG8_SCHED __builtin_amdgcn_sched_barrier(0)
; template <class Epi, class Sched, bool ALIGN_EPI = false, bool SP2 = false>
; __device__ __forceinline__ void gemm_phase(PG8_LAS unsigned char* lds, const Gemm g, const Sched S, const Epi E, const int tid) {
;     ...
;             PG8_WAIT_V(8); PG8_WAIT_L(0); PG8_BAR; PG8_MMA(0, 0, At, B0); PG8_MMA(0, 1, At, B1); PG8_BAR; PG8_SCHED;
;             PG8_LDA(At, 0, 1); PG8_STAGE(PG8_SB(0, 0), b2, voffB); PG8_STAGE(PG8_SB(0, 1), b2 + hstepB, voffB); PG8_STAGE(PG8_SA(0, 0), a2, voffA);
;             PG8_WAIT_V(8); PG8_WAIT_L(0); PG8_BAR; PG8_MMA(1, 0, At, B0); PG8_MMA(1, 1, At, B1); PG8_BAR; PG8_SCHED;
	s_waitcnt lgkmcnt(0)
	v_mfma_f32_16x16x32_bf16 v[124:127], v[150:153], v[196:199], v[124:127]
	v_mfma_f32_16x16x32_bf16 v[120:123], v[170:173], v[196:199], v[120:123]
	v_mfma_f32_16x16x32_bf16 v[112:115], v[150:153], v[204:207], v[112:115]
	v_mfma_f32_16x16x32_bf16 v[104:107], v[170:173], v[204:207], v[104:107]
	v_mfma_f32_16x16x32_bf16 v[96:99], v[150:153], v[212:215], v[96:99]
	v_mfma_f32_16x16x32_bf16 v[88:91], v[170:173], v[212:215], v[88:91]
	v_mfma_f32_16x16x32_bf16 v[80:83], v[150:153], v[220:223], v[80:83]
	v_mfma_f32_16x16x32_bf16 v[72:75], v[170:173], v[220:223], v[72:75]
	v_mfma_f32_16x16x32_bf16 v[124:127], v[166:169], v[200:203], v[124:127]
	v_mfma_f32_16x16x32_bf16 v[120:123], v[174:177], v[200:203], v[120:123]
	v_mfma_f32_16x16x32_bf16 v[112:115], v[166:169], v[208:211], v[112:115]
	v_mfma_f32_16x16x32_bf16 v[104:107], v[174:177], v[208:211], v[104:107]
	v_mfma_f32_16x16x32_bf16 v[96:99], v[166:169], v[216:219], v[96:99]
	v_mfma_f32_16x16x32_bf16 v[88:91], v[174:177], v[216:219], v[88:91]
	v_mfma_f32_16x16x32_bf16 v[80:83], v[166:169], v[224:227], v[80:83]
	v_mfma_f32_16x16x32_bf16 v[72:75], v[174:177], v[224:227], v[72:75]
	v_mfma_f32_16x16x32_bf16 v[116:119], v[178:181], v[196:199], v[116:119]
	v_mfma_f32_16x16x32_bf16 v[108:111], v[188:191], v[196:199], v[108:111]
	v_mfma_f32_16x16x32_bf16 v[100:103], v[178:181], v[204:207], v[100:103]
	v_mfma_f32_16x16x32_bf16 v[92:95], v[188:191], v[204:207], v[92:95]
	v_mfma_f32_16x16x32_bf16 v[84:87], v[178:181], v[212:215], v[84:87]
	v_mfma_f32_16x16x32_bf16 v[76:79], v[188:191], v[212:215], v[76:79]
	v_mfma_f32_16x16x32_bf16 v[68:71], v[178:181], v[220:223], v[68:71]
	v_mfma_f32_16x16x32_bf16 v[64:67], v[188:191], v[220:223], v[64:67]
	v_mfma_f32_16x16x32_bf16 v[116:119], v[182:185], v[200:203], v[116:119]
	v_mfma_f32_16x16x32_bf16 v[108:111], v[192:195], v[200:203], v[108:111]
	v_mfma_f32_16x16x32_bf16 v[100:103], v[182:185], v[208:211], v[100:103]
	v_mfma_f32_16x16x32_bf16 v[92:95], v[192:195], v[208:211], v[92:95]
	v_mfma_f32_16x16x32_bf16 v[84:87], v[182:185], v[216:219], v[84:87]
	v_mfma_f32_16x16x32_bf16 v[76:79], v[192:195], v[216:219], v[76:79]
	v_mfma_f32_16x16x32_bf16 v[68:71], v[182:185], v[224:227], v[68:71]
	v_mfma_f32_16x16x32_bf16 v[64:67], v[192:195], v[224:227], v[64:67]
	s_barrier
	s_add_u32 s98, s52, 0x80
	s_addc_u32 s99, s53, 0
	s_add_u32 s100, s54, 0x80
	s_addc_u32 s101, s55, 0
	s_add_i32 s81, s73, s65
	s_mov_b32 m0, s81
	ds_read_b128 v[196:199], v149 offset:16384
	ds_read_b128 v[200:203], v149 offset:17408
	ds_read_b128 v[204:207], v149 offset:18432
	ds_read_b128 v[208:211], v149 offset:19456
	ds_read_b128 v[212:215], v149 offset:20480
	ds_read_b128 v[216:219], v149 offset:21504
	ds_read_b128 v[220:223], v149 offset:22528
	ds_read_b128 v[224:227], v149 offset:23552
	global_load_lds_dwordx4 v130, s[52:53]
	s_add_i32 m0, s81, 0x2000
	s_add_u32 s82, s52, 0x40000
	s_addc_u32 s83, s53, 0
	s_add_i32 s81, s74, s65
	global_load_lds_dwordx4 v134, s[52:53]
	s_mov_b32 m0, s81
	s_nop 0
	global_load_lds_dwordx4 v130, s[82:83]
	s_add_i32 m0, s81, 0x2000
	s_nop 0
	global_load_lds_dwordx4 v134, s[82:83]
	s_mov_b32 m0, s49
	s_nop 0
	global_load_lds_dwordx4 v128, s[54:55]
	s_mov_b32 m0, s66
	s_nop 0
	global_load_lds_dwordx4 v132, s[54:55]
	s_waitcnt vmcnt(8)
	s_waitcnt lgkmcnt(0)
	s_barrier
	s_waitcnt lgkmcnt(0)
	v_mfma_f32_16x16x32_bf16 v[60:63], v[150:153], v[196:199], v[60:63]
	v_mfma_f32_16x16x32_bf16 v[56:59], v[170:173], v[196:199], v[56:59]
	v_mfma_f32_16x16x32_bf16 v[52:55], v[150:153], v[204:207], v[52:55]
	v_mfma_f32_16x16x32_bf16 v[44:47], v[170:173], v[204:207], v[44:47]
	v_mfma_f32_16x16x32_bf16 v[36:39], v[150:153], v[212:215], v[36:39]
	v_mfma_f32_16x16x32_bf16 v[28:31], v[170:173], v[212:215], v[28:31]
	v_mfma_f32_16x16x32_bf16 v[20:23], v[150:153], v[220:223], v[20:23]
	v_mfma_f32_16x16x32_bf16 v[12:15], v[170:173], v[220:223], v[12:15]
	v_mfma_f32_16x16x32_bf16 v[60:63], v[166:169], v[200:203], v[60:63]
	v_mfma_f32_16x16x32_bf16 v[56:59], v[174:177], v[200:203], v[56:59]
	v_mfma_f32_16x16x32_bf16 v[52:55], v[166:169], v[208:211], v[52:55]
	v_mfma_f32_16x16x32_bf16 v[44:47], v[174:177], v[208:211], v[44:47]
	v_mfma_f32_16x16x32_bf16 v[36:39], v[166:169], v[216:219], v[36:39]
	v_mfma_f32_16x16x32_bf16 v[28:31], v[174:177], v[216:219], v[28:31]
	v_mfma_f32_16x16x32_bf16 v[20:23], v[166:169], v[224:227], v[20:23]
	v_mfma_f32_16x16x32_bf16 v[12:15], v[174:177], v[224:227], v[12:15]
	v_mfma_f32_16x16x32_bf16 v[48:51], v[178:181], v[196:199], v[48:51]
	v_mfma_f32_16x16x32_bf16 v[40:43], v[188:191], v[196:199], v[40:43]
	v_mfma_f32_16x16x32_bf16 v[32:35], v[178:181], v[204:207], v[32:35]
	v_mfma_f32_16x16x32_bf16 v[24:27], v[188:191], v[204:207], v[24:27]
	v_mfma_f32_16x16x32_bf16 v[16:19], v[178:181], v[212:215], v[16:19]
	v_mfma_f32_16x16x32_bf16 v[8:11], v[188:191], v[212:215], v[8:11]
	v_mfma_f32_16x16x32_bf16 v[4:7], v[178:181], v[220:223], v[4:7]
	v_mfma_f32_16x16x32_bf16 v[0:3], v[188:191], v[220:223], v[0:3]
	v_mfma_f32_16x16x32_bf16 v[48:51], v[182:185], v[200:203], v[48:51]
	v_mfma_f32_16x16x32_bf16 v[40:43], v[192:195], v[200:203], v[40:43]
	v_mfma_f32_16x16x32_bf16 v[32:35], v[182:185], v[208:211], v[32:35]
	v_mfma_f32_16x16x32_bf16 v[24:27], v[192:195], v[208:211], v[24:27]
	v_mfma_f32_16x16x32_bf16 v[16:19], v[182:185], v[216:219], v[16:19]
	v_mfma_f32_16x16x32_bf16 v[8:11], v[192:195], v[216:219], v[8:11]
	v_mfma_f32_16x16x32_bf16 v[4:7], v[182:185], v[224:227], v[4:7]
	v_mfma_f32_16x16x32_bf16 v[0:3], v[192:195], v[224:227], v[0:3]
	s_barrier
; #define PG8_STAGE(bufoff, gbase, voff) do { _Pragma("unroll") for (int _i = 0; _i < 2; ++_i) \
;         __builtin_amdgcn_global_load_lds((const unsigned*)((const char*)(gbase) + (voff)[_i]), (PG8_LAS unsigned*)(lds + (bufoff) + ldsw + _i * 8192), 16, 0, 0); } while (0)
; #define PG8_LDA(dst, b, h) do { _Pragma("unroll") for (int m = 0; m < 4; ++m) _Pragma("unroll") for (int k = 0; k < 2; ++k) dst[m][k] = *(const PG8_LAS bf16x8*)(lds + PG8_SA(b, h) + aoff + m * 2048 + k * 1024); } while (0)
; #define PG8_LDB(dst, b, h) do { _Pragma("unroll") for (int n = 0; n < 2; ++n) _Pragma("unroll") for (int k = 0; k < 2; ++k) dst[n][k] = *(const PG8_LAS bf16x8*)(lds + PG8_SB(b, h) + boff + n * 2048 + k * 1024); } while (0)
; #define PG8_MMA(ai, bj, At, Bt) do { __builtin_amdgcn_s_setprio(1); _Pragma("unroll") for (int m = 0; m < 4; ++m) _Pragma("unroll") for (int n = 0; n < 2; ++n) _Pragma("unroll") for (int k = 0; k < 2; ++k) \
;         acc[ai][bj][m][n] = __builtin_amdgcn_mfma_f32_16x16x32_bf16(Bt[n][k], At[m][k], acc[ai][bj][m][n], 0, 0, 0); __builtin_amdgcn_s_setprio(0); } while (0)
; #define PG8_WAIT_V(n) asm volatile("s_waitcnt vmcnt(" #n ")" ::: "memory")
; #define PG8_WAIT_L(n) asm volatile("s_waitcnt lgkmcnt(" #n ")" ::: "memory")
; template <class Epi, class Sched, bool ALIGN_EPI = false, bool SP2 = false>
; __device__ __forceinline__ void gemm_phase(PG8_LAS unsigned char* lds, const Gemm g, const Sched S, const Epi E, const int tid) {
;     ...
;         for (int t = 0; t < nt; t += 2) {
;             const bool last = (t == nt - 2);
;             const char* a1 = cA + (size_t)(t + 1) * kstep;
;             const char* a2 = last ? nA : cA + (size_t)(t + 2) * kstep; const char* b2 = last ? nB : cB + (size_t)(t + 2) * kstep;
;             const char* a3 = a2 + kstep; const char* b3 = b2 + kstep;
;             if (last && has_next) S.a_ready(nxt);
;     ...
;             PG8_LDB(B0, 1, 0); PG8_LDB(B1, 1, 1); PG8_SCHED; PG8_LDA(At, 1, 0); PG8_STAGE(PG8_SA(0, 1), a2 + hstepA, voffA);
;             PG8_WAIT_V(8); PG8_WAIT_L(0); PG8_BAR; PG8_MMA(0, 0, At, B0); PG8_MMA(0, 1, At, B1); PG8_BAR; PG8_SCHED;
;             PG8_LDA(At, 1, 1); PG8_STAGE(PG8_SB(1, 0), b3, voffB); PG8_STAGE(PG8_SB(1, 1), b3 + hstepB, voffB); PG8_STAGE(PG8_SA(1, 0), a3, voffA);
;             PG8_WAIT_V(8); PG8_WAIT_L(0); PG8_BAR; PG8_MMA(1, 0, At, B0); PG8_MMA(1, 1, At, B1); PG8_BAR; PG8_SCHED;
	s_add_i32 s81, 0, 0x18000
	v_add_u32_e32 v165, s81, v145
	s_add_i32 s82, 0, 0x1c000
	ds_read_b128 v[150:153], v165
	ds_read_b128 v[166:169], v165 offset:1024
	ds_read_b128 v[170:173], v165 offset:2048
	ds_read_b128 v[174:177], v165 offset:3072
	v_add_u32_e32 v165, s82, v145
	ds_read_b128 v[178:181], v165
	ds_read_b128 v[182:185], v165 offset:1024
	ds_read_b128 v[188:191], v165 offset:2048
	ds_read_b128 v[192:195], v165 offset:3072
	s_add_u32 s54, s54, 0x40000
	s_addc_u32 s55, s55, 0
	s_mov_b32 m0, s67
	ds_read_b128 v[196:199], v149 offset:32768
	ds_read_b128 v[200:203], v149 offset:33792
	ds_read_b128 v[204:207], v149 offset:34816
	ds_read_b128 v[208:211], v149 offset:35840
	ds_read_b128 v[212:215], v149 offset:36864
	ds_read_b128 v[216:219], v149 offset:37888
	ds_read_b128 v[220:223], v149 offset:38912
	ds_read_b128 v[224:227], v149 offset:39936
	global_load_lds_dwordx4 v128, s[54:55]
	s_mov_b32 m0, s69
	s_nop 0
	global_load_lds_dwordx4 v132, s[54:55]
	s_waitcnt vmcnt(8)
	s_waitcnt lgkmcnt(0)
	s_barrier
	s_waitcnt lgkmcnt(0)
	v_mfma_f32_16x16x32_bf16 v[124:127], v[150:153], v[196:199], v[124:127]
	v_mfma_f32_16x16x32_bf16 v[120:123], v[170:173], v[196:199], v[120:123]
	v_mfma_f32_16x16x32_bf16 v[112:115], v[150:153], v[204:207], v[112:115]
	v_mfma_f32_16x16x32_bf16 v[104:107], v[170:173], v[204:207], v[104:107]
	v_mfma_f32_16x16x32_bf16 v[96:99], v[150:153], v[212:215], v[96:99]
	v_mfma_f32_16x16x32_bf16 v[88:91], v[170:173], v[212:215], v[88:91]
	v_mfma_f32_16x16x32_bf16 v[80:83], v[150:153], v[220:223], v[80:83]
	v_mfma_f32_16x16x32_bf16 v[72:75], v[170:173], v[220:223], v[72:75]
	v_mfma_f32_16x16x32_bf16 v[124:127], v[166:169], v[200:203], v[124:127]
	v_mfma_f32_16x16x32_bf16 v[120:123], v[174:177], v[200:203], v[120:123]
	v_mfma_f32_16x16x32_bf16 v[112:115], v[166:169], v[208:211], v[112:115]
	v_mfma_f32_16x16x32_bf16 v[104:107], v[174:177], v[208:211], v[104:107]
	v_mfma_f32_16x16x32_bf16 v[96:99], v[166:169], v[216:219], v[96:99]
	v_mfma_f32_16x16x32_bf16 v[88:91], v[174:177], v[216:219], v[88:91]
	v_mfma_f32_16x16x32_bf16 v[80:83], v[166:169], v[224:227], v[80:83]
	v_mfma_f32_16x16x32_bf16 v[72:75], v[174:177], v[224:227], v[72:75]
	v_mfma_f32_16x16x32_bf16 v[116:119], v[178:181], v[196:199], v[116:119]
	v_mfma_f32_16x16x32_bf16 v[108:111], v[188:191], v[196:199], v[108:111]
	v_mfma_f32_16x16x32_bf16 v[100:103], v[178:181], v[204:207], v[100:103]
	v_mfma_f32_16x16x32_bf16 v[92:95], v[188:191], v[204:207], v[92:95]
	v_mfma_f32_16x16x32_bf16 v[84:87], v[178:181], v[212:215], v[84:87]
	v_mfma_f32_16x16x32_bf16 v[76:79], v[188:191], v[212:215], v[76:79]
	v_mfma_f32_16x16x32_bf16 v[68:71], v[178:181], v[220:223], v[68:71]
	v_mfma_f32_16x16x32_bf16 v[64:67], v[188:191], v[220:223], v[64:67]
	v_mfma_f32_16x16x32_bf16 v[116:119], v[182:185], v[200:203], v[116:119]
	v_mfma_f32_16x16x32_bf16 v[108:111], v[192:195], v[200:203], v[108:111]
	v_mfma_f32_16x16x32_bf16 v[100:103], v[182:185], v[208:211], v[100:103]
	v_mfma_f32_16x16x32_bf16 v[92:95], v[192:195], v[208:211], v[92:95]
	v_mfma_f32_16x16x32_bf16 v[84:87], v[182:185], v[216:219], v[84:87]
	v_mfma_f32_16x16x32_bf16 v[76:79], v[192:195], v[216:219], v[76:79]
	v_mfma_f32_16x16x32_bf16 v[68:71], v[182:185], v[224:227], v[68:71]
	v_mfma_f32_16x16x32_bf16 v[64:67], v[192:195], v[224:227], v[64:67]
	s_barrier
	s_add_i32 s54, s81, s65
	s_mov_b32 m0, s54
	ds_read_b128 v[196:199], v149 offset:49152
	ds_read_b128 v[200:203], v149 offset:50176
	ds_read_b128 v[204:207], v149 offset:51200
	ds_read_b128 v[208:211], v149 offset:52224
	ds_read_b128 v[212:215], v149 offset:53248
	ds_read_b128 v[216:219], v149 offset:54272
	ds_read_b128 v[220:223], v149 offset:55296
	ds_read_b128 v[224:227], v149 offset:56320
	global_load_lds_dwordx4 v130, s[98:99]
	s_add_i32 m0, s54, 0x2000
	s_add_u32 s52, s52, 0x40080
	s_addc_u32 s53, s53, 0
	s_add_i32 s54, s82, s65
	global_load_lds_dwordx4 v134, s[98:99]
	s_mov_b32 m0, s54
	s_nop 0
	global_load_lds_dwordx4 v130, s[52:53]
	s_add_i32 m0, s54, 0x2000
	s_nop 0
	global_load_lds_dwordx4 v134, s[52:53]
	s_mov_b32 m0, s71
	s_nop 0
	global_load_lds_dwordx4 v128, s[100:101]
	s_mov_b32 m0, s72
	s_nop 0
	global_load_lds_dwordx4 v132, s[100:101]
	s_waitcnt vmcnt(8)
	s_waitcnt lgkmcnt(0)
	s_barrier
	s_waitcnt lgkmcnt(0)
	v_mfma_f32_16x16x32_bf16 v[60:63], v[150:153], v[196:199], v[60:63]
	v_mfma_f32_16x16x32_bf16 v[56:59], v[170:173], v[196:199], v[56:59]
	v_mfma_f32_16x16x32_bf16 v[52:55], v[150:153], v[204:207], v[52:55]
	v_mfma_f32_16x16x32_bf16 v[44:47], v[170:173], v[204:207], v[44:47]
	v_mfma_f32_16x16x32_bf16 v[36:39], v[150:153], v[212:215], v[36:39]
	v_mfma_f32_16x16x32_bf16 v[28:31], v[170:173], v[212:215], v[28:31]
	v_mfma_f32_16x16x32_bf16 v[20:23], v[150:153], v[220:223], v[20:23]
	v_mfma_f32_16x16x32_bf16 v[12:15], v[170:173], v[220:223], v[12:15]
	v_mfma_f32_16x16x32_bf16 v[60:63], v[166:169], v[200:203], v[60:63]
	v_mfma_f32_16x16x32_bf16 v[56:59], v[174:177], v[200:203], v[56:59]
	v_mfma_f32_16x16x32_bf16 v[52:55], v[166:169], v[208:211], v[52:55]
	v_mfma_f32_16x16x32_bf16 v[44:47], v[174:177], v[208:211], v[44:47]
	v_mfma_f32_16x16x32_bf16 v[36:39], v[166:169], v[216:219], v[36:39]
	v_mfma_f32_16x16x32_bf16 v[28:31], v[174:177], v[216:219], v[28:31]
	v_mfma_f32_16x16x32_bf16 v[20:23], v[166:169], v[224:227], v[20:23]
	v_mfma_f32_16x16x32_bf16 v[12:15], v[174:177], v[224:227], v[12:15]
	v_mfma_f32_16x16x32_bf16 v[48:51], v[178:181], v[196:199], v[48:51]
	v_mfma_f32_16x16x32_bf16 v[40:43], v[188:191], v[196:199], v[40:43]
	v_mfma_f32_16x16x32_bf16 v[32:35], v[178:181], v[204:207], v[32:35]
	v_mfma_f32_16x16x32_bf16 v[24:27], v[188:191], v[204:207], v[24:27]
	v_mfma_f32_16x16x32_bf16 v[16:19], v[178:181], v[212:215], v[16:19]
	v_mfma_f32_16x16x32_bf16 v[8:11], v[188:191], v[212:215], v[8:11]
	v_mfma_f32_16x16x32_bf16 v[4:7], v[178:181], v[220:223], v[4:7]
	v_mfma_f32_16x16x32_bf16 v[0:3], v[188:191], v[220:223], v[0:3]
	v_mfma_f32_16x16x32_bf16 v[48:51], v[182:185], v[200:203], v[48:51]
	v_mfma_f32_16x16x32_bf16 v[40:43], v[192:195], v[200:203], v[40:43]
	v_mfma_f32_16x16x32_bf16 v[32:35], v[182:185], v[208:211], v[32:35]
	v_mfma_f32_16x16x32_bf16 v[24:27], v[192:195], v[208:211], v[24:27]
	v_mfma_f32_16x16x32_bf16 v[16:19], v[182:185], v[216:219], v[16:19]
	v_mfma_f32_16x16x32_bf16 v[8:11], v[192:195], v[216:219], v[8:11]
	v_mfma_f32_16x16x32_bf16 v[4:7], v[182:185], v[224:227], v[4:7]
	v_mfma_f32_16x16x32_bf16 v[0:3], v[192:195], v[224:227], v[0:3]
	s_barrier
	s_add_i32 s80, s80, 2
	s_add_u32 s50, s50, 0x100
	s_addc_u32 s51, s51, 0
	s_add_u32 s78, s78, 0x100
	s_addc_u32 s79, s79, 0
	s_cmp_gt_u32 s80, 13
	s_cbranch_scc0 .LBB0_204
	s_setprio 0
	s_and_b64 vcc, exec, s[10:11]
	s_cbranch_vccz .LBB0_207
	s_barrier

; #define PG8_STAGE(bufoff, gbase, voff) do { _Pragma("unroll") for (int _i = 0; _i < 2; ++_i) \
;         __builtin_amdgcn_global_load_lds((const unsigned*)((const char*)(gbase) + (voff)[_i]), (PG8_LAS unsigned*)(lds + (bufoff) + ldsw + _i * 8192), 16, 0, 0); } while (0)
; #define PG8_LDA(dst, b, h) do { _Pragma("unroll") for (int m = 0; m < 4; ++m) _Pragma("unroll") for (int k = 0; k < 2; ++k) dst[m][k] = *(const PG8_LAS bf16x8*)(lds + PG8_SA(b, h) + aoff + m * 2048 + k * 1024); } while (0)
; #define PG8_LDB(dst, b, h) do { _Pragma("unroll") for (int n = 0; n < 2; ++n) _Pragma("unroll") for (int k = 0; k < 2; ++k) dst[n][k] = *(const PG8_LAS bf16x8*)(lds + PG8_SB(b, h) + boff + n * 2048 + k * 1024); } while (0)
; #define PG8_WAIT_V(n) asm volatile("s_waitcnt vmcnt(" #n ")" ::: "memory")
; #define PG8_WAIT_L(n) asm volatile("s_waitcnt lgkmcnt(" #n ")" ::: "memory")
; #define PG8_BAR __builtin_amdgcn_s_barrier()
; template <class Epi, class Sched, bool ALIGN_EPI = false, bool SP2 = false>
; __device__ __forceinline__ void gemm_phase(PG8_LAS unsigned char* lds, const Gemm g, const Sched S, const Epi E, const int tid) {
;     ...
;         const char* nA = has_next ? (const char*)g.A + (size_t)nxt.pm * tstepA + (size_t)nxt.pn * apn : cA; const char* nB = has_next ? (const char*)g.Bt + (size_t)nxt.pn * bpn : cB;
;         for (int t = 0; t < nt; t += 2) {
;             const bool last = (t == nt - 2);
;             const char* a1 = cA + (size_t)(t + 1) * kstep;
;             const char* a2 = last ? nA : cA + (size_t)(t + 2) * kstep; const char* b2 = last ? nB : cB + (size_t)(t + 2) * kstep;
;             const char* a3 = a2 + kstep; const char* b3 = b2 + kstep;
;             if (last && has_next) S.a_ready(nxt);
;             if constexpr (SP2) {
;             PG8_LDB(B0, 0, 0); PG8_LDB(B1, 0, 1); PG8_SCHED; PG8_LDA(At, 0, 0); PG8_STAGE(PG8_SA(1, 1), a1 + hstepA, voffA);
;             PG8_WAIT_V(8); PG8_WAIT_L(0); PG8_BAR; PG8_MMA(0, 0, At, B0); PG8_MMA(0, 1, At, B1); PG8_BAR; PG8_SCHED;
;     ...
; #pragma unroll
;         for (int a = 0; a < 2; ++a)
; #pragma unroll
;             for (int b = 0; b < 2; ++b)
; #pragma unroll
;                 for (int m = 0; m < 4; ++m)
; #pragma unroll
;                     for (int n = 0; n < 2; ++n) acc[a][b][m][n] = (f32x4){0.f, 0.f, 0.f, 0.f};
;         }
;         cur = nxt; cA = nA; cB = nB; ++ui;
.LBB0_219:
	s_ashr_i32 s37, s36, 31
	s_lshl_b64 s[40:41], s[36:37], 19
	s_add_u32 s40, s59, s40
	s_addc_u32 s41, s60, s41
	s_and_b64 s[46:47], s[38:39], exec
	s_cselect_b32 s37, s41, s51
	s_cselect_b32 s73, s40, s50
	s_ashr_i32 s35, s34, 31
	s_lshl_b64 s[46:47], s[34:35], 19
	s_add_u32 s46, s18, s46
	s_addc_u32 s47, s19, s47
	s_and_b64 s[54:55], s[38:39], exec
	s_cselect_b32 s35, s47, s53
	s_cselect_b32 s74, s46, s52
	s_add_u32 s50, s50, 0x40080
	s_addc_u32 s51, s51, 0
	s_add_u32 s75, s52, 0x100
	v_mov_b32_e32 v0, 0
	s_addc_u32 s76, s53, 0
	s_mov_b32 s77, -2
	v_mov_b32_e32 v1, v0
	v_mov_b32_e32 v2, v0
	v_mov_b32_e32 v3, v0
	v_mov_b32_e32 v4, v0
	v_mov_b32_e32 v5, v0
	v_mov_b32_e32 v6, v0
	v_mov_b32_e32 v7, v0
	v_mov_b32_e32 v8, v0
	v_mov_b32_e32 v9, v0
	v_mov_b32_e32 v10, v0
	v_mov_b32_e32 v11, v0
	v_mov_b32_e32 v16, v0
	v_mov_b32_e32 v17, v0
	v_mov_b32_e32 v18, v0
	v_mov_b32_e32 v19, v0
	v_mov_b32_e32 v24, v0
	v_mov_b32_e32 v25, v0
	v_mov_b32_e32 v26, v0
	v_mov_b32_e32 v27, v0
	v_mov_b32_e32 v32, v0
	v_mov_b32_e32 v33, v0
	v_mov_b32_e32 v34, v0
	v_mov_b32_e32 v35, v0
	v_mov_b32_e32 v40, v0
	v_mov_b32_e32 v41, v0
	v_mov_b32_e32 v42, v0
	v_mov_b32_e32 v43, v0
	v_mov_b32_e32 v48, v0
	v_mov_b32_e32 v49, v0
	v_mov_b32_e32 v50, v0
	v_mov_b32_e32 v51, v0
	v_mov_b32_e32 v12, v0
	v_mov_b32_e32 v13, v0
	v_mov_b32_e32 v14, v0
	v_mov_b32_e32 v15, v0
	v_mov_b32_e32 v20, v0
	v_mov_b32_e32 v21, v0
	v_mov_b32_e32 v22, v0
	v_mov_b32_e32 v23, v0
	v_mov_b32_e32 v28, v0
	v_mov_b32_e32 v29, v0
	v_mov_b32_e32 v30, v0
	v_mov_b32_e32 v31, v0
	v_mov_b32_e32 v36, v0
	v_mov_b32_e32 v37, v0
	v_mov_b32_e32 v38, v0
	v_mov_b32_e32 v39, v0
	v_mov_b32_e32 v44, v0
	v_mov_b32_e32 v45, v0
	v_mov_b32_e32 v46, v0
	v_mov_b32_e32 v47, v0
	v_mov_b32_e32 v52, v0
	v_mov_b32_e32 v53, v0
	v_mov_b32_e32 v54, v0
	v_mov_b32_e32 v55, v0
	v_mov_b32_e32 v56, v0
	v_mov_b32_e32 v57, v0
	v_mov_b32_e32 v58, v0
	v_mov_b32_e32 v59, v0
	v_mov_b32_e32 v60, v0
	v_mov_b32_e32 v61, v0
	v_mov_b32_e32 v62, v0
	v_mov_b32_e32 v63, v0
	v_mov_b32_e32 v64, v0
	v_mov_b32_e32 v65, v0
	v_mov_b32_e32 v66, v0
	v_mov_b32_e32 v67, v0
	v_mov_b32_e32 v68, v0
	v_mov_b32_e32 v69, v0
	v_mov_b32_e32 v70, v0
	v_mov_b32_e32 v71, v0
	v_mov_b32_e32 v76, v0
	v_mov_b32_e32 v77, v0
	v_mov_b32_e32 v78, v0
	v_mov_b32_e32 v79, v0
	v_mov_b32_e32 v84, v0
	v_mov_b32_e32 v85, v0
	v_mov_b32_e32 v86, v0
	v_mov_b32_e32 v87, v0
	v_mov_b32_e32 v92, v0
	v_mov_b32_e32 v93, v0
	v_mov_b32_e32 v94, v0
	v_mov_b32_e32 v95, v0
	v_mov_b32_e32 v100, v0
	v_mov_b32_e32 v101, v0
	v_mov_b32_e32 v102, v0
	v_mov_b32_e32 v103, v0
	v_mov_b32_e32 v108, v0
	v_mov_b32_e32 v109, v0
	v_mov_b32_e32 v110, v0
	v_mov_b32_e32 v111, v0
	v_mov_b32_e32 v116, v0
	v_mov_b32_e32 v117, v0
	v_mov_b32_e32 v118, v0
	v_mov_b32_e32 v119, v0
	v_mov_b32_e32 v72, v0
	v_mov_b32_e32 v73, v0
	v_mov_b32_e32 v74, v0
	v_mov_b32_e32 v75, v0
	v_mov_b32_e32 v80, v0
	v_mov_b32_e32 v81, v0
	v_mov_b32_e32 v82, v0
	v_mov_b32_e32 v83, v0
	v_mov_b32_e32 v88, v0
	v_mov_b32_e32 v89, v0
	v_mov_b32_e32 v90, v0
	v_mov_b32_e32 v91, v0
	v_mov_b32_e32 v96, v0
	v_mov_b32_e32 v97, v0
	v_mov_b32_e32 v98, v0
	v_mov_b32_e32 v99, v0
	v_mov_b32_e32 v104, v0
	v_mov_b32_e32 v105, v0
	v_mov_b32_e32 v106, v0
	v_mov_b32_e32 v107, v0
	v_mov_b32_e32 v112, v0
	v_mov_b32_e32 v113, v0
	v_mov_b32_e32 v114, v0
	v_mov_b32_e32 v115, v0
	v_mov_b32_e32 v120, v0
	v_mov_b32_e32 v121, v0
	v_mov_b32_e32 v122, v0
	v_mov_b32_e32 v123, v0
	v_mov_b32_e32 v124, v0
	v_mov_b32_e32 v125, v0
	v_mov_b32_e32 v126, v0
	v_mov_b32_e32 v127, v0
	v_readfirstlane_b32 s98, v186
	s_lshr_b32 s98, s98, 8
	s_cmp_eq_u32 s98, 0
	s_cbranch_scc1 .Lprio_skip_2
	s_setprio 1
.Lprio_skip_2:
.LBB0_220:
	ds_read_b128 v[148:151], v145
	ds_read_b128 v[152:155], v145 offset:1024
	ds_read_b128 v[156:159], v145 offset:2048
	ds_read_b128 v[160:163], v145 offset:3072
	ds_read_b128 v[164:167], v146
	ds_read_b128 v[168:171], v146 offset:1024
	ds_read_b128 v[172:175], v146 offset:2048
	ds_read_b128 v[176:179], v146 offset:3072
	s_add_u32 s52, s50, 0xfffc0080
	s_addc_u32 s53, s51, -1
	s_cmp_eq_u32 s77, 12
	s_cselect_b32 s55, s37, s53
	s_cselect_b32 s54, s73, s52
	s_cselect_b32 s53, s35, s76
	s_cselect_b32 s52, s74, s75
	s_add_i32 m0, s49, 0xc000
	ds_read_b128 v[180:183], v147
	ds_read_b128 v[188:191], v147 offset:1024
	ds_read_b128 v[192:195], v147 offset:2048
	ds_read_b128 v[196:199], v147 offset:3072
	ds_read_b128 v[200:203], v147 offset:4096
	ds_read_b128 v[204:207], v147 offset:5120
	ds_read_b128 v[208:211], v147 offset:6144
	ds_read_b128 v[212:215], v147 offset:7168
	global_load_lds_dwordx4 v136, s[50:51]
	s_add_i32 m0, s49, 0xe000
	s_nop 0
	global_load_lds_dwordx4 v138, s[50:51]
	s_waitcnt vmcnt(8)
	s_waitcnt lgkmcnt(0)
	s_barrier
; #define PG8_STAGE(bufoff, gbase, voff) do { _Pragma("unroll") for (int _i = 0; _i < 2; ++_i) \
;         __builtin_amdgcn_global_load_lds((const unsigned*)((const char*)(gbase) + (voff)[_i]), (PG8_LAS unsigned*)(lds + (bufoff) + ldsw + _i * 8192), 16, 0, 0); } while (0)
; #define PG8_LDA(dst, b, h) do { _Pragma("unroll") for (int m = 0; m < 4; ++m) _Pragma("unroll") for (int k = 0; k < 2; ++k) dst[m][k] = *(const PG8_LAS bf16x8*)(lds + PG8_SA(b, h) + aoff + m * 2048 + k * 1024); } while (0)
; #define PG8_MMA(ai, bj, At, Bt) do { __builtin_amdgcn_s_setprio(1); _Pragma("unroll") for (int m = 0; m < 4; ++m) _Pragma("unroll") for (int n = 0; n < 2; ++n) _Pragma("unroll") for (int k = 0; k < 2; ++k) \
;         acc[ai][bj][m][n] = __builtin_amdgcn_mfma_f32_16x16x32_bf16(Bt[n][k], At[m][k], acc[ai][bj][m][n], 0, 0, 0); __builtin_amdgcn_s_setprio(0); } while (0)
; #define PG8_WAIT_V(n) asm volatile("s_waitcnt vmcnt(" #n ")" ::: "memory")
; #define PG8_WAIT_L(n) asm volatile("s_waitcnt lgkmcnt(" #n ")" ::: "memory")
; #define PG8_BAR __builtin_amdgcn_s_barrier()
; #define PG8_SCHED __builtin_amdgcn_sched_barrier(0)
; template <class Epi, class Sched, bool ALIGN_EPI = false, bool SP2 = false>
; __device__ __forceinline__ void gemm_phase(PG8_LAS unsigned char* lds, const Gemm g, const Sched S, const Epi E, const int tid) {
;     ...
;             PG8_WAIT_V(8); PG8_WAIT_L(0); PG8_BAR; PG8_MMA(0, 0, At, B0); PG8_MMA(0, 1, At, B1); PG8_BAR; PG8_SCHED;
;             PG8_LDA(At, 0, 1); PG8_STAGE(PG8_SB(0, 0), b2, voffB); PG8_STAGE(PG8_SB(0, 1), b2 + hstepB, voffB); PG8_STAGE(PG8_SA(0, 0), a2, voffA);
;             PG8_WAIT_V(8); PG8_WAIT_L(0); PG8_BAR; PG8_MMA(1, 0, At, B0); PG8_MMA(1, 1, At, B1); PG8_BAR; PG8_SCHED;
	s_waitcnt lgkmcnt(0)
	v_mfma_f32_16x16x32_bf16 v[124:127], v[148:151], v[180:183], v[124:127]
	v_mfma_f32_16x16x32_bf16 v[120:123], v[156:159], v[180:183], v[120:123]
	v_mfma_f32_16x16x32_bf16 v[112:115], v[148:151], v[192:195], v[112:115]
	v_mfma_f32_16x16x32_bf16 v[104:107], v[156:159], v[192:195], v[104:107]
	v_mfma_f32_16x16x32_bf16 v[96:99], v[148:151], v[200:203], v[96:99]
	v_mfma_f32_16x16x32_bf16 v[88:91], v[156:159], v[200:203], v[88:91]
	v_mfma_f32_16x16x32_bf16 v[80:83], v[148:151], v[208:211], v[80:83]
	v_mfma_f32_16x16x32_bf16 v[72:75], v[156:159], v[208:211], v[72:75]
	v_mfma_f32_16x16x32_bf16 v[124:127], v[152:155], v[188:191], v[124:127]
	v_mfma_f32_16x16x32_bf16 v[120:123], v[160:163], v[188:191], v[120:123]
	v_mfma_f32_16x16x32_bf16 v[112:115], v[152:155], v[196:199], v[112:115]
	v_mfma_f32_16x16x32_bf16 v[104:107], v[160:163], v[196:199], v[104:107]
	v_mfma_f32_16x16x32_bf16 v[96:99], v[152:155], v[204:207], v[96:99]
	v_mfma_f32_16x16x32_bf16 v[88:91], v[160:163], v[204:207], v[88:91]
	v_mfma_f32_16x16x32_bf16 v[80:83], v[152:155], v[212:215], v[80:83]
	v_mfma_f32_16x16x32_bf16 v[72:75], v[160:163], v[212:215], v[72:75]
	v_mfma_f32_16x16x32_bf16 v[116:119], v[164:167], v[180:183], v[116:119]
	v_mfma_f32_16x16x32_bf16 v[108:111], v[172:175], v[180:183], v[108:111]
	v_mfma_f32_16x16x32_bf16 v[100:103], v[164:167], v[192:195], v[100:103]
	v_mfma_f32_16x16x32_bf16 v[92:95], v[172:175], v[192:195], v[92:95]
	v_mfma_f32_16x16x32_bf16 v[84:87], v[164:167], v[200:203], v[84:87]
	v_mfma_f32_16x16x32_bf16 v[76:79], v[172:175], v[200:203], v[76:79]
	v_mfma_f32_16x16x32_bf16 v[68:71], v[164:167], v[208:211], v[68:71]
	v_mfma_f32_16x16x32_bf16 v[64:67], v[172:175], v[208:211], v[64:67]
	v_mfma_f32_16x16x32_bf16 v[116:119], v[168:171], v[188:191], v[116:119]
	v_mfma_f32_16x16x32_bf16 v[108:111], v[176:179], v[188:191], v[108:111]
	v_mfma_f32_16x16x32_bf16 v[100:103], v[168:171], v[196:199], v[100:103]
	v_mfma_f32_16x16x32_bf16 v[92:95], v[176:179], v[196:199], v[92:95]
	v_mfma_f32_16x16x32_bf16 v[84:87], v[168:171], v[204:207], v[84:87]
	v_mfma_f32_16x16x32_bf16 v[76:79], v[176:179], v[204:207], v[76:79]
	v_mfma_f32_16x16x32_bf16 v[68:71], v[168:171], v[212:215], v[68:71]
	v_mfma_f32_16x16x32_bf16 v[64:67], v[176:179], v[212:215], v[64:67]
	s_barrier
	s_add_u32 s98, s52, 0x80
	s_addc_u32 s99, s53, 0
	s_add_u32 s100, s54, 0x80
	s_addc_u32 s101, s55, 0
	s_add_i32 s78, s70, s62
	s_mov_b32 m0, s78
	ds_read_b128 v[180:183], v147 offset:16384
	ds_read_b128 v[188:191], v147 offset:17408
	ds_read_b128 v[192:195], v147 offset:18432
	ds_read_b128 v[196:199], v147 offset:19456
	ds_read_b128 v[200:203], v147 offset:20480
	ds_read_b128 v[204:207], v147 offset:21504
	ds_read_b128 v[208:211], v147 offset:22528
	ds_read_b128 v[212:215], v147 offset:23552
	global_load_lds_dwordx4 v130, s[52:53]
	s_add_i32 m0, s78, 0x2000
	s_add_u32 s78, s52, 0x40000
	s_addc_u32 s79, s53, 0
	s_add_i32 s80, s71, s62
	global_load_lds_dwordx4 v134, s[52:53]
	s_mov_b32 m0, s80
	s_nop 0
	global_load_lds_dwordx4 v130, s[78:79]
	s_add_i32 m0, s80, 0x2000
	s_nop 0
	global_load_lds_dwordx4 v134, s[78:79]
	s_mov_b32 m0, s49
	s_nop 0
	global_load_lds_dwordx4 v128, s[54:55]
	s_mov_b32 m0, s63
	s_nop 0
	global_load_lds_dwordx4 v132, s[54:55]
	s_waitcnt vmcnt(8)
	s_waitcnt lgkmcnt(0)
	s_barrier
	s_waitcnt lgkmcnt(0)
	v_mfma_f32_16x16x32_bf16 v[60:63], v[148:151], v[180:183], v[60:63]
	v_mfma_f32_16x16x32_bf16 v[56:59], v[156:159], v[180:183], v[56:59]
	v_mfma_f32_16x16x32_bf16 v[52:55], v[148:151], v[192:195], v[52:55]
	v_mfma_f32_16x16x32_bf16 v[44:47], v[156:159], v[192:195], v[44:47]
	v_mfma_f32_16x16x32_bf16 v[36:39], v[148:151], v[200:203], v[36:39]
	v_mfma_f32_16x16x32_bf16 v[28:31], v[156:159], v[200:203], v[28:31]
	v_mfma_f32_16x16x32_bf16 v[20:23], v[148:151], v[208:211], v[20:23]
	v_mfma_f32_16x16x32_bf16 v[12:15], v[156:159], v[208:211], v[12:15]
	v_mfma_f32_16x16x32_bf16 v[60:63], v[152:155], v[188:191], v[60:63]
	v_mfma_f32_16x16x32_bf16 v[56:59], v[160:163], v[188:191], v[56:59]
	v_mfma_f32_16x16x32_bf16 v[52:55], v[152:155], v[196:199], v[52:55]
	v_mfma_f32_16x16x32_bf16 v[44:47], v[160:163], v[196:199], v[44:47]
	v_mfma_f32_16x16x32_bf16 v[36:39], v[152:155], v[204:207], v[36:39]
	v_mfma_f32_16x16x32_bf16 v[28:31], v[160:163], v[204:207], v[28:31]
	v_mfma_f32_16x16x32_bf16 v[20:23], v[152:155], v[212:215], v[20:23]
	v_mfma_f32_16x16x32_bf16 v[12:15], v[160:163], v[212:215], v[12:15]
	v_mfma_f32_16x16x32_bf16 v[48:51], v[164:167], v[180:183], v[48:51]
	v_mfma_f32_16x16x32_bf16 v[40:43], v[172:175], v[180:183], v[40:43]
	v_mfma_f32_16x16x32_bf16 v[32:35], v[164:167], v[192:195], v[32:35]
	v_mfma_f32_16x16x32_bf16 v[24:27], v[172:175], v[192:195], v[24:27]
	v_mfma_f32_16x16x32_bf16 v[16:19], v[164:167], v[200:203], v[16:19]
	v_mfma_f32_16x16x32_bf16 v[8:11], v[172:175], v[200:203], v[8:11]
	v_mfma_f32_16x16x32_bf16 v[4:7], v[164:167], v[208:211], v[4:7]
	v_mfma_f32_16x16x32_bf16 v[0:3], v[172:175], v[208:211], v[0:3]
	v_mfma_f32_16x16x32_bf16 v[48:51], v[168:171], v[188:191], v[48:51]
	v_mfma_f32_16x16x32_bf16 v[40:43], v[176:179], v[188:191], v[40:43]
	v_mfma_f32_16x16x32_bf16 v[32:35], v[168:171], v[196:199], v[32:35]
	v_mfma_f32_16x16x32_bf16 v[24:27], v[176:179], v[196:199], v[24:27]
	v_mfma_f32_16x16x32_bf16 v[16:19], v[168:171], v[204:207], v[16:19]
	v_mfma_f32_16x16x32_bf16 v[8:11], v[176:179], v[204:207], v[8:11]
	v_mfma_f32_16x16x32_bf16 v[4:7], v[168:171], v[212:215], v[4:7]
	v_mfma_f32_16x16x32_bf16 v[0:3], v[176:179], v[212:215], v[0:3]
	s_barrier
; #define PG8_STAGE(bufoff, gbase, voff) do { _Pragma("unroll") for (int _i = 0; _i < 2; ++_i) \
;         __builtin_amdgcn_global_load_lds((const unsigned*)((const char*)(gbase) + (voff)[_i]), (PG8_LAS unsigned*)(lds + (bufoff) + ldsw + _i * 8192), 16, 0, 0); } while (0)
; #define PG8_LDA(dst, b, h) do { _Pragma("unroll") for (int m = 0; m < 4; ++m) _Pragma("unroll") for (int k = 0; k < 2; ++k) dst[m][k] = *(const PG8_LAS bf16x8*)(lds + PG8_SA(b, h) + aoff + m * 2048 + k * 1024); } while (0)
; #define PG8_LDB(dst, b, h) do { _Pragma("unroll") for (int n = 0; n < 2; ++n) _Pragma("unroll") for (int k = 0; k < 2; ++k) dst[n][k] = *(const PG8_LAS bf16x8*)(lds + PG8_SB(b, h) + boff + n * 2048 + k * 1024); } while (0)
; #define PG8_MMA(ai, bj, At, Bt) do { __builtin_amdgcn_s_setprio(1); _Pragma("unroll") for (int m = 0; m < 4; ++m) _Pragma("unroll") for (int n = 0; n < 2; ++n) _Pragma("unroll") for (int k = 0; k < 2; ++k) \
;         acc[ai][bj][m][n] = __builtin_amdgcn_mfma_f32_16x16x32_bf16(Bt[n][k], At[m][k], acc[ai][bj][m][n], 0, 0, 0); __builtin_amdgcn_s_setprio(0); } while (0)
; #define PG8_WAIT_V(n) asm volatile("s_waitcnt vmcnt(" #n ")" ::: "memory")
; #define PG8_WAIT_L(n) asm volatile("s_waitcnt lgkmcnt(" #n ")" ::: "memory")
; template <class Epi, class Sched, bool ALIGN_EPI = false, bool SP2 = false>
; __device__ __forceinline__ void gemm_phase(PG8_LAS unsigned char* lds, const Gemm g, const Sched S, const Epi E, const int tid) {
;     ...
;         for (int t = 0; t < nt; t += 2) {
;             const bool last = (t == nt - 2);
;             const char* a1 = cA + (size_t)(t + 1) * kstep;
;             const char* a2 = last ? nA : cA + (size_t)(t + 2) * kstep; const char* b2 = last ? nB : cB + (size_t)(t + 2) * kstep;
;             const char* a3 = a2 + kstep; const char* b3 = b2 + kstep;
;             if (last && has_next) S.a_ready(nxt);
;     ...
;             PG8_LDB(B0, 1, 0); PG8_LDB(B1, 1, 1); PG8_SCHED; PG8_LDA(At, 1, 0); PG8_STAGE(PG8_SA(0, 1), a2 + hstepA, voffA);
;             PG8_WAIT_V(8); PG8_WAIT_L(0); PG8_BAR; PG8_MMA(0, 0, At, B0); PG8_MMA(0, 1, At, B1); PG8_BAR; PG8_SCHED;
;             PG8_LDA(At, 1, 1); PG8_STAGE(PG8_SB(1, 0), b3, voffB); PG8_STAGE(PG8_SB(1, 1), b3 + hstepB, voffB); PG8_STAGE(PG8_SA(1, 0), a3, voffA);
;             PG8_WAIT_V(8); PG8_WAIT_L(0); PG8_BAR; PG8_MMA(1, 0, At, B0); PG8_MMA(1, 1, At, B1); PG8_BAR; PG8_SCHED;
	s_add_i32 s78, 0, 0x18000
	s_add_i32 s79, 0, 0x1c000
	v_add_u32_e32 v160, s78, v143
	v_add_u32_e32 v176, s79, v143
	ds_read_b128 v[148:151], v160
	ds_read_b128 v[152:155], v160 offset:1024
	ds_read_b128 v[156:159], v160 offset:2048
	ds_read_b128 v[160:163], v160 offset:3072
	ds_read_b128 v[164:167], v176
	ds_read_b128 v[168:171], v176 offset:1024
	ds_read_b128 v[172:175], v176 offset:2048
	ds_read_b128 v[176:179], v176 offset:3072
	s_add_u32 s54, s54, 0x40000
	s_addc_u32 s55, s55, 0
	s_mov_b32 m0, s64
	ds_read_b128 v[180:183], v147 offset:32768
	ds_read_b128 v[188:191], v147 offset:33792
	ds_read_b128 v[192:195], v147 offset:34816
	ds_read_b128 v[196:199], v147 offset:35840
	ds_read_b128 v[200:203], v147 offset:36864
	ds_read_b128 v[204:207], v147 offset:37888
	ds_read_b128 v[208:211], v147 offset:38912
	ds_read_b128 v[212:215], v147 offset:39936
	global_load_lds_dwordx4 v128, s[54:55]
	s_mov_b32 m0, s65
	s_nop 0
	global_load_lds_dwordx4 v132, s[54:55]
	s_waitcnt vmcnt(8)
	s_waitcnt lgkmcnt(0)
	s_barrier
	s_waitcnt lgkmcnt(0)
	v_mfma_f32_16x16x32_bf16 v[124:127], v[148:151], v[180:183], v[124:127]
	v_mfma_f32_16x16x32_bf16 v[120:123], v[156:159], v[180:183], v[120:123]
	v_mfma_f32_16x16x32_bf16 v[112:115], v[148:151], v[192:195], v[112:115]
	v_mfma_f32_16x16x32_bf16 v[104:107], v[156:159], v[192:195], v[104:107]
	v_mfma_f32_16x16x32_bf16 v[96:99], v[148:151], v[200:203], v[96:99]
	v_mfma_f32_16x16x32_bf16 v[88:91], v[156:159], v[200:203], v[88:91]
	v_mfma_f32_16x16x32_bf16 v[80:83], v[148:151], v[208:211], v[80:83]
	v_mfma_f32_16x16x32_bf16 v[72:75], v[156:159], v[208:211], v[72:75]
	v_mfma_f32_16x16x32_bf16 v[124:127], v[152:155], v[188:191], v[124:127]
	v_mfma_f32_16x16x32_bf16 v[120:123], v[160:163], v[188:191], v[120:123]
	v_mfma_f32_16x16x32_bf16 v[112:115], v[152:155], v[196:199], v[112:115]
	v_mfma_f32_16x16x32_bf16 v[104:107], v[160:163], v[196:199], v[104:107]
	v_mfma_f32_16x16x32_bf16 v[96:99], v[152:155], v[204:207], v[96:99]
	v_mfma_f32_16x16x32_bf16 v[88:91], v[160:163], v[204:207], v[88:91]
	v_mfma_f32_16x16x32_bf16 v[80:83], v[152:155], v[212:215], v[80:83]
	v_mfma_f32_16x16x32_bf16 v[72:75], v[160:163], v[212:215], v[72:75]
	v_mfma_f32_16x16x32_bf16 v[116:119], v[164:167], v[180:183], v[116:119]
	v_mfma_f32_16x16x32_bf16 v[108:111], v[172:175], v[180:183], v[108:111]
	v_mfma_f32_16x16x32_bf16 v[100:103], v[164:167], v[192:195], v[100:103]
	v_mfma_f32_16x16x32_bf16 v[92:95], v[172:175], v[192:195], v[92:95]
	v_mfma_f32_16x16x32_bf16 v[84:87], v[164:167], v[200:203], v[84:87]
	v_mfma_f32_16x16x32_bf16 v[76:79], v[172:175], v[200:203], v[76:79]
	v_mfma_f32_16x16x32_bf16 v[68:71], v[164:167], v[208:211], v[68:71]
	v_mfma_f32_16x16x32_bf16 v[64:67], v[172:175], v[208:211], v[64:67]
	v_mfma_f32_16x16x32_bf16 v[116:119], v[168:171], v[188:191], v[116:119]
	v_mfma_f32_16x16x32_bf16 v[108:111], v[176:179], v[188:191], v[108:111]
	v_mfma_f32_16x16x32_bf16 v[100:103], v[168:171], v[196:199], v[100:103]
	v_mfma_f32_16x16x32_bf16 v[92:95], v[176:179], v[196:199], v[92:95]
	v_mfma_f32_16x16x32_bf16 v[84:87], v[168:171], v[204:207], v[84:87]
	v_mfma_f32_16x16x32_bf16 v[76:79], v[176:179], v[204:207], v[76:79]
	v_mfma_f32_16x16x32_bf16 v[68:71], v[168:171], v[212:215], v[68:71]
	v_mfma_f32_16x16x32_bf16 v[64:67], v[176:179], v[212:215], v[64:67]
	s_barrier
	s_add_i32 s54, s78, s62
	s_mov_b32 m0, s54
	ds_read_b128 v[180:183], v147 offset:49152
	ds_read_b128 v[188:191], v147 offset:50176
	ds_read_b128 v[192:195], v147 offset:51200
	ds_read_b128 v[196:199], v147 offset:52224
	ds_read_b128 v[200:203], v147 offset:53248
	ds_read_b128 v[204:207], v147 offset:54272
	ds_read_b128 v[208:211], v147 offset:55296
	ds_read_b128 v[212:215], v147 offset:56320
	global_load_lds_dwordx4 v130, s[98:99]
	s_add_i32 m0, s54, 0x2000
	s_add_u32 s52, s52, 0x40080
	s_addc_u32 s53, s53, 0
	s_add_i32 s54, s79, s62
	global_load_lds_dwordx4 v134, s[98:99]
	s_mov_b32 m0, s54
	s_nop 0
	global_load_lds_dwordx4 v130, s[52:53]
	s_add_i32 m0, s54, 0x2000
	s_nop 0
	global_load_lds_dwordx4 v134, s[52:53]
	s_mov_b32 m0, s67
	s_nop 0
	global_load_lds_dwordx4 v128, s[100:101]
	s_mov_b32 m0, s69
	s_nop 0
	global_load_lds_dwordx4 v132, s[100:101]
	s_waitcnt vmcnt(8)
	s_waitcnt lgkmcnt(0)
	s_barrier
	s_waitcnt lgkmcnt(0)
	v_mfma_f32_16x16x32_bf16 v[60:63], v[148:151], v[180:183], v[60:63]
	v_mfma_f32_16x16x32_bf16 v[56:59], v[156:159], v[180:183], v[56:59]
	v_mfma_f32_16x16x32_bf16 v[52:55], v[148:151], v[192:195], v[52:55]
	v_mfma_f32_16x16x32_bf16 v[44:47], v[156:159], v[192:195], v[44:47]
	v_mfma_f32_16x16x32_bf16 v[36:39], v[148:151], v[200:203], v[36:39]
	v_mfma_f32_16x16x32_bf16 v[28:31], v[156:159], v[200:203], v[28:31]
	v_mfma_f32_16x16x32_bf16 v[20:23], v[148:151], v[208:211], v[20:23]
	v_mfma_f32_16x16x32_bf16 v[12:15], v[156:159], v[208:211], v[12:15]
	v_mfma_f32_16x16x32_bf16 v[60:63], v[152:155], v[188:191], v[60:63]
	v_mfma_f32_16x16x32_bf16 v[56:59], v[160:163], v[188:191], v[56:59]
	v_mfma_f32_16x16x32_bf16 v[52:55], v[152:155], v[196:199], v[52:55]
	v_mfma_f32_16x16x32_bf16 v[44:47], v[160:163], v[196:199], v[44:47]
	v_mfma_f32_16x16x32_bf16 v[36:39], v[152:155], v[204:207], v[36:39]
	v_mfma_f32_16x16x32_bf16 v[28:31], v[160:163], v[204:207], v[28:31]
	v_mfma_f32_16x16x32_bf16 v[20:23], v[152:155], v[212:215], v[20:23]
	v_mfma_f32_16x16x32_bf16 v[12:15], v[160:163], v[212:215], v[12:15]
	v_mfma_f32_16x16x32_bf16 v[48:51], v[164:167], v[180:183], v[48:51]
	v_mfma_f32_16x16x32_bf16 v[40:43], v[172:175], v[180:183], v[40:43]
	v_mfma_f32_16x16x32_bf16 v[32:35], v[164:167], v[192:195], v[32:35]
	v_mfma_f32_16x16x32_bf16 v[24:27], v[172:175], v[192:195], v[24:27]
	v_mfma_f32_16x16x32_bf16 v[16:19], v[164:167], v[200:203], v[16:19]
	v_mfma_f32_16x16x32_bf16 v[8:11], v[172:175], v[200:203], v[8:11]
	v_mfma_f32_16x16x32_bf16 v[4:7], v[164:167], v[208:211], v[4:7]
	v_mfma_f32_16x16x32_bf16 v[0:3], v[172:175], v[208:211], v[0:3]
	v_mfma_f32_16x16x32_bf16 v[48:51], v[168:171], v[188:191], v[48:51]
	v_mfma_f32_16x16x32_bf16 v[40:43], v[176:179], v[188:191], v[40:43]
	v_mfma_f32_16x16x32_bf16 v[32:35], v[168:171], v[196:199], v[32:35]
	v_mfma_f32_16x16x32_bf16 v[24:27], v[176:179], v[196:199], v[24:27]
	v_mfma_f32_16x16x32_bf16 v[16:19], v[168:171], v[204:207], v[16:19]
	v_mfma_f32_16x16x32_bf16 v[8:11], v[176:179], v[204:207], v[8:11]
	v_mfma_f32_16x16x32_bf16 v[4:7], v[168:171], v[212:215], v[4:7]
	v_mfma_f32_16x16x32_bf16 v[0:3], v[176:179], v[212:215], v[0:3]
	s_barrier
	s_add_i32 s77, s77, 2
	s_add_u32 s50, s50, 0x100
	s_addc_u32 s51, s51, 0
	s_add_u32 s75, s75, 0x100
	s_addc_u32 s76, s76, 0
	s_cmp_gt_u32 s77, 13
	s_cbranch_scc0 .LBB0_220
	s_setprio 0
	s_and_b64 vcc, exec, s[8:9]
	s_cbranch_vccz .LBB0_223
	s_barrier

; #define PG8_STAGE(bufoff, gbase, voff) do { _Pragma("unroll") for (int _i = 0; _i < 2; ++_i) \
;         __builtin_amdgcn_global_load_lds((const unsigned*)((const char*)(gbase) + (voff)[_i]), (PG8_LAS unsigned*)(lds + (bufoff) + ldsw + _i * 8192), 16, 0, 0); } while (0)
; #define PG8_LDA(dst, b, h) do { _Pragma("unroll") for (int m = 0; m < 4; ++m) _Pragma("unroll") for (int k = 0; k < 2; ++k) dst[m][k] = *(const PG8_LAS bf16x8*)(lds + PG8_SA(b, h) + aoff + m * 2048 + k * 1024); } while (0)
; #define PG8_LDB(dst, b, h) do { _Pragma("unroll") for (int n = 0; n < 2; ++n) _Pragma("unroll") for (int k = 0; k < 2; ++k) dst[n][k] = *(const PG8_LAS bf16x8*)(lds + PG8_SB(b, h) + boff + n * 2048 + k * 1024); } while (0)
; #define PG8_WAIT_V(n) asm volatile("s_waitcnt vmcnt(" #n ")" ::: "memory")
; #define PG8_WAIT_L(n) asm volatile("s_waitcnt lgkmcnt(" #n ")" ::: "memory")
; #define PG8_BAR __builtin_amdgcn_s_barrier()
; #define PG8_SCHED __builtin_amdgcn_sched_barrier(0)
; template <class Epi, class Sched, bool ALIGN_EPI = false, bool SP2 = false>
; __device__ __forceinline__ void gemm_phase(PG8_LAS unsigned char* lds, const Gemm g, const Sched S, const Epi E, const int tid) {
;     ...
;         const char* nA = has_next ? (const char*)g.A + (size_t)nxt.pm * tstepA + (size_t)nxt.pn * apn : cA; const char* nB = has_next ? (const char*)g.Bt + (size_t)nxt.pn * bpn : cB;
;         for (int t = 0; t < nt; t += 2) {
;             const bool last = (t == nt - 2);
;             const char* a1 = cA + (size_t)(t + 1) * kstep;
;             const char* a2 = last ? nA : cA + (size_t)(t + 2) * kstep; const char* b2 = last ? nB : cB + (size_t)(t + 2) * kstep;
;             const char* a3 = a2 + kstep; const char* b3 = b2 + kstep;
;             if (last && has_next) S.a_ready(nxt);
;             if constexpr (SP2) {
;             PG8_LDB(B0, 0, 0); PG8_LDB(B1, 0, 1); PG8_SCHED; PG8_LDA(At, 0, 0); PG8_STAGE(PG8_SA(1, 1), a1 + hstepA, voffA);
;             PG8_WAIT_V(8); PG8_WAIT_L(0); PG8_BAR; PG8_MMA(0, 0, At, B0); PG8_MMA(0, 1, At, B1); PG8_BAR; PG8_SCHED;
;             PG8_LDA(At, 0, 1); PG8_STAGE(PG8_SB(0, 0), b2, voffB); PG8_STAGE(PG8_SB(0, 1), b2 + hstepB, voffB); PG8_STAGE(PG8_SA(0, 0), a2, voffA);
;             PG8_WAIT_V(8); PG8_WAIT_L(0); PG8_BAR; PG8_MMA(1, 0, At, B0); PG8_MMA(1, 1, At, B1); PG8_BAR; PG8_SCHED;
.LBB0_296:
	s_add_u32 s71, s34, 0x100
	s_addc_u32 s72, s35, 0
	s_mov_b32 s73, -2
	v_readfirstlane_b32 s98, v186
	s_lshr_b32 s98, s98, 8
	s_cmp_eq_u32 s98, 0
	s_cbranch_scc1 .Lprio_skip_3
	s_setprio 1
.Lprio_skip_3:
.LBB0_297:
	v_add_u32_e32 v162, s64, v149
	v_add_u32_e32 v178, s65, v149
	ds_read_b128 v[144:147], v162
	ds_read_b128 v[154:157], v162 offset:1024
	ds_read_b128 v[158:161], v162 offset:2048
	ds_read_b128 v[162:165], v162 offset:3072
	ds_read_b128 v[166:169], v178
	ds_read_b128 v[170:173], v178 offset:1024
	ds_read_b128 v[174:177], v178 offset:2048
	ds_read_b128 v[178:181], v178 offset:3072
	s_add_u32 s34, s30, 0x100
	s_addc_u32 s35, s31, 0
	s_cmp_eq_u32 s73, 40
	s_cselect_b32 s39, s7, s35
	s_cselect_b32 s38, s6, s34
	s_cselect_b32 s37, s29, s72
	s_cselect_b32 s36, s28, s71
	s_add_i32 m0, s54, 0xc000
	ds_read_b128 v[182:185], v153
	ds_read_b128 v[188:191], v153 offset:1024
	ds_read_b128 v[192:195], v153 offset:2048
	ds_read_b128 v[196:199], v153 offset:3072
	ds_read_b128 v[200:203], v153 offset:4096
	ds_read_b128 v[204:207], v153 offset:5120
	ds_read_b128 v[208:211], v153 offset:6144
	ds_read_b128 v[212:215], v153 offset:7168
	global_load_lds_dwordx4 v136, s[30:31]
	s_add_i32 m0, s54, 0xe000
	s_nop 0
	global_load_lds_dwordx4 v138, s[30:31]
	s_waitcnt vmcnt(8)
	s_waitcnt lgkmcnt(0)
	s_barrier
	s_waitcnt lgkmcnt(0)
	v_mfma_f32_16x16x32_bf16 v[112:115], v[144:147], v[182:185], v[112:115]
	v_mfma_f32_16x16x32_bf16 v[120:123], v[158:161], v[182:185], v[120:123]
	v_mfma_f32_16x16x32_bf16 v[96:99], v[144:147], v[192:195], v[96:99]
	v_mfma_f32_16x16x32_bf16 v[104:107], v[158:161], v[192:195], v[104:107]
	v_mfma_f32_16x16x32_bf16 v[80:83], v[144:147], v[200:203], v[80:83]
	v_mfma_f32_16x16x32_bf16 v[88:91], v[158:161], v[200:203], v[88:91]
	v_mfma_f32_16x16x32_bf16 v[64:67], v[144:147], v[208:211], v[64:67]
	v_mfma_f32_16x16x32_bf16 v[72:75], v[158:161], v[208:211], v[72:75]
	v_mfma_f32_16x16x32_bf16 v[112:115], v[154:157], v[188:191], v[112:115]
	v_mfma_f32_16x16x32_bf16 v[120:123], v[162:165], v[188:191], v[120:123]
	v_mfma_f32_16x16x32_bf16 v[96:99], v[154:157], v[196:199], v[96:99]
	v_mfma_f32_16x16x32_bf16 v[104:107], v[162:165], v[196:199], v[104:107]
	v_mfma_f32_16x16x32_bf16 v[80:83], v[154:157], v[204:207], v[80:83]
	v_mfma_f32_16x16x32_bf16 v[88:91], v[162:165], v[204:207], v[88:91]
	v_mfma_f32_16x16x32_bf16 v[64:67], v[154:157], v[212:215], v[64:67]
	v_mfma_f32_16x16x32_bf16 v[72:75], v[162:165], v[212:215], v[72:75]
	v_mfma_f32_16x16x32_bf16 v[116:119], v[166:169], v[182:185], v[116:119]
	v_mfma_f32_16x16x32_bf16 v[124:127], v[174:177], v[182:185], v[124:127]
	v_mfma_f32_16x16x32_bf16 v[100:103], v[166:169], v[192:195], v[100:103]
	v_mfma_f32_16x16x32_bf16 v[108:111], v[174:177], v[192:195], v[108:111]
	v_mfma_f32_16x16x32_bf16 v[84:87], v[166:169], v[200:203], v[84:87]
	v_mfma_f32_16x16x32_bf16 v[92:95], v[174:177], v[200:203], v[92:95]
	v_mfma_f32_16x16x32_bf16 v[68:71], v[166:169], v[208:211], v[68:71]
	v_mfma_f32_16x16x32_bf16 v[76:79], v[174:177], v[208:211], v[76:79]
	v_mfma_f32_16x16x32_bf16 v[116:119], v[170:173], v[188:191], v[116:119]
	v_mfma_f32_16x16x32_bf16 v[124:127], v[178:181], v[188:191], v[124:127]
	v_mfma_f32_16x16x32_bf16 v[100:103], v[170:173], v[196:199], v[100:103]
	v_mfma_f32_16x16x32_bf16 v[108:111], v[178:181], v[196:199], v[108:111]
	v_mfma_f32_16x16x32_bf16 v[84:87], v[170:173], v[204:207], v[84:87]
	v_mfma_f32_16x16x32_bf16 v[92:95], v[178:181], v[204:207], v[92:95]
	v_mfma_f32_16x16x32_bf16 v[68:71], v[170:173], v[212:215], v[68:71]
	v_mfma_f32_16x16x32_bf16 v[76:79], v[178:181], v[212:215], v[76:79]
	s_barrier
	s_add_u32 s98, s36, 0x80
	s_addc_u32 s99, s37, 0
	s_add_u32 s100, s38, 0x80
	s_addc_u32 s101, s39, 0
	s_add_i32 s30, s64, s51
	s_mov_b32 m0, s30
	ds_read_b128 v[182:185], v153 offset:16384
	ds_read_b128 v[188:191], v153 offset:17408
	ds_read_b128 v[192:195], v153 offset:18432
	ds_read_b128 v[196:199], v153 offset:19456
	ds_read_b128 v[200:203], v153 offset:20480
	ds_read_b128 v[204:207], v153 offset:21504
	ds_read_b128 v[208:211], v153 offset:22528
	ds_read_b128 v[212:215], v153 offset:23552
	global_load_lds_dwordx4 v130, s[36:37]
	s_add_i32 m0, s30, 0x2000
	s_add_u32 s30, s36, 0xb0000
	s_addc_u32 s31, s37, 0
	s_add_i32 s74, s65, s51
	global_load_lds_dwordx4 v134, s[36:37]
	s_mov_b32 m0, s74
	s_nop 0
	global_load_lds_dwordx4 v130, s[30:31]
	s_add_i32 m0, s74, 0x2000
	s_nop 0
	global_load_lds_dwordx4 v134, s[30:31]
	s_mov_b32 m0, s54
	s_nop 0
	global_load_lds_dwordx4 v128, s[38:39]
	s_mov_b32 m0, s55
	s_nop 0
	global_load_lds_dwordx4 v132, s[38:39]
	s_waitcnt vmcnt(8)
	s_waitcnt lgkmcnt(0)
	s_barrier
; #define PG8_STAGE(bufoff, gbase, voff) do { _Pragma("unroll") for (int _i = 0; _i < 2; ++_i) \
;         __builtin_amdgcn_global_load_lds((const unsigned*)((const char*)(gbase) + (voff)[_i]), (PG8_LAS unsigned*)(lds + (bufoff) + ldsw + _i * 8192), 16, 0, 0); } while (0)
; #define PG8_LDA(dst, b, h) do { _Pragma("unroll") for (int m = 0; m < 4; ++m) _Pragma("unroll") for (int k = 0; k < 2; ++k) dst[m][k] = *(const PG8_LAS bf16x8*)(lds + PG8_SA(b, h) + aoff + m * 2048 + k * 1024); } while (0)
; #define PG8_LDB(dst, b, h) do { _Pragma("unroll") for (int n = 0; n < 2; ++n) _Pragma("unroll") for (int k = 0; k < 2; ++k) dst[n][k] = *(const PG8_LAS bf16x8*)(lds + PG8_SB(b, h) + boff + n * 2048 + k * 1024); } while (0)
; #define PG8_MMA(ai, bj, At, Bt) do { __builtin_amdgcn_s_setprio(1); _Pragma("unroll") for (int m = 0; m < 4; ++m) _Pragma("unroll") for (int n = 0; n < 2; ++n) _Pragma("unroll") for (int k = 0; k < 2; ++k) \
;         acc[ai][bj][m][n] = __builtin_amdgcn_mfma_f32_16x16x32_bf16(Bt[n][k], At[m][k], acc[ai][bj][m][n], 0, 0, 0); __builtin_amdgcn_s_setprio(0); } while (0)
; #define PG8_WAIT_V(n) asm volatile("s_waitcnt vmcnt(" #n ")" ::: "memory")
; #define PG8_WAIT_L(n) asm volatile("s_waitcnt lgkmcnt(" #n ")" ::: "memory")
; #define PG8_BAR __builtin_amdgcn_s_barrier()
; #define PG8_SCHED __builtin_amdgcn_sched_barrier(0)
; template <class Epi, class Sched, bool ALIGN_EPI = false, bool SP2 = false>
; __device__ __forceinline__ void gemm_phase(PG8_LAS unsigned char* lds, const Gemm g, const Sched S, const Epi E, const int tid) {
;     ...
;             PG8_WAIT_V(8); PG8_WAIT_L(0); PG8_BAR; PG8_MMA(1, 0, At, B0); PG8_MMA(1, 1, At, B1); PG8_BAR; PG8_SCHED;
;             PG8_LDB(B0, 1, 0); PG8_LDB(B1, 1, 1); PG8_SCHED; PG8_LDA(At, 1, 0); PG8_STAGE(PG8_SA(0, 1), a2 + hstepA, voffA);
;             PG8_WAIT_V(8); PG8_WAIT_L(0); PG8_BAR; PG8_MMA(0, 0, At, B0); PG8_MMA(0, 1, At, B1); PG8_BAR; PG8_SCHED;
;             PG8_LDA(At, 1, 1); PG8_STAGE(PG8_SB(1, 0), b3, voffB); PG8_STAGE(PG8_SB(1, 1), b3 + hstepB, voffB); PG8_STAGE(PG8_SA(1, 0), a3, voffA);
	s_waitcnt lgkmcnt(0)
	v_mfma_f32_16x16x32_bf16 v[48:51], v[144:147], v[182:185], v[48:51]
	v_mfma_f32_16x16x32_bf16 v[56:59], v[158:161], v[182:185], v[56:59]
	v_mfma_f32_16x16x32_bf16 v[24:27], v[144:147], v[192:195], v[24:27]
	v_mfma_f32_16x16x32_bf16 v[32:35], v[158:161], v[192:195], v[32:35]
	v_mfma_f32_16x16x32_bf16 v[0:3], v[144:147], v[200:203], v[0:3]
	v_mfma_f32_16x16x32_bf16 v[4:7], v[158:161], v[200:203], v[4:7]
	v_mfma_f32_16x16x32_bf16 v[8:11], v[144:147], v[208:211], v[8:11]
	v_mfma_f32_16x16x32_bf16 v[16:19], v[158:161], v[208:211], v[16:19]
	v_mfma_f32_16x16x32_bf16 v[48:51], v[154:157], v[188:191], v[48:51]
	v_mfma_f32_16x16x32_bf16 v[56:59], v[162:165], v[188:191], v[56:59]
	v_mfma_f32_16x16x32_bf16 v[24:27], v[154:157], v[196:199], v[24:27]
	v_mfma_f32_16x16x32_bf16 v[32:35], v[162:165], v[196:199], v[32:35]
	v_mfma_f32_16x16x32_bf16 v[0:3], v[154:157], v[204:207], v[0:3]
	v_mfma_f32_16x16x32_bf16 v[4:7], v[162:165], v[204:207], v[4:7]
	v_mfma_f32_16x16x32_bf16 v[8:11], v[154:157], v[212:215], v[8:11]
	v_mfma_f32_16x16x32_bf16 v[16:19], v[162:165], v[212:215], v[16:19]
	v_mfma_f32_16x16x32_bf16 v[52:55], v[166:169], v[182:185], v[52:55]
	v_mfma_f32_16x16x32_bf16 v[60:63], v[174:177], v[182:185], v[60:63]
	v_mfma_f32_16x16x32_bf16 v[28:31], v[166:169], v[192:195], v[28:31]
	v_mfma_f32_16x16x32_bf16 v[36:39], v[174:177], v[192:195], v[36:39]
	v_mfma_f32_16x16x32_bf16 v[40:43], v[166:169], v[200:203], v[40:43]
	v_mfma_f32_16x16x32_bf16 v[44:47], v[174:177], v[200:203], v[44:47]
	v_mfma_f32_16x16x32_bf16 v[12:15], v[166:169], v[208:211], v[12:15]
	v_mfma_f32_16x16x32_bf16 v[20:23], v[174:177], v[208:211], v[20:23]
	v_mfma_f32_16x16x32_bf16 v[52:55], v[170:173], v[188:191], v[52:55]
	v_mfma_f32_16x16x32_bf16 v[60:63], v[178:181], v[188:191], v[60:63]
	v_mfma_f32_16x16x32_bf16 v[28:31], v[170:173], v[196:199], v[28:31]
	v_mfma_f32_16x16x32_bf16 v[36:39], v[178:181], v[196:199], v[36:39]
	v_mfma_f32_16x16x32_bf16 v[40:43], v[170:173], v[204:207], v[40:43]
	v_mfma_f32_16x16x32_bf16 v[44:47], v[178:181], v[204:207], v[44:47]
	v_mfma_f32_16x16x32_bf16 v[12:15], v[170:173], v[212:215], v[12:15]
	v_mfma_f32_16x16x32_bf16 v[20:23], v[178:181], v[212:215], v[20:23]
	s_barrier
	s_add_i32 s74, 0, 0x18000
	s_add_i32 s75, 0, 0x1c000
	v_add_u32_e32 v162, s74, v149
	v_add_u32_e32 v178, s75, v149
	ds_read_b128 v[144:147], v162
	ds_read_b128 v[154:157], v162 offset:1024
	ds_read_b128 v[158:161], v162 offset:2048
	ds_read_b128 v[162:165], v162 offset:3072
	ds_read_b128 v[166:169], v178
	ds_read_b128 v[170:173], v178 offset:1024
	ds_read_b128 v[174:177], v178 offset:2048
	ds_read_b128 v[178:181], v178 offset:3072
	s_add_u32 s30, s38, 0xb0000
	s_addc_u32 s31, s39, 0
	s_mov_b32 m0, s56
	ds_read_b128 v[182:185], v153 offset:32768
	ds_read_b128 v[188:191], v153 offset:33792
	ds_read_b128 v[192:195], v153 offset:34816
	ds_read_b128 v[196:199], v153 offset:35840
	ds_read_b128 v[200:203], v153 offset:36864
	ds_read_b128 v[204:207], v153 offset:37888
	ds_read_b128 v[208:211], v153 offset:38912
	ds_read_b128 v[212:215], v153 offset:39936
	global_load_lds_dwordx4 v128, s[30:31]
	s_mov_b32 m0, s57
	s_nop 0
	global_load_lds_dwordx4 v132, s[30:31]
	s_waitcnt vmcnt(8)
	s_waitcnt lgkmcnt(0)
	s_barrier
	s_waitcnt lgkmcnt(0)
	v_mfma_f32_16x16x32_bf16 v[112:115], v[144:147], v[182:185], v[112:115]
	v_mfma_f32_16x16x32_bf16 v[120:123], v[158:161], v[182:185], v[120:123]
	v_mfma_f32_16x16x32_bf16 v[96:99], v[144:147], v[192:195], v[96:99]
	v_mfma_f32_16x16x32_bf16 v[104:107], v[158:161], v[192:195], v[104:107]
	v_mfma_f32_16x16x32_bf16 v[80:83], v[144:147], v[200:203], v[80:83]
	v_mfma_f32_16x16x32_bf16 v[88:91], v[158:161], v[200:203], v[88:91]
	v_mfma_f32_16x16x32_bf16 v[64:67], v[144:147], v[208:211], v[64:67]
	v_mfma_f32_16x16x32_bf16 v[72:75], v[158:161], v[208:211], v[72:75]
	v_mfma_f32_16x16x32_bf16 v[112:115], v[154:157], v[188:191], v[112:115]
	v_mfma_f32_16x16x32_bf16 v[120:123], v[162:165], v[188:191], v[120:123]
	v_mfma_f32_16x16x32_bf16 v[96:99], v[154:157], v[196:199], v[96:99]
	v_mfma_f32_16x16x32_bf16 v[104:107], v[162:165], v[196:199], v[104:107]
	v_mfma_f32_16x16x32_bf16 v[80:83], v[154:157], v[204:207], v[80:83]
	v_mfma_f32_16x16x32_bf16 v[88:91], v[162:165], v[204:207], v[88:91]
	v_mfma_f32_16x16x32_bf16 v[64:67], v[154:157], v[212:215], v[64:67]
	v_mfma_f32_16x16x32_bf16 v[72:75], v[162:165], v[212:215], v[72:75]
	v_mfma_f32_16x16x32_bf16 v[116:119], v[166:169], v[182:185], v[116:119]
	v_mfma_f32_16x16x32_bf16 v[124:127], v[174:177], v[182:185], v[124:127]
	v_mfma_f32_16x16x32_bf16 v[100:103], v[166:169], v[192:195], v[100:103]
	v_mfma_f32_16x16x32_bf16 v[108:111], v[174:177], v[192:195], v[108:111]
	v_mfma_f32_16x16x32_bf16 v[84:87], v[166:169], v[200:203], v[84:87]
	v_mfma_f32_16x16x32_bf16 v[92:95], v[174:177], v[200:203], v[92:95]
	v_mfma_f32_16x16x32_bf16 v[68:71], v[166:169], v[208:211], v[68:71]
	v_mfma_f32_16x16x32_bf16 v[76:79], v[174:177], v[208:211], v[76:79]
	v_mfma_f32_16x16x32_bf16 v[116:119], v[170:173], v[188:191], v[116:119]
	v_mfma_f32_16x16x32_bf16 v[124:127], v[178:181], v[188:191], v[124:127]
	v_mfma_f32_16x16x32_bf16 v[100:103], v[170:173], v[196:199], v[100:103]
	v_mfma_f32_16x16x32_bf16 v[108:111], v[178:181], v[196:199], v[108:111]
	v_mfma_f32_16x16x32_bf16 v[84:87], v[170:173], v[204:207], v[84:87]
	v_mfma_f32_16x16x32_bf16 v[92:95], v[178:181], v[204:207], v[92:95]
	v_mfma_f32_16x16x32_bf16 v[68:71], v[170:173], v[212:215], v[68:71]
	v_mfma_f32_16x16x32_bf16 v[76:79], v[178:181], v[212:215], v[76:79]
	s_barrier
; #define PG8_STAGE(bufoff, gbase, voff) do { _Pragma("unroll") for (int _i = 0; _i < 2; ++_i) \
;         __builtin_amdgcn_global_load_lds((const unsigned*)((const char*)(gbase) + (voff)[_i]), (PG8_LAS unsigned*)(lds + (bufoff) + ldsw + _i * 8192), 16, 0, 0); } while (0)
; #define PG8_LDA(dst, b, h) do { _Pragma("unroll") for (int m = 0; m < 4; ++m) _Pragma("unroll") for (int k = 0; k < 2; ++k) dst[m][k] = *(const PG8_LAS bf16x8*)(lds + PG8_SA(b, h) + aoff + m * 2048 + k * 1024); } while (0)
; #define PG8_MMA(ai, bj, At, Bt) do { __builtin_amdgcn_s_setprio(1); _Pragma("unroll") for (int m = 0; m < 4; ++m) _Pragma("unroll") for (int n = 0; n < 2; ++n) _Pragma("unroll") for (int k = 0; k < 2; ++k) \
;         acc[ai][bj][m][n] = __builtin_amdgcn_mfma_f32_16x16x32_bf16(Bt[n][k], At[m][k], acc[ai][bj][m][n], 0, 0, 0); __builtin_amdgcn_s_setprio(0); } while (0)
; #define PG8_WAIT_V(n) asm volatile("s_waitcnt vmcnt(" #n ")" ::: "memory")
; #define PG8_WAIT_L(n) asm volatile("s_waitcnt lgkmcnt(" #n ")" ::: "memory")
; #define PG8_BAR __builtin_amdgcn_s_barrier()
; #define PG8_SCHED __builtin_amdgcn_sched_barrier(0)
; template <class Epi, class Sched, bool ALIGN_EPI = false, bool SP2 = false>
; __device__ __forceinline__ void gemm_phase(PG8_LAS unsigned char* lds, const Gemm g, const Sched S, const Epi E, const int tid) {
;     ...
;         for (int t = 0; t < nt; t += 2) {
;     ...
;             PG8_LDA(At, 1, 1); PG8_STAGE(PG8_SB(1, 0), b3, voffB); PG8_STAGE(PG8_SB(1, 1), b3 + hstepB, voffB); PG8_STAGE(PG8_SA(1, 0), a3, voffA);
;             PG8_WAIT_V(8); PG8_WAIT_L(0); PG8_BAR; PG8_MMA(1, 0, At, B0); PG8_MMA(1, 1, At, B1); PG8_BAR; PG8_SCHED;
	s_add_i32 s30, s74, s51
	s_mov_b32 m0, s30
	ds_read_b128 v[182:185], v153 offset:49152
	ds_read_b128 v[188:191], v153 offset:50176
	ds_read_b128 v[192:195], v153 offset:51200
	ds_read_b128 v[196:199], v153 offset:52224
	ds_read_b128 v[200:203], v153 offset:53248
	ds_read_b128 v[204:207], v153 offset:54272
	ds_read_b128 v[208:211], v153 offset:55296
	ds_read_b128 v[212:215], v153 offset:56320
	global_load_lds_dwordx4 v130, s[98:99]
	s_add_i32 m0, s30, 0x2000
	s_add_u32 s30, s36, 0xb0080
	s_addc_u32 s31, s37, 0
	s_add_i32 s36, s75, s51
	global_load_lds_dwordx4 v134, s[98:99]
	s_mov_b32 m0, s36
	s_nop 0
	global_load_lds_dwordx4 v130, s[30:31]
	s_add_i32 m0, s36, 0x2000
	s_nop 0
	global_load_lds_dwordx4 v134, s[30:31]
	s_mov_b32 m0, s59
	s_nop 0
	global_load_lds_dwordx4 v128, s[100:101]
	s_mov_b32 m0, s60
	s_nop 0
	global_load_lds_dwordx4 v132, s[100:101]
	s_waitcnt vmcnt(8)
	s_waitcnt lgkmcnt(0)
	s_barrier
	s_waitcnt lgkmcnt(0)
	v_mfma_f32_16x16x32_bf16 v[48:51], v[144:147], v[182:185], v[48:51]
	v_mfma_f32_16x16x32_bf16 v[56:59], v[158:161], v[182:185], v[56:59]
	v_mfma_f32_16x16x32_bf16 v[24:27], v[144:147], v[192:195], v[24:27]
	v_mfma_f32_16x16x32_bf16 v[32:35], v[158:161], v[192:195], v[32:35]
	v_mfma_f32_16x16x32_bf16 v[0:3], v[144:147], v[200:203], v[0:3]
	v_mfma_f32_16x16x32_bf16 v[4:7], v[158:161], v[200:203], v[4:7]
	v_mfma_f32_16x16x32_bf16 v[8:11], v[144:147], v[208:211], v[8:11]
	v_mfma_f32_16x16x32_bf16 v[16:19], v[158:161], v[208:211], v[16:19]
	v_mfma_f32_16x16x32_bf16 v[48:51], v[154:157], v[188:191], v[48:51]
	v_mfma_f32_16x16x32_bf16 v[56:59], v[162:165], v[188:191], v[56:59]
	v_mfma_f32_16x16x32_bf16 v[24:27], v[154:157], v[196:199], v[24:27]
	v_mfma_f32_16x16x32_bf16 v[32:35], v[162:165], v[196:199], v[32:35]
	v_mfma_f32_16x16x32_bf16 v[0:3], v[154:157], v[204:207], v[0:3]
	v_mfma_f32_16x16x32_bf16 v[4:7], v[162:165], v[204:207], v[4:7]
	v_mfma_f32_16x16x32_bf16 v[8:11], v[154:157], v[212:215], v[8:11]
	v_mfma_f32_16x16x32_bf16 v[16:19], v[162:165], v[212:215], v[16:19]
	v_mfma_f32_16x16x32_bf16 v[52:55], v[166:169], v[182:185], v[52:55]
	v_mfma_f32_16x16x32_bf16 v[60:63], v[174:177], v[182:185], v[60:63]
	v_mfma_f32_16x16x32_bf16 v[28:31], v[166:169], v[192:195], v[28:31]
	v_mfma_f32_16x16x32_bf16 v[36:39], v[174:177], v[192:195], v[36:39]
	v_mfma_f32_16x16x32_bf16 v[40:43], v[166:169], v[200:203], v[40:43]
	v_mfma_f32_16x16x32_bf16 v[44:47], v[174:177], v[200:203], v[44:47]
	v_mfma_f32_16x16x32_bf16 v[12:15], v[166:169], v[208:211], v[12:15]
	v_mfma_f32_16x16x32_bf16 v[20:23], v[174:177], v[208:211], v[20:23]
	v_mfma_f32_16x16x32_bf16 v[52:55], v[170:173], v[188:191], v[52:55]
	v_mfma_f32_16x16x32_bf16 v[60:63], v[178:181], v[188:191], v[60:63]
	v_mfma_f32_16x16x32_bf16 v[28:31], v[170:173], v[196:199], v[28:31]
	v_mfma_f32_16x16x32_bf16 v[36:39], v[178:181], v[196:199], v[36:39]
	v_mfma_f32_16x16x32_bf16 v[40:43], v[170:173], v[204:207], v[40:43]
	v_mfma_f32_16x16x32_bf16 v[44:47], v[178:181], v[204:207], v[44:47]
	v_mfma_f32_16x16x32_bf16 v[12:15], v[170:173], v[212:215], v[12:15]
	v_mfma_f32_16x16x32_bf16 v[20:23], v[178:181], v[212:215], v[20:23]
	s_barrier
	s_add_i32 s73, s73, 2
	s_add_u32 s71, s71, 0x100
	s_addc_u32 s72, s72, 0
	s_cmp_gt_u32 s73, 41
	s_mov_b64 s[30:31], s[34:35]
	s_cbranch_scc0 .LBB0_297
	s_setprio 0
	s_and_b64 vcc, exec, s[24:25]
	s_cbranch_vccz .LBB0_300
	s_barrier

; #define PG8_STAGE(bufoff, gbase, voff) do { _Pragma("unroll") for (int _i = 0; _i < 2; ++_i) \
;         __builtin_amdgcn_global_load_lds((const unsigned*)((const char*)(gbase) + (voff)[_i]), (PG8_LAS unsigned*)(lds + (bufoff) + ldsw + _i * 8192), 16, 0, 0); } while (0)
; #define PG8_LDA(dst, b, h) do { _Pragma("unroll") for (int m = 0; m < 4; ++m) _Pragma("unroll") for (int k = 0; k < 2; ++k) dst[m][k] = *(const PG8_LAS bf16x8*)(lds + PG8_SA(b, h) + aoff + m * 2048 + k * 1024); } while (0)
; #define PG8_LDB(dst, b, h) do { _Pragma("unroll") for (int n = 0; n < 2; ++n) _Pragma("unroll") for (int k = 0; k < 2; ++k) dst[n][k] = *(const PG8_LAS bf16x8*)(lds + PG8_SB(b, h) + boff + n * 2048 + k * 1024); } while (0)
; #define PG8_WAIT_V(n) asm volatile("s_waitcnt vmcnt(" #n ")" ::: "memory")
; #define PG8_WAIT_L(n) asm volatile("s_waitcnt lgkmcnt(" #n ")" ::: "memory")
; #define PG8_BAR __builtin_amdgcn_s_barrier()
; template <class Epi, class Sched, bool ALIGN_EPI = false, bool SP2 = false>
; __device__ __forceinline__ void gemm_phase(PG8_LAS unsigned char* lds, const Gemm g, const Sched S, const Epi E, const int tid) {
;     ...
;         const char* nA = has_next ? (const char*)g.A + (size_t)nxt.pm * tstepA + (size_t)nxt.pn * apn : cA; const char* nB = has_next ? (const char*)g.Bt + (size_t)nxt.pn * bpn : cB;
;         for (int t = 0; t < nt; t += 2) {
;             const bool last = (t == nt - 2);
;             const char* a1 = cA + (size_t)(t + 1) * kstep;
;             const char* a2 = last ? nA : cA + (size_t)(t + 2) * kstep; const char* b2 = last ? nB : cB + (size_t)(t + 2) * kstep;
;             const char* a3 = a2 + kstep; const char* b3 = b2 + kstep;
;             if (last && has_next) S.a_ready(nxt);
;             if constexpr (SP2) {
;             PG8_LDB(B0, 0, 0); PG8_LDB(B1, 0, 1); PG8_SCHED; PG8_LDA(At, 0, 0); PG8_STAGE(PG8_SA(1, 1), a1 + hstepA, voffA);
;             PG8_WAIT_V(8); PG8_WAIT_L(0); PG8_BAR; PG8_MMA(0, 0, At, B0); PG8_MMA(0, 1, At, B1); PG8_BAR; PG8_SCHED;
;     ...
; #pragma unroll
;         for (int a = 0; a < 2; ++a)
; #pragma unroll
;             for (int b = 0; b < 2; ++b)
; #pragma unroll
;                 for (int m = 0; m < 4; ++m)
; #pragma unroll
;                     for (int n = 0; n < 2; ++n) acc[a][b][m][n] = (f32x4){0.f, 0.f, 0.f, 0.f};
;         }
;         cur = nxt; cA = nA; cB = nB; ++ui;
.LBB0_401:
	s_ashr_i32 s25, s24, 31
	s_lshl_b64 s[26:27], s[24:25], 19
	s_add_u32 s26, s8, s26
	s_addc_u32 s27, s9, s27
	s_and_b64 s[28:29], s[4:5], exec
	s_cselect_b32 s25, s27, s31
	s_cselect_b32 s70, s26, s30
	s_ashr_i32 s23, s22, 31
	s_lshl_b64 s[28:29], s[22:23], 19
	s_add_u32 s28, s41, s28
	s_addc_u32 s29, s50, s29
	s_and_b64 s[36:37], s[4:5], exec
	s_cselect_b32 s23, s29, s35
	s_cselect_b32 s71, s28, s34
	s_add_u32 s30, s30, 0x40080
	s_addc_u32 s31, s31, 0
	s_add_u32 s72, s34, 0x100
	v_mov_b32_e32 v0, 0
	s_addc_u32 s73, s35, 0
	s_mov_b32 s74, -2
	s_waitcnt lgkmcnt(0)
	v_mov_b32_e32 v1, v0
	v_mov_b32_e32 v2, v0
	v_mov_b32_e32 v3, v0
	v_mov_b32_e32 v4, v0
	v_mov_b32_e32 v5, v0
	v_mov_b32_e32 v6, v0
	v_mov_b32_e32 v7, v0
	v_mov_b32_e32 v8, v0
	v_mov_b32_e32 v9, v0
	v_mov_b32_e32 v10, v0
	v_mov_b32_e32 v11, v0
	v_mov_b32_e32 v12, v0
	v_mov_b32_e32 v13, v0
	v_mov_b32_e32 v14, v0
	v_mov_b32_e32 v15, v0
	v_mov_b32_e32 v16, v0
	v_mov_b32_e32 v17, v0
	v_mov_b32_e32 v18, v0
	v_mov_b32_e32 v19, v0
	v_mov_b32_e32 v20, v0
	v_mov_b32_e32 v21, v0
	v_mov_b32_e32 v22, v0
	v_mov_b32_e32 v23, v0
	v_mov_b32_e32 v24, v0
	v_mov_b32_e32 v25, v0
	v_mov_b32_e32 v26, v0
	v_mov_b32_e32 v27, v0
	v_mov_b32_e32 v28, v0
	v_mov_b32_e32 v29, v0
	v_mov_b32_e32 v30, v0
	v_mov_b32_e32 v31, v0
	v_mov_b32_e32 v64, v0
	v_mov_b32_e32 v65, v0
	v_mov_b32_e32 v66, v0
	v_mov_b32_e32 v67, v0
	v_mov_b32_e32 v68, v0
	v_mov_b32_e32 v69, v0
	v_mov_b32_e32 v70, v0
	v_mov_b32_e32 v71, v0
	v_mov_b32_e32 v72, v0
	v_mov_b32_e32 v73, v0
	v_mov_b32_e32 v74, v0
	v_mov_b32_e32 v75, v0
	v_mov_b32_e32 v76, v0
	v_mov_b32_e32 v77, v0
	v_mov_b32_e32 v78, v0
	v_mov_b32_e32 v79, v0
	v_mov_b32_e32 v80, v0
	v_mov_b32_e32 v81, v0
	v_mov_b32_e32 v82, v0
	v_mov_b32_e32 v83, v0
	v_mov_b32_e32 v84, v0
	v_mov_b32_e32 v85, v0
	v_mov_b32_e32 v86, v0
	v_mov_b32_e32 v87, v0
	v_mov_b32_e32 v88, v0
	v_mov_b32_e32 v89, v0
	v_mov_b32_e32 v90, v0
	v_mov_b32_e32 v91, v0
	v_mov_b32_e32 v92, v0
	v_mov_b32_e32 v93, v0
	v_mov_b32_e32 v94, v0
	v_mov_b32_e32 v95, v0
	v_mov_b32_e32 v32, v0
	v_mov_b32_e32 v33, v0
	v_mov_b32_e32 v34, v0
	v_mov_b32_e32 v35, v0
	v_mov_b32_e32 v36, v0
	v_mov_b32_e32 v37, v0
	v_mov_b32_e32 v38, v0
	v_mov_b32_e32 v39, v0
	v_mov_b32_e32 v40, v0
	v_mov_b32_e32 v41, v0
	v_mov_b32_e32 v42, v0
	v_mov_b32_e32 v43, v0
	v_mov_b32_e32 v44, v0
	v_mov_b32_e32 v45, v0
	v_mov_b32_e32 v46, v0
	v_mov_b32_e32 v47, v0
	v_mov_b32_e32 v48, v0
	v_mov_b32_e32 v49, v0
	v_mov_b32_e32 v50, v0
	v_mov_b32_e32 v51, v0
	v_mov_b32_e32 v52, v0
	v_mov_b32_e32 v53, v0
	v_mov_b32_e32 v54, v0
	v_mov_b32_e32 v55, v0
	v_mov_b32_e32 v56, v0
	v_mov_b32_e32 v57, v0
	v_mov_b32_e32 v58, v0
	v_mov_b32_e32 v59, v0
	v_mov_b32_e32 v60, v0
	v_mov_b32_e32 v61, v0
	v_mov_b32_e32 v62, v0
	v_mov_b32_e32 v63, v0
	v_mov_b32_e32 v96, v0
	v_mov_b32_e32 v97, v0
	v_mov_b32_e32 v98, v0
	v_mov_b32_e32 v99, v0
	v_mov_b32_e32 v100, v0
	v_mov_b32_e32 v101, v0
	v_mov_b32_e32 v102, v0
	v_mov_b32_e32 v103, v0
	v_mov_b32_e32 v104, v0
	v_mov_b32_e32 v105, v0
	v_mov_b32_e32 v106, v0
	v_mov_b32_e32 v107, v0
	v_mov_b32_e32 v108, v0
	v_mov_b32_e32 v109, v0
	v_mov_b32_e32 v110, v0
	v_mov_b32_e32 v111, v0
	v_mov_b32_e32 v112, v0
	v_mov_b32_e32 v113, v0
	v_mov_b32_e32 v114, v0
	v_mov_b32_e32 v115, v0
	v_mov_b32_e32 v116, v0
	v_mov_b32_e32 v117, v0
	v_mov_b32_e32 v118, v0
	v_mov_b32_e32 v119, v0
	v_mov_b32_e32 v120, v0
	v_mov_b32_e32 v121, v0
	v_mov_b32_e32 v122, v0
	v_mov_b32_e32 v123, v0
	v_mov_b32_e32 v124, v0
	v_mov_b32_e32 v125, v0
	v_mov_b32_e32 v126, v0
	v_mov_b32_e32 v127, v0
	v_readfirstlane_b32 s98, v186
	s_lshr_b32 s98, s98, 8
	s_cmp_eq_u32 s98, 0
	s_cbranch_scc1 .Lprio_skip_4
	s_setprio 1
.Lprio_skip_4:
.LBB0_402:
	ds_read_b128 v[146:149], v169
	ds_read_b128 v[150:153], v169 offset:1024
	ds_read_b128 v[154:157], v169 offset:2048
	ds_read_b128 v[174:177], v169 offset:3072
	ds_read_b128 v[178:181], v170
	ds_read_b128 v[182:185], v170 offset:1024
	ds_read_b128 v[188:191], v170 offset:2048
	ds_read_b128 v[192:195], v170 offset:3072
	s_add_u32 s34, s30, 0xfffc0080
	s_addc_u32 s35, s31, -1
	s_cmp_eq_u32 s74, 12
	s_cselect_b32 s37, s25, s35
	s_cselect_b32 s36, s70, s34
	s_cselect_b32 s35, s23, s73
	s_cselect_b32 s34, s71, s72
	s_add_i32 m0, s52, 0xc000
	ds_read_b128 v[196:199], v171
	ds_read_b128 v[200:203], v171 offset:1024
	ds_read_b128 v[204:207], v171 offset:2048
	ds_read_b128 v[208:211], v171 offset:3072
	ds_read_b128 v[212:215], v171 offset:4096
	ds_read_b128 v[216:219], v171 offset:5120
	ds_read_b128 v[220:223], v171 offset:6144
	ds_read_b128 v[224:227], v171 offset:7168
	global_load_lds_dwordx4 v138, s[30:31]
	s_add_i32 m0, s52, 0xe000
	s_nop 0
	global_load_lds_dwordx4 v140, s[30:31]
	s_waitcnt vmcnt(8)
	s_waitcnt lgkmcnt(0)
	s_barrier
; #define PG8_STAGE(bufoff, gbase, voff) do { _Pragma("unroll") for (int _i = 0; _i < 2; ++_i) \
;         __builtin_amdgcn_global_load_lds((const unsigned*)((const char*)(gbase) + (voff)[_i]), (PG8_LAS unsigned*)(lds + (bufoff) + ldsw + _i * 8192), 16, 0, 0); } while (0)
; #define PG8_LDA(dst, b, h) do { _Pragma("unroll") for (int m = 0; m < 4; ++m) _Pragma("unroll") for (int k = 0; k < 2; ++k) dst[m][k] = *(const PG8_LAS bf16x8*)(lds + PG8_SA(b, h) + aoff + m * 2048 + k * 1024); } while (0)
; #define PG8_MMA(ai, bj, At, Bt) do { __builtin_amdgcn_s_setprio(1); _Pragma("unroll") for (int m = 0; m < 4; ++m) _Pragma("unroll") for (int n = 0; n < 2; ++n) _Pragma("unroll") for (int k = 0; k < 2; ++k) \
;         acc[ai][bj][m][n] = __builtin_amdgcn_mfma_f32_16x16x32_bf16(Bt[n][k], At[m][k], acc[ai][bj][m][n], 0, 0, 0); __builtin_amdgcn_s_setprio(0); } while (0)
; #define PG8_WAIT_V(n) asm volatile("s_waitcnt vmcnt(" #n ")" ::: "memory")
; #define PG8_WAIT_L(n) asm volatile("s_waitcnt lgkmcnt(" #n ")" ::: "memory")
; #define PG8_BAR __builtin_amdgcn_s_barrier()
; #define PG8_SCHED __builtin_amdgcn_sched_barrier(0)
; template <class Epi, class Sched, bool ALIGN_EPI = false, bool SP2 = false>
; __device__ __forceinline__ void gemm_phase(PG8_LAS unsigned char* lds, const Gemm g, const Sched S, const Epi E, const int tid) {
;     ...
;             PG8_WAIT_V(8); PG8_WAIT_L(0); PG8_BAR; PG8_MMA(0, 0, At, B0); PG8_MMA(0, 1, At, B1); PG8_BAR; PG8_SCHED;
;             PG8_LDA(At, 0, 1); PG8_STAGE(PG8_SB(0, 0), b2, voffB); PG8_STAGE(PG8_SB(0, 1), b2 + hstepB, voffB); PG8_STAGE(PG8_SA(0, 0), a2, voffA);
;             PG8_WAIT_V(8); PG8_WAIT_L(0); PG8_BAR; PG8_MMA(1, 0, At, B0); PG8_MMA(1, 1, At, B1); PG8_BAR; PG8_SCHED;
	s_waitcnt lgkmcnt(0)
	v_mfma_f32_16x16x32_bf16 v[124:127], v[146:149], v[196:199], v[124:127]
	v_mfma_f32_16x16x32_bf16 v[120:123], v[154:157], v[196:199], v[120:123]
	v_mfma_f32_16x16x32_bf16 v[116:119], v[146:149], v[204:207], v[116:119]
	v_mfma_f32_16x16x32_bf16 v[112:115], v[154:157], v[204:207], v[112:115]
	v_mfma_f32_16x16x32_bf16 v[108:111], v[146:149], v[212:215], v[108:111]
	v_mfma_f32_16x16x32_bf16 v[104:107], v[154:157], v[212:215], v[104:107]
	v_mfma_f32_16x16x32_bf16 v[100:103], v[146:149], v[220:223], v[100:103]
	v_mfma_f32_16x16x32_bf16 v[96:99], v[154:157], v[220:223], v[96:99]
	v_mfma_f32_16x16x32_bf16 v[124:127], v[150:153], v[200:203], v[124:127]
	v_mfma_f32_16x16x32_bf16 v[120:123], v[174:177], v[200:203], v[120:123]
	v_mfma_f32_16x16x32_bf16 v[116:119], v[150:153], v[208:211], v[116:119]
	v_mfma_f32_16x16x32_bf16 v[112:115], v[174:177], v[208:211], v[112:115]
	v_mfma_f32_16x16x32_bf16 v[108:111], v[150:153], v[216:219], v[108:111]
	v_mfma_f32_16x16x32_bf16 v[104:107], v[174:177], v[216:219], v[104:107]
	v_mfma_f32_16x16x32_bf16 v[100:103], v[150:153], v[224:227], v[100:103]
	v_mfma_f32_16x16x32_bf16 v[96:99], v[174:177], v[224:227], v[96:99]
	v_mfma_f32_16x16x32_bf16 v[60:63], v[178:181], v[196:199], v[60:63]
	v_mfma_f32_16x16x32_bf16 v[56:59], v[188:191], v[196:199], v[56:59]
	v_mfma_f32_16x16x32_bf16 v[52:55], v[178:181], v[204:207], v[52:55]
	v_mfma_f32_16x16x32_bf16 v[48:51], v[188:191], v[204:207], v[48:51]
	v_mfma_f32_16x16x32_bf16 v[44:47], v[178:181], v[212:215], v[44:47]
	v_mfma_f32_16x16x32_bf16 v[40:43], v[188:191], v[212:215], v[40:43]
	v_mfma_f32_16x16x32_bf16 v[36:39], v[178:181], v[220:223], v[36:39]
	v_mfma_f32_16x16x32_bf16 v[32:35], v[188:191], v[220:223], v[32:35]
	v_mfma_f32_16x16x32_bf16 v[60:63], v[182:185], v[200:203], v[60:63]
	v_mfma_f32_16x16x32_bf16 v[56:59], v[192:195], v[200:203], v[56:59]
	v_mfma_f32_16x16x32_bf16 v[52:55], v[182:185], v[208:211], v[52:55]
	v_mfma_f32_16x16x32_bf16 v[48:51], v[192:195], v[208:211], v[48:51]
	v_mfma_f32_16x16x32_bf16 v[44:47], v[182:185], v[216:219], v[44:47]
	v_mfma_f32_16x16x32_bf16 v[40:43], v[192:195], v[216:219], v[40:43]
	v_mfma_f32_16x16x32_bf16 v[36:39], v[182:185], v[224:227], v[36:39]
	v_mfma_f32_16x16x32_bf16 v[32:35], v[192:195], v[224:227], v[32:35]
	s_barrier
	s_add_u32 s98, s34, 0x80
	s_addc_u32 s99, s35, 0
	s_add_u32 s100, s36, 0x80
	s_addc_u32 s101, s37, 0
	s_add_i32 s75, s63, s33
	s_mov_b32 m0, s75
	ds_read_b128 v[196:199], v171 offset:16384
	ds_read_b128 v[200:203], v171 offset:17408
	ds_read_b128 v[204:207], v171 offset:18432
	ds_read_b128 v[208:211], v171 offset:19456
	ds_read_b128 v[212:215], v171 offset:20480
	ds_read_b128 v[216:219], v171 offset:21504
	ds_read_b128 v[220:223], v171 offset:22528
	ds_read_b128 v[224:227], v171 offset:23552
	global_load_lds_dwordx4 v134, s[34:35]
	s_add_i32 m0, s75, 0x2000
	s_add_u32 s76, s34, 0x40000
	s_addc_u32 s77, s35, 0
	s_add_i32 s75, s64, s33
	global_load_lds_dwordx4 v130, s[34:35]
	s_mov_b32 m0, s75
	s_nop 0
	global_load_lds_dwordx4 v134, s[76:77]
	s_add_i32 m0, s75, 0x2000
	s_nop 0
	global_load_lds_dwordx4 v130, s[76:77]
	s_mov_b32 m0, s52
	s_nop 0
	global_load_lds_dwordx4 v136, s[36:37]
	s_mov_b32 m0, s54
	s_nop 0
	global_load_lds_dwordx4 v132, s[36:37]
	s_waitcnt vmcnt(8)
	s_waitcnt lgkmcnt(0)
	s_barrier
	s_waitcnt lgkmcnt(0)
	v_mfma_f32_16x16x32_bf16 v[92:95], v[146:149], v[196:199], v[92:95]
	v_mfma_f32_16x16x32_bf16 v[88:91], v[154:157], v[196:199], v[88:91]
	v_mfma_f32_16x16x32_bf16 v[84:87], v[146:149], v[204:207], v[84:87]
	v_mfma_f32_16x16x32_bf16 v[80:83], v[154:157], v[204:207], v[80:83]
	v_mfma_f32_16x16x32_bf16 v[76:79], v[146:149], v[212:215], v[76:79]
	v_mfma_f32_16x16x32_bf16 v[72:75], v[154:157], v[212:215], v[72:75]
	v_mfma_f32_16x16x32_bf16 v[68:71], v[146:149], v[220:223], v[68:71]
	v_mfma_f32_16x16x32_bf16 v[64:67], v[154:157], v[220:223], v[64:67]
	v_mfma_f32_16x16x32_bf16 v[92:95], v[150:153], v[200:203], v[92:95]
	v_mfma_f32_16x16x32_bf16 v[88:91], v[174:177], v[200:203], v[88:91]
	v_mfma_f32_16x16x32_bf16 v[84:87], v[150:153], v[208:211], v[84:87]
	v_mfma_f32_16x16x32_bf16 v[80:83], v[174:177], v[208:211], v[80:83]
	v_mfma_f32_16x16x32_bf16 v[76:79], v[150:153], v[216:219], v[76:79]
	v_mfma_f32_16x16x32_bf16 v[72:75], v[174:177], v[216:219], v[72:75]
	v_mfma_f32_16x16x32_bf16 v[68:71], v[150:153], v[224:227], v[68:71]
	v_mfma_f32_16x16x32_bf16 v[64:67], v[174:177], v[224:227], v[64:67]
	v_mfma_f32_16x16x32_bf16 v[28:31], v[178:181], v[196:199], v[28:31]
	v_mfma_f32_16x16x32_bf16 v[24:27], v[188:191], v[196:199], v[24:27]
	v_mfma_f32_16x16x32_bf16 v[20:23], v[178:181], v[204:207], v[20:23]
	v_mfma_f32_16x16x32_bf16 v[16:19], v[188:191], v[204:207], v[16:19]
	v_mfma_f32_16x16x32_bf16 v[12:15], v[178:181], v[212:215], v[12:15]
	v_mfma_f32_16x16x32_bf16 v[8:11], v[188:191], v[212:215], v[8:11]
	v_mfma_f32_16x16x32_bf16 v[4:7], v[178:181], v[220:223], v[4:7]
	v_mfma_f32_16x16x32_bf16 v[0:3], v[188:191], v[220:223], v[0:3]
	v_mfma_f32_16x16x32_bf16 v[28:31], v[182:185], v[200:203], v[28:31]
	v_mfma_f32_16x16x32_bf16 v[24:27], v[192:195], v[200:203], v[24:27]
	v_mfma_f32_16x16x32_bf16 v[20:23], v[182:185], v[208:211], v[20:23]
	v_mfma_f32_16x16x32_bf16 v[16:19], v[192:195], v[208:211], v[16:19]
	v_mfma_f32_16x16x32_bf16 v[12:15], v[182:185], v[216:219], v[12:15]
	v_mfma_f32_16x16x32_bf16 v[8:11], v[192:195], v[216:219], v[8:11]
	v_mfma_f32_16x16x32_bf16 v[4:7], v[182:185], v[224:227], v[4:7]
	v_mfma_f32_16x16x32_bf16 v[0:3], v[192:195], v[224:227], v[0:3]
	s_barrier
; #define PG8_STAGE(bufoff, gbase, voff) do { _Pragma("unroll") for (int _i = 0; _i < 2; ++_i) \
;         __builtin_amdgcn_global_load_lds((const unsigned*)((const char*)(gbase) + (voff)[_i]), (PG8_LAS unsigned*)(lds + (bufoff) + ldsw + _i * 8192), 16, 0, 0); } while (0)
; #define PG8_LDA(dst, b, h) do { _Pragma("unroll") for (int m = 0; m < 4; ++m) _Pragma("unroll") for (int k = 0; k < 2; ++k) dst[m][k] = *(const PG8_LAS bf16x8*)(lds + PG8_SA(b, h) + aoff + m * 2048 + k * 1024); } while (0)
; #define PG8_LDB(dst, b, h) do { _Pragma("unroll") for (int n = 0; n < 2; ++n) _Pragma("unroll") for (int k = 0; k < 2; ++k) dst[n][k] = *(const PG8_LAS bf16x8*)(lds + PG8_SB(b, h) + boff + n * 2048 + k * 1024); } while (0)
; #define PG8_MMA(ai, bj, At, Bt) do { __builtin_amdgcn_s_setprio(1); _Pragma("unroll") for (int m = 0; m < 4; ++m) _Pragma("unroll") for (int n = 0; n < 2; ++n) _Pragma("unroll") for (int k = 0; k < 2; ++k) \
;         acc[ai][bj][m][n] = __builtin_amdgcn_mfma_f32_16x16x32_bf16(Bt[n][k], At[m][k], acc[ai][bj][m][n], 0, 0, 0); __builtin_amdgcn_s_setprio(0); } while (0)
; #define PG8_WAIT_V(n) asm volatile("s_waitcnt vmcnt(" #n ")" ::: "memory")
; #define PG8_WAIT_L(n) asm volatile("s_waitcnt lgkmcnt(" #n ")" ::: "memory")
; template <class Epi, class Sched, bool ALIGN_EPI = false, bool SP2 = false>
; __device__ __forceinline__ void gemm_phase(PG8_LAS unsigned char* lds, const Gemm g, const Sched S, const Epi E, const int tid) {
;     ...
;         for (int t = 0; t < nt; t += 2) {
;             const bool last = (t == nt - 2);
;             const char* a1 = cA + (size_t)(t + 1) * kstep;
;             const char* a2 = last ? nA : cA + (size_t)(t + 2) * kstep; const char* b2 = last ? nB : cB + (size_t)(t + 2) * kstep;
;             const char* a3 = a2 + kstep; const char* b3 = b2 + kstep;
;             if (last && has_next) S.a_ready(nxt);
;     ...
;             PG8_LDB(B0, 1, 0); PG8_LDB(B1, 1, 1); PG8_SCHED; PG8_LDA(At, 1, 0); PG8_STAGE(PG8_SA(0, 1), a2 + hstepA, voffA);
;             PG8_WAIT_V(8); PG8_WAIT_L(0); PG8_BAR; PG8_MMA(0, 0, At, B0); PG8_MMA(0, 1, At, B1); PG8_BAR; PG8_SCHED;
;             PG8_LDA(At, 1, 1); PG8_STAGE(PG8_SB(1, 0), b3, voffB); PG8_STAGE(PG8_SB(1, 1), b3 + hstepB, voffB); PG8_STAGE(PG8_SA(1, 0), a3, voffA);
;             PG8_WAIT_V(8); PG8_WAIT_L(0); PG8_BAR; PG8_MMA(1, 0, At, B0); PG8_MMA(1, 1, At, B1); PG8_BAR; PG8_SCHED;
	s_add_i32 s75, 0, 0x18000
	v_add_u32_e32 v173, s75, v160
	s_add_i32 s76, 0, 0x1c000
	ds_read_b128 v[146:149], v173
	ds_read_b128 v[150:153], v173 offset:1024
	ds_read_b128 v[154:157], v173 offset:2048
	ds_read_b128 v[174:177], v173 offset:3072
	v_add_u32_e32 v173, s76, v160
	ds_read_b128 v[178:181], v173
	ds_read_b128 v[182:185], v173 offset:1024
	ds_read_b128 v[188:191], v173 offset:2048
	ds_read_b128 v[192:195], v173 offset:3072
	s_add_u32 s36, s36, 0x40000
	s_addc_u32 s37, s37, 0
	s_mov_b32 m0, s55
	ds_read_b128 v[196:199], v171 offset:32768
	ds_read_b128 v[200:203], v171 offset:33792
	ds_read_b128 v[204:207], v171 offset:34816
	ds_read_b128 v[208:211], v171 offset:35840
	ds_read_b128 v[212:215], v171 offset:36864
	ds_read_b128 v[216:219], v171 offset:37888
	ds_read_b128 v[220:223], v171 offset:38912
	ds_read_b128 v[224:227], v171 offset:39936
	global_load_lds_dwordx4 v136, s[36:37]
	s_mov_b32 m0, s57
	s_nop 0
	global_load_lds_dwordx4 v132, s[36:37]
	s_waitcnt vmcnt(8)
	s_waitcnt lgkmcnt(0)
	s_barrier
	s_waitcnt lgkmcnt(0)
	v_mfma_f32_16x16x32_bf16 v[124:127], v[146:149], v[196:199], v[124:127]
	v_mfma_f32_16x16x32_bf16 v[120:123], v[154:157], v[196:199], v[120:123]
	v_mfma_f32_16x16x32_bf16 v[116:119], v[146:149], v[204:207], v[116:119]
	v_mfma_f32_16x16x32_bf16 v[112:115], v[154:157], v[204:207], v[112:115]
	v_mfma_f32_16x16x32_bf16 v[108:111], v[146:149], v[212:215], v[108:111]
	v_mfma_f32_16x16x32_bf16 v[104:107], v[154:157], v[212:215], v[104:107]
	v_mfma_f32_16x16x32_bf16 v[100:103], v[146:149], v[220:223], v[100:103]
	v_mfma_f32_16x16x32_bf16 v[96:99], v[154:157], v[220:223], v[96:99]
	v_mfma_f32_16x16x32_bf16 v[124:127], v[150:153], v[200:203], v[124:127]
	v_mfma_f32_16x16x32_bf16 v[120:123], v[174:177], v[200:203], v[120:123]
	v_mfma_f32_16x16x32_bf16 v[116:119], v[150:153], v[208:211], v[116:119]
	v_mfma_f32_16x16x32_bf16 v[112:115], v[174:177], v[208:211], v[112:115]
	v_mfma_f32_16x16x32_bf16 v[108:111], v[150:153], v[216:219], v[108:111]
	v_mfma_f32_16x16x32_bf16 v[104:107], v[174:177], v[216:219], v[104:107]
	v_mfma_f32_16x16x32_bf16 v[100:103], v[150:153], v[224:227], v[100:103]
	v_mfma_f32_16x16x32_bf16 v[96:99], v[174:177], v[224:227], v[96:99]
	v_mfma_f32_16x16x32_bf16 v[60:63], v[178:181], v[196:199], v[60:63]
	v_mfma_f32_16x16x32_bf16 v[56:59], v[188:191], v[196:199], v[56:59]
	v_mfma_f32_16x16x32_bf16 v[52:55], v[178:181], v[204:207], v[52:55]
	v_mfma_f32_16x16x32_bf16 v[48:51], v[188:191], v[204:207], v[48:51]
	v_mfma_f32_16x16x32_bf16 v[44:47], v[178:181], v[212:215], v[44:47]
	v_mfma_f32_16x16x32_bf16 v[40:43], v[188:191], v[212:215], v[40:43]
	v_mfma_f32_16x16x32_bf16 v[36:39], v[178:181], v[220:223], v[36:39]
	v_mfma_f32_16x16x32_bf16 v[32:35], v[188:191], v[220:223], v[32:35]
	v_mfma_f32_16x16x32_bf16 v[60:63], v[182:185], v[200:203], v[60:63]
	v_mfma_f32_16x16x32_bf16 v[56:59], v[192:195], v[200:203], v[56:59]
	v_mfma_f32_16x16x32_bf16 v[52:55], v[182:185], v[208:211], v[52:55]
	v_mfma_f32_16x16x32_bf16 v[48:51], v[192:195], v[208:211], v[48:51]
	v_mfma_f32_16x16x32_bf16 v[44:47], v[182:185], v[216:219], v[44:47]
	v_mfma_f32_16x16x32_bf16 v[40:43], v[192:195], v[216:219], v[40:43]
	v_mfma_f32_16x16x32_bf16 v[36:39], v[182:185], v[224:227], v[36:39]
	v_mfma_f32_16x16x32_bf16 v[32:35], v[192:195], v[224:227], v[32:35]
	s_barrier
	s_add_i32 s36, s75, s33
	s_mov_b32 m0, s36
	ds_read_b128 v[196:199], v171 offset:49152
	ds_read_b128 v[200:203], v171 offset:50176
	ds_read_b128 v[204:207], v171 offset:51200
	ds_read_b128 v[208:211], v171 offset:52224
	ds_read_b128 v[212:215], v171 offset:53248
	ds_read_b128 v[216:219], v171 offset:54272
	ds_read_b128 v[220:223], v171 offset:55296
	ds_read_b128 v[224:227], v171 offset:56320
	global_load_lds_dwordx4 v134, s[98:99]
	s_add_i32 m0, s36, 0x2000
	s_add_u32 s34, s34, 0x40080
	s_addc_u32 s35, s35, 0
	s_add_i32 s36, s76, s33
	global_load_lds_dwordx4 v130, s[98:99]
	s_mov_b32 m0, s36
	s_nop 0
	global_load_lds_dwordx4 v134, s[34:35]
	s_add_i32 m0, s36, 0x2000
	s_nop 0
	global_load_lds_dwordx4 v130, s[34:35]
	s_mov_b32 m0, s58
	s_nop 0
	global_load_lds_dwordx4 v136, s[100:101]
	s_mov_b32 m0, s59
	s_nop 0
	global_load_lds_dwordx4 v132, s[100:101]
	s_waitcnt vmcnt(8)
	s_waitcnt lgkmcnt(0)
	s_barrier
	s_waitcnt lgkmcnt(0)
	v_mfma_f32_16x16x32_bf16 v[92:95], v[146:149], v[196:199], v[92:95]
	v_mfma_f32_16x16x32_bf16 v[88:91], v[154:157], v[196:199], v[88:91]
	v_mfma_f32_16x16x32_bf16 v[84:87], v[146:149], v[204:207], v[84:87]
	v_mfma_f32_16x16x32_bf16 v[80:83], v[154:157], v[204:207], v[80:83]
	v_mfma_f32_16x16x32_bf16 v[76:79], v[146:149], v[212:215], v[76:79]
	v_mfma_f32_16x16x32_bf16 v[72:75], v[154:157], v[212:215], v[72:75]
	v_mfma_f32_16x16x32_bf16 v[68:71], v[146:149], v[220:223], v[68:71]
	v_mfma_f32_16x16x32_bf16 v[64:67], v[154:157], v[220:223], v[64:67]
	v_mfma_f32_16x16x32_bf16 v[92:95], v[150:153], v[200:203], v[92:95]
	v_mfma_f32_16x16x32_bf16 v[88:91], v[174:177], v[200:203], v[88:91]
	v_mfma_f32_16x16x32_bf16 v[84:87], v[150:153], v[208:211], v[84:87]
	v_mfma_f32_16x16x32_bf16 v[80:83], v[174:177], v[208:211], v[80:83]
	v_mfma_f32_16x16x32_bf16 v[76:79], v[150:153], v[216:219], v[76:79]
	v_mfma_f32_16x16x32_bf16 v[72:75], v[174:177], v[216:219], v[72:75]
	v_mfma_f32_16x16x32_bf16 v[68:71], v[150:153], v[224:227], v[68:71]
	v_mfma_f32_16x16x32_bf16 v[64:67], v[174:177], v[224:227], v[64:67]
	v_mfma_f32_16x16x32_bf16 v[28:31], v[178:181], v[196:199], v[28:31]
	v_mfma_f32_16x16x32_bf16 v[24:27], v[188:191], v[196:199], v[24:27]
	v_mfma_f32_16x16x32_bf16 v[20:23], v[178:181], v[204:207], v[20:23]
	v_mfma_f32_16x16x32_bf16 v[16:19], v[188:191], v[204:207], v[16:19]
	v_mfma_f32_16x16x32_bf16 v[12:15], v[178:181], v[212:215], v[12:15]
	v_mfma_f32_16x16x32_bf16 v[8:11], v[188:191], v[212:215], v[8:11]
	v_mfma_f32_16x16x32_bf16 v[4:7], v[178:181], v[220:223], v[4:7]
	v_mfma_f32_16x16x32_bf16 v[0:3], v[188:191], v[220:223], v[0:3]
	v_mfma_f32_16x16x32_bf16 v[28:31], v[182:185], v[200:203], v[28:31]
	v_mfma_f32_16x16x32_bf16 v[24:27], v[192:195], v[200:203], v[24:27]
	v_mfma_f32_16x16x32_bf16 v[20:23], v[182:185], v[208:211], v[20:23]
	v_mfma_f32_16x16x32_bf16 v[16:19], v[192:195], v[208:211], v[16:19]
	v_mfma_f32_16x16x32_bf16 v[12:15], v[182:185], v[216:219], v[12:15]
	v_mfma_f32_16x16x32_bf16 v[8:11], v[192:195], v[216:219], v[8:11]
	v_mfma_f32_16x16x32_bf16 v[4:7], v[182:185], v[224:227], v[4:7]
	v_mfma_f32_16x16x32_bf16 v[0:3], v[192:195], v[224:227], v[0:3]
	s_barrier
	s_add_i32 s74, s74, 2
	s_add_u32 s30, s30, 0x100
	s_addc_u32 s31, s31, 0
	s_add_u32 s72, s72, 0x100
	s_addc_u32 s73, s73, 0
	s_cmp_gt_u32 s74, 13
	s_cbranch_scc0 .LBB0_402
	s_setprio 0
	s_and_b64 vcc, exec, s[18:19]
	s_cbranch_vccz .LBB0_405
	s_barrier

; #define PG8_STAGE(bufoff, gbase, voff) do { _Pragma("unroll") for (int _i = 0; _i < 2; ++_i) \
;         __builtin_amdgcn_global_load_lds((const unsigned*)((const char*)(gbase) + (voff)[_i]), (PG8_LAS unsigned*)(lds + (bufoff) + ldsw + _i * 8192), 16, 0, 0); } while (0)
; #define PG8_LDA(dst, b, h) do { _Pragma("unroll") for (int m = 0; m < 4; ++m) _Pragma("unroll") for (int k = 0; k < 2; ++k) dst[m][k] = *(const PG8_LAS bf16x8*)(lds + PG8_SA(b, h) + aoff + m * 2048 + k * 1024); } while (0)
; #define PG8_LDB(dst, b, h) do { _Pragma("unroll") for (int n = 0; n < 2; ++n) _Pragma("unroll") for (int k = 0; k < 2; ++k) dst[n][k] = *(const PG8_LAS bf16x8*)(lds + PG8_SB(b, h) + boff + n * 2048 + k * 1024); } while (0)
; #define PG8_WAIT_V(n) asm volatile("s_waitcnt vmcnt(" #n ")" ::: "memory")
; #define PG8_WAIT_L(n) asm volatile("s_waitcnt lgkmcnt(" #n ")" ::: "memory")
; #define PG8_BAR __builtin_amdgcn_s_barrier()
; #define PG8_SCHED __builtin_amdgcn_sched_barrier(0)
; template <class Epi, class Sched, bool ALIGN_EPI = false, bool SP2 = false>
; __device__ __forceinline__ void gemm_phase(PG8_LAS unsigned char* lds, const Gemm g, const Sched S, const Epi E, const int tid) {
;     ...
;         const char* nA = has_next ? (const char*)g.A + (size_t)nxt.pm * tstepA + (size_t)nxt.pn * apn : cA; const char* nB = has_next ? (const char*)g.Bt + (size_t)nxt.pn * bpn : cB;
;         for (int t = 0; t < nt; t += 2) {
;             const bool last = (t == nt - 2);
;             const char* a1 = cA + (size_t)(t + 1) * kstep;
;             const char* a2 = last ? nA : cA + (size_t)(t + 2) * kstep; const char* b2 = last ? nB : cB + (size_t)(t + 2) * kstep;
;             const char* a3 = a2 + kstep; const char* b3 = b2 + kstep;
;             if (last && has_next) S.a_ready(nxt);
;             if constexpr (SP2) {
;             PG8_LDB(B0, 0, 0); PG8_LDB(B1, 0, 1); PG8_SCHED; PG8_LDA(At, 0, 0); PG8_STAGE(PG8_SA(1, 1), a1 + hstepA, voffA);
;             PG8_WAIT_V(8); PG8_WAIT_L(0); PG8_BAR; PG8_MMA(0, 0, At, B0); PG8_MMA(0, 1, At, B1); PG8_BAR; PG8_SCHED;
;             PG8_LDA(At, 0, 1); PG8_STAGE(PG8_SB(0, 0), b2, voffB); PG8_STAGE(PG8_SB(0, 1), b2 + hstepB, voffB); PG8_STAGE(PG8_SA(0, 0), a2, voffA);
;             PG8_WAIT_V(8); PG8_WAIT_L(0); PG8_BAR; PG8_MMA(1, 0, At, B0); PG8_MMA(1, 1, At, B1); PG8_BAR; PG8_SCHED;
.LBB0_671:
	s_ashr_i32 s29, s28, 31
	s_lshl_b64 s[34:35], s[28:29], 19
	s_add_u32 s34, s54, s34
	s_addc_u32 s35, s55, s35
	s_and_b64 s[6:7], s[6:7], exec
	s_cselect_b32 s29, s35, s41
	s_cselect_b32 s37, s34, s40
	s_add_u32 s73, s40, 0x100
	s_addc_u32 s74, s41, 0
	s_mov_b32 s75, -2
	v_readfirstlane_b32 s98, v186
	s_lshr_b32 s98, s98, 8
	s_cmp_eq_u32 s98, 0
	s_cbranch_scc1 .Lprio_skip_5
	s_setprio 1
.Lprio_skip_5:
.LBB0_672:
	v_add_u32_e32 v162, s69, v149
	v_add_u32_e32 v178, s70, v149
	ds_read_b128 v[144:147], v162
	ds_read_b128 v[154:157], v162 offset:1024
	ds_read_b128 v[158:161], v162 offset:2048
	ds_read_b128 v[162:165], v162 offset:3072
	ds_read_b128 v[166:169], v178
	ds_read_b128 v[170:173], v178 offset:1024
	ds_read_b128 v[174:177], v178 offset:2048
	ds_read_b128 v[178:181], v178 offset:3072
	s_add_u32 s6, s38, 0x100
	s_addc_u32 s7, s39, 0
	s_cmp_eq_u32 s75, 12
	s_cselect_b32 s47, s31, s7
	s_cselect_b32 s46, s30, s6
	s_cselect_b32 s41, s29, s74
	s_cselect_b32 s40, s37, s73
	s_add_i32 m0, s58, 0xc000
	ds_read_b128 v[182:185], v153
	ds_read_b128 v[188:191], v153 offset:1024
	ds_read_b128 v[192:195], v153 offset:2048
	ds_read_b128 v[196:199], v153 offset:3072
	ds_read_b128 v[200:203], v153 offset:4096
	ds_read_b128 v[204:207], v153 offset:5120
	ds_read_b128 v[208:211], v153 offset:6144
	ds_read_b128 v[212:215], v153 offset:7168
	global_load_lds_dwordx4 v136, s[38:39]
	s_add_i32 m0, s58, 0xe000
	s_nop 0
	global_load_lds_dwordx4 v138, s[38:39]
	s_waitcnt vmcnt(8)
	s_waitcnt lgkmcnt(0)
	s_barrier
	s_waitcnt lgkmcnt(0)
	v_mfma_f32_16x16x32_bf16 v[112:115], v[144:147], v[182:185], v[112:115]
	v_mfma_f32_16x16x32_bf16 v[120:123], v[158:161], v[182:185], v[120:123]
	v_mfma_f32_16x16x32_bf16 v[96:99], v[144:147], v[192:195], v[96:99]
	v_mfma_f32_16x16x32_bf16 v[104:107], v[158:161], v[192:195], v[104:107]
	v_mfma_f32_16x16x32_bf16 v[80:83], v[144:147], v[200:203], v[80:83]
	v_mfma_f32_16x16x32_bf16 v[88:91], v[158:161], v[200:203], v[88:91]
	v_mfma_f32_16x16x32_bf16 v[64:67], v[144:147], v[208:211], v[64:67]
	v_mfma_f32_16x16x32_bf16 v[72:75], v[158:161], v[208:211], v[72:75]
	v_mfma_f32_16x16x32_bf16 v[112:115], v[154:157], v[188:191], v[112:115]
	v_mfma_f32_16x16x32_bf16 v[120:123], v[162:165], v[188:191], v[120:123]
	v_mfma_f32_16x16x32_bf16 v[96:99], v[154:157], v[196:199], v[96:99]
	v_mfma_f32_16x16x32_bf16 v[104:107], v[162:165], v[196:199], v[104:107]
	v_mfma_f32_16x16x32_bf16 v[80:83], v[154:157], v[204:207], v[80:83]
	v_mfma_f32_16x16x32_bf16 v[88:91], v[162:165], v[204:207], v[88:91]
	v_mfma_f32_16x16x32_bf16 v[64:67], v[154:157], v[212:215], v[64:67]
	v_mfma_f32_16x16x32_bf16 v[72:75], v[162:165], v[212:215], v[72:75]
	v_mfma_f32_16x16x32_bf16 v[116:119], v[166:169], v[182:185], v[116:119]
	v_mfma_f32_16x16x32_bf16 v[124:127], v[174:177], v[182:185], v[124:127]
	v_mfma_f32_16x16x32_bf16 v[100:103], v[166:169], v[192:195], v[100:103]
	v_mfma_f32_16x16x32_bf16 v[108:111], v[174:177], v[192:195], v[108:111]
	v_mfma_f32_16x16x32_bf16 v[84:87], v[166:169], v[200:203], v[84:87]
	v_mfma_f32_16x16x32_bf16 v[92:95], v[174:177], v[200:203], v[92:95]
	v_mfma_f32_16x16x32_bf16 v[68:71], v[166:169], v[208:211], v[68:71]
	v_mfma_f32_16x16x32_bf16 v[76:79], v[174:177], v[208:211], v[76:79]
	v_mfma_f32_16x16x32_bf16 v[116:119], v[170:173], v[188:191], v[116:119]
	v_mfma_f32_16x16x32_bf16 v[124:127], v[178:181], v[188:191], v[124:127]
	v_mfma_f32_16x16x32_bf16 v[100:103], v[170:173], v[196:199], v[100:103]
	v_mfma_f32_16x16x32_bf16 v[108:111], v[178:181], v[196:199], v[108:111]
	v_mfma_f32_16x16x32_bf16 v[84:87], v[170:173], v[204:207], v[84:87]
	v_mfma_f32_16x16x32_bf16 v[92:95], v[178:181], v[204:207], v[92:95]
	v_mfma_f32_16x16x32_bf16 v[68:71], v[170:173], v[212:215], v[68:71]
	v_mfma_f32_16x16x32_bf16 v[76:79], v[178:181], v[212:215], v[76:79]
	s_barrier
	s_add_u32 s98, s40, 0x80
	s_addc_u32 s99, s41, 0
	s_add_u32 s100, s46, 0x80
	s_addc_u32 s101, s47, 0
	s_add_i32 s38, s69, s33
	s_mov_b32 m0, s38
	ds_read_b128 v[182:185], v153 offset:16384
	ds_read_b128 v[188:191], v153 offset:17408
	ds_read_b128 v[192:195], v153 offset:18432
	ds_read_b128 v[196:199], v153 offset:19456
	ds_read_b128 v[200:203], v153 offset:20480
	ds_read_b128 v[204:207], v153 offset:21504
	ds_read_b128 v[208:211], v153 offset:22528
	ds_read_b128 v[212:215], v153 offset:23552
	global_load_lds_dwordx4 v130, s[40:41]
	s_add_i32 m0, s38, 0x2000
	s_add_u32 s38, s40, 0x40000
	s_addc_u32 s39, s41, 0
	s_add_i32 s76, s70, s33
	global_load_lds_dwordx4 v134, s[40:41]
	s_mov_b32 m0, s76
	s_nop 0
	global_load_lds_dwordx4 v130, s[38:39]
	s_add_i32 m0, s76, 0x2000
	s_nop 0
	global_load_lds_dwordx4 v134, s[38:39]
	s_mov_b32 m0, s58
	s_nop 0
	global_load_lds_dwordx4 v128, s[46:47]
	s_mov_b32 m0, s59
	s_nop 0
	global_load_lds_dwordx4 v132, s[46:47]
	s_waitcnt vmcnt(8)
	s_waitcnt lgkmcnt(0)
	s_barrier
; #define PG8_STAGE(bufoff, gbase, voff) do { _Pragma("unroll") for (int _i = 0; _i < 2; ++_i) \
;         __builtin_amdgcn_global_load_lds((const unsigned*)((const char*)(gbase) + (voff)[_i]), (PG8_LAS unsigned*)(lds + (bufoff) + ldsw + _i * 8192), 16, 0, 0); } while (0)
; #define PG8_LDA(dst, b, h) do { _Pragma("unroll") for (int m = 0; m < 4; ++m) _Pragma("unroll") for (int k = 0; k < 2; ++k) dst[m][k] = *(const PG8_LAS bf16x8*)(lds + PG8_SA(b, h) + aoff + m * 2048 + k * 1024); } while (0)
; #define PG8_LDB(dst, b, h) do { _Pragma("unroll") for (int n = 0; n < 2; ++n) _Pragma("unroll") for (int k = 0; k < 2; ++k) dst[n][k] = *(const PG8_LAS bf16x8*)(lds + PG8_SB(b, h) + boff + n * 2048 + k * 1024); } while (0)
; #define PG8_MMA(ai, bj, At, Bt) do { __builtin_amdgcn_s_setprio(1); _Pragma("unroll") for (int m = 0; m < 4; ++m) _Pragma("unroll") for (int n = 0; n < 2; ++n) _Pragma("unroll") for (int k = 0; k < 2; ++k) \
;         acc[ai][bj][m][n] = __builtin_amdgcn_mfma_f32_16x16x32_bf16(Bt[n][k], At[m][k], acc[ai][bj][m][n], 0, 0, 0); __builtin_amdgcn_s_setprio(0); } while (0)
; #define PG8_WAIT_V(n) asm volatile("s_waitcnt vmcnt(" #n ")" ::: "memory")
; #define PG8_WAIT_L(n) asm volatile("s_waitcnt lgkmcnt(" #n ")" ::: "memory")
; #define PG8_BAR __builtin_amdgcn_s_barrier()
; #define PG8_SCHED __builtin_amdgcn_sched_barrier(0)
; template <class Epi, class Sched, bool ALIGN_EPI = false, bool SP2 = false>
; __device__ __forceinline__ void gemm_phase(PG8_LAS unsigned char* lds, const Gemm g, const Sched S, const Epi E, const int tid) {
;     ...
;             PG8_WAIT_V(8); PG8_WAIT_L(0); PG8_BAR; PG8_MMA(1, 0, At, B0); PG8_MMA(1, 1, At, B1); PG8_BAR; PG8_SCHED;
;             PG8_LDB(B0, 1, 0); PG8_LDB(B1, 1, 1); PG8_SCHED; PG8_LDA(At, 1, 0); PG8_STAGE(PG8_SA(0, 1), a2 + hstepA, voffA);
;             PG8_WAIT_V(8); PG8_WAIT_L(0); PG8_BAR; PG8_MMA(0, 0, At, B0); PG8_MMA(0, 1, At, B1); PG8_BAR; PG8_SCHED;
;             PG8_LDA(At, 1, 1); PG8_STAGE(PG8_SB(1, 0), b3, voffB); PG8_STAGE(PG8_SB(1, 1), b3 + hstepB, voffB); PG8_STAGE(PG8_SA(1, 0), a3, voffA);
	s_waitcnt lgkmcnt(0)
	v_mfma_f32_16x16x32_bf16 v[48:51], v[144:147], v[182:185], v[48:51]
	v_mfma_f32_16x16x32_bf16 v[56:59], v[158:161], v[182:185], v[56:59]
	v_mfma_f32_16x16x32_bf16 v[24:27], v[144:147], v[192:195], v[24:27]
	v_mfma_f32_16x16x32_bf16 v[32:35], v[158:161], v[192:195], v[32:35]
	v_mfma_f32_16x16x32_bf16 v[0:3], v[144:147], v[200:203], v[0:3]
	v_mfma_f32_16x16x32_bf16 v[4:7], v[158:161], v[200:203], v[4:7]
	v_mfma_f32_16x16x32_bf16 v[8:11], v[144:147], v[208:211], v[8:11]
	v_mfma_f32_16x16x32_bf16 v[16:19], v[158:161], v[208:211], v[16:19]
	v_mfma_f32_16x16x32_bf16 v[48:51], v[154:157], v[188:191], v[48:51]
	v_mfma_f32_16x16x32_bf16 v[56:59], v[162:165], v[188:191], v[56:59]
	v_mfma_f32_16x16x32_bf16 v[24:27], v[154:157], v[196:199], v[24:27]
	v_mfma_f32_16x16x32_bf16 v[32:35], v[162:165], v[196:199], v[32:35]
	v_mfma_f32_16x16x32_bf16 v[0:3], v[154:157], v[204:207], v[0:3]
	v_mfma_f32_16x16x32_bf16 v[4:7], v[162:165], v[204:207], v[4:7]
	v_mfma_f32_16x16x32_bf16 v[8:11], v[154:157], v[212:215], v[8:11]
	v_mfma_f32_16x16x32_bf16 v[16:19], v[162:165], v[212:215], v[16:19]
	v_mfma_f32_16x16x32_bf16 v[52:55], v[166:169], v[182:185], v[52:55]
	v_mfma_f32_16x16x32_bf16 v[60:63], v[174:177], v[182:185], v[60:63]
	v_mfma_f32_16x16x32_bf16 v[28:31], v[166:169], v[192:195], v[28:31]
	v_mfma_f32_16x16x32_bf16 v[36:39], v[174:177], v[192:195], v[36:39]
	v_mfma_f32_16x16x32_bf16 v[40:43], v[166:169], v[200:203], v[40:43]
	v_mfma_f32_16x16x32_bf16 v[44:47], v[174:177], v[200:203], v[44:47]
	v_mfma_f32_16x16x32_bf16 v[12:15], v[166:169], v[208:211], v[12:15]
	v_mfma_f32_16x16x32_bf16 v[20:23], v[174:177], v[208:211], v[20:23]
	v_mfma_f32_16x16x32_bf16 v[52:55], v[170:173], v[188:191], v[52:55]
	v_mfma_f32_16x16x32_bf16 v[60:63], v[178:181], v[188:191], v[60:63]
	v_mfma_f32_16x16x32_bf16 v[28:31], v[170:173], v[196:199], v[28:31]
	v_mfma_f32_16x16x32_bf16 v[36:39], v[178:181], v[196:199], v[36:39]
	v_mfma_f32_16x16x32_bf16 v[40:43], v[170:173], v[204:207], v[40:43]
	v_mfma_f32_16x16x32_bf16 v[44:47], v[178:181], v[204:207], v[44:47]
	v_mfma_f32_16x16x32_bf16 v[12:15], v[170:173], v[212:215], v[12:15]
	v_mfma_f32_16x16x32_bf16 v[20:23], v[178:181], v[212:215], v[20:23]
	s_barrier
	s_add_i32 s76, 0, 0x18000
	s_add_i32 s77, 0, 0x1c000
	v_add_u32_e32 v162, s76, v149
	v_add_u32_e32 v178, s77, v149
	ds_read_b128 v[144:147], v162
	ds_read_b128 v[154:157], v162 offset:1024
	ds_read_b128 v[158:161], v162 offset:2048
	ds_read_b128 v[162:165], v162 offset:3072
	ds_read_b128 v[166:169], v178
	ds_read_b128 v[170:173], v178 offset:1024
	ds_read_b128 v[174:177], v178 offset:2048
	ds_read_b128 v[178:181], v178 offset:3072
	s_add_u32 s38, s46, 0xc0000
	s_addc_u32 s39, s47, 0
	s_mov_b32 m0, s60
	ds_read_b128 v[182:185], v153 offset:32768
	ds_read_b128 v[188:191], v153 offset:33792
	ds_read_b128 v[192:195], v153 offset:34816
	ds_read_b128 v[196:199], v153 offset:35840
	ds_read_b128 v[200:203], v153 offset:36864
	ds_read_b128 v[204:207], v153 offset:37888
	ds_read_b128 v[208:211], v153 offset:38912
	ds_read_b128 v[212:215], v153 offset:39936
	global_load_lds_dwordx4 v128, s[38:39]
	s_mov_b32 m0, s61
	s_nop 0
	global_load_lds_dwordx4 v132, s[38:39]
	s_waitcnt vmcnt(8)
	s_waitcnt lgkmcnt(0)
	s_barrier
	s_waitcnt lgkmcnt(0)
	v_mfma_f32_16x16x32_bf16 v[112:115], v[144:147], v[182:185], v[112:115]
	v_mfma_f32_16x16x32_bf16 v[120:123], v[158:161], v[182:185], v[120:123]
	v_mfma_f32_16x16x32_bf16 v[96:99], v[144:147], v[192:195], v[96:99]
	v_mfma_f32_16x16x32_bf16 v[104:107], v[158:161], v[192:195], v[104:107]
	v_mfma_f32_16x16x32_bf16 v[80:83], v[144:147], v[200:203], v[80:83]
	v_mfma_f32_16x16x32_bf16 v[88:91], v[158:161], v[200:203], v[88:91]
	v_mfma_f32_16x16x32_bf16 v[64:67], v[144:147], v[208:211], v[64:67]
	v_mfma_f32_16x16x32_bf16 v[72:75], v[158:161], v[208:211], v[72:75]
	v_mfma_f32_16x16x32_bf16 v[112:115], v[154:157], v[188:191], v[112:115]
	v_mfma_f32_16x16x32_bf16 v[120:123], v[162:165], v[188:191], v[120:123]
	v_mfma_f32_16x16x32_bf16 v[96:99], v[154:157], v[196:199], v[96:99]
	v_mfma_f32_16x16x32_bf16 v[104:107], v[162:165], v[196:199], v[104:107]
	v_mfma_f32_16x16x32_bf16 v[80:83], v[154:157], v[204:207], v[80:83]
	v_mfma_f32_16x16x32_bf16 v[88:91], v[162:165], v[204:207], v[88:91]
	v_mfma_f32_16x16x32_bf16 v[64:67], v[154:157], v[212:215], v[64:67]
	v_mfma_f32_16x16x32_bf16 v[72:75], v[162:165], v[212:215], v[72:75]
	v_mfma_f32_16x16x32_bf16 v[116:119], v[166:169], v[182:185], v[116:119]
	v_mfma_f32_16x16x32_bf16 v[124:127], v[174:177], v[182:185], v[124:127]
	v_mfma_f32_16x16x32_bf16 v[100:103], v[166:169], v[192:195], v[100:103]
	v_mfma_f32_16x16x32_bf16 v[108:111], v[174:177], v[192:195], v[108:111]
	v_mfma_f32_16x16x32_bf16 v[84:87], v[166:169], v[200:203], v[84:87]
	v_mfma_f32_16x16x32_bf16 v[92:95], v[174:177], v[200:203], v[92:95]
	v_mfma_f32_16x16x32_bf16 v[68:71], v[166:169], v[208:211], v[68:71]
	v_mfma_f32_16x16x32_bf16 v[76:79], v[174:177], v[208:211], v[76:79]
	v_mfma_f32_16x16x32_bf16 v[116:119], v[170:173], v[188:191], v[116:119]
	v_mfma_f32_16x16x32_bf16 v[124:127], v[178:181], v[188:191], v[124:127]
	v_mfma_f32_16x16x32_bf16 v[100:103], v[170:173], v[196:199], v[100:103]
	v_mfma_f32_16x16x32_bf16 v[108:111], v[178:181], v[196:199], v[108:111]
	v_mfma_f32_16x16x32_bf16 v[84:87], v[170:173], v[204:207], v[84:87]
	v_mfma_f32_16x16x32_bf16 v[92:95], v[178:181], v[204:207], v[92:95]
	v_mfma_f32_16x16x32_bf16 v[68:71], v[170:173], v[212:215], v[68:71]
	v_mfma_f32_16x16x32_bf16 v[76:79], v[178:181], v[212:215], v[76:79]
	s_barrier
; #define PG8_STAGE(bufoff, gbase, voff) do { _Pragma("unroll") for (int _i = 0; _i < 2; ++_i) \
;         __builtin_amdgcn_global_load_lds((const unsigned*)((const char*)(gbase) + (voff)[_i]), (PG8_LAS unsigned*)(lds + (bufoff) + ldsw + _i * 8192), 16, 0, 0); } while (0)
; #define PG8_LDA(dst, b, h) do { _Pragma("unroll") for (int m = 0; m < 4; ++m) _Pragma("unroll") for (int k = 0; k < 2; ++k) dst[m][k] = *(const PG8_LAS bf16x8*)(lds + PG8_SA(b, h) + aoff + m * 2048 + k * 1024); } while (0)
; #define PG8_MMA(ai, bj, At, Bt) do { __builtin_amdgcn_s_setprio(1); _Pragma("unroll") for (int m = 0; m < 4; ++m) _Pragma("unroll") for (int n = 0; n < 2; ++n) _Pragma("unroll") for (int k = 0; k < 2; ++k) \
;         acc[ai][bj][m][n] = __builtin_amdgcn_mfma_f32_16x16x32_bf16(Bt[n][k], At[m][k], acc[ai][bj][m][n], 0, 0, 0); __builtin_amdgcn_s_setprio(0); } while (0)
; #define PG8_WAIT_V(n) asm volatile("s_waitcnt vmcnt(" #n ")" ::: "memory")
; #define PG8_WAIT_L(n) asm volatile("s_waitcnt lgkmcnt(" #n ")" ::: "memory")
; #define PG8_BAR __builtin_amdgcn_s_barrier()
; #define PG8_SCHED __builtin_amdgcn_sched_barrier(0)
; template <class Epi, class Sched, bool ALIGN_EPI = false, bool SP2 = false>
; __device__ __forceinline__ void gemm_phase(PG8_LAS unsigned char* lds, const Gemm g, const Sched S, const Epi E, const int tid) {
;     ...
;         for (int t = 0; t < nt; t += 2) {
;     ...
;             PG8_LDA(At, 1, 1); PG8_STAGE(PG8_SB(1, 0), b3, voffB); PG8_STAGE(PG8_SB(1, 1), b3 + hstepB, voffB); PG8_STAGE(PG8_SA(1, 0), a3, voffA);
;             PG8_WAIT_V(8); PG8_WAIT_L(0); PG8_BAR; PG8_MMA(1, 0, At, B0); PG8_MMA(1, 1, At, B1); PG8_BAR; PG8_SCHED;
	s_add_i32 s38, s76, s33
	s_mov_b32 m0, s38
	ds_read_b128 v[182:185], v153 offset:49152
	ds_read_b128 v[188:191], v153 offset:50176
	ds_read_b128 v[192:195], v153 offset:51200
	ds_read_b128 v[196:199], v153 offset:52224
	ds_read_b128 v[200:203], v153 offset:53248
	ds_read_b128 v[204:207], v153 offset:54272
	ds_read_b128 v[208:211], v153 offset:55296
	ds_read_b128 v[212:215], v153 offset:56320
	global_load_lds_dwordx4 v130, s[98:99]
	s_add_i32 m0, s38, 0x2000
	s_add_u32 s38, s40, 0x40080
	s_addc_u32 s39, s41, 0
	s_add_i32 s40, s77, s33
	global_load_lds_dwordx4 v134, s[98:99]
	s_mov_b32 m0, s40
	s_nop 0
	global_load_lds_dwordx4 v130, s[38:39]
	s_add_i32 m0, s40, 0x2000
	s_nop 0
	global_load_lds_dwordx4 v134, s[38:39]
	s_mov_b32 m0, s63
	s_nop 0
	global_load_lds_dwordx4 v128, s[100:101]
	s_mov_b32 m0, s64
	s_nop 0
	global_load_lds_dwordx4 v132, s[100:101]
	s_waitcnt vmcnt(8)
	s_waitcnt lgkmcnt(0)
	s_barrier
	s_waitcnt lgkmcnt(0)
	v_mfma_f32_16x16x32_bf16 v[48:51], v[144:147], v[182:185], v[48:51]
	v_mfma_f32_16x16x32_bf16 v[56:59], v[158:161], v[182:185], v[56:59]
	v_mfma_f32_16x16x32_bf16 v[24:27], v[144:147], v[192:195], v[24:27]
	v_mfma_f32_16x16x32_bf16 v[32:35], v[158:161], v[192:195], v[32:35]
	v_mfma_f32_16x16x32_bf16 v[0:3], v[144:147], v[200:203], v[0:3]
	v_mfma_f32_16x16x32_bf16 v[4:7], v[158:161], v[200:203], v[4:7]
	v_mfma_f32_16x16x32_bf16 v[8:11], v[144:147], v[208:211], v[8:11]
	v_mfma_f32_16x16x32_bf16 v[16:19], v[158:161], v[208:211], v[16:19]
	v_mfma_f32_16x16x32_bf16 v[48:51], v[154:157], v[188:191], v[48:51]
	v_mfma_f32_16x16x32_bf16 v[56:59], v[162:165], v[188:191], v[56:59]
	v_mfma_f32_16x16x32_bf16 v[24:27], v[154:157], v[196:199], v[24:27]
	v_mfma_f32_16x16x32_bf16 v[32:35], v[162:165], v[196:199], v[32:35]
	v_mfma_f32_16x16x32_bf16 v[0:3], v[154:157], v[204:207], v[0:3]
	v_mfma_f32_16x16x32_bf16 v[4:7], v[162:165], v[204:207], v[4:7]
	v_mfma_f32_16x16x32_bf16 v[8:11], v[154:157], v[212:215], v[8:11]
	v_mfma_f32_16x16x32_bf16 v[16:19], v[162:165], v[212:215], v[16:19]
	v_mfma_f32_16x16x32_bf16 v[52:55], v[166:169], v[182:185], v[52:55]
	v_mfma_f32_16x16x32_bf16 v[60:63], v[174:177], v[182:185], v[60:63]
	v_mfma_f32_16x16x32_bf16 v[28:31], v[166:169], v[192:195], v[28:31]
	v_mfma_f32_16x16x32_bf16 v[36:39], v[174:177], v[192:195], v[36:39]
	v_mfma_f32_16x16x32_bf16 v[40:43], v[166:169], v[200:203], v[40:43]
	v_mfma_f32_16x16x32_bf16 v[44:47], v[174:177], v[200:203], v[44:47]
	v_mfma_f32_16x16x32_bf16 v[12:15], v[166:169], v[208:211], v[12:15]
	v_mfma_f32_16x16x32_bf16 v[20:23], v[174:177], v[208:211], v[20:23]
	v_mfma_f32_16x16x32_bf16 v[52:55], v[170:173], v[188:191], v[52:55]
	v_mfma_f32_16x16x32_bf16 v[60:63], v[178:181], v[188:191], v[60:63]
	v_mfma_f32_16x16x32_bf16 v[28:31], v[170:173], v[196:199], v[28:31]
	v_mfma_f32_16x16x32_bf16 v[36:39], v[178:181], v[196:199], v[36:39]
	v_mfma_f32_16x16x32_bf16 v[40:43], v[170:173], v[204:207], v[40:43]
	v_mfma_f32_16x16x32_bf16 v[44:47], v[178:181], v[204:207], v[44:47]
	v_mfma_f32_16x16x32_bf16 v[12:15], v[170:173], v[212:215], v[12:15]
	v_mfma_f32_16x16x32_bf16 v[20:23], v[178:181], v[212:215], v[20:23]
	s_barrier
	s_add_i32 s75, s75, 2
	s_add_u32 s73, s73, 0x100
	s_addc_u32 s74, s74, 0
	s_cmp_gt_u32 s75, 13
	s_mov_b64 s[38:39], s[6:7]
	s_cbranch_scc0 .LBB0_672
	s_setprio 0
	s_and_b64 vcc, exec, s[24:25]
	s_cbranch_vccz .LBB0_675
	s_barrier

; #define PG8_STAGE(bufoff, gbase, voff) do { _Pragma("unroll") for (int _i = 0; _i < 2; ++_i) \
;         __builtin_amdgcn_global_load_lds((const unsigned*)((const char*)(gbase) + (voff)[_i]), (PG8_LAS unsigned*)(lds + (bufoff) + ldsw + _i * 8192), 16, 0, 0); } while (0)
; #define PG8_LDA(dst, b, h) do { _Pragma("unroll") for (int m = 0; m < 4; ++m) _Pragma("unroll") for (int k = 0; k < 2; ++k) dst[m][k] = *(const PG8_LAS bf16x8*)(lds + PG8_SA(b, h) + aoff + m * 2048 + k * 1024); } while (0)
; #define PG8_LDB(dst, b, h) do { _Pragma("unroll") for (int n = 0; n < 2; ++n) _Pragma("unroll") for (int k = 0; k < 2; ++k) dst[n][k] = *(const PG8_LAS bf16x8*)(lds + PG8_SB(b, h) + boff + n * 2048 + k * 1024); } while (0)
; #define PG8_WAIT_V(n) asm volatile("s_waitcnt vmcnt(" #n ")" ::: "memory")
; #define PG8_WAIT_L(n) asm volatile("s_waitcnt lgkmcnt(" #n ")" ::: "memory")
; #define PG8_BAR __builtin_amdgcn_s_barrier()
; template <class Epi, class Sched, bool ALIGN_EPI = false, bool SP2 = false>
; __device__ __forceinline__ void gemm_phase(PG8_LAS unsigned char* lds, const Gemm g, const Sched S, const Epi E, const int tid) {
;     ...
;         const char* nA = has_next ? (const char*)g.A + (size_t)nxt.pm * tstepA + (size_t)nxt.pn * apn : cA; const char* nB = has_next ? (const char*)g.Bt + (size_t)nxt.pn * bpn : cB;
;         for (int t = 0; t < nt; t += 2) {
;             const bool last = (t == nt - 2);
;             const char* a1 = cA + (size_t)(t + 1) * kstep;
;             const char* a2 = last ? nA : cA + (size_t)(t + 2) * kstep; const char* b2 = last ? nB : cB + (size_t)(t + 2) * kstep;
;             const char* a3 = a2 + kstep; const char* b3 = b2 + kstep;
;             if (last && has_next) S.a_ready(nxt);
;             if constexpr (SP2) {
;             PG8_LDB(B0, 0, 0); PG8_LDB(B1, 0, 1); PG8_SCHED; PG8_LDA(At, 0, 0); PG8_STAGE(PG8_SA(1, 1), a1 + hstepA, voffA);
;             PG8_WAIT_V(8); PG8_WAIT_L(0); PG8_BAR; PG8_MMA(0, 0, At, B0); PG8_MMA(0, 1, At, B1); PG8_BAR; PG8_SCHED;
;     ...
; #pragma unroll
;         for (int a = 0; a < 2; ++a)
; #pragma unroll
;             for (int b = 0; b < 2; ++b)
; #pragma unroll
;                 for (int m = 0; m < 4; ++m)
; #pragma unroll
;                     for (int n = 0; n < 2; ++n) acc[a][b][m][n] = (f32x4){0.f, 0.f, 0.f, 0.f};
;         }
;         cur = nxt; cA = nA; cB = nB; ++ui;
.LBB0_756:
	s_ashr_i32 s29, s28, 31
	s_lshl_b64 s[30:31], s[28:29], 19
	s_add_u32 s30, s12, s30
	s_addc_u32 s31, s13, s31
	s_and_b64 s[34:35], s[2:3], exec
	s_cselect_b32 s5, s31, s37
	s_cselect_b32 s29, s30, s36
	s_ashr_i32 s27, s26, 31
	s_lshl_b64 s[34:35], s[26:27], 19
	s_add_u32 s34, s23, s34
	s_addc_u32 s35, s25, s35
	s_and_b64 s[40:41], s[2:3], exec
	s_cselect_b32 s27, s35, s39
	s_cselect_b32 s58, s34, s38
	s_add_u32 s36, s36, 0x40080
	s_addc_u32 s37, s37, 0
	s_add_u32 s59, s38, 0x100
	v_mov_b32_e32 v0, 0
	s_addc_u32 s60, s39, 0
	s_mov_b32 s61, -2
	v_mov_b32_e32 v1, v0
	v_mov_b32_e32 v2, v0
	v_mov_b32_e32 v3, v0
	v_mov_b32_e32 v4, v0
	v_mov_b32_e32 v5, v0
	v_mov_b32_e32 v6, v0
	v_mov_b32_e32 v7, v0
	v_mov_b32_e32 v12, v0
	v_mov_b32_e32 v13, v0
	v_mov_b32_e32 v14, v0
	v_mov_b32_e32 v15, v0
	v_mov_b32_e32 v20, v0
	v_mov_b32_e32 v21, v0
	v_mov_b32_e32 v22, v0
	v_mov_b32_e32 v23, v0
	v_mov_b32_e32 v28, v0
	v_mov_b32_e32 v29, v0
	v_mov_b32_e32 v30, v0
	v_mov_b32_e32 v31, v0
	v_mov_b32_e32 v36, v0
	v_mov_b32_e32 v37, v0
	v_mov_b32_e32 v38, v0
	v_mov_b32_e32 v39, v0
	v_mov_b32_e32 v44, v0
	v_mov_b32_e32 v45, v0
	v_mov_b32_e32 v46, v0
	v_mov_b32_e32 v47, v0
	v_mov_b32_e32 v52, v0
	v_mov_b32_e32 v53, v0
	v_mov_b32_e32 v54, v0
	v_mov_b32_e32 v55, v0
	v_mov_b32_e32 v8, v0
	v_mov_b32_e32 v9, v0
	v_mov_b32_e32 v10, v0
	v_mov_b32_e32 v11, v0
	v_mov_b32_e32 v16, v0
	v_mov_b32_e32 v17, v0
	v_mov_b32_e32 v18, v0
	v_mov_b32_e32 v19, v0
	v_mov_b32_e32 v24, v0
	v_mov_b32_e32 v25, v0
	v_mov_b32_e32 v26, v0
	v_mov_b32_e32 v27, v0
	v_mov_b32_e32 v32, v0
	v_mov_b32_e32 v33, v0
	v_mov_b32_e32 v34, v0
	v_mov_b32_e32 v35, v0
	v_mov_b32_e32 v40, v0
	v_mov_b32_e32 v41, v0
	v_mov_b32_e32 v42, v0
	v_mov_b32_e32 v43, v0
	v_mov_b32_e32 v48, v0
	v_mov_b32_e32 v49, v0
	v_mov_b32_e32 v50, v0
	v_mov_b32_e32 v51, v0
	v_mov_b32_e32 v56, v0
	v_mov_b32_e32 v57, v0
	v_mov_b32_e32 v58, v0
	v_mov_b32_e32 v59, v0
	v_mov_b32_e32 v60, v0
	v_mov_b32_e32 v61, v0
	v_mov_b32_e32 v62, v0
	v_mov_b32_e32 v63, v0
	v_mov_b32_e32 v64, v0
	v_mov_b32_e32 v65, v0
	v_mov_b32_e32 v66, v0
	v_mov_b32_e32 v67, v0
	v_mov_b32_e32 v68, v0
	v_mov_b32_e32 v69, v0
	v_mov_b32_e32 v70, v0
	v_mov_b32_e32 v71, v0
	v_mov_b32_e32 v76, v0
	v_mov_b32_e32 v77, v0
	v_mov_b32_e32 v78, v0
	v_mov_b32_e32 v79, v0
	v_mov_b32_e32 v84, v0
	v_mov_b32_e32 v85, v0
	v_mov_b32_e32 v86, v0
	v_mov_b32_e32 v87, v0
	v_mov_b32_e32 v92, v0
	v_mov_b32_e32 v93, v0
	v_mov_b32_e32 v94, v0
	v_mov_b32_e32 v95, v0
	v_mov_b32_e32 v100, v0
	v_mov_b32_e32 v101, v0
	v_mov_b32_e32 v102, v0
	v_mov_b32_e32 v103, v0
	v_mov_b32_e32 v108, v0
	v_mov_b32_e32 v109, v0
	v_mov_b32_e32 v110, v0
	v_mov_b32_e32 v111, v0
	v_mov_b32_e32 v116, v0
	v_mov_b32_e32 v117, v0
	v_mov_b32_e32 v118, v0
	v_mov_b32_e32 v119, v0
	v_mov_b32_e32 v72, v0
	v_mov_b32_e32 v73, v0
	v_mov_b32_e32 v74, v0
	v_mov_b32_e32 v75, v0
	v_mov_b32_e32 v80, v0
	v_mov_b32_e32 v81, v0
	v_mov_b32_e32 v82, v0
	v_mov_b32_e32 v83, v0
	v_mov_b32_e32 v88, v0
	v_mov_b32_e32 v89, v0
	v_mov_b32_e32 v90, v0
	v_mov_b32_e32 v91, v0
	v_mov_b32_e32 v96, v0
	v_mov_b32_e32 v97, v0
	v_mov_b32_e32 v98, v0
	v_mov_b32_e32 v99, v0
	v_mov_b32_e32 v104, v0
	v_mov_b32_e32 v105, v0
	v_mov_b32_e32 v106, v0
	v_mov_b32_e32 v107, v0
	v_mov_b32_e32 v112, v0
	v_mov_b32_e32 v113, v0
	v_mov_b32_e32 v114, v0
	v_mov_b32_e32 v115, v0
	v_mov_b32_e32 v120, v0
	v_mov_b32_e32 v121, v0
	v_mov_b32_e32 v122, v0
	v_mov_b32_e32 v123, v0
	v_mov_b32_e32 v124, v0
	v_mov_b32_e32 v125, v0
	v_mov_b32_e32 v126, v0
	v_mov_b32_e32 v127, v0
	v_readfirstlane_b32 s98, v186
	s_lshr_b32 s98, s98, 8
	s_cmp_eq_u32 s98, 0
	s_cbranch_scc1 .Lprio_skip_6
	s_setprio 1
.Lprio_skip_6:
.LBB0_757:
	ds_read_b128 v[128:131], v206
	ds_read_b128 v[132:135], v206 offset:1024
	ds_read_b128 v[136:139], v206 offset:2048
	ds_read_b128 v[156:159], v206 offset:3072
	ds_read_b128 v[160:163], v207
	ds_read_b128 v[164:167], v207 offset:1024
	ds_read_b128 v[168:171], v207 offset:2048
	ds_read_b128 v[172:175], v207 offset:3072
	s_add_u32 s38, s36, 0xfffc0080
	s_addc_u32 s39, s37, -1
	s_cmp_eq_u32 s61, 12
	s_cselect_b32 s41, s5, s39
	s_cselect_b32 s40, s29, s38
	s_cselect_b32 s39, s27, s60
	s_cselect_b32 s38, s58, s59
	s_add_i32 m0, s47, 0xc000
	ds_read_b128 v[210:213], v208
	ds_read_b128 v[214:217], v208 offset:1024
	ds_read_b128 v[218:221], v208 offset:2048
	ds_read_b128 v[222:225], v208 offset:3072
	ds_read_b128 v[226:229], v208 offset:4096
	ds_read_b128 v[230:233], v208 offset:5120
	ds_read_b128 v[234:237], v208 offset:6144
	ds_read_b128 v[238:241], v208 offset:7168
	global_load_lds_dwordx4 v148, s[36:37]
	s_add_i32 m0, s47, 0xe000
	s_nop 0
	global_load_lds_dwordx4 v150, s[36:37]
	s_waitcnt vmcnt(8)
	s_waitcnt lgkmcnt(0)
	s_barrier
; #define PG8_STAGE(bufoff, gbase, voff) do { _Pragma("unroll") for (int _i = 0; _i < 2; ++_i) \
;         __builtin_amdgcn_global_load_lds((const unsigned*)((const char*)(gbase) + (voff)[_i]), (PG8_LAS unsigned*)(lds + (bufoff) + ldsw + _i * 8192), 16, 0, 0); } while (0)
; #define PG8_LDA(dst, b, h) do { _Pragma("unroll") for (int m = 0; m < 4; ++m) _Pragma("unroll") for (int k = 0; k < 2; ++k) dst[m][k] = *(const PG8_LAS bf16x8*)(lds + PG8_SA(b, h) + aoff + m * 2048 + k * 1024); } while (0)
; #define PG8_MMA(ai, bj, At, Bt) do { __builtin_amdgcn_s_setprio(1); _Pragma("unroll") for (int m = 0; m < 4; ++m) _Pragma("unroll") for (int n = 0; n < 2; ++n) _Pragma("unroll") for (int k = 0; k < 2; ++k) \
;         acc[ai][bj][m][n] = __builtin_amdgcn_mfma_f32_16x16x32_bf16(Bt[n][k], At[m][k], acc[ai][bj][m][n], 0, 0, 0); __builtin_amdgcn_s_setprio(0); } while (0)
; #define PG8_WAIT_V(n) asm volatile("s_waitcnt vmcnt(" #n ")" ::: "memory")
; #define PG8_WAIT_L(n) asm volatile("s_waitcnt lgkmcnt(" #n ")" ::: "memory")
; #define PG8_BAR __builtin_amdgcn_s_barrier()
; #define PG8_SCHED __builtin_amdgcn_sched_barrier(0)
; template <class Epi, class Sched, bool ALIGN_EPI = false, bool SP2 = false>
; __device__ __forceinline__ void gemm_phase(PG8_LAS unsigned char* lds, const Gemm g, const Sched S, const Epi E, const int tid) {
;     ...
;             PG8_WAIT_V(8); PG8_WAIT_L(0); PG8_BAR; PG8_MMA(0, 0, At, B0); PG8_MMA(0, 1, At, B1); PG8_BAR; PG8_SCHED;
;             PG8_LDA(At, 0, 1); PG8_STAGE(PG8_SB(0, 0), b2, voffB); PG8_STAGE(PG8_SB(0, 1), b2 + hstepB, voffB); PG8_STAGE(PG8_SA(0, 0), a2, voffA);
;             PG8_WAIT_V(8); PG8_WAIT_L(0); PG8_BAR; PG8_MMA(1, 0, At, B0); PG8_MMA(1, 1, At, B1); PG8_BAR; PG8_SCHED;
	s_waitcnt lgkmcnt(0)
	v_mfma_f32_16x16x32_bf16 v[124:127], v[128:131], v[210:213], v[124:127]
	v_mfma_f32_16x16x32_bf16 v[120:123], v[136:139], v[210:213], v[120:123]
	v_mfma_f32_16x16x32_bf16 v[112:115], v[128:131], v[218:221], v[112:115]
	v_mfma_f32_16x16x32_bf16 v[104:107], v[136:139], v[218:221], v[104:107]
	v_mfma_f32_16x16x32_bf16 v[96:99], v[128:131], v[226:229], v[96:99]
	v_mfma_f32_16x16x32_bf16 v[88:91], v[136:139], v[226:229], v[88:91]
	v_mfma_f32_16x16x32_bf16 v[80:83], v[128:131], v[234:237], v[80:83]
	v_mfma_f32_16x16x32_bf16 v[72:75], v[136:139], v[234:237], v[72:75]
	v_mfma_f32_16x16x32_bf16 v[124:127], v[132:135], v[214:217], v[124:127]
	v_mfma_f32_16x16x32_bf16 v[120:123], v[156:159], v[214:217], v[120:123]
	v_mfma_f32_16x16x32_bf16 v[112:115], v[132:135], v[222:225], v[112:115]
	v_mfma_f32_16x16x32_bf16 v[104:107], v[156:159], v[222:225], v[104:107]
	v_mfma_f32_16x16x32_bf16 v[96:99], v[132:135], v[230:233], v[96:99]
	v_mfma_f32_16x16x32_bf16 v[88:91], v[156:159], v[230:233], v[88:91]
	v_mfma_f32_16x16x32_bf16 v[80:83], v[132:135], v[238:241], v[80:83]
	v_mfma_f32_16x16x32_bf16 v[72:75], v[156:159], v[238:241], v[72:75]
	v_mfma_f32_16x16x32_bf16 v[116:119], v[160:163], v[210:213], v[116:119]
	v_mfma_f32_16x16x32_bf16 v[108:111], v[168:171], v[210:213], v[108:111]
	v_mfma_f32_16x16x32_bf16 v[100:103], v[160:163], v[218:221], v[100:103]
	v_mfma_f32_16x16x32_bf16 v[92:95], v[168:171], v[218:221], v[92:95]
	v_mfma_f32_16x16x32_bf16 v[84:87], v[160:163], v[226:229], v[84:87]
	v_mfma_f32_16x16x32_bf16 v[76:79], v[168:171], v[226:229], v[76:79]
	v_mfma_f32_16x16x32_bf16 v[68:71], v[160:163], v[234:237], v[68:71]
	v_mfma_f32_16x16x32_bf16 v[64:67], v[168:171], v[234:237], v[64:67]
	v_mfma_f32_16x16x32_bf16 v[116:119], v[164:167], v[214:217], v[116:119]
	v_mfma_f32_16x16x32_bf16 v[108:111], v[172:175], v[214:217], v[108:111]
	v_mfma_f32_16x16x32_bf16 v[100:103], v[164:167], v[222:225], v[100:103]
	v_mfma_f32_16x16x32_bf16 v[92:95], v[172:175], v[222:225], v[92:95]
	v_mfma_f32_16x16x32_bf16 v[84:87], v[164:167], v[230:233], v[84:87]
	v_mfma_f32_16x16x32_bf16 v[76:79], v[172:175], v[230:233], v[76:79]
	v_mfma_f32_16x16x32_bf16 v[68:71], v[164:167], v[238:241], v[68:71]
	v_mfma_f32_16x16x32_bf16 v[64:67], v[172:175], v[238:241], v[64:67]
	s_barrier
	s_add_u32 s98, s38, 0x80
	s_addc_u32 s99, s39, 0
	s_add_u32 s100, s40, 0x80
	s_addc_u32 s101, s41, 0
	s_add_i32 s62, s55, s46
	s_mov_b32 m0, s62
	ds_read_b128 v[210:213], v208 offset:16384
	ds_read_b128 v[214:217], v208 offset:17408
	ds_read_b128 v[218:221], v208 offset:18432
	ds_read_b128 v[222:225], v208 offset:19456
	ds_read_b128 v[226:229], v208 offset:20480
	ds_read_b128 v[230:233], v208 offset:21504
	ds_read_b128 v[234:237], v208 offset:22528
	ds_read_b128 v[238:241], v208 offset:23552
	global_load_lds_dwordx4 v142, s[38:39]
	s_add_i32 m0, s62, 0x2000
	s_add_u32 s62, s38, 0x40000
	s_addc_u32 s63, s39, 0
	s_add_i32 s64, s56, s46
	global_load_lds_dwordx4 v146, s[38:39]
	s_mov_b32 m0, s64
	s_nop 0
	global_load_lds_dwordx4 v142, s[62:63]
	s_add_i32 m0, s64, 0x2000
	s_nop 0
	global_load_lds_dwordx4 v146, s[62:63]
	s_mov_b32 m0, s47
	s_nop 0
	global_load_lds_dwordx4 v140, s[40:41]
	s_mov_b32 m0, s48
	s_nop 0
	global_load_lds_dwordx4 v144, s[40:41]
	s_waitcnt vmcnt(8)
	s_waitcnt lgkmcnt(0)
	s_barrier
	s_waitcnt lgkmcnt(0)
	v_mfma_f32_16x16x32_bf16 v[60:63], v[128:131], v[210:213], v[60:63]
	v_mfma_f32_16x16x32_bf16 v[56:59], v[136:139], v[210:213], v[56:59]
	v_mfma_f32_16x16x32_bf16 v[48:51], v[128:131], v[218:221], v[48:51]
	v_mfma_f32_16x16x32_bf16 v[40:43], v[136:139], v[218:221], v[40:43]
	v_mfma_f32_16x16x32_bf16 v[32:35], v[128:131], v[226:229], v[32:35]
	v_mfma_f32_16x16x32_bf16 v[24:27], v[136:139], v[226:229], v[24:27]
	v_mfma_f32_16x16x32_bf16 v[16:19], v[128:131], v[234:237], v[16:19]
	v_mfma_f32_16x16x32_bf16 v[8:11], v[136:139], v[234:237], v[8:11]
	v_mfma_f32_16x16x32_bf16 v[60:63], v[132:135], v[214:217], v[60:63]
	v_mfma_f32_16x16x32_bf16 v[56:59], v[156:159], v[214:217], v[56:59]
	v_mfma_f32_16x16x32_bf16 v[48:51], v[132:135], v[222:225], v[48:51]
	v_mfma_f32_16x16x32_bf16 v[40:43], v[156:159], v[222:225], v[40:43]
	v_mfma_f32_16x16x32_bf16 v[32:35], v[132:135], v[230:233], v[32:35]
	v_mfma_f32_16x16x32_bf16 v[24:27], v[156:159], v[230:233], v[24:27]
	v_mfma_f32_16x16x32_bf16 v[16:19], v[132:135], v[238:241], v[16:19]
	v_mfma_f32_16x16x32_bf16 v[8:11], v[156:159], v[238:241], v[8:11]
	v_mfma_f32_16x16x32_bf16 v[52:55], v[160:163], v[210:213], v[52:55]
	v_mfma_f32_16x16x32_bf16 v[44:47], v[168:171], v[210:213], v[44:47]
	v_mfma_f32_16x16x32_bf16 v[36:39], v[160:163], v[218:221], v[36:39]
	v_mfma_f32_16x16x32_bf16 v[28:31], v[168:171], v[218:221], v[28:31]
	v_mfma_f32_16x16x32_bf16 v[20:23], v[160:163], v[226:229], v[20:23]
	v_mfma_f32_16x16x32_bf16 v[12:15], v[168:171], v[226:229], v[12:15]
	v_mfma_f32_16x16x32_bf16 v[4:7], v[160:163], v[234:237], v[4:7]
	v_mfma_f32_16x16x32_bf16 v[0:3], v[168:171], v[234:237], v[0:3]
	v_mfma_f32_16x16x32_bf16 v[52:55], v[164:167], v[214:217], v[52:55]
	v_mfma_f32_16x16x32_bf16 v[44:47], v[172:175], v[214:217], v[44:47]
	v_mfma_f32_16x16x32_bf16 v[36:39], v[164:167], v[222:225], v[36:39]
	v_mfma_f32_16x16x32_bf16 v[28:31], v[172:175], v[222:225], v[28:31]
	v_mfma_f32_16x16x32_bf16 v[20:23], v[164:167], v[230:233], v[20:23]
	v_mfma_f32_16x16x32_bf16 v[12:15], v[172:175], v[230:233], v[12:15]
	v_mfma_f32_16x16x32_bf16 v[4:7], v[164:167], v[238:241], v[4:7]
	v_mfma_f32_16x16x32_bf16 v[0:3], v[172:175], v[238:241], v[0:3]
	s_barrier
; #define PG8_STAGE(bufoff, gbase, voff) do { _Pragma("unroll") for (int _i = 0; _i < 2; ++_i) \
;         __builtin_amdgcn_global_load_lds((const unsigned*)((const char*)(gbase) + (voff)[_i]), (PG8_LAS unsigned*)(lds + (bufoff) + ldsw + _i * 8192), 16, 0, 0); } while (0)
; #define PG8_LDA(dst, b, h) do { _Pragma("unroll") for (int m = 0; m < 4; ++m) _Pragma("unroll") for (int k = 0; k < 2; ++k) dst[m][k] = *(const PG8_LAS bf16x8*)(lds + PG8_SA(b, h) + aoff + m * 2048 + k * 1024); } while (0)
; #define PG8_LDB(dst, b, h) do { _Pragma("unroll") for (int n = 0; n < 2; ++n) _Pragma("unroll") for (int k = 0; k < 2; ++k) dst[n][k] = *(const PG8_LAS bf16x8*)(lds + PG8_SB(b, h) + boff + n * 2048 + k * 1024); } while (0)
; #define PG8_MMA(ai, bj, At, Bt) do { __builtin_amdgcn_s_setprio(1); _Pragma("unroll") for (int m = 0; m < 4; ++m) _Pragma("unroll") for (int n = 0; n < 2; ++n) _Pragma("unroll") for (int k = 0; k < 2; ++k) \
;         acc[ai][bj][m][n] = __builtin_amdgcn_mfma_f32_16x16x32_bf16(Bt[n][k], At[m][k], acc[ai][bj][m][n], 0, 0, 0); __builtin_amdgcn_s_setprio(0); } while (0)
; #define PG8_WAIT_V(n) asm volatile("s_waitcnt vmcnt(" #n ")" ::: "memory")
; #define PG8_WAIT_L(n) asm volatile("s_waitcnt lgkmcnt(" #n ")" ::: "memory")
; template <class Epi, class Sched, bool ALIGN_EPI = false, bool SP2 = false>
; __device__ __forceinline__ void gemm_phase(PG8_LAS unsigned char* lds, const Gemm g, const Sched S, const Epi E, const int tid) {
;     ...
;         for (int t = 0; t < nt; t += 2) {
;             const bool last = (t == nt - 2);
;             const char* a1 = cA + (size_t)(t + 1) * kstep;
;             const char* a2 = last ? nA : cA + (size_t)(t + 2) * kstep; const char* b2 = last ? nB : cB + (size_t)(t + 2) * kstep;
;             const char* a3 = a2 + kstep; const char* b3 = b2 + kstep;
;             if (last && has_next) S.a_ready(nxt);
;     ...
;             PG8_LDB(B0, 1, 0); PG8_LDB(B1, 1, 1); PG8_SCHED; PG8_LDA(At, 1, 0); PG8_STAGE(PG8_SA(0, 1), a2 + hstepA, voffA);
;             PG8_WAIT_V(8); PG8_WAIT_L(0); PG8_BAR; PG8_MMA(0, 0, At, B0); PG8_MMA(0, 1, At, B1); PG8_BAR; PG8_SCHED;
;             PG8_LDA(At, 1, 1); PG8_STAGE(PG8_SB(1, 0), b3, voffB); PG8_STAGE(PG8_SB(1, 1), b3 + hstepB, voffB); PG8_STAGE(PG8_SA(1, 0), a3, voffA);
;             PG8_WAIT_V(8); PG8_WAIT_L(0); PG8_BAR; PG8_MMA(1, 0, At, B0); PG8_MMA(1, 1, At, B1); PG8_BAR; PG8_SCHED;
	s_add_i32 s62, 0, 0x18000
	s_add_i32 s63, 0, 0x1c000
	v_add_u32_e32 v156, s62, v204
	v_add_u32_e32 v172, s63, v204
	ds_read_b128 v[128:131], v156
	ds_read_b128 v[132:135], v156 offset:1024
	ds_read_b128 v[136:139], v156 offset:2048
	ds_read_b128 v[156:159], v156 offset:3072
	ds_read_b128 v[160:163], v172
	ds_read_b128 v[164:167], v172 offset:1024
	ds_read_b128 v[168:171], v172 offset:2048
	ds_read_b128 v[172:175], v172 offset:3072
	s_add_u32 s40, s40, 0x40000
	s_addc_u32 s41, s41, 0
	s_mov_b32 m0, s49
	ds_read_b128 v[210:213], v208 offset:32768
	ds_read_b128 v[214:217], v208 offset:33792
	ds_read_b128 v[218:221], v208 offset:34816
	ds_read_b128 v[222:225], v208 offset:35840
	ds_read_b128 v[226:229], v208 offset:36864
	ds_read_b128 v[230:233], v208 offset:37888
	ds_read_b128 v[234:237], v208 offset:38912
	ds_read_b128 v[238:241], v208 offset:39936
	global_load_lds_dwordx4 v140, s[40:41]
	s_mov_b32 m0, s50
	s_nop 0
	global_load_lds_dwordx4 v144, s[40:41]
	s_waitcnt vmcnt(8)
	s_waitcnt lgkmcnt(0)
	s_barrier
	s_waitcnt lgkmcnt(0)
	v_mfma_f32_16x16x32_bf16 v[124:127], v[128:131], v[210:213], v[124:127]
	v_mfma_f32_16x16x32_bf16 v[120:123], v[136:139], v[210:213], v[120:123]
	v_mfma_f32_16x16x32_bf16 v[112:115], v[128:131], v[218:221], v[112:115]
	v_mfma_f32_16x16x32_bf16 v[104:107], v[136:139], v[218:221], v[104:107]
	v_mfma_f32_16x16x32_bf16 v[96:99], v[128:131], v[226:229], v[96:99]
	v_mfma_f32_16x16x32_bf16 v[88:91], v[136:139], v[226:229], v[88:91]
	v_mfma_f32_16x16x32_bf16 v[80:83], v[128:131], v[234:237], v[80:83]
	v_mfma_f32_16x16x32_bf16 v[72:75], v[136:139], v[234:237], v[72:75]
	v_mfma_f32_16x16x32_bf16 v[124:127], v[132:135], v[214:217], v[124:127]
	v_mfma_f32_16x16x32_bf16 v[120:123], v[156:159], v[214:217], v[120:123]
	v_mfma_f32_16x16x32_bf16 v[112:115], v[132:135], v[222:225], v[112:115]
	v_mfma_f32_16x16x32_bf16 v[104:107], v[156:159], v[222:225], v[104:107]
	v_mfma_f32_16x16x32_bf16 v[96:99], v[132:135], v[230:233], v[96:99]
	v_mfma_f32_16x16x32_bf16 v[88:91], v[156:159], v[230:233], v[88:91]
	v_mfma_f32_16x16x32_bf16 v[80:83], v[132:135], v[238:241], v[80:83]
	v_mfma_f32_16x16x32_bf16 v[72:75], v[156:159], v[238:241], v[72:75]
	v_mfma_f32_16x16x32_bf16 v[116:119], v[160:163], v[210:213], v[116:119]
	v_mfma_f32_16x16x32_bf16 v[108:111], v[168:171], v[210:213], v[108:111]
	v_mfma_f32_16x16x32_bf16 v[100:103], v[160:163], v[218:221], v[100:103]
	v_mfma_f32_16x16x32_bf16 v[92:95], v[168:171], v[218:221], v[92:95]
	v_mfma_f32_16x16x32_bf16 v[84:87], v[160:163], v[226:229], v[84:87]
	v_mfma_f32_16x16x32_bf16 v[76:79], v[168:171], v[226:229], v[76:79]
	v_mfma_f32_16x16x32_bf16 v[68:71], v[160:163], v[234:237], v[68:71]
	v_mfma_f32_16x16x32_bf16 v[64:67], v[168:171], v[234:237], v[64:67]
	v_mfma_f32_16x16x32_bf16 v[116:119], v[164:167], v[214:217], v[116:119]
	v_mfma_f32_16x16x32_bf16 v[108:111], v[172:175], v[214:217], v[108:111]
	v_mfma_f32_16x16x32_bf16 v[100:103], v[164:167], v[222:225], v[100:103]
	v_mfma_f32_16x16x32_bf16 v[92:95], v[172:175], v[222:225], v[92:95]
	v_mfma_f32_16x16x32_bf16 v[84:87], v[164:167], v[230:233], v[84:87]
	v_mfma_f32_16x16x32_bf16 v[76:79], v[172:175], v[230:233], v[76:79]
	v_mfma_f32_16x16x32_bf16 v[68:71], v[164:167], v[238:241], v[68:71]
	v_mfma_f32_16x16x32_bf16 v[64:67], v[172:175], v[238:241], v[64:67]
	s_barrier
	s_add_i32 s40, s62, s46
	s_mov_b32 m0, s40
	ds_read_b128 v[210:213], v208 offset:49152
	ds_read_b128 v[214:217], v208 offset:50176
	ds_read_b128 v[218:221], v208 offset:51200
	ds_read_b128 v[222:225], v208 offset:52224
	ds_read_b128 v[226:229], v208 offset:53248
	ds_read_b128 v[230:233], v208 offset:54272
	ds_read_b128 v[234:237], v208 offset:55296
	ds_read_b128 v[238:241], v208 offset:56320
	global_load_lds_dwordx4 v142, s[98:99]
	s_add_i32 m0, s40, 0x2000
	s_add_u32 s38, s38, 0x40080
	s_addc_u32 s39, s39, 0
	s_add_i32 s40, s63, s46
	global_load_lds_dwordx4 v146, s[98:99]
	s_mov_b32 m0, s40
	s_nop 0
	global_load_lds_dwordx4 v142, s[38:39]
	s_add_i32 m0, s40, 0x2000
	s_nop 0
	global_load_lds_dwordx4 v146, s[38:39]
	s_mov_b32 m0, s52
	s_nop 0
	global_load_lds_dwordx4 v140, s[100:101]
	s_mov_b32 m0, s53
	s_nop 0
	global_load_lds_dwordx4 v144, s[100:101]
	s_waitcnt vmcnt(8)
	s_waitcnt lgkmcnt(0)
	s_barrier
	s_waitcnt lgkmcnt(0)
	v_mfma_f32_16x16x32_bf16 v[60:63], v[128:131], v[210:213], v[60:63]
	v_mfma_f32_16x16x32_bf16 v[56:59], v[136:139], v[210:213], v[56:59]
	v_mfma_f32_16x16x32_bf16 v[48:51], v[128:131], v[218:221], v[48:51]
	v_mfma_f32_16x16x32_bf16 v[40:43], v[136:139], v[218:221], v[40:43]
	v_mfma_f32_16x16x32_bf16 v[32:35], v[128:131], v[226:229], v[32:35]
	v_mfma_f32_16x16x32_bf16 v[24:27], v[136:139], v[226:229], v[24:27]
	v_mfma_f32_16x16x32_bf16 v[16:19], v[128:131], v[234:237], v[16:19]
	v_mfma_f32_16x16x32_bf16 v[8:11], v[136:139], v[234:237], v[8:11]
	v_mfma_f32_16x16x32_bf16 v[60:63], v[132:135], v[214:217], v[60:63]
	v_mfma_f32_16x16x32_bf16 v[56:59], v[156:159], v[214:217], v[56:59]
	v_mfma_f32_16x16x32_bf16 v[48:51], v[132:135], v[222:225], v[48:51]
	v_mfma_f32_16x16x32_bf16 v[40:43], v[156:159], v[222:225], v[40:43]
	v_mfma_f32_16x16x32_bf16 v[32:35], v[132:135], v[230:233], v[32:35]
	v_mfma_f32_16x16x32_bf16 v[24:27], v[156:159], v[230:233], v[24:27]
	v_mfma_f32_16x16x32_bf16 v[16:19], v[132:135], v[238:241], v[16:19]
	v_mfma_f32_16x16x32_bf16 v[8:11], v[156:159], v[238:241], v[8:11]
	v_mfma_f32_16x16x32_bf16 v[52:55], v[160:163], v[210:213], v[52:55]
	v_mfma_f32_16x16x32_bf16 v[44:47], v[168:171], v[210:213], v[44:47]
	v_mfma_f32_16x16x32_bf16 v[36:39], v[160:163], v[218:221], v[36:39]
	v_mfma_f32_16x16x32_bf16 v[28:31], v[168:171], v[218:221], v[28:31]
	v_mfma_f32_16x16x32_bf16 v[20:23], v[160:163], v[226:229], v[20:23]
	v_mfma_f32_16x16x32_bf16 v[12:15], v[168:171], v[226:229], v[12:15]
	v_mfma_f32_16x16x32_bf16 v[4:7], v[160:163], v[234:237], v[4:7]
	v_mfma_f32_16x16x32_bf16 v[0:3], v[168:171], v[234:237], v[0:3]
	v_mfma_f32_16x16x32_bf16 v[52:55], v[164:167], v[214:217], v[52:55]
	v_mfma_f32_16x16x32_bf16 v[44:47], v[172:175], v[214:217], v[44:47]
	v_mfma_f32_16x16x32_bf16 v[36:39], v[164:167], v[222:225], v[36:39]
	v_mfma_f32_16x16x32_bf16 v[28:31], v[172:175], v[222:225], v[28:31]
	v_mfma_f32_16x16x32_bf16 v[20:23], v[164:167], v[230:233], v[20:23]
	v_mfma_f32_16x16x32_bf16 v[12:15], v[172:175], v[230:233], v[12:15]
	v_mfma_f32_16x16x32_bf16 v[4:7], v[164:167], v[238:241], v[4:7]
	v_mfma_f32_16x16x32_bf16 v[0:3], v[172:175], v[238:241], v[0:3]
	s_barrier
	s_add_i32 s61, s61, 2
	s_add_u32 s36, s36, 0x100
	s_addc_u32 s37, s37, 0
	s_add_u32 s59, s59, 0x100
	s_addc_u32 s60, s60, 0
	s_cmp_gt_u32 s61, 13
	s_cbranch_scc0 .LBB0_757
	s_setprio 0
	s_and_b64 vcc, exec, s[20:21]
	s_cbranch_vccz .LBB0_760
	s_barrier

; #define PG8_STAGE(bufoff, gbase, voff) do { _Pragma("unroll") for (int _i = 0; _i < 2; ++_i) \
;         __builtin_amdgcn_global_load_lds((const unsigned*)((const char*)(gbase) + (voff)[_i]), (PG8_LAS unsigned*)(lds + (bufoff) + ldsw + _i * 8192), 16, 0, 0); } while (0)
; #define PG8_LDA(dst, b, h) do { _Pragma("unroll") for (int m = 0; m < 4; ++m) _Pragma("unroll") for (int k = 0; k < 2; ++k) dst[m][k] = *(const PG8_LAS bf16x8*)(lds + PG8_SA(b, h) + aoff + m * 2048 + k * 1024); } while (0)
; #define PG8_LDB(dst, b, h) do { _Pragma("unroll") for (int n = 0; n < 2; ++n) _Pragma("unroll") for (int k = 0; k < 2; ++k) dst[n][k] = *(const PG8_LAS bf16x8*)(lds + PG8_SB(b, h) + boff + n * 2048 + k * 1024); } while (0)
; #define PG8_WAIT_V(n) asm volatile("s_waitcnt vmcnt(" #n ")" ::: "memory")
; #define PG8_WAIT_L(n) asm volatile("s_waitcnt lgkmcnt(" #n ")" ::: "memory")
; #define PG8_BAR __builtin_amdgcn_s_barrier()
; #define PG8_SCHED __builtin_amdgcn_sched_barrier(0)
; template <class Epi, class Sched, bool ALIGN_EPI = false, bool SP2 = false>
; __device__ __forceinline__ void gemm_phase(PG8_LAS unsigned char* lds, const Gemm g, const Sched S, const Epi E, const int tid) {
;     ...
;         const char* nA = has_next ? (const char*)g.A + (size_t)nxt.pm * tstepA + (size_t)nxt.pn * apn : cA; const char* nB = has_next ? (const char*)g.Bt + (size_t)nxt.pn * bpn : cB;
;         for (int t = 0; t < nt; t += 2) {
;             const bool last = (t == nt - 2);
;             const char* a1 = cA + (size_t)(t + 1) * kstep;
;             const char* a2 = last ? nA : cA + (size_t)(t + 2) * kstep; const char* b2 = last ? nB : cB + (size_t)(t + 2) * kstep;
;             const char* a3 = a2 + kstep; const char* b3 = b2 + kstep;
;             if (last && has_next) S.a_ready(nxt);
;             if constexpr (SP2) {
;             PG8_LDB(B0, 0, 0); PG8_LDB(B1, 0, 1); PG8_SCHED; PG8_LDA(At, 0, 0); PG8_STAGE(PG8_SA(1, 1), a1 + hstepA, voffA);
;             PG8_WAIT_V(8); PG8_WAIT_L(0); PG8_BAR; PG8_MMA(0, 0, At, B0); PG8_MMA(0, 1, At, B1); PG8_BAR; PG8_SCHED;
;             PG8_LDA(At, 0, 1); PG8_STAGE(PG8_SB(0, 0), b2, voffB); PG8_STAGE(PG8_SB(0, 1), b2 + hstepB, voffB); PG8_STAGE(PG8_SA(0, 0), a2, voffA);
;             PG8_WAIT_V(8); PG8_WAIT_L(0); PG8_BAR; PG8_MMA(1, 0, At, B0); PG8_MMA(1, 1, At, B1); PG8_BAR; PG8_SCHED;
.LBB0_885:
	s_ashr_i32 s31, s30, 31
	s_lshl_b64 s[34:35], s[30:31], 19
	s_add_u32 s34, s8, s34
	s_addc_u32 s35, s9, s35
	s_and_b64 s[36:37], s[4:5], exec
	s_cselect_b32 s31, s35, s49
	s_cselect_b32 s39, s34, s48
	s_ashr_i32 s29, s28, 31
	s_lshl_b64 s[36:37], s[28:29], 19
	s_add_u32 s36, s33, s36
	s_addc_u32 s37, s52, s37
	s_and_b64 s[50:51], s[4:5], exec
	s_cselect_b32 s29, s37, s47
	s_cselect_b32 s41, s36, s46
	s_add_u32 s48, s48, 0x40080
	s_addc_u32 s49, s49, 0
	s_add_u32 s69, s46, 0x100
	s_addc_u32 s74, s47, 0
	s_mov_b32 s75, -2
	v_readfirstlane_b32 s98, v186
	s_lshr_b32 s98, s98, 8
	s_cmp_eq_u32 s98, 0
	s_cbranch_scc1 .Lprio_skip_7
	s_setprio 1
.Lprio_skip_7:
.LBB0_886:
	v_add_u32_e32 v162, s66, v149
	v_add_u32_e32 v178, s67, v149
	ds_read_b128 v[136:139], v162
	ds_read_b128 v[154:157], v162 offset:1024
	ds_read_b128 v[158:161], v162 offset:2048
	ds_read_b128 v[162:165], v162 offset:3072
	ds_read_b128 v[166:169], v178
	ds_read_b128 v[170:173], v178 offset:1024
	ds_read_b128 v[174:177], v178 offset:2048
	ds_read_b128 v[178:181], v178 offset:3072
	s_add_u32 s46, s48, 0xfffc0080
	s_addc_u32 s47, s49, -1
	s_cmp_eq_u32 s75, 12
	s_cselect_b32 s51, s31, s47
	s_cselect_b32 s50, s39, s46
	s_cselect_b32 s47, s29, s74
	s_cselect_b32 s46, s41, s69
	s_add_i32 m0, s56, 0xc000
	ds_read_b128 v[182:185], v153
	ds_read_b128 v[188:191], v153 offset:1024
	ds_read_b128 v[192:195], v153 offset:2048
	ds_read_b128 v[196:199], v153 offset:3072
	ds_read_b128 v[200:203], v153 offset:4096
	ds_read_b128 v[204:207], v153 offset:5120
	ds_read_b128 v[208:211], v153 offset:6144
	ds_read_b128 v[212:215], v153 offset:7168
	global_load_lds_dwordx4 v128, s[48:49]
	s_add_i32 m0, s56, 0xe000
	s_nop 0
	global_load_lds_dwordx4 v130, s[48:49]
	s_waitcnt vmcnt(8)
	s_waitcnt lgkmcnt(0)
	s_barrier
	s_waitcnt lgkmcnt(0)
	v_mfma_f32_16x16x32_bf16 v[112:115], v[136:139], v[182:185], v[112:115]
	v_mfma_f32_16x16x32_bf16 v[120:123], v[158:161], v[182:185], v[120:123]
	v_mfma_f32_16x16x32_bf16 v[96:99], v[136:139], v[192:195], v[96:99]
	v_mfma_f32_16x16x32_bf16 v[104:107], v[158:161], v[192:195], v[104:107]
	v_mfma_f32_16x16x32_bf16 v[80:83], v[136:139], v[200:203], v[80:83]
	v_mfma_f32_16x16x32_bf16 v[88:91], v[158:161], v[200:203], v[88:91]
	v_mfma_f32_16x16x32_bf16 v[64:67], v[136:139], v[208:211], v[64:67]
	v_mfma_f32_16x16x32_bf16 v[72:75], v[158:161], v[208:211], v[72:75]
	v_mfma_f32_16x16x32_bf16 v[112:115], v[154:157], v[188:191], v[112:115]
	v_mfma_f32_16x16x32_bf16 v[120:123], v[162:165], v[188:191], v[120:123]
	v_mfma_f32_16x16x32_bf16 v[96:99], v[154:157], v[196:199], v[96:99]
	v_mfma_f32_16x16x32_bf16 v[104:107], v[162:165], v[196:199], v[104:107]
	v_mfma_f32_16x16x32_bf16 v[80:83], v[154:157], v[204:207], v[80:83]
	v_mfma_f32_16x16x32_bf16 v[88:91], v[162:165], v[204:207], v[88:91]
	v_mfma_f32_16x16x32_bf16 v[64:67], v[154:157], v[212:215], v[64:67]
	v_mfma_f32_16x16x32_bf16 v[72:75], v[162:165], v[212:215], v[72:75]
	v_mfma_f32_16x16x32_bf16 v[116:119], v[166:169], v[182:185], v[116:119]
	v_mfma_f32_16x16x32_bf16 v[124:127], v[174:177], v[182:185], v[124:127]
	v_mfma_f32_16x16x32_bf16 v[100:103], v[166:169], v[192:195], v[100:103]
	v_mfma_f32_16x16x32_bf16 v[108:111], v[174:177], v[192:195], v[108:111]
	v_mfma_f32_16x16x32_bf16 v[84:87], v[166:169], v[200:203], v[84:87]
	v_mfma_f32_16x16x32_bf16 v[92:95], v[174:177], v[200:203], v[92:95]
	v_mfma_f32_16x16x32_bf16 v[68:71], v[166:169], v[208:211], v[68:71]
	v_mfma_f32_16x16x32_bf16 v[76:79], v[174:177], v[208:211], v[76:79]
	v_mfma_f32_16x16x32_bf16 v[116:119], v[170:173], v[188:191], v[116:119]
	v_mfma_f32_16x16x32_bf16 v[124:127], v[178:181], v[188:191], v[124:127]
	v_mfma_f32_16x16x32_bf16 v[100:103], v[170:173], v[196:199], v[100:103]
	v_mfma_f32_16x16x32_bf16 v[108:111], v[178:181], v[196:199], v[108:111]
	v_mfma_f32_16x16x32_bf16 v[84:87], v[170:173], v[204:207], v[84:87]
	v_mfma_f32_16x16x32_bf16 v[92:95], v[178:181], v[204:207], v[92:95]
	v_mfma_f32_16x16x32_bf16 v[68:71], v[170:173], v[212:215], v[68:71]
	v_mfma_f32_16x16x32_bf16 v[76:79], v[178:181], v[212:215], v[76:79]
	s_barrier
	s_add_u32 s98, s46, 0x80
	s_addc_u32 s99, s47, 0
	s_add_u32 s100, s50, 0x80
	s_addc_u32 s101, s51, 0
	s_add_i32 s70, s66, s53
	s_mov_b32 m0, s70
	ds_read_b128 v[182:185], v153 offset:16384
	ds_read_b128 v[188:191], v153 offset:17408
	ds_read_b128 v[192:195], v153 offset:18432
	ds_read_b128 v[196:199], v153 offset:19456
	ds_read_b128 v[200:203], v153 offset:20480
	ds_read_b128 v[204:207], v153 offset:21504
	ds_read_b128 v[208:211], v153 offset:22528
	ds_read_b128 v[212:215], v153 offset:23552
	global_load_lds_dwordx4 v142, s[46:47]
	s_add_i32 m0, s70, 0x2000
	s_add_u32 s76, s46, 0x40000
	s_addc_u32 s77, s47, 0
	s_add_i32 s70, s67, s53
	global_load_lds_dwordx4 v146, s[46:47]
	s_mov_b32 m0, s70
	s_nop 0
	global_load_lds_dwordx4 v142, s[76:77]
	s_add_i32 m0, s70, 0x2000
	s_nop 0
	global_load_lds_dwordx4 v146, s[76:77]
	s_mov_b32 m0, s56
	s_nop 0
	global_load_lds_dwordx4 v140, s[50:51]
	s_mov_b32 m0, s57
	s_nop 0
	global_load_lds_dwordx4 v144, s[50:51]
	s_waitcnt vmcnt(8)
	s_waitcnt lgkmcnt(0)
	s_barrier
; #define PG8_STAGE(bufoff, gbase, voff) do { _Pragma("unroll") for (int _i = 0; _i < 2; ++_i) \
;         __builtin_amdgcn_global_load_lds((const unsigned*)((const char*)(gbase) + (voff)[_i]), (PG8_LAS unsigned*)(lds + (bufoff) + ldsw + _i * 8192), 16, 0, 0); } while (0)
; #define PG8_LDA(dst, b, h) do { _Pragma("unroll") for (int m = 0; m < 4; ++m) _Pragma("unroll") for (int k = 0; k < 2; ++k) dst[m][k] = *(const PG8_LAS bf16x8*)(lds + PG8_SA(b, h) + aoff + m * 2048 + k * 1024); } while (0)
; #define PG8_LDB(dst, b, h) do { _Pragma("unroll") for (int n = 0; n < 2; ++n) _Pragma("unroll") for (int k = 0; k < 2; ++k) dst[n][k] = *(const PG8_LAS bf16x8*)(lds + PG8_SB(b, h) + boff + n * 2048 + k * 1024); } while (0)
; #define PG8_MMA(ai, bj, At, Bt) do { __builtin_amdgcn_s_setprio(1); _Pragma("unroll") for (int m = 0; m < 4; ++m) _Pragma("unroll") for (int n = 0; n < 2; ++n) _Pragma("unroll") for (int k = 0; k < 2; ++k) \
;         acc[ai][bj][m][n] = __builtin_amdgcn_mfma_f32_16x16x32_bf16(Bt[n][k], At[m][k], acc[ai][bj][m][n], 0, 0, 0); __builtin_amdgcn_s_setprio(0); } while (0)
; #define PG8_WAIT_V(n) asm volatile("s_waitcnt vmcnt(" #n ")" ::: "memory")
; #define PG8_WAIT_L(n) asm volatile("s_waitcnt lgkmcnt(" #n ")" ::: "memory")
; #define PG8_BAR __builtin_amdgcn_s_barrier()
; #define PG8_SCHED __builtin_amdgcn_sched_barrier(0)
; template <class Epi, class Sched, bool ALIGN_EPI = false, bool SP2 = false>
; __device__ __forceinline__ void gemm_phase(PG8_LAS unsigned char* lds, const Gemm g, const Sched S, const Epi E, const int tid) {
;     ...
;             PG8_WAIT_V(8); PG8_WAIT_L(0); PG8_BAR; PG8_MMA(1, 0, At, B0); PG8_MMA(1, 1, At, B1); PG8_BAR; PG8_SCHED;
;             PG8_LDB(B0, 1, 0); PG8_LDB(B1, 1, 1); PG8_SCHED; PG8_LDA(At, 1, 0); PG8_STAGE(PG8_SA(0, 1), a2 + hstepA, voffA);
;             PG8_WAIT_V(8); PG8_WAIT_L(0); PG8_BAR; PG8_MMA(0, 0, At, B0); PG8_MMA(0, 1, At, B1); PG8_BAR; PG8_SCHED;
;             PG8_LDA(At, 1, 1); PG8_STAGE(PG8_SB(1, 0), b3, voffB); PG8_STAGE(PG8_SB(1, 1), b3 + hstepB, voffB); PG8_STAGE(PG8_SA(1, 0), a3, voffA);
	s_waitcnt lgkmcnt(0)
	v_mfma_f32_16x16x32_bf16 v[48:51], v[136:139], v[182:185], v[48:51]
	v_mfma_f32_16x16x32_bf16 v[56:59], v[158:161], v[182:185], v[56:59]
	v_mfma_f32_16x16x32_bf16 v[16:19], v[136:139], v[192:195], v[16:19]
	v_mfma_f32_16x16x32_bf16 v[24:27], v[158:161], v[192:195], v[24:27]
	v_mfma_f32_16x16x32_bf16 v[32:35], v[136:139], v[200:203], v[32:35]
	v_mfma_f32_16x16x32_bf16 v[40:43], v[158:161], v[200:203], v[40:43]
	v_mfma_f32_16x16x32_bf16 v[0:3], v[136:139], v[208:211], v[0:3]
	v_mfma_f32_16x16x32_bf16 v[8:11], v[158:161], v[208:211], v[8:11]
	v_mfma_f32_16x16x32_bf16 v[48:51], v[154:157], v[188:191], v[48:51]
	v_mfma_f32_16x16x32_bf16 v[56:59], v[162:165], v[188:191], v[56:59]
	v_mfma_f32_16x16x32_bf16 v[16:19], v[154:157], v[196:199], v[16:19]
	v_mfma_f32_16x16x32_bf16 v[24:27], v[162:165], v[196:199], v[24:27]
	v_mfma_f32_16x16x32_bf16 v[32:35], v[154:157], v[204:207], v[32:35]
	v_mfma_f32_16x16x32_bf16 v[40:43], v[162:165], v[204:207], v[40:43]
	v_mfma_f32_16x16x32_bf16 v[0:3], v[154:157], v[212:215], v[0:3]
	v_mfma_f32_16x16x32_bf16 v[8:11], v[162:165], v[212:215], v[8:11]
	v_mfma_f32_16x16x32_bf16 v[52:55], v[166:169], v[182:185], v[52:55]
	v_mfma_f32_16x16x32_bf16 v[60:63], v[174:177], v[182:185], v[60:63]
	v_mfma_f32_16x16x32_bf16 v[20:23], v[166:169], v[192:195], v[20:23]
	v_mfma_f32_16x16x32_bf16 v[28:31], v[174:177], v[192:195], v[28:31]
	v_mfma_f32_16x16x32_bf16 v[36:39], v[166:169], v[200:203], v[36:39]
	v_mfma_f32_16x16x32_bf16 v[44:47], v[174:177], v[200:203], v[44:47]
	v_mfma_f32_16x16x32_bf16 v[4:7], v[166:169], v[208:211], v[4:7]
	v_mfma_f32_16x16x32_bf16 v[12:15], v[174:177], v[208:211], v[12:15]
	v_mfma_f32_16x16x32_bf16 v[52:55], v[170:173], v[188:191], v[52:55]
	v_mfma_f32_16x16x32_bf16 v[60:63], v[178:181], v[188:191], v[60:63]
	v_mfma_f32_16x16x32_bf16 v[20:23], v[170:173], v[196:199], v[20:23]
	v_mfma_f32_16x16x32_bf16 v[28:31], v[178:181], v[196:199], v[28:31]
	v_mfma_f32_16x16x32_bf16 v[36:39], v[170:173], v[204:207], v[36:39]
	v_mfma_f32_16x16x32_bf16 v[44:47], v[178:181], v[204:207], v[44:47]
	v_mfma_f32_16x16x32_bf16 v[4:7], v[170:173], v[212:215], v[4:7]
	v_mfma_f32_16x16x32_bf16 v[12:15], v[178:181], v[212:215], v[12:15]
	s_barrier
	s_add_i32 s70, 0, 0x18000
	s_add_i32 s76, 0, 0x1c000
	v_add_u32_e32 v162, s70, v149
	v_add_u32_e32 v178, s76, v149
	ds_read_b128 v[136:139], v162
	ds_read_b128 v[154:157], v162 offset:1024
	ds_read_b128 v[158:161], v162 offset:2048
	ds_read_b128 v[162:165], v162 offset:3072
	ds_read_b128 v[166:169], v178
	ds_read_b128 v[170:173], v178 offset:1024
	ds_read_b128 v[174:177], v178 offset:2048
	ds_read_b128 v[178:181], v178 offset:3072
	s_add_u32 s50, s50, 0x40000
	s_addc_u32 s51, s51, 0
	s_mov_b32 m0, s58
	ds_read_b128 v[182:185], v153 offset:32768
	ds_read_b128 v[188:191], v153 offset:33792
	ds_read_b128 v[192:195], v153 offset:34816
	ds_read_b128 v[196:199], v153 offset:35840
	ds_read_b128 v[200:203], v153 offset:36864
	ds_read_b128 v[204:207], v153 offset:37888
	ds_read_b128 v[208:211], v153 offset:38912
	ds_read_b128 v[212:215], v153 offset:39936
	global_load_lds_dwordx4 v140, s[50:51]
	s_mov_b32 m0, s59
	s_nop 0
	global_load_lds_dwordx4 v144, s[50:51]
	s_waitcnt vmcnt(8)
	s_waitcnt lgkmcnt(0)
	s_barrier
	s_waitcnt lgkmcnt(0)
	v_mfma_f32_16x16x32_bf16 v[112:115], v[136:139], v[182:185], v[112:115]
	v_mfma_f32_16x16x32_bf16 v[120:123], v[158:161], v[182:185], v[120:123]
	v_mfma_f32_16x16x32_bf16 v[96:99], v[136:139], v[192:195], v[96:99]
	v_mfma_f32_16x16x32_bf16 v[104:107], v[158:161], v[192:195], v[104:107]
	v_mfma_f32_16x16x32_bf16 v[80:83], v[136:139], v[200:203], v[80:83]
	v_mfma_f32_16x16x32_bf16 v[88:91], v[158:161], v[200:203], v[88:91]
	v_mfma_f32_16x16x32_bf16 v[64:67], v[136:139], v[208:211], v[64:67]
	v_mfma_f32_16x16x32_bf16 v[72:75], v[158:161], v[208:211], v[72:75]
	v_mfma_f32_16x16x32_bf16 v[112:115], v[154:157], v[188:191], v[112:115]
	v_mfma_f32_16x16x32_bf16 v[120:123], v[162:165], v[188:191], v[120:123]
	v_mfma_f32_16x16x32_bf16 v[96:99], v[154:157], v[196:199], v[96:99]
	v_mfma_f32_16x16x32_bf16 v[104:107], v[162:165], v[196:199], v[104:107]
	v_mfma_f32_16x16x32_bf16 v[80:83], v[154:157], v[204:207], v[80:83]
	v_mfma_f32_16x16x32_bf16 v[88:91], v[162:165], v[204:207], v[88:91]
	v_mfma_f32_16x16x32_bf16 v[64:67], v[154:157], v[212:215], v[64:67]
	v_mfma_f32_16x16x32_bf16 v[72:75], v[162:165], v[212:215], v[72:75]
	v_mfma_f32_16x16x32_bf16 v[116:119], v[166:169], v[182:185], v[116:119]
	v_mfma_f32_16x16x32_bf16 v[124:127], v[174:177], v[182:185], v[124:127]
	v_mfma_f32_16x16x32_bf16 v[100:103], v[166:169], v[192:195], v[100:103]
	v_mfma_f32_16x16x32_bf16 v[108:111], v[174:177], v[192:195], v[108:111]
	v_mfma_f32_16x16x32_bf16 v[84:87], v[166:169], v[200:203], v[84:87]
	v_mfma_f32_16x16x32_bf16 v[92:95], v[174:177], v[200:203], v[92:95]
	v_mfma_f32_16x16x32_bf16 v[68:71], v[166:169], v[208:211], v[68:71]
	v_mfma_f32_16x16x32_bf16 v[76:79], v[174:177], v[208:211], v[76:79]
	v_mfma_f32_16x16x32_bf16 v[116:119], v[170:173], v[188:191], v[116:119]
	v_mfma_f32_16x16x32_bf16 v[124:127], v[178:181], v[188:191], v[124:127]
	v_mfma_f32_16x16x32_bf16 v[100:103], v[170:173], v[196:199], v[100:103]
	v_mfma_f32_16x16x32_bf16 v[108:111], v[178:181], v[196:199], v[108:111]
	v_mfma_f32_16x16x32_bf16 v[84:87], v[170:173], v[204:207], v[84:87]
	v_mfma_f32_16x16x32_bf16 v[92:95], v[178:181], v[204:207], v[92:95]
	v_mfma_f32_16x16x32_bf16 v[68:71], v[170:173], v[212:215], v[68:71]
	v_mfma_f32_16x16x32_bf16 v[76:79], v[178:181], v[212:215], v[76:79]
	s_barrier
; #define PG8_STAGE(bufoff, gbase, voff) do { _Pragma("unroll") for (int _i = 0; _i < 2; ++_i) \
;         __builtin_amdgcn_global_load_lds((const unsigned*)((const char*)(gbase) + (voff)[_i]), (PG8_LAS unsigned*)(lds + (bufoff) + ldsw + _i * 8192), 16, 0, 0); } while (0)
; #define PG8_LDA(dst, b, h) do { _Pragma("unroll") for (int m = 0; m < 4; ++m) _Pragma("unroll") for (int k = 0; k < 2; ++k) dst[m][k] = *(const PG8_LAS bf16x8*)(lds + PG8_SA(b, h) + aoff + m * 2048 + k * 1024); } while (0)
; #define PG8_MMA(ai, bj, At, Bt) do { __builtin_amdgcn_s_setprio(1); _Pragma("unroll") for (int m = 0; m < 4; ++m) _Pragma("unroll") for (int n = 0; n < 2; ++n) _Pragma("unroll") for (int k = 0; k < 2; ++k) \
;         acc[ai][bj][m][n] = __builtin_amdgcn_mfma_f32_16x16x32_bf16(Bt[n][k], At[m][k], acc[ai][bj][m][n], 0, 0, 0); __builtin_amdgcn_s_setprio(0); } while (0)
; #define PG8_WAIT_V(n) asm volatile("s_waitcnt vmcnt(" #n ")" ::: "memory")
; #define PG8_WAIT_L(n) asm volatile("s_waitcnt lgkmcnt(" #n ")" ::: "memory")
; #define PG8_BAR __builtin_amdgcn_s_barrier()
; #define PG8_SCHED __builtin_amdgcn_sched_barrier(0)
; template <class Epi, class Sched, bool ALIGN_EPI = false, bool SP2 = false>
; __device__ __forceinline__ void gemm_phase(PG8_LAS unsigned char* lds, const Gemm g, const Sched S, const Epi E, const int tid) {
;     ...
;         for (int t = 0; t < nt; t += 2) {
;     ...
;             PG8_LDA(At, 1, 1); PG8_STAGE(PG8_SB(1, 0), b3, voffB); PG8_STAGE(PG8_SB(1, 1), b3 + hstepB, voffB); PG8_STAGE(PG8_SA(1, 0), a3, voffA);
;             PG8_WAIT_V(8); PG8_WAIT_L(0); PG8_BAR; PG8_MMA(1, 0, At, B0); PG8_MMA(1, 1, At, B1); PG8_BAR; PG8_SCHED;
	s_add_i32 s50, s70, s53
	s_mov_b32 m0, s50
	ds_read_b128 v[182:185], v153 offset:49152
	ds_read_b128 v[188:191], v153 offset:50176
	ds_read_b128 v[192:195], v153 offset:51200
	ds_read_b128 v[196:199], v153 offset:52224
	ds_read_b128 v[200:203], v153 offset:53248
	ds_read_b128 v[204:207], v153 offset:54272
	ds_read_b128 v[208:211], v153 offset:55296
	ds_read_b128 v[212:215], v153 offset:56320
	global_load_lds_dwordx4 v142, s[98:99]
	s_add_i32 m0, s50, 0x2000
	s_add_u32 s46, s46, 0x40080
	s_addc_u32 s47, s47, 0
	s_add_i32 s50, s76, s53
	global_load_lds_dwordx4 v146, s[98:99]
	s_mov_b32 m0, s50
	s_nop 0
	global_load_lds_dwordx4 v142, s[46:47]
	s_add_i32 m0, s50, 0x2000
	s_nop 0
	global_load_lds_dwordx4 v146, s[46:47]
	s_mov_b32 m0, s61
	s_nop 0
	global_load_lds_dwordx4 v140, s[100:101]
	s_mov_b32 m0, s62
	s_nop 0
	global_load_lds_dwordx4 v144, s[100:101]
	s_waitcnt vmcnt(8)
	s_waitcnt lgkmcnt(0)
	s_barrier
	s_waitcnt lgkmcnt(0)
	v_mfma_f32_16x16x32_bf16 v[48:51], v[136:139], v[182:185], v[48:51]
	v_mfma_f32_16x16x32_bf16 v[56:59], v[158:161], v[182:185], v[56:59]
	v_mfma_f32_16x16x32_bf16 v[16:19], v[136:139], v[192:195], v[16:19]
	v_mfma_f32_16x16x32_bf16 v[24:27], v[158:161], v[192:195], v[24:27]
	v_mfma_f32_16x16x32_bf16 v[32:35], v[136:139], v[200:203], v[32:35]
	v_mfma_f32_16x16x32_bf16 v[40:43], v[158:161], v[200:203], v[40:43]
	v_mfma_f32_16x16x32_bf16 v[0:3], v[136:139], v[208:211], v[0:3]
	v_mfma_f32_16x16x32_bf16 v[8:11], v[158:161], v[208:211], v[8:11]
	v_mfma_f32_16x16x32_bf16 v[48:51], v[154:157], v[188:191], v[48:51]
	v_mfma_f32_16x16x32_bf16 v[56:59], v[162:165], v[188:191], v[56:59]
	v_mfma_f32_16x16x32_bf16 v[16:19], v[154:157], v[196:199], v[16:19]
	v_mfma_f32_16x16x32_bf16 v[24:27], v[162:165], v[196:199], v[24:27]
	v_mfma_f32_16x16x32_bf16 v[32:35], v[154:157], v[204:207], v[32:35]
	v_mfma_f32_16x16x32_bf16 v[40:43], v[162:165], v[204:207], v[40:43]
	v_mfma_f32_16x16x32_bf16 v[0:3], v[154:157], v[212:215], v[0:3]
	v_mfma_f32_16x16x32_bf16 v[8:11], v[162:165], v[212:215], v[8:11]
	v_mfma_f32_16x16x32_bf16 v[52:55], v[166:169], v[182:185], v[52:55]
	v_mfma_f32_16x16x32_bf16 v[60:63], v[174:177], v[182:185], v[60:63]
	v_mfma_f32_16x16x32_bf16 v[20:23], v[166:169], v[192:195], v[20:23]
	v_mfma_f32_16x16x32_bf16 v[28:31], v[174:177], v[192:195], v[28:31]
	v_mfma_f32_16x16x32_bf16 v[36:39], v[166:169], v[200:203], v[36:39]
	v_mfma_f32_16x16x32_bf16 v[44:47], v[174:177], v[200:203], v[44:47]
	v_mfma_f32_16x16x32_bf16 v[4:7], v[166:169], v[208:211], v[4:7]
	v_mfma_f32_16x16x32_bf16 v[12:15], v[174:177], v[208:211], v[12:15]
	v_mfma_f32_16x16x32_bf16 v[52:55], v[170:173], v[188:191], v[52:55]
	v_mfma_f32_16x16x32_bf16 v[60:63], v[178:181], v[188:191], v[60:63]
	v_mfma_f32_16x16x32_bf16 v[20:23], v[170:173], v[196:199], v[20:23]
	v_mfma_f32_16x16x32_bf16 v[28:31], v[178:181], v[196:199], v[28:31]
	v_mfma_f32_16x16x32_bf16 v[36:39], v[170:173], v[204:207], v[36:39]
	v_mfma_f32_16x16x32_bf16 v[44:47], v[178:181], v[204:207], v[44:47]
	v_mfma_f32_16x16x32_bf16 v[4:7], v[170:173], v[212:215], v[4:7]
	v_mfma_f32_16x16x32_bf16 v[12:15], v[178:181], v[212:215], v[12:15]
	s_barrier
	s_add_i32 s75, s75, 2
	s_add_u32 s48, s48, 0x100
	s_addc_u32 s49, s49, 0
	s_add_u32 s69, s69, 0x100
	s_addc_u32 s74, s74, 0
	s_cmp_gt_u32 s75, 13
	s_cbranch_scc0 .LBB0_886
	s_setprio 0
	s_and_b64 vcc, exec, s[26:27]
	s_cbranch_vccz .LBB0_889
	s_barrier

; #define PG8_STAGE(bufoff, gbase, voff) do { _Pragma("unroll") for (int _i = 0; _i < 2; ++_i) \
;         __builtin_amdgcn_global_load_lds((const unsigned*)((const char*)(gbase) + (voff)[_i]), (PG8_LAS unsigned*)(lds + (bufoff) + ldsw + _i * 8192), 16, 0, 0); } while (0)
; #define PG8_LDA(dst, b, h) do { _Pragma("unroll") for (int m = 0; m < 4; ++m) _Pragma("unroll") for (int k = 0; k < 2; ++k) dst[m][k] = *(const PG8_LAS bf16x8*)(lds + PG8_SA(b, h) + aoff + m * 2048 + k * 1024); } while (0)
; #define PG8_LDB(dst, b, h) do { _Pragma("unroll") for (int n = 0; n < 2; ++n) _Pragma("unroll") for (int k = 0; k < 2; ++k) dst[n][k] = *(const PG8_LAS bf16x8*)(lds + PG8_SB(b, h) + boff + n * 2048 + k * 1024); } while (0)
; #define PG8_WAIT_V(n) asm volatile("s_waitcnt vmcnt(" #n ")" ::: "memory")
; #define PG8_WAIT_L(n) asm volatile("s_waitcnt lgkmcnt(" #n ")" ::: "memory")
; #define PG8_BAR __builtin_amdgcn_s_barrier()
; template <class Epi, class Sched, bool ALIGN_EPI = false, bool SP2 = false>
; __device__ __forceinline__ void gemm_phase(PG8_LAS unsigned char* lds, const Gemm g, const Sched S, const Epi E, const int tid) {
;     ...
;         const bool has_next = S.next(ui + 1, nxt);
;         const char* nA = has_next ? (const char*)g.A + (size_t)nxt.pm * tstepA + (size_t)nxt.pn * apn : cA; const char* nB = has_next ? (const char*)g.Bt + (size_t)nxt.pn * bpn : cB;
;         for (int t = 0; t < nt; t += 2) {
;             const bool last = (t == nt - 2);
;             const char* a1 = cA + (size_t)(t + 1) * kstep;
;             const char* a2 = last ? nA : cA + (size_t)(t + 2) * kstep; const char* b2 = last ? nB : cB + (size_t)(t + 2) * kstep;
;             const char* a3 = a2 + kstep; const char* b3 = b2 + kstep;
;             if (last && has_next) S.a_ready(nxt);
;             if constexpr (SP2) {
;             PG8_LDB(B0, 0, 0); PG8_LDB(B1, 0, 1); PG8_SCHED; PG8_LDA(At, 0, 0); PG8_STAGE(PG8_SA(1, 1), a1 + hstepA, voffA);
;             PG8_WAIT_V(8); PG8_WAIT_L(0); PG8_BAR; PG8_MMA(0, 0, At, B0); PG8_MMA(0, 1, At, B1); PG8_BAR; PG8_SCHED;
;     ...
;         else {
; #pragma unroll
;         for (int a = 0; a < 2; ++a)
; #pragma unroll
;             for (int b = 0; b < 2; ++b)
; #pragma unroll
;                 for (int m = 0; m < 4; ++m)
; #pragma unroll
;                     for (int n = 0; n < 2; ++n) acc[a][b][m][n] = (f32x4){0.f, 0.f, 0.f, 0.f};
;         }
.LBB0_990:
	s_ashr_i32 s23, s22, 31
	s_lshl_b64 s[24:25], s[22:23], 19
	s_add_u32 s24, s41, s24
	s_addc_u32 s25, s46, s25
	s_and_b64 s[26:27], s[2:3], exec
	s_cselect_b32 s23, s25, s31
	s_cselect_b32 s61, s24, s30
	s_ashr_i32 s21, s20, 31
	s_lshl_b64 s[26:27], s[20:21], 19
	s_add_u32 s26, s47, s26
	s_addc_u32 s27, s48, s27
	s_and_b64 s[36:37], s[2:3], exec
	s_cselect_b32 s21, s27, s35
	s_cselect_b32 s62, s26, s34
	s_add_u32 s30, s30, 0x40080
	s_addc_u32 s31, s31, 0
	s_add_u32 s63, s34, 0x100
	v_mov_b32_e32 v0, 0
	s_addc_u32 s64, s35, 0
	s_mov_b32 s65, -2
	v_mov_b32_e32 v1, v0
	v_mov_b32_e32 v2, v0
	v_mov_b32_e32 v3, v0
	v_mov_b32_e32 v4, v0
	v_mov_b32_e32 v5, v0
	v_mov_b32_e32 v6, v0
	v_mov_b32_e32 v7, v0
	v_mov_b32_e32 v16, v0
	v_mov_b32_e32 v17, v0
	v_mov_b32_e32 v18, v0
	v_mov_b32_e32 v19, v0
	v_mov_b32_e32 v20, v0
	v_mov_b32_e32 v21, v0
	v_mov_b32_e32 v22, v0
	v_mov_b32_e32 v23, v0
	v_mov_b32_e32 v32, v0
	v_mov_b32_e32 v33, v0
	v_mov_b32_e32 v34, v0
	v_mov_b32_e32 v35, v0
	v_mov_b32_e32 v36, v0
	v_mov_b32_e32 v37, v0
	v_mov_b32_e32 v38, v0
	v_mov_b32_e32 v39, v0
	v_mov_b32_e32 v48, v0
	v_mov_b32_e32 v49, v0
	v_mov_b32_e32 v50, v0
	v_mov_b32_e32 v51, v0
	v_mov_b32_e32 v52, v0
	v_mov_b32_e32 v53, v0
	v_mov_b32_e32 v54, v0
	v_mov_b32_e32 v55, v0
	v_mov_b32_e32 v8, v0
	v_mov_b32_e32 v9, v0
	v_mov_b32_e32 v10, v0
	v_mov_b32_e32 v11, v0
	v_mov_b32_e32 v12, v0
	v_mov_b32_e32 v13, v0
	v_mov_b32_e32 v14, v0
	v_mov_b32_e32 v15, v0
	v_mov_b32_e32 v24, v0
	v_mov_b32_e32 v25, v0
	v_mov_b32_e32 v26, v0
	v_mov_b32_e32 v27, v0
	v_mov_b32_e32 v28, v0
	v_mov_b32_e32 v29, v0
	v_mov_b32_e32 v30, v0
	v_mov_b32_e32 v31, v0
	v_mov_b32_e32 v40, v0
	v_mov_b32_e32 v41, v0
	v_mov_b32_e32 v42, v0
	v_mov_b32_e32 v43, v0
	v_mov_b32_e32 v44, v0
	v_mov_b32_e32 v45, v0
	v_mov_b32_e32 v46, v0
	v_mov_b32_e32 v47, v0
	v_mov_b32_e32 v56, v0
	v_mov_b32_e32 v57, v0
	v_mov_b32_e32 v58, v0
	v_mov_b32_e32 v59, v0
	v_mov_b32_e32 v60, v0
	v_mov_b32_e32 v61, v0
	v_mov_b32_e32 v62, v0
	v_mov_b32_e32 v63, v0
	v_mov_b32_e32 v64, v0
	v_mov_b32_e32 v65, v0
	v_mov_b32_e32 v66, v0
	v_mov_b32_e32 v67, v0
	v_mov_b32_e32 v68, v0
	v_mov_b32_e32 v69, v0
	v_mov_b32_e32 v70, v0
	v_mov_b32_e32 v71, v0
	v_mov_b32_e32 v80, v0
	v_mov_b32_e32 v81, v0
	v_mov_b32_e32 v82, v0
	v_mov_b32_e32 v83, v0
	v_mov_b32_e32 v84, v0
	v_mov_b32_e32 v85, v0
	v_mov_b32_e32 v86, v0
	v_mov_b32_e32 v87, v0
	v_mov_b32_e32 v96, v0
	v_mov_b32_e32 v97, v0
	v_mov_b32_e32 v98, v0
	v_mov_b32_e32 v99, v0
	v_mov_b32_e32 v100, v0
	v_mov_b32_e32 v101, v0
	v_mov_b32_e32 v102, v0
	v_mov_b32_e32 v103, v0
	v_mov_b32_e32 v112, v0
	v_mov_b32_e32 v113, v0
	v_mov_b32_e32 v114, v0
	v_mov_b32_e32 v115, v0
	v_mov_b32_e32 v116, v0
	v_mov_b32_e32 v117, v0
	v_mov_b32_e32 v118, v0
	v_mov_b32_e32 v119, v0
	v_mov_b32_e32 v72, v0
	v_mov_b32_e32 v73, v0
	v_mov_b32_e32 v74, v0
	v_mov_b32_e32 v75, v0
	v_mov_b32_e32 v76, v0
	v_mov_b32_e32 v77, v0
	v_mov_b32_e32 v78, v0
	v_mov_b32_e32 v79, v0
	v_mov_b32_e32 v88, v0
	v_mov_b32_e32 v89, v0
	v_mov_b32_e32 v90, v0
	v_mov_b32_e32 v91, v0
	v_mov_b32_e32 v92, v0
	v_mov_b32_e32 v93, v0
	v_mov_b32_e32 v94, v0
	v_mov_b32_e32 v95, v0
	v_mov_b32_e32 v104, v0
	v_mov_b32_e32 v105, v0
	v_mov_b32_e32 v106, v0
	v_mov_b32_e32 v107, v0
	v_mov_b32_e32 v108, v0
	v_mov_b32_e32 v109, v0
	v_mov_b32_e32 v110, v0
	v_mov_b32_e32 v111, v0
	v_mov_b32_e32 v120, v0
	v_mov_b32_e32 v121, v0
	v_mov_b32_e32 v122, v0
	v_mov_b32_e32 v123, v0
	v_mov_b32_e32 v124, v0
	v_mov_b32_e32 v125, v0
	v_mov_b32_e32 v126, v0
	v_mov_b32_e32 v127, v0
	v_readfirstlane_b32 s98, v186
	s_lshr_b32 s98, s98, 8
	s_cmp_eq_u32 s98, 0
	s_cbranch_scc1 .Lprio_skip_8
	s_setprio 1
.Lprio_skip_8:
.LBB0_991:
	ds_read_b128 v[144:147], v159
	ds_read_b128 v[148:151], v159 offset:1024
	ds_read_b128 v[162:165], v159 offset:2048
	ds_read_b128 v[166:169], v159 offset:3072
	ds_read_b128 v[170:173], v160
	ds_read_b128 v[174:177], v160 offset:1024
	ds_read_b128 v[178:181], v160 offset:2048
	ds_read_b128 v[182:185], v160 offset:3072
	s_add_u32 s34, s30, 0xfffc0080
	s_addc_u32 s35, s31, -1
	s_cmp_eq_u32 s65, 12
	s_cselect_b32 s37, s23, s35
	s_cselect_b32 s36, s61, s34
	s_cselect_b32 s35, s21, s64
	s_cselect_b32 s34, s62, s63
	s_add_i32 m0, s29, 0xc000
	ds_read_b128 v[188:191], v161
	ds_read_b128 v[192:195], v161 offset:1024
	ds_read_b128 v[196:199], v161 offset:2048
	ds_read_b128 v[200:203], v161 offset:3072
	ds_read_b128 v[204:207], v161 offset:4096
	ds_read_b128 v[208:211], v161 offset:5120
	ds_read_b128 v[212:215], v161 offset:6144
	ds_read_b128 v[216:219], v161 offset:7168
	global_load_lds_dwordx4 v136, s[30:31]
	s_add_i32 m0, s29, 0xe000
	s_nop 0
	global_load_lds_dwordx4 v138, s[30:31]
	s_waitcnt vmcnt(8)
	s_waitcnt lgkmcnt(0)
	s_barrier
; #define PG8_STAGE(bufoff, gbase, voff) do { _Pragma("unroll") for (int _i = 0; _i < 2; ++_i) \
;         __builtin_amdgcn_global_load_lds((const unsigned*)((const char*)(gbase) + (voff)[_i]), (PG8_LAS unsigned*)(lds + (bufoff) + ldsw + _i * 8192), 16, 0, 0); } while (0)
; #define PG8_LDA(dst, b, h) do { _Pragma("unroll") for (int m = 0; m < 4; ++m) _Pragma("unroll") for (int k = 0; k < 2; ++k) dst[m][k] = *(const PG8_LAS bf16x8*)(lds + PG8_SA(b, h) + aoff + m * 2048 + k * 1024); } while (0)
; #define PG8_LDB(dst, b, h) do { _Pragma("unroll") for (int n = 0; n < 2; ++n) _Pragma("unroll") for (int k = 0; k < 2; ++k) dst[n][k] = *(const PG8_LAS bf16x8*)(lds + PG8_SB(b, h) + boff + n * 2048 + k * 1024); } while (0)
; #define PG8_MMA(ai, bj, At, Bt) do { __builtin_amdgcn_s_setprio(1); _Pragma("unroll") for (int m = 0; m < 4; ++m) _Pragma("unroll") for (int n = 0; n < 2; ++n) _Pragma("unroll") for (int k = 0; k < 2; ++k) \
;         acc[ai][bj][m][n] = __builtin_amdgcn_mfma_f32_16x16x32_bf16(Bt[n][k], At[m][k], acc[ai][bj][m][n], 0, 0, 0); __builtin_amdgcn_s_setprio(0); } while (0)
; #define PG8_WAIT_V(n) asm volatile("s_waitcnt vmcnt(" #n ")" ::: "memory")
; #define PG8_WAIT_L(n) asm volatile("s_waitcnt lgkmcnt(" #n ")" ::: "memory")
; #define PG8_BAR __builtin_amdgcn_s_barrier()
; #define PG8_SCHED __builtin_amdgcn_sched_barrier(0)
; template <class Epi, class Sched, bool ALIGN_EPI = false, bool SP2 = false>
; __device__ __forceinline__ void gemm_phase(PG8_LAS unsigned char* lds, const Gemm g, const Sched S, const Epi E, const int tid) {
;     ...
;             PG8_LDB(B0, 0, 0); PG8_LDB(B1, 0, 1); PG8_SCHED; PG8_LDA(At, 0, 0); PG8_STAGE(PG8_SA(1, 1), a1 + hstepA, voffA);
;             PG8_WAIT_V(8); PG8_WAIT_L(0); PG8_BAR; PG8_MMA(0, 0, At, B0); PG8_MMA(0, 1, At, B1); PG8_BAR; PG8_SCHED;
;             PG8_LDA(At, 0, 1); PG8_STAGE(PG8_SB(0, 0), b2, voffB); PG8_STAGE(PG8_SB(0, 1), b2 + hstepB, voffB); PG8_STAGE(PG8_SA(0, 0), a2, voffA);
;             PG8_WAIT_V(8); PG8_WAIT_L(0); PG8_BAR; PG8_MMA(1, 0, At, B0); PG8_MMA(1, 1, At, B1); PG8_BAR; PG8_SCHED;
	s_waitcnt lgkmcnt(0)
	v_mfma_f32_16x16x32_bf16 v[124:127], v[144:147], v[188:191], v[124:127]
	v_mfma_f32_16x16x32_bf16 v[120:123], v[162:165], v[188:191], v[120:123]
	v_mfma_f32_16x16x32_bf16 v[108:111], v[144:147], v[196:199], v[108:111]
	v_mfma_f32_16x16x32_bf16 v[104:107], v[162:165], v[196:199], v[104:107]
	v_mfma_f32_16x16x32_bf16 v[92:95], v[144:147], v[204:207], v[92:95]
	v_mfma_f32_16x16x32_bf16 v[88:91], v[162:165], v[204:207], v[88:91]
	v_mfma_f32_16x16x32_bf16 v[76:79], v[144:147], v[212:215], v[76:79]
	v_mfma_f32_16x16x32_bf16 v[72:75], v[162:165], v[212:215], v[72:75]
	v_mfma_f32_16x16x32_bf16 v[124:127], v[148:151], v[192:195], v[124:127]
	v_mfma_f32_16x16x32_bf16 v[120:123], v[166:169], v[192:195], v[120:123]
	v_mfma_f32_16x16x32_bf16 v[108:111], v[148:151], v[200:203], v[108:111]
	v_mfma_f32_16x16x32_bf16 v[104:107], v[166:169], v[200:203], v[104:107]
	v_mfma_f32_16x16x32_bf16 v[92:95], v[148:151], v[208:211], v[92:95]
	v_mfma_f32_16x16x32_bf16 v[88:91], v[166:169], v[208:211], v[88:91]
	v_mfma_f32_16x16x32_bf16 v[76:79], v[148:151], v[216:219], v[76:79]
	v_mfma_f32_16x16x32_bf16 v[72:75], v[166:169], v[216:219], v[72:75]
	v_mfma_f32_16x16x32_bf16 v[116:119], v[170:173], v[188:191], v[116:119]
	v_mfma_f32_16x16x32_bf16 v[112:115], v[178:181], v[188:191], v[112:115]
	v_mfma_f32_16x16x32_bf16 v[100:103], v[170:173], v[196:199], v[100:103]
	v_mfma_f32_16x16x32_bf16 v[96:99], v[178:181], v[196:199], v[96:99]
	v_mfma_f32_16x16x32_bf16 v[84:87], v[170:173], v[204:207], v[84:87]
	v_mfma_f32_16x16x32_bf16 v[80:83], v[178:181], v[204:207], v[80:83]
	v_mfma_f32_16x16x32_bf16 v[68:71], v[170:173], v[212:215], v[68:71]
	v_mfma_f32_16x16x32_bf16 v[64:67], v[178:181], v[212:215], v[64:67]
	v_mfma_f32_16x16x32_bf16 v[116:119], v[174:177], v[192:195], v[116:119]
	v_mfma_f32_16x16x32_bf16 v[112:115], v[182:185], v[192:195], v[112:115]
	v_mfma_f32_16x16x32_bf16 v[100:103], v[174:177], v[200:203], v[100:103]
	v_mfma_f32_16x16x32_bf16 v[96:99], v[182:185], v[200:203], v[96:99]
	v_mfma_f32_16x16x32_bf16 v[84:87], v[174:177], v[208:211], v[84:87]
	v_mfma_f32_16x16x32_bf16 v[80:83], v[182:185], v[208:211], v[80:83]
	v_mfma_f32_16x16x32_bf16 v[68:71], v[174:177], v[216:219], v[68:71]
	v_mfma_f32_16x16x32_bf16 v[64:67], v[182:185], v[216:219], v[64:67]
	s_barrier
	s_add_u32 s98, s34, 0x80
	s_addc_u32 s99, s35, 0
	s_add_u32 s100, s36, 0x80
	s_addc_u32 s101, s37, 0
	s_add_i32 s66, s55, s19
	s_mov_b32 m0, s66
	ds_read_b128 v[188:191], v161 offset:16384
	ds_read_b128 v[192:195], v161 offset:17408
	ds_read_b128 v[196:199], v161 offset:18432
	ds_read_b128 v[200:203], v161 offset:19456
	ds_read_b128 v[204:207], v161 offset:20480
	ds_read_b128 v[208:211], v161 offset:21504
	ds_read_b128 v[212:215], v161 offset:22528
	ds_read_b128 v[216:219], v161 offset:23552
	global_load_lds_dwordx4 v132, s[34:35]
	s_add_i32 m0, s66, 0x2000
	s_add_u32 s66, s34, 0x40000
	s_addc_u32 s67, s35, 0
	s_add_i32 s69, s56, s19
	global_load_lds_dwordx4 v128, s[34:35]
	s_mov_b32 m0, s69
	s_nop 0
	global_load_lds_dwordx4 v132, s[66:67]
	s_add_i32 m0, s69, 0x2000
	s_nop 0
	global_load_lds_dwordx4 v128, s[66:67]
	s_mov_b32 m0, s29
	s_nop 0
	global_load_lds_dwordx4 v134, s[36:37]
	s_mov_b32 m0, s50
	s_nop 0
	global_load_lds_dwordx4 v130, s[36:37]
	s_waitcnt vmcnt(8)
	s_waitcnt lgkmcnt(0)
	s_barrier
	s_waitcnt lgkmcnt(0)
	v_mfma_f32_16x16x32_bf16 v[60:63], v[144:147], v[188:191], v[60:63]
	v_mfma_f32_16x16x32_bf16 v[56:59], v[162:165], v[188:191], v[56:59]
	v_mfma_f32_16x16x32_bf16 v[44:47], v[144:147], v[196:199], v[44:47]
	v_mfma_f32_16x16x32_bf16 v[40:43], v[162:165], v[196:199], v[40:43]
	v_mfma_f32_16x16x32_bf16 v[28:31], v[144:147], v[204:207], v[28:31]
	v_mfma_f32_16x16x32_bf16 v[24:27], v[162:165], v[204:207], v[24:27]
	v_mfma_f32_16x16x32_bf16 v[12:15], v[144:147], v[212:215], v[12:15]
	v_mfma_f32_16x16x32_bf16 v[8:11], v[162:165], v[212:215], v[8:11]
	v_mfma_f32_16x16x32_bf16 v[60:63], v[148:151], v[192:195], v[60:63]
	v_mfma_f32_16x16x32_bf16 v[56:59], v[166:169], v[192:195], v[56:59]
	v_mfma_f32_16x16x32_bf16 v[44:47], v[148:151], v[200:203], v[44:47]
	v_mfma_f32_16x16x32_bf16 v[40:43], v[166:169], v[200:203], v[40:43]
	v_mfma_f32_16x16x32_bf16 v[28:31], v[148:151], v[208:211], v[28:31]
	v_mfma_f32_16x16x32_bf16 v[24:27], v[166:169], v[208:211], v[24:27]
	v_mfma_f32_16x16x32_bf16 v[12:15], v[148:151], v[216:219], v[12:15]
	v_mfma_f32_16x16x32_bf16 v[8:11], v[166:169], v[216:219], v[8:11]
	v_mfma_f32_16x16x32_bf16 v[52:55], v[170:173], v[188:191], v[52:55]
	v_mfma_f32_16x16x32_bf16 v[48:51], v[178:181], v[188:191], v[48:51]
	v_mfma_f32_16x16x32_bf16 v[36:39], v[170:173], v[196:199], v[36:39]
	v_mfma_f32_16x16x32_bf16 v[32:35], v[178:181], v[196:199], v[32:35]
	v_mfma_f32_16x16x32_bf16 v[20:23], v[170:173], v[204:207], v[20:23]
	v_mfma_f32_16x16x32_bf16 v[16:19], v[178:181], v[204:207], v[16:19]
	v_mfma_f32_16x16x32_bf16 v[4:7], v[170:173], v[212:215], v[4:7]
	v_mfma_f32_16x16x32_bf16 v[0:3], v[178:181], v[212:215], v[0:3]
	v_mfma_f32_16x16x32_bf16 v[52:55], v[174:177], v[192:195], v[52:55]
	v_mfma_f32_16x16x32_bf16 v[48:51], v[182:185], v[192:195], v[48:51]
	v_mfma_f32_16x16x32_bf16 v[36:39], v[174:177], v[200:203], v[36:39]
	v_mfma_f32_16x16x32_bf16 v[32:35], v[182:185], v[200:203], v[32:35]
	v_mfma_f32_16x16x32_bf16 v[20:23], v[174:177], v[208:211], v[20:23]
	v_mfma_f32_16x16x32_bf16 v[16:19], v[182:185], v[208:211], v[16:19]
	v_mfma_f32_16x16x32_bf16 v[4:7], v[174:177], v[216:219], v[4:7]
	v_mfma_f32_16x16x32_bf16 v[0:3], v[182:185], v[216:219], v[0:3]
	s_barrier
; #define PG8_STAGE(bufoff, gbase, voff) do { _Pragma("unroll") for (int _i = 0; _i < 2; ++_i) \
;         __builtin_amdgcn_global_load_lds((const unsigned*)((const char*)(gbase) + (voff)[_i]), (PG8_LAS unsigned*)(lds + (bufoff) + ldsw + _i * 8192), 16, 0, 0); } while (0)
; #define PG8_LDA(dst, b, h) do { _Pragma("unroll") for (int m = 0; m < 4; ++m) _Pragma("unroll") for (int k = 0; k < 2; ++k) dst[m][k] = *(const PG8_LAS bf16x8*)(lds + PG8_SA(b, h) + aoff + m * 2048 + k * 1024); } while (0)
; #define PG8_LDB(dst, b, h) do { _Pragma("unroll") for (int n = 0; n < 2; ++n) _Pragma("unroll") for (int k = 0; k < 2; ++k) dst[n][k] = *(const PG8_LAS bf16x8*)(lds + PG8_SB(b, h) + boff + n * 2048 + k * 1024); } while (0)
; #define PG8_MMA(ai, bj, At, Bt) do { __builtin_amdgcn_s_setprio(1); _Pragma("unroll") for (int m = 0; m < 4; ++m) _Pragma("unroll") for (int n = 0; n < 2; ++n) _Pragma("unroll") for (int k = 0; k < 2; ++k) \
;         acc[ai][bj][m][n] = __builtin_amdgcn_mfma_f32_16x16x32_bf16(Bt[n][k], At[m][k], acc[ai][bj][m][n], 0, 0, 0); __builtin_amdgcn_s_setprio(0); } while (0)
; #define PG8_WAIT_V(n) asm volatile("s_waitcnt vmcnt(" #n ")" ::: "memory")
; #define PG8_WAIT_L(n) asm volatile("s_waitcnt lgkmcnt(" #n ")" ::: "memory")
; #define PG8_BAR __builtin_amdgcn_s_barrier()
; template <class Epi, class Sched, bool ALIGN_EPI = false, bool SP2 = false>
; __device__ __forceinline__ void gemm_phase(PG8_LAS unsigned char* lds, const Gemm g, const Sched S, const Epi E, const int tid) {
;     ...
;         for (int t = 0; t < nt; t += 2) {
;             const bool last = (t == nt - 2);
;             const char* a1 = cA + (size_t)(t + 1) * kstep;
;             const char* a2 = last ? nA : cA + (size_t)(t + 2) * kstep; const char* b2 = last ? nB : cB + (size_t)(t + 2) * kstep;
;             const char* a3 = a2 + kstep; const char* b3 = b2 + kstep;
;     ...
;             PG8_LDB(B0, 1, 0); PG8_LDB(B1, 1, 1); PG8_SCHED; PG8_LDA(At, 1, 0); PG8_STAGE(PG8_SA(0, 1), a2 + hstepA, voffA);
;             PG8_WAIT_V(8); PG8_WAIT_L(0); PG8_BAR; PG8_MMA(0, 0, At, B0); PG8_MMA(0, 1, At, B1); PG8_BAR; PG8_SCHED;
;             PG8_LDA(At, 1, 1); PG8_STAGE(PG8_SB(1, 0), b3, voffB); PG8_STAGE(PG8_SB(1, 1), b3 + hstepB, voffB); PG8_STAGE(PG8_SA(1, 0), a3, voffA);
;             PG8_WAIT_V(8); PG8_WAIT_L(0); PG8_BAR; PG8_MMA(1, 0, At, B0); PG8_MMA(1, 1, At, B1); PG8_BAR; PG8_SCHED;
	s_add_i32 s66, 0, 0x18000
	s_add_i32 s67, 0, 0x1c000
	v_add_u32_e32 v166, s66, v156
	v_add_u32_e32 v182, s67, v156
	ds_read_b128 v[144:147], v166
	ds_read_b128 v[148:151], v166 offset:1024
	ds_read_b128 v[162:165], v166 offset:2048
	ds_read_b128 v[166:169], v166 offset:3072
	ds_read_b128 v[170:173], v182
	ds_read_b128 v[174:177], v182 offset:1024
	ds_read_b128 v[178:181], v182 offset:2048
	ds_read_b128 v[182:185], v182 offset:3072
	s_add_u32 s36, s36, 0x40000
	s_addc_u32 s37, s37, 0
	s_mov_b32 m0, s51
	ds_read_b128 v[188:191], v161 offset:32768
	ds_read_b128 v[192:195], v161 offset:33792
	ds_read_b128 v[196:199], v161 offset:34816
	ds_read_b128 v[200:203], v161 offset:35840
	ds_read_b128 v[204:207], v161 offset:36864
	ds_read_b128 v[208:211], v161 offset:37888
	ds_read_b128 v[212:215], v161 offset:38912
	ds_read_b128 v[216:219], v161 offset:39936
	global_load_lds_dwordx4 v134, s[36:37]
	s_mov_b32 m0, s52
	s_nop 0
	global_load_lds_dwordx4 v130, s[36:37]
	s_waitcnt vmcnt(8)
	s_waitcnt lgkmcnt(0)
	s_barrier
	s_waitcnt lgkmcnt(0)
	v_mfma_f32_16x16x32_bf16 v[124:127], v[144:147], v[188:191], v[124:127]
	v_mfma_f32_16x16x32_bf16 v[120:123], v[162:165], v[188:191], v[120:123]
	v_mfma_f32_16x16x32_bf16 v[108:111], v[144:147], v[196:199], v[108:111]
	v_mfma_f32_16x16x32_bf16 v[104:107], v[162:165], v[196:199], v[104:107]
	v_mfma_f32_16x16x32_bf16 v[92:95], v[144:147], v[204:207], v[92:95]
	v_mfma_f32_16x16x32_bf16 v[88:91], v[162:165], v[204:207], v[88:91]
	v_mfma_f32_16x16x32_bf16 v[76:79], v[144:147], v[212:215], v[76:79]
	v_mfma_f32_16x16x32_bf16 v[72:75], v[162:165], v[212:215], v[72:75]
	v_mfma_f32_16x16x32_bf16 v[124:127], v[148:151], v[192:195], v[124:127]
	v_mfma_f32_16x16x32_bf16 v[120:123], v[166:169], v[192:195], v[120:123]
	v_mfma_f32_16x16x32_bf16 v[108:111], v[148:151], v[200:203], v[108:111]
	v_mfma_f32_16x16x32_bf16 v[104:107], v[166:169], v[200:203], v[104:107]
	v_mfma_f32_16x16x32_bf16 v[92:95], v[148:151], v[208:211], v[92:95]
	v_mfma_f32_16x16x32_bf16 v[88:91], v[166:169], v[208:211], v[88:91]
	v_mfma_f32_16x16x32_bf16 v[76:79], v[148:151], v[216:219], v[76:79]
	v_mfma_f32_16x16x32_bf16 v[72:75], v[166:169], v[216:219], v[72:75]
	v_mfma_f32_16x16x32_bf16 v[116:119], v[170:173], v[188:191], v[116:119]
	v_mfma_f32_16x16x32_bf16 v[112:115], v[178:181], v[188:191], v[112:115]
	v_mfma_f32_16x16x32_bf16 v[100:103], v[170:173], v[196:199], v[100:103]
	v_mfma_f32_16x16x32_bf16 v[96:99], v[178:181], v[196:199], v[96:99]
	v_mfma_f32_16x16x32_bf16 v[84:87], v[170:173], v[204:207], v[84:87]
	v_mfma_f32_16x16x32_bf16 v[80:83], v[178:181], v[204:207], v[80:83]
	v_mfma_f32_16x16x32_bf16 v[68:71], v[170:173], v[212:215], v[68:71]
	v_mfma_f32_16x16x32_bf16 v[64:67], v[178:181], v[212:215], v[64:67]
	v_mfma_f32_16x16x32_bf16 v[116:119], v[174:177], v[192:195], v[116:119]
	v_mfma_f32_16x16x32_bf16 v[112:115], v[182:185], v[192:195], v[112:115]
	v_mfma_f32_16x16x32_bf16 v[100:103], v[174:177], v[200:203], v[100:103]
	v_mfma_f32_16x16x32_bf16 v[96:99], v[182:185], v[200:203], v[96:99]
	v_mfma_f32_16x16x32_bf16 v[84:87], v[174:177], v[208:211], v[84:87]
	v_mfma_f32_16x16x32_bf16 v[80:83], v[182:185], v[208:211], v[80:83]
	v_mfma_f32_16x16x32_bf16 v[68:71], v[174:177], v[216:219], v[68:71]
	v_mfma_f32_16x16x32_bf16 v[64:67], v[182:185], v[216:219], v[64:67]
	s_barrier
	s_add_i32 s36, s66, s19
	s_mov_b32 m0, s36
	ds_read_b128 v[188:191], v161 offset:49152
	ds_read_b128 v[192:195], v161 offset:50176
	ds_read_b128 v[196:199], v161 offset:51200
	ds_read_b128 v[200:203], v161 offset:52224
	ds_read_b128 v[204:207], v161 offset:53248
	ds_read_b128 v[208:211], v161 offset:54272
	ds_read_b128 v[212:215], v161 offset:55296
	ds_read_b128 v[216:219], v161 offset:56320
	global_load_lds_dwordx4 v132, s[98:99]
	s_add_i32 m0, s36, 0x2000
	s_add_u32 s34, s34, 0x40080
	s_addc_u32 s35, s35, 0
	s_add_i32 s36, s67, s19
	global_load_lds_dwordx4 v128, s[98:99]
	s_mov_b32 m0, s36
	s_nop 0
	global_load_lds_dwordx4 v132, s[34:35]
	s_add_i32 m0, s36, 0x2000
	s_nop 0
	global_load_lds_dwordx4 v128, s[34:35]
	s_mov_b32 m0, s53
	s_nop 0
	global_load_lds_dwordx4 v134, s[100:101]
	s_mov_b32 m0, s54
	s_nop 0
	global_load_lds_dwordx4 v130, s[100:101]
	s_waitcnt vmcnt(8)
	s_waitcnt lgkmcnt(0)
	s_barrier
	s_waitcnt lgkmcnt(0)
	v_mfma_f32_16x16x32_bf16 v[60:63], v[144:147], v[188:191], v[60:63]
	v_mfma_f32_16x16x32_bf16 v[56:59], v[162:165], v[188:191], v[56:59]
	v_mfma_f32_16x16x32_bf16 v[44:47], v[144:147], v[196:199], v[44:47]
	v_mfma_f32_16x16x32_bf16 v[40:43], v[162:165], v[196:199], v[40:43]
	v_mfma_f32_16x16x32_bf16 v[28:31], v[144:147], v[204:207], v[28:31]
	v_mfma_f32_16x16x32_bf16 v[24:27], v[162:165], v[204:207], v[24:27]
	v_mfma_f32_16x16x32_bf16 v[12:15], v[144:147], v[212:215], v[12:15]
	v_mfma_f32_16x16x32_bf16 v[8:11], v[162:165], v[212:215], v[8:11]
	v_mfma_f32_16x16x32_bf16 v[60:63], v[148:151], v[192:195], v[60:63]
	v_mfma_f32_16x16x32_bf16 v[56:59], v[166:169], v[192:195], v[56:59]
	v_mfma_f32_16x16x32_bf16 v[44:47], v[148:151], v[200:203], v[44:47]
	v_mfma_f32_16x16x32_bf16 v[40:43], v[166:169], v[200:203], v[40:43]
	v_mfma_f32_16x16x32_bf16 v[28:31], v[148:151], v[208:211], v[28:31]
	v_mfma_f32_16x16x32_bf16 v[24:27], v[166:169], v[208:211], v[24:27]
	v_mfma_f32_16x16x32_bf16 v[12:15], v[148:151], v[216:219], v[12:15]
	v_mfma_f32_16x16x32_bf16 v[8:11], v[166:169], v[216:219], v[8:11]
	v_mfma_f32_16x16x32_bf16 v[52:55], v[170:173], v[188:191], v[52:55]
	v_mfma_f32_16x16x32_bf16 v[48:51], v[178:181], v[188:191], v[48:51]
	v_mfma_f32_16x16x32_bf16 v[36:39], v[170:173], v[196:199], v[36:39]
	v_mfma_f32_16x16x32_bf16 v[32:35], v[178:181], v[196:199], v[32:35]
	v_mfma_f32_16x16x32_bf16 v[20:23], v[170:173], v[204:207], v[20:23]
	v_mfma_f32_16x16x32_bf16 v[16:19], v[178:181], v[204:207], v[16:19]
	v_mfma_f32_16x16x32_bf16 v[4:7], v[170:173], v[212:215], v[4:7]
	v_mfma_f32_16x16x32_bf16 v[0:3], v[178:181], v[212:215], v[0:3]
	v_mfma_f32_16x16x32_bf16 v[52:55], v[174:177], v[192:195], v[52:55]
	v_mfma_f32_16x16x32_bf16 v[48:51], v[182:185], v[192:195], v[48:51]
	v_mfma_f32_16x16x32_bf16 v[36:39], v[174:177], v[200:203], v[36:39]
	v_mfma_f32_16x16x32_bf16 v[32:35], v[182:185], v[200:203], v[32:35]
	v_mfma_f32_16x16x32_bf16 v[20:23], v[174:177], v[208:211], v[20:23]
	v_mfma_f32_16x16x32_bf16 v[16:19], v[182:185], v[208:211], v[16:19]
	v_mfma_f32_16x16x32_bf16 v[4:7], v[174:177], v[216:219], v[4:7]
	v_mfma_f32_16x16x32_bf16 v[0:3], v[182:185], v[216:219], v[0:3]
	s_barrier
	s_add_i32 s65, s65, 2
	s_add_u32 s30, s30, 0x100
	s_addc_u32 s31, s31, 0
	s_add_u32 s63, s63, 0x100
	s_addc_u32 s64, s64, 0
	s_cmp_gt_u32 s65, 13
	s_cbranch_scc0 .LBB0_991
	s_setprio 0
	s_and_b64 vcc, exec, s[16:17]
	s_cbranch_vccz .LBB0_994
	s_barrier

; #define PG8_STAGE(bufoff, gbase, voff) do { _Pragma("unroll") for (int _i = 0; _i < 2; ++_i) \
;         __builtin_amdgcn_global_load_lds((const unsigned*)((const char*)(gbase) + (voff)[_i]), (PG8_LAS unsigned*)(lds + (bufoff) + ldsw + _i * 8192), 16, 0, 0); } while (0)
; #define PG8_LDA(dst, b, h) do { _Pragma("unroll") for (int m = 0; m < 4; ++m) _Pragma("unroll") for (int k = 0; k < 2; ++k) dst[m][k] = *(const PG8_LAS bf16x8*)(lds + PG8_SA(b, h) + aoff + m * 2048 + k * 1024); } while (0)
; #define PG8_LDB(dst, b, h) do { _Pragma("unroll") for (int n = 0; n < 2; ++n) _Pragma("unroll") for (int k = 0; k < 2; ++k) dst[n][k] = *(const PG8_LAS bf16x8*)(lds + PG8_SB(b, h) + boff + n * 2048 + k * 1024); } while (0)
; #define PG8_WAIT_V(n) asm volatile("s_waitcnt vmcnt(" #n ")" ::: "memory")
; #define PG8_WAIT_L(n) asm volatile("s_waitcnt lgkmcnt(" #n ")" ::: "memory")
; #define PG8_BAR __builtin_amdgcn_s_barrier()
; template <class Epi, class Sched, bool ALIGN_EPI = false, bool SP2 = false>
; __device__ __forceinline__ void gemm_phase(PG8_LAS unsigned char* lds, const Gemm g, const Sched S, const Epi E, const int tid) {
;     ...
;         const bool has_next = S.next(ui + 1, nxt);
;         const char* nA = has_next ? (const char*)g.A + (size_t)nxt.pm * tstepA + (size_t)nxt.pn * apn : cA; const char* nB = has_next ? (const char*)g.Bt + (size_t)nxt.pn * bpn : cB;
;         for (int t = 0; t < nt; t += 2) {
;             const bool last = (t == nt - 2);
;             const char* a1 = cA + (size_t)(t + 1) * kstep;
;             const char* a2 = last ? nA : cA + (size_t)(t + 2) * kstep; const char* b2 = last ? nB : cB + (size_t)(t + 2) * kstep;
;             const char* a3 = a2 + kstep; const char* b3 = b2 + kstep;
;             if (last && has_next) S.a_ready(nxt);
;             if constexpr (SP2) {
;             PG8_LDB(B0, 0, 0); PG8_LDB(B1, 0, 1); PG8_SCHED; PG8_LDA(At, 0, 0); PG8_STAGE(PG8_SA(1, 1), a1 + hstepA, voffA);
;             PG8_WAIT_V(8); PG8_WAIT_L(0); PG8_BAR; PG8_MMA(0, 0, At, B0); PG8_MMA(0, 1, At, B1); PG8_BAR; PG8_SCHED;
;     ...
;         else {
; #pragma unroll
;         for (int a = 0; a < 2; ++a)
; #pragma unroll
;             for (int b = 0; b < 2; ++b)
; #pragma unroll
;                 for (int m = 0; m < 4; ++m)
; #pragma unroll
;                     for (int n = 0; n < 2; ++n) acc[a][b][m][n] = (f32x4){0.f, 0.f, 0.f, 0.f};
;         }
.LBB0_1195:
	s_ashr_i32 s23, s22, 31
	s_lshl_b64 s[24:25], s[22:23], 19
	s_add_u32 s24, s38, s24
	s_addc_u32 s25, s39, s25
	s_and_b64 s[26:27], s[2:3], exec
	s_cselect_b32 s23, s25, s31
	s_cselect_b32 s60, s24, s30
	s_ashr_i32 s15, s14, 31
	s_lshl_b64 s[26:27], s[14:15], 19
	s_add_u32 s26, s40, s26
	s_addc_u32 s27, s41, s27
	s_and_b64 s[36:37], s[2:3], exec
	s_cselect_b32 s15, s27, s35
	s_cselect_b32 s61, s26, s34
	s_add_u32 s30, s30, 0x40080
	s_addc_u32 s31, s31, 0
	s_add_u32 s62, s34, 0x100
	v_mov_b32_e32 v0, 0
	s_addc_u32 s63, s35, 0
	s_mov_b32 s64, -2
	v_mov_b32_e32 v1, v0
	v_mov_b32_e32 v2, v0
	v_mov_b32_e32 v3, v0
	v_mov_b32_e32 v4, v0
	v_mov_b32_e32 v5, v0
	v_mov_b32_e32 v6, v0
	v_mov_b32_e32 v7, v0
	v_mov_b32_e32 v16, v0
	v_mov_b32_e32 v17, v0
	v_mov_b32_e32 v18, v0
	v_mov_b32_e32 v19, v0
	v_mov_b32_e32 v20, v0
	v_mov_b32_e32 v21, v0
	v_mov_b32_e32 v22, v0
	v_mov_b32_e32 v23, v0
	v_mov_b32_e32 v32, v0
	v_mov_b32_e32 v33, v0
	v_mov_b32_e32 v34, v0
	v_mov_b32_e32 v35, v0
	v_mov_b32_e32 v36, v0
	v_mov_b32_e32 v37, v0
	v_mov_b32_e32 v38, v0
	v_mov_b32_e32 v39, v0
	v_mov_b32_e32 v48, v0
	v_mov_b32_e32 v49, v0
	v_mov_b32_e32 v50, v0
	v_mov_b32_e32 v51, v0
	v_mov_b32_e32 v52, v0
	v_mov_b32_e32 v53, v0
	v_mov_b32_e32 v54, v0
	v_mov_b32_e32 v55, v0
	v_mov_b32_e32 v8, v0
	v_mov_b32_e32 v9, v0
	v_mov_b32_e32 v10, v0
	v_mov_b32_e32 v11, v0
	v_mov_b32_e32 v12, v0
	v_mov_b32_e32 v13, v0
	v_mov_b32_e32 v14, v0
	v_mov_b32_e32 v15, v0
	v_mov_b32_e32 v24, v0
	v_mov_b32_e32 v25, v0
	v_mov_b32_e32 v26, v0
	v_mov_b32_e32 v27, v0
	v_mov_b32_e32 v28, v0
	v_mov_b32_e32 v29, v0
	v_mov_b32_e32 v30, v0
	v_mov_b32_e32 v31, v0
	v_mov_b32_e32 v40, v0
	v_mov_b32_e32 v41, v0
	v_mov_b32_e32 v42, v0
	v_mov_b32_e32 v43, v0
	v_mov_b32_e32 v44, v0
	v_mov_b32_e32 v45, v0
	v_mov_b32_e32 v46, v0
	v_mov_b32_e32 v47, v0
	v_mov_b32_e32 v56, v0
	v_mov_b32_e32 v57, v0
	v_mov_b32_e32 v58, v0
	v_mov_b32_e32 v59, v0
	v_mov_b32_e32 v60, v0
	v_mov_b32_e32 v61, v0
	v_mov_b32_e32 v62, v0
	v_mov_b32_e32 v63, v0
	v_mov_b32_e32 v64, v0
	v_mov_b32_e32 v65, v0
	v_mov_b32_e32 v66, v0
	v_mov_b32_e32 v67, v0
	v_mov_b32_e32 v68, v0
	v_mov_b32_e32 v69, v0
	v_mov_b32_e32 v70, v0
	v_mov_b32_e32 v71, v0
	v_mov_b32_e32 v80, v0
	v_mov_b32_e32 v81, v0
	v_mov_b32_e32 v82, v0
	v_mov_b32_e32 v83, v0
	v_mov_b32_e32 v84, v0
	v_mov_b32_e32 v85, v0
	v_mov_b32_e32 v86, v0
	v_mov_b32_e32 v87, v0
	v_mov_b32_e32 v96, v0
	v_mov_b32_e32 v97, v0
	v_mov_b32_e32 v98, v0
	v_mov_b32_e32 v99, v0
	v_mov_b32_e32 v100, v0
	v_mov_b32_e32 v101, v0
	v_mov_b32_e32 v102, v0
	v_mov_b32_e32 v103, v0
	v_mov_b32_e32 v112, v0
	v_mov_b32_e32 v113, v0
	v_mov_b32_e32 v114, v0
	v_mov_b32_e32 v115, v0
	v_mov_b32_e32 v116, v0
	v_mov_b32_e32 v117, v0
	v_mov_b32_e32 v118, v0
	v_mov_b32_e32 v119, v0
	v_mov_b32_e32 v72, v0
	v_mov_b32_e32 v73, v0
	v_mov_b32_e32 v74, v0
	v_mov_b32_e32 v75, v0
	v_mov_b32_e32 v76, v0
	v_mov_b32_e32 v77, v0
	v_mov_b32_e32 v78, v0
	v_mov_b32_e32 v79, v0
	v_mov_b32_e32 v88, v0
	v_mov_b32_e32 v89, v0
	v_mov_b32_e32 v90, v0
	v_mov_b32_e32 v91, v0
	v_mov_b32_e32 v92, v0
	v_mov_b32_e32 v93, v0
	v_mov_b32_e32 v94, v0
	v_mov_b32_e32 v95, v0
	v_mov_b32_e32 v104, v0
	v_mov_b32_e32 v105, v0
	v_mov_b32_e32 v106, v0
	v_mov_b32_e32 v107, v0
	v_mov_b32_e32 v108, v0
	v_mov_b32_e32 v109, v0
	v_mov_b32_e32 v110, v0
	v_mov_b32_e32 v111, v0
	v_mov_b32_e32 v120, v0
	v_mov_b32_e32 v121, v0
	v_mov_b32_e32 v122, v0
	v_mov_b32_e32 v123, v0
	v_mov_b32_e32 v124, v0
	v_mov_b32_e32 v125, v0
	v_mov_b32_e32 v126, v0
	v_mov_b32_e32 v127, v0
	v_readfirstlane_b32 s98, v186
	s_lshr_b32 s98, s98, 8
	s_cmp_eq_u32 s98, 0
	s_cbranch_scc1 .Lprio_skip_10
	s_setprio 1
.Lprio_skip_10:
.LBB0_1196:
	ds_read_b128 v[146:149], v169
	ds_read_b128 v[150:153], v169 offset:1024
	ds_read_b128 v[172:175], v169 offset:2048
	ds_read_b128 v[176:179], v169 offset:3072
	ds_read_b128 v[180:183], v170
	ds_read_b128 v[188:191], v170 offset:1024
	ds_read_b128 v[192:195], v170 offset:2048
	ds_read_b128 v[196:199], v170 offset:3072
	s_add_u32 s34, s30, 0xfffc0080
	s_addc_u32 s35, s31, -1
	s_cmp_eq_u32 s64, 12
	s_cselect_b32 s37, s23, s35
	s_cselect_b32 s36, s60, s34
	s_cselect_b32 s35, s15, s63
	s_cselect_b32 s34, s61, s62
	s_add_i32 m0, s29, 0xc000
	ds_read_b128 v[200:203], v171
	ds_read_b128 v[204:207], v171 offset:1024
	ds_read_b128 v[208:211], v171 offset:2048
	ds_read_b128 v[212:215], v171 offset:3072
	ds_read_b128 v[216:219], v171 offset:4096
	ds_read_b128 v[220:223], v171 offset:5120
	ds_read_b128 v[224:227], v171 offset:6144
	ds_read_b128 v[228:231], v171 offset:7168
	global_load_lds_dwordx4 v138, s[30:31]
	s_add_i32 m0, s29, 0xe000
	s_nop 0
	global_load_lds_dwordx4 v140, s[30:31]
	s_waitcnt vmcnt(8)
	s_waitcnt lgkmcnt(0)
	s_barrier
; #define PG8_STAGE(bufoff, gbase, voff) do { _Pragma("unroll") for (int _i = 0; _i < 2; ++_i) \
;         __builtin_amdgcn_global_load_lds((const unsigned*)((const char*)(gbase) + (voff)[_i]), (PG8_LAS unsigned*)(lds + (bufoff) + ldsw + _i * 8192), 16, 0, 0); } while (0)
; #define PG8_LDA(dst, b, h) do { _Pragma("unroll") for (int m = 0; m < 4; ++m) _Pragma("unroll") for (int k = 0; k < 2; ++k) dst[m][k] = *(const PG8_LAS bf16x8*)(lds + PG8_SA(b, h) + aoff + m * 2048 + k * 1024); } while (0)
; #define PG8_LDB(dst, b, h) do { _Pragma("unroll") for (int n = 0; n < 2; ++n) _Pragma("unroll") for (int k = 0; k < 2; ++k) dst[n][k] = *(const PG8_LAS bf16x8*)(lds + PG8_SB(b, h) + boff + n * 2048 + k * 1024); } while (0)
; #define PG8_MMA(ai, bj, At, Bt) do { __builtin_amdgcn_s_setprio(1); _Pragma("unroll") for (int m = 0; m < 4; ++m) _Pragma("unroll") for (int n = 0; n < 2; ++n) _Pragma("unroll") for (int k = 0; k < 2; ++k) \
;         acc[ai][bj][m][n] = __builtin_amdgcn_mfma_f32_16x16x32_bf16(Bt[n][k], At[m][k], acc[ai][bj][m][n], 0, 0, 0); __builtin_amdgcn_s_setprio(0); } while (0)
; #define PG8_WAIT_V(n) asm volatile("s_waitcnt vmcnt(" #n ")" ::: "memory")
; #define PG8_WAIT_L(n) asm volatile("s_waitcnt lgkmcnt(" #n ")" ::: "memory")
; #define PG8_BAR __builtin_amdgcn_s_barrier()
; #define PG8_SCHED __builtin_amdgcn_sched_barrier(0)
; template <class Epi, class Sched, bool ALIGN_EPI = false, bool SP2 = false>
; __device__ __forceinline__ void gemm_phase(PG8_LAS unsigned char* lds, const Gemm g, const Sched S, const Epi E, const int tid) {
;     ...
;             PG8_LDB(B0, 0, 0); PG8_LDB(B1, 0, 1); PG8_SCHED; PG8_LDA(At, 0, 0); PG8_STAGE(PG8_SA(1, 1), a1 + hstepA, voffA);
;             PG8_WAIT_V(8); PG8_WAIT_L(0); PG8_BAR; PG8_MMA(0, 0, At, B0); PG8_MMA(0, 1, At, B1); PG8_BAR; PG8_SCHED;
;             PG8_LDA(At, 0, 1); PG8_STAGE(PG8_SB(0, 0), b2, voffB); PG8_STAGE(PG8_SB(0, 1), b2 + hstepB, voffB); PG8_STAGE(PG8_SA(0, 0), a2, voffA);
;             PG8_WAIT_V(8); PG8_WAIT_L(0); PG8_BAR; PG8_MMA(1, 0, At, B0); PG8_MMA(1, 1, At, B1); PG8_BAR; PG8_SCHED;
	s_waitcnt lgkmcnt(0)
	v_mfma_f32_16x16x32_bf16 v[124:127], v[146:149], v[200:203], v[124:127]
	v_mfma_f32_16x16x32_bf16 v[120:123], v[172:175], v[200:203], v[120:123]
	v_mfma_f32_16x16x32_bf16 v[108:111], v[146:149], v[208:211], v[108:111]
	v_mfma_f32_16x16x32_bf16 v[104:107], v[172:175], v[208:211], v[104:107]
	v_mfma_f32_16x16x32_bf16 v[92:95], v[146:149], v[216:219], v[92:95]
	v_mfma_f32_16x16x32_bf16 v[88:91], v[172:175], v[216:219], v[88:91]
	v_mfma_f32_16x16x32_bf16 v[76:79], v[146:149], v[224:227], v[76:79]
	v_mfma_f32_16x16x32_bf16 v[72:75], v[172:175], v[224:227], v[72:75]
	v_mfma_f32_16x16x32_bf16 v[124:127], v[150:153], v[204:207], v[124:127]
	v_mfma_f32_16x16x32_bf16 v[120:123], v[176:179], v[204:207], v[120:123]
	v_mfma_f32_16x16x32_bf16 v[108:111], v[150:153], v[212:215], v[108:111]
	v_mfma_f32_16x16x32_bf16 v[104:107], v[176:179], v[212:215], v[104:107]
	v_mfma_f32_16x16x32_bf16 v[92:95], v[150:153], v[220:223], v[92:95]
	v_mfma_f32_16x16x32_bf16 v[88:91], v[176:179], v[220:223], v[88:91]
	v_mfma_f32_16x16x32_bf16 v[76:79], v[150:153], v[228:231], v[76:79]
	v_mfma_f32_16x16x32_bf16 v[72:75], v[176:179], v[228:231], v[72:75]
	v_mfma_f32_16x16x32_bf16 v[116:119], v[180:183], v[200:203], v[116:119]
	v_mfma_f32_16x16x32_bf16 v[112:115], v[192:195], v[200:203], v[112:115]
	v_mfma_f32_16x16x32_bf16 v[100:103], v[180:183], v[208:211], v[100:103]
	v_mfma_f32_16x16x32_bf16 v[96:99], v[192:195], v[208:211], v[96:99]
	v_mfma_f32_16x16x32_bf16 v[84:87], v[180:183], v[216:219], v[84:87]
	v_mfma_f32_16x16x32_bf16 v[80:83], v[192:195], v[216:219], v[80:83]
	v_mfma_f32_16x16x32_bf16 v[68:71], v[180:183], v[224:227], v[68:71]
	v_mfma_f32_16x16x32_bf16 v[64:67], v[192:195], v[224:227], v[64:67]
	v_mfma_f32_16x16x32_bf16 v[116:119], v[188:191], v[204:207], v[116:119]
	v_mfma_f32_16x16x32_bf16 v[112:115], v[196:199], v[204:207], v[112:115]
	v_mfma_f32_16x16x32_bf16 v[100:103], v[188:191], v[212:215], v[100:103]
	v_mfma_f32_16x16x32_bf16 v[96:99], v[196:199], v[212:215], v[96:99]
	v_mfma_f32_16x16x32_bf16 v[84:87], v[188:191], v[220:223], v[84:87]
	v_mfma_f32_16x16x32_bf16 v[80:83], v[196:199], v[220:223], v[80:83]
	v_mfma_f32_16x16x32_bf16 v[68:71], v[188:191], v[228:231], v[68:71]
	v_mfma_f32_16x16x32_bf16 v[64:67], v[196:199], v[228:231], v[64:67]
	s_barrier
	s_add_u32 s98, s34, 0x80
	s_addc_u32 s99, s35, 0
	s_add_u32 s100, s36, 0x80
	s_addc_u32 s101, s37, 0
	s_add_i32 s65, s52, s13
	s_mov_b32 m0, s65
	ds_read_b128 v[200:203], v171 offset:16384
	ds_read_b128 v[204:207], v171 offset:17408
	ds_read_b128 v[208:211], v171 offset:18432
	ds_read_b128 v[212:215], v171 offset:19456
	ds_read_b128 v[216:219], v171 offset:20480
	ds_read_b128 v[220:223], v171 offset:21504
	ds_read_b128 v[224:227], v171 offset:22528
	ds_read_b128 v[228:231], v171 offset:23552
	global_load_lds_dwordx4 v130, s[34:35]
	s_add_i32 m0, s65, 0x2000
	s_add_u32 s66, s34, 0x40000
	s_addc_u32 s67, s35, 0
	s_add_i32 s65, s53, s13
	global_load_lds_dwordx4 v134, s[34:35]
	s_mov_b32 m0, s65
	s_nop 0
	global_load_lds_dwordx4 v130, s[66:67]
	s_add_i32 m0, s65, 0x2000
	s_nop 0
	global_load_lds_dwordx4 v134, s[66:67]
	s_mov_b32 m0, s29
	s_nop 0
	global_load_lds_dwordx4 v128, s[36:37]
	s_mov_b32 m0, s47
	s_nop 0
	global_load_lds_dwordx4 v132, s[36:37]
	s_waitcnt vmcnt(8)
	s_waitcnt lgkmcnt(0)
	s_barrier
	s_waitcnt lgkmcnt(0)
	v_mfma_f32_16x16x32_bf16 v[60:63], v[146:149], v[200:203], v[60:63]
	v_mfma_f32_16x16x32_bf16 v[56:59], v[172:175], v[200:203], v[56:59]
	v_mfma_f32_16x16x32_bf16 v[44:47], v[146:149], v[208:211], v[44:47]
	v_mfma_f32_16x16x32_bf16 v[40:43], v[172:175], v[208:211], v[40:43]
	v_mfma_f32_16x16x32_bf16 v[28:31], v[146:149], v[216:219], v[28:31]
	v_mfma_f32_16x16x32_bf16 v[24:27], v[172:175], v[216:219], v[24:27]
	v_mfma_f32_16x16x32_bf16 v[12:15], v[146:149], v[224:227], v[12:15]
	v_mfma_f32_16x16x32_bf16 v[8:11], v[172:175], v[224:227], v[8:11]
	v_mfma_f32_16x16x32_bf16 v[60:63], v[150:153], v[204:207], v[60:63]
	v_mfma_f32_16x16x32_bf16 v[56:59], v[176:179], v[204:207], v[56:59]
	v_mfma_f32_16x16x32_bf16 v[44:47], v[150:153], v[212:215], v[44:47]
	v_mfma_f32_16x16x32_bf16 v[40:43], v[176:179], v[212:215], v[40:43]
	v_mfma_f32_16x16x32_bf16 v[28:31], v[150:153], v[220:223], v[28:31]
	v_mfma_f32_16x16x32_bf16 v[24:27], v[176:179], v[220:223], v[24:27]
	v_mfma_f32_16x16x32_bf16 v[12:15], v[150:153], v[228:231], v[12:15]
	v_mfma_f32_16x16x32_bf16 v[8:11], v[176:179], v[228:231], v[8:11]
	v_mfma_f32_16x16x32_bf16 v[52:55], v[180:183], v[200:203], v[52:55]
	v_mfma_f32_16x16x32_bf16 v[48:51], v[192:195], v[200:203], v[48:51]
	v_mfma_f32_16x16x32_bf16 v[36:39], v[180:183], v[208:211], v[36:39]
	v_mfma_f32_16x16x32_bf16 v[32:35], v[192:195], v[208:211], v[32:35]
	v_mfma_f32_16x16x32_bf16 v[20:23], v[180:183], v[216:219], v[20:23]
	v_mfma_f32_16x16x32_bf16 v[16:19], v[192:195], v[216:219], v[16:19]
	v_mfma_f32_16x16x32_bf16 v[4:7], v[180:183], v[224:227], v[4:7]
	v_mfma_f32_16x16x32_bf16 v[0:3], v[192:195], v[224:227], v[0:3]
	v_mfma_f32_16x16x32_bf16 v[52:55], v[188:191], v[204:207], v[52:55]
	v_mfma_f32_16x16x32_bf16 v[48:51], v[196:199], v[204:207], v[48:51]
	v_mfma_f32_16x16x32_bf16 v[36:39], v[188:191], v[212:215], v[36:39]
	v_mfma_f32_16x16x32_bf16 v[32:35], v[196:199], v[212:215], v[32:35]
	v_mfma_f32_16x16x32_bf16 v[20:23], v[188:191], v[220:223], v[20:23]
	v_mfma_f32_16x16x32_bf16 v[16:19], v[196:199], v[220:223], v[16:19]
	v_mfma_f32_16x16x32_bf16 v[4:7], v[188:191], v[228:231], v[4:7]
	v_mfma_f32_16x16x32_bf16 v[0:3], v[196:199], v[228:231], v[0:3]
	s_barrier
; #define PG8_STAGE(bufoff, gbase, voff) do { _Pragma("unroll") for (int _i = 0; _i < 2; ++_i) \
;         __builtin_amdgcn_global_load_lds((const unsigned*)((const char*)(gbase) + (voff)[_i]), (PG8_LAS unsigned*)(lds + (bufoff) + ldsw + _i * 8192), 16, 0, 0); } while (0)
; #define PG8_LDA(dst, b, h) do { _Pragma("unroll") for (int m = 0; m < 4; ++m) _Pragma("unroll") for (int k = 0; k < 2; ++k) dst[m][k] = *(const PG8_LAS bf16x8*)(lds + PG8_SA(b, h) + aoff + m * 2048 + k * 1024); } while (0)
; #define PG8_LDB(dst, b, h) do { _Pragma("unroll") for (int n = 0; n < 2; ++n) _Pragma("unroll") for (int k = 0; k < 2; ++k) dst[n][k] = *(const PG8_LAS bf16x8*)(lds + PG8_SB(b, h) + boff + n * 2048 + k * 1024); } while (0)
; #define PG8_MMA(ai, bj, At, Bt) do { __builtin_amdgcn_s_setprio(1); _Pragma("unroll") for (int m = 0; m < 4; ++m) _Pragma("unroll") for (int n = 0; n < 2; ++n) _Pragma("unroll") for (int k = 0; k < 2; ++k) \
;         acc[ai][bj][m][n] = __builtin_amdgcn_mfma_f32_16x16x32_bf16(Bt[n][k], At[m][k], acc[ai][bj][m][n], 0, 0, 0); __builtin_amdgcn_s_setprio(0); } while (0)
; #define PG8_WAIT_V(n) asm volatile("s_waitcnt vmcnt(" #n ")" ::: "memory")
; #define PG8_WAIT_L(n) asm volatile("s_waitcnt lgkmcnt(" #n ")" ::: "memory")
; #define PG8_BAR __builtin_amdgcn_s_barrier()
; template <class Epi, class Sched, bool ALIGN_EPI = false, bool SP2 = false>
; __device__ __forceinline__ void gemm_phase(PG8_LAS unsigned char* lds, const Gemm g, const Sched S, const Epi E, const int tid) {
;     ...
;         for (int t = 0; t < nt; t += 2) {
;             const bool last = (t == nt - 2);
;             const char* a1 = cA + (size_t)(t + 1) * kstep;
;             const char* a2 = last ? nA : cA + (size_t)(t + 2) * kstep; const char* b2 = last ? nB : cB + (size_t)(t + 2) * kstep;
;             const char* a3 = a2 + kstep; const char* b3 = b2 + kstep;
;     ...
;             PG8_LDB(B0, 1, 0); PG8_LDB(B1, 1, 1); PG8_SCHED; PG8_LDA(At, 1, 0); PG8_STAGE(PG8_SA(0, 1), a2 + hstepA, voffA);
;             PG8_WAIT_V(8); PG8_WAIT_L(0); PG8_BAR; PG8_MMA(0, 0, At, B0); PG8_MMA(0, 1, At, B1); PG8_BAR; PG8_SCHED;
;             PG8_LDA(At, 1, 1); PG8_STAGE(PG8_SB(1, 0), b3, voffB); PG8_STAGE(PG8_SB(1, 1), b3 + hstepB, voffB); PG8_STAGE(PG8_SA(1, 0), a3, voffA);
;             PG8_WAIT_V(8); PG8_WAIT_L(0); PG8_BAR; PG8_MMA(1, 0, At, B0); PG8_MMA(1, 1, At, B1); PG8_BAR; PG8_SCHED;
	s_add_i32 s65, 0, 0x18000
	s_add_i32 s66, 0, 0x1c000
	v_add_u32_e32 v176, s65, v166
	v_add_u32_e32 v187, s66, v166
	ds_read_b128 v[146:149], v176
	ds_read_b128 v[150:153], v176 offset:1024
	ds_read_b128 v[172:175], v176 offset:2048
	ds_read_b128 v[176:179], v176 offset:3072
	ds_read_b128 v[180:183], v187
	ds_read_b128 v[188:191], v187 offset:1024
	ds_read_b128 v[192:195], v187 offset:2048
	ds_read_b128 v[196:199], v187 offset:3072
	s_add_u32 s36, s36, 0x40000
	s_addc_u32 s37, s37, 0
	s_mov_b32 m0, s48
	ds_read_b128 v[200:203], v171 offset:32768
	ds_read_b128 v[204:207], v171 offset:33792
	ds_read_b128 v[208:211], v171 offset:34816
	ds_read_b128 v[212:215], v171 offset:35840
	ds_read_b128 v[216:219], v171 offset:36864
	ds_read_b128 v[220:223], v171 offset:37888
	ds_read_b128 v[224:227], v171 offset:38912
	ds_read_b128 v[228:231], v171 offset:39936
	global_load_lds_dwordx4 v128, s[36:37]
	s_mov_b32 m0, s49
	s_nop 0
	global_load_lds_dwordx4 v132, s[36:37]
	s_waitcnt vmcnt(8)
	s_waitcnt lgkmcnt(0)
	s_barrier
	s_waitcnt lgkmcnt(0)
	v_mfma_f32_16x16x32_bf16 v[124:127], v[146:149], v[200:203], v[124:127]
	v_mfma_f32_16x16x32_bf16 v[120:123], v[172:175], v[200:203], v[120:123]
	v_mfma_f32_16x16x32_bf16 v[108:111], v[146:149], v[208:211], v[108:111]
	v_mfma_f32_16x16x32_bf16 v[104:107], v[172:175], v[208:211], v[104:107]
	v_mfma_f32_16x16x32_bf16 v[92:95], v[146:149], v[216:219], v[92:95]
	v_mfma_f32_16x16x32_bf16 v[88:91], v[172:175], v[216:219], v[88:91]
	v_mfma_f32_16x16x32_bf16 v[76:79], v[146:149], v[224:227], v[76:79]
	v_mfma_f32_16x16x32_bf16 v[72:75], v[172:175], v[224:227], v[72:75]
	v_mfma_f32_16x16x32_bf16 v[124:127], v[150:153], v[204:207], v[124:127]
	v_mfma_f32_16x16x32_bf16 v[120:123], v[176:179], v[204:207], v[120:123]
	v_mfma_f32_16x16x32_bf16 v[108:111], v[150:153], v[212:215], v[108:111]
	v_mfma_f32_16x16x32_bf16 v[104:107], v[176:179], v[212:215], v[104:107]
	v_mfma_f32_16x16x32_bf16 v[92:95], v[150:153], v[220:223], v[92:95]
	v_mfma_f32_16x16x32_bf16 v[88:91], v[176:179], v[220:223], v[88:91]
	v_mfma_f32_16x16x32_bf16 v[76:79], v[150:153], v[228:231], v[76:79]
	v_mfma_f32_16x16x32_bf16 v[72:75], v[176:179], v[228:231], v[72:75]
	v_mfma_f32_16x16x32_bf16 v[116:119], v[180:183], v[200:203], v[116:119]
	v_mfma_f32_16x16x32_bf16 v[112:115], v[192:195], v[200:203], v[112:115]
	v_mfma_f32_16x16x32_bf16 v[100:103], v[180:183], v[208:211], v[100:103]
	v_mfma_f32_16x16x32_bf16 v[96:99], v[192:195], v[208:211], v[96:99]
	v_mfma_f32_16x16x32_bf16 v[84:87], v[180:183], v[216:219], v[84:87]
	v_mfma_f32_16x16x32_bf16 v[80:83], v[192:195], v[216:219], v[80:83]
	v_mfma_f32_16x16x32_bf16 v[68:71], v[180:183], v[224:227], v[68:71]
	v_mfma_f32_16x16x32_bf16 v[64:67], v[192:195], v[224:227], v[64:67]
	v_mfma_f32_16x16x32_bf16 v[116:119], v[188:191], v[204:207], v[116:119]
	v_mfma_f32_16x16x32_bf16 v[112:115], v[196:199], v[204:207], v[112:115]
	v_mfma_f32_16x16x32_bf16 v[100:103], v[188:191], v[212:215], v[100:103]
	v_mfma_f32_16x16x32_bf16 v[96:99], v[196:199], v[212:215], v[96:99]
	v_mfma_f32_16x16x32_bf16 v[84:87], v[188:191], v[220:223], v[84:87]
	v_mfma_f32_16x16x32_bf16 v[80:83], v[196:199], v[220:223], v[80:83]
	v_mfma_f32_16x16x32_bf16 v[68:71], v[188:191], v[228:231], v[68:71]
	v_mfma_f32_16x16x32_bf16 v[64:67], v[196:199], v[228:231], v[64:67]
	s_barrier
	s_add_i32 s36, s65, s13
	s_mov_b32 m0, s36
	ds_read_b128 v[200:203], v171 offset:49152
	ds_read_b128 v[204:207], v171 offset:50176
	ds_read_b128 v[208:211], v171 offset:51200
	ds_read_b128 v[212:215], v171 offset:52224
	ds_read_b128 v[216:219], v171 offset:53248
	ds_read_b128 v[220:223], v171 offset:54272
	ds_read_b128 v[224:227], v171 offset:55296
	ds_read_b128 v[228:231], v171 offset:56320
	global_load_lds_dwordx4 v130, s[98:99]
	s_add_i32 m0, s36, 0x2000
	s_add_u32 s34, s34, 0x40080
	s_addc_u32 s35, s35, 0
	s_add_i32 s36, s66, s13
	global_load_lds_dwordx4 v134, s[98:99]
	s_mov_b32 m0, s36
	s_nop 0
	global_load_lds_dwordx4 v130, s[34:35]
	s_add_i32 m0, s36, 0x2000
	s_nop 0
	global_load_lds_dwordx4 v134, s[34:35]
	s_mov_b32 m0, s50
	s_nop 0
	global_load_lds_dwordx4 v128, s[100:101]
	s_mov_b32 m0, s51
	s_nop 0
	global_load_lds_dwordx4 v132, s[100:101]
	s_waitcnt vmcnt(8)
	s_waitcnt lgkmcnt(0)
	s_barrier
	s_waitcnt lgkmcnt(0)
	v_mfma_f32_16x16x32_bf16 v[60:63], v[146:149], v[200:203], v[60:63]
	v_mfma_f32_16x16x32_bf16 v[56:59], v[172:175], v[200:203], v[56:59]
	v_mfma_f32_16x16x32_bf16 v[44:47], v[146:149], v[208:211], v[44:47]
	v_mfma_f32_16x16x32_bf16 v[40:43], v[172:175], v[208:211], v[40:43]
	v_mfma_f32_16x16x32_bf16 v[28:31], v[146:149], v[216:219], v[28:31]
	v_mfma_f32_16x16x32_bf16 v[24:27], v[172:175], v[216:219], v[24:27]
	v_mfma_f32_16x16x32_bf16 v[12:15], v[146:149], v[224:227], v[12:15]
	v_mfma_f32_16x16x32_bf16 v[8:11], v[172:175], v[224:227], v[8:11]
	v_mfma_f32_16x16x32_bf16 v[60:63], v[150:153], v[204:207], v[60:63]
	v_mfma_f32_16x16x32_bf16 v[56:59], v[176:179], v[204:207], v[56:59]
	v_mfma_f32_16x16x32_bf16 v[44:47], v[150:153], v[212:215], v[44:47]
	v_mfma_f32_16x16x32_bf16 v[40:43], v[176:179], v[212:215], v[40:43]
	v_mfma_f32_16x16x32_bf16 v[28:31], v[150:153], v[220:223], v[28:31]
	v_mfma_f32_16x16x32_bf16 v[24:27], v[176:179], v[220:223], v[24:27]
	v_mfma_f32_16x16x32_bf16 v[12:15], v[150:153], v[228:231], v[12:15]
	v_mfma_f32_16x16x32_bf16 v[8:11], v[176:179], v[228:231], v[8:11]
	v_mfma_f32_16x16x32_bf16 v[52:55], v[180:183], v[200:203], v[52:55]
	v_mfma_f32_16x16x32_bf16 v[48:51], v[192:195], v[200:203], v[48:51]
	v_mfma_f32_16x16x32_bf16 v[36:39], v[180:183], v[208:211], v[36:39]
	v_mfma_f32_16x16x32_bf16 v[32:35], v[192:195], v[208:211], v[32:35]
	v_mfma_f32_16x16x32_bf16 v[20:23], v[180:183], v[216:219], v[20:23]
	v_mfma_f32_16x16x32_bf16 v[16:19], v[192:195], v[216:219], v[16:19]
	v_mfma_f32_16x16x32_bf16 v[4:7], v[180:183], v[224:227], v[4:7]
	v_mfma_f32_16x16x32_bf16 v[0:3], v[192:195], v[224:227], v[0:3]
	v_mfma_f32_16x16x32_bf16 v[52:55], v[188:191], v[204:207], v[52:55]
	v_mfma_f32_16x16x32_bf16 v[48:51], v[196:199], v[204:207], v[48:51]
	v_mfma_f32_16x16x32_bf16 v[36:39], v[188:191], v[212:215], v[36:39]
	v_mfma_f32_16x16x32_bf16 v[32:35], v[196:199], v[212:215], v[32:35]
	v_mfma_f32_16x16x32_bf16 v[20:23], v[188:191], v[220:223], v[20:23]
	v_mfma_f32_16x16x32_bf16 v[16:19], v[196:199], v[220:223], v[16:19]
	v_mfma_f32_16x16x32_bf16 v[4:7], v[188:191], v[228:231], v[4:7]
	v_mfma_f32_16x16x32_bf16 v[0:3], v[196:199], v[228:231], v[0:3]
	s_barrier
	s_add_i32 s64, s64, 2
	s_add_u32 s30, s30, 0x100
	s_addc_u32 s31, s31, 0
	s_add_u32 s62, s62, 0x100
	s_addc_u32 s63, s63, 0
	s_cmp_gt_u32 s64, 13
	s_cbranch_scc0 .LBB0_1196
	s_setprio 0
	s_and_b64 vcc, exec, s[10:11]
	s_cbranch_vccz .LBB0_1199
	s_barrier

; #define PG8_STAGE(bufoff, gbase, voff) do { _Pragma("unroll") for (int _i = 0; _i < 2; ++_i) \
;         __builtin_amdgcn_global_load_lds((const unsigned*)((const char*)(gbase) + (voff)[_i]), (PG8_LAS unsigned*)(lds + (bufoff) + ldsw + _i * 8192), 16, 0, 0); } while (0)
; #define PG8_LDA(dst, b, h) do { _Pragma("unroll") for (int m = 0; m < 4; ++m) _Pragma("unroll") for (int k = 0; k < 2; ++k) dst[m][k] = *(const PG8_LAS bf16x8*)(lds + PG8_SA(b, h) + aoff + m * 2048 + k * 1024); } while (0)
; #define PG8_LDB(dst, b, h) do { _Pragma("unroll") for (int n = 0; n < 2; ++n) _Pragma("unroll") for (int k = 0; k < 2; ++k) dst[n][k] = *(const PG8_LAS bf16x8*)(lds + PG8_SB(b, h) + boff + n * 2048 + k * 1024); } while (0)
; #define PG8_WAIT_V(n) asm volatile("s_waitcnt vmcnt(" #n ")" ::: "memory")
; #define PG8_WAIT_L(n) asm volatile("s_waitcnt lgkmcnt(" #n ")" ::: "memory")
; #define PG8_BAR __builtin_amdgcn_s_barrier()
; template <class Epi, class Sched, bool ALIGN_EPI = false, bool SP2 = false>
; __device__ __forceinline__ void gemm_phase(PG8_LAS unsigned char* lds, const Gemm g, const Sched S, const Epi E, const int tid) {
;     ...
;         const bool has_next = S.next(ui + 1, nxt);
;         const char* nA = has_next ? (const char*)g.A + (size_t)nxt.pm * tstepA + (size_t)nxt.pn * apn : cA; const char* nB = has_next ? (const char*)g.Bt + (size_t)nxt.pn * bpn : cB;
;         for (int t = 0; t < nt; t += 2) {
;             const bool last = (t == nt - 2);
;             const char* a1 = cA + (size_t)(t + 1) * kstep;
;             const char* a2 = last ? nA : cA + (size_t)(t + 2) * kstep; const char* b2 = last ? nB : cB + (size_t)(t + 2) * kstep;
;             const char* a3 = a2 + kstep; const char* b3 = b2 + kstep;
;             if (last && has_next) S.a_ready(nxt);
;             if constexpr (SP2) {
;             PG8_LDB(B0, 0, 0); PG8_LDB(B1, 0, 1); PG8_SCHED; PG8_LDA(At, 0, 0); PG8_STAGE(PG8_SA(1, 1), a1 + hstepA, voffA);
;             PG8_WAIT_V(8); PG8_WAIT_L(0); PG8_BAR; PG8_MMA(0, 0, At, B0); PG8_MMA(0, 1, At, B1); PG8_BAR; PG8_SCHED;
;     ...
;         else {
; #pragma unroll
;         for (int a = 0; a < 2; ++a)
; #pragma unroll
;             for (int b = 0; b < 2; ++b)
; #pragma unroll
;                 for (int m = 0; m < 4; ++m)
; #pragma unroll
;                     for (int n = 0; n < 2; ++n) acc[a][b][m][n] = (f32x4){0.f, 0.f, 0.f, 0.f};
;         }
.LBB0_1238:
	s_ashr_i32 s37, s36, 31
	s_lshl_b64 s[40:41], s[36:37], 19
	s_add_u32 s40, s18, s40
	s_addc_u32 s41, s19, s41
	s_and_b64 s[46:47], s[38:39], exec
	s_cselect_b32 s37, s41, s51
	s_cselect_b32 s75, s40, s50
	s_ashr_i32 s35, s34, 31
	s_lshl_b64 s[46:47], s[34:35], 19
	s_add_u32 s46, s61, s46
	s_addc_u32 s47, s62, s47
	s_and_b64 s[54:55], s[38:39], exec
	s_cselect_b32 s35, s47, s53
	s_cselect_b32 s76, s46, s52
	s_add_u32 s50, s50, 0x40080
	s_addc_u32 s51, s51, 0
	s_add_u32 s77, s52, 0x100
	v_mov_b32_e32 v0, 0
	s_addc_u32 s78, s53, 0
	s_mov_b32 s79, -2
	v_mov_b32_e32 v1, v0
	v_mov_b32_e32 v2, v0
	v_mov_b32_e32 v3, v0
	v_mov_b32_e32 v4, v0
	v_mov_b32_e32 v5, v0
	v_mov_b32_e32 v6, v0
	v_mov_b32_e32 v7, v0
	v_mov_b32_e32 v8, v0
	v_mov_b32_e32 v9, v0
	v_mov_b32_e32 v10, v0
	v_mov_b32_e32 v11, v0
	v_mov_b32_e32 v16, v0
	v_mov_b32_e32 v17, v0
	v_mov_b32_e32 v18, v0
	v_mov_b32_e32 v19, v0
	v_mov_b32_e32 v24, v0
	v_mov_b32_e32 v25, v0
	v_mov_b32_e32 v26, v0
	v_mov_b32_e32 v27, v0
	v_mov_b32_e32 v32, v0
	v_mov_b32_e32 v33, v0
	v_mov_b32_e32 v34, v0
	v_mov_b32_e32 v35, v0
	v_mov_b32_e32 v40, v0
	v_mov_b32_e32 v41, v0
	v_mov_b32_e32 v42, v0
	v_mov_b32_e32 v43, v0
	v_mov_b32_e32 v48, v0
	v_mov_b32_e32 v49, v0
	v_mov_b32_e32 v50, v0
	v_mov_b32_e32 v51, v0
	v_mov_b32_e32 v12, v0
	v_mov_b32_e32 v13, v0
	v_mov_b32_e32 v14, v0
	v_mov_b32_e32 v15, v0
	v_mov_b32_e32 v20, v0
	v_mov_b32_e32 v21, v0
	v_mov_b32_e32 v22, v0
	v_mov_b32_e32 v23, v0
	v_mov_b32_e32 v28, v0
	v_mov_b32_e32 v29, v0
	v_mov_b32_e32 v30, v0
	v_mov_b32_e32 v31, v0
	v_mov_b32_e32 v36, v0
	v_mov_b32_e32 v37, v0
	v_mov_b32_e32 v38, v0
	v_mov_b32_e32 v39, v0
	v_mov_b32_e32 v44, v0
	v_mov_b32_e32 v45, v0
	v_mov_b32_e32 v46, v0
	v_mov_b32_e32 v47, v0
	v_mov_b32_e32 v52, v0
	v_mov_b32_e32 v53, v0
	v_mov_b32_e32 v54, v0
	v_mov_b32_e32 v55, v0
	v_mov_b32_e32 v56, v0
	v_mov_b32_e32 v57, v0
	v_mov_b32_e32 v58, v0
	v_mov_b32_e32 v59, v0
	v_mov_b32_e32 v60, v0
	v_mov_b32_e32 v61, v0
	v_mov_b32_e32 v62, v0
	v_mov_b32_e32 v63, v0
	v_mov_b32_e32 v64, v0
	v_mov_b32_e32 v65, v0
	v_mov_b32_e32 v66, v0
	v_mov_b32_e32 v67, v0
	v_mov_b32_e32 v68, v0
	v_mov_b32_e32 v69, v0
	v_mov_b32_e32 v70, v0
	v_mov_b32_e32 v71, v0
	v_mov_b32_e32 v76, v0
	v_mov_b32_e32 v77, v0
	v_mov_b32_e32 v78, v0
	v_mov_b32_e32 v79, v0
	v_mov_b32_e32 v84, v0
	v_mov_b32_e32 v85, v0
	v_mov_b32_e32 v86, v0
	v_mov_b32_e32 v87, v0
	v_mov_b32_e32 v92, v0
	v_mov_b32_e32 v93, v0
	v_mov_b32_e32 v94, v0
	v_mov_b32_e32 v95, v0
	v_mov_b32_e32 v100, v0
	v_mov_b32_e32 v101, v0
	v_mov_b32_e32 v102, v0
	v_mov_b32_e32 v103, v0
	v_mov_b32_e32 v108, v0
	v_mov_b32_e32 v109, v0
	v_mov_b32_e32 v110, v0
	v_mov_b32_e32 v111, v0
	v_mov_b32_e32 v116, v0
	v_mov_b32_e32 v117, v0
	v_mov_b32_e32 v118, v0
	v_mov_b32_e32 v119, v0
	v_mov_b32_e32 v72, v0
	v_mov_b32_e32 v73, v0
	v_mov_b32_e32 v74, v0
	v_mov_b32_e32 v75, v0
	v_mov_b32_e32 v80, v0
	v_mov_b32_e32 v81, v0
	v_mov_b32_e32 v82, v0
	v_mov_b32_e32 v83, v0
	v_mov_b32_e32 v88, v0
	v_mov_b32_e32 v89, v0
	v_mov_b32_e32 v90, v0
	v_mov_b32_e32 v91, v0
	v_mov_b32_e32 v96, v0
	v_mov_b32_e32 v97, v0
	v_mov_b32_e32 v98, v0
	v_mov_b32_e32 v99, v0
	v_mov_b32_e32 v104, v0
	v_mov_b32_e32 v105, v0
	v_mov_b32_e32 v106, v0
	v_mov_b32_e32 v107, v0
	v_mov_b32_e32 v112, v0
	v_mov_b32_e32 v113, v0
	v_mov_b32_e32 v114, v0
	v_mov_b32_e32 v115, v0
	v_mov_b32_e32 v120, v0
	v_mov_b32_e32 v121, v0
	v_mov_b32_e32 v122, v0
	v_mov_b32_e32 v123, v0
	v_mov_b32_e32 v124, v0
	v_mov_b32_e32 v125, v0
	v_mov_b32_e32 v126, v0
	v_mov_b32_e32 v127, v0
	v_readfirstlane_b32 s98, v186
	s_lshr_b32 s98, s98, 8
	s_cmp_eq_u32 s98, 0
	s_cbranch_scc1 .Lprio_skip_11
	s_setprio 1
.Lprio_skip_11:
.LBB0_1239:
	ds_read_b128 v[150:153], v147
	ds_read_b128 v[166:169], v147 offset:1024
	ds_read_b128 v[170:173], v147 offset:2048
	ds_read_b128 v[174:177], v147 offset:3072
	ds_read_b128 v[178:181], v148
	ds_read_b128 v[182:185], v148 offset:1024
	ds_read_b128 v[188:191], v148 offset:2048
	ds_read_b128 v[192:195], v148 offset:3072
	s_add_u32 s52, s50, 0xfffc0080
	s_addc_u32 s53, s51, -1
	s_cmp_eq_u32 s79, 12
	s_cselect_b32 s55, s37, s53
	s_cselect_b32 s54, s75, s52
	s_cselect_b32 s53, s35, s78
	s_cselect_b32 s52, s76, s77
	s_add_i32 m0, s49, 0xc000
	ds_read_b128 v[196:199], v149
	ds_read_b128 v[200:203], v149 offset:1024
	ds_read_b128 v[204:207], v149 offset:2048
	ds_read_b128 v[208:211], v149 offset:3072
	ds_read_b128 v[212:215], v149 offset:4096
	ds_read_b128 v[216:219], v149 offset:5120
	ds_read_b128 v[220:223], v149 offset:6144
	ds_read_b128 v[224:227], v149 offset:7168
	global_load_lds_dwordx4 v138, s[50:51]
	s_add_i32 m0, s49, 0xe000
	s_nop 0
	global_load_lds_dwordx4 v140, s[50:51]
	s_waitcnt vmcnt(8)
	s_waitcnt lgkmcnt(0)
	s_barrier
; #define PG8_STAGE(bufoff, gbase, voff) do { _Pragma("unroll") for (int _i = 0; _i < 2; ++_i) \
;         __builtin_amdgcn_global_load_lds((const unsigned*)((const char*)(gbase) + (voff)[_i]), (PG8_LAS unsigned*)(lds + (bufoff) + ldsw + _i * 8192), 16, 0, 0); } while (0)
; #define PG8_LDA(dst, b, h) do { _Pragma("unroll") for (int m = 0; m < 4; ++m) _Pragma("unroll") for (int k = 0; k < 2; ++k) dst[m][k] = *(const PG8_LAS bf16x8*)(lds + PG8_SA(b, h) + aoff + m * 2048 + k * 1024); } while (0)
; #define PG8_LDB(dst, b, h) do { _Pragma("unroll") for (int n = 0; n < 2; ++n) _Pragma("unroll") for (int k = 0; k < 2; ++k) dst[n][k] = *(const PG8_LAS bf16x8*)(lds + PG8_SB(b, h) + boff + n * 2048 + k * 1024); } while (0)
; #define PG8_MMA(ai, bj, At, Bt) do { __builtin_amdgcn_s_setprio(1); _Pragma("unroll") for (int m = 0; m < 4; ++m) _Pragma("unroll") for (int n = 0; n < 2; ++n) _Pragma("unroll") for (int k = 0; k < 2; ++k) \
;         acc[ai][bj][m][n] = __builtin_amdgcn_mfma_f32_16x16x32_bf16(Bt[n][k], At[m][k], acc[ai][bj][m][n], 0, 0, 0); __builtin_amdgcn_s_setprio(0); } while (0)
; #define PG8_WAIT_V(n) asm volatile("s_waitcnt vmcnt(" #n ")" ::: "memory")
; #define PG8_WAIT_L(n) asm volatile("s_waitcnt lgkmcnt(" #n ")" ::: "memory")
; #define PG8_BAR __builtin_amdgcn_s_barrier()
; #define PG8_SCHED __builtin_amdgcn_sched_barrier(0)
; template <class Epi, class Sched, bool ALIGN_EPI = false, bool SP2 = false>
; __device__ __forceinline__ void gemm_phase(PG8_LAS unsigned char* lds, const Gemm g, const Sched S, const Epi E, const int tid) {
;     ...
;             PG8_LDB(B0, 0, 0); PG8_LDB(B1, 0, 1); PG8_SCHED; PG8_LDA(At, 0, 0); PG8_STAGE(PG8_SA(1, 1), a1 + hstepA, voffA);
;             PG8_WAIT_V(8); PG8_WAIT_L(0); PG8_BAR; PG8_MMA(0, 0, At, B0); PG8_MMA(0, 1, At, B1); PG8_BAR; PG8_SCHED;
;             PG8_LDA(At, 0, 1); PG8_STAGE(PG8_SB(0, 0), b2, voffB); PG8_STAGE(PG8_SB(0, 1), b2 + hstepB, voffB); PG8_STAGE(PG8_SA(0, 0), a2, voffA);
;             PG8_WAIT_V(8); PG8_WAIT_L(0); PG8_BAR; PG8_MMA(1, 0, At, B0); PG8_MMA(1, 1, At, B1); PG8_BAR; PG8_SCHED;
	s_waitcnt lgkmcnt(0)
	v_mfma_f32_16x16x32_bf16 v[124:127], v[150:153], v[196:199], v[124:127]
	v_mfma_f32_16x16x32_bf16 v[120:123], v[170:173], v[196:199], v[120:123]
	v_mfma_f32_16x16x32_bf16 v[112:115], v[150:153], v[204:207], v[112:115]
	v_mfma_f32_16x16x32_bf16 v[104:107], v[170:173], v[204:207], v[104:107]
	v_mfma_f32_16x16x32_bf16 v[96:99], v[150:153], v[212:215], v[96:99]
	v_mfma_f32_16x16x32_bf16 v[88:91], v[170:173], v[212:215], v[88:91]
	v_mfma_f32_16x16x32_bf16 v[80:83], v[150:153], v[220:223], v[80:83]
	v_mfma_f32_16x16x32_bf16 v[72:75], v[170:173], v[220:223], v[72:75]
	v_mfma_f32_16x16x32_bf16 v[124:127], v[166:169], v[200:203], v[124:127]
	v_mfma_f32_16x16x32_bf16 v[120:123], v[174:177], v[200:203], v[120:123]
	v_mfma_f32_16x16x32_bf16 v[112:115], v[166:169], v[208:211], v[112:115]
	v_mfma_f32_16x16x32_bf16 v[104:107], v[174:177], v[208:211], v[104:107]
	v_mfma_f32_16x16x32_bf16 v[96:99], v[166:169], v[216:219], v[96:99]
	v_mfma_f32_16x16x32_bf16 v[88:91], v[174:177], v[216:219], v[88:91]
	v_mfma_f32_16x16x32_bf16 v[80:83], v[166:169], v[224:227], v[80:83]
	v_mfma_f32_16x16x32_bf16 v[72:75], v[174:177], v[224:227], v[72:75]
	v_mfma_f32_16x16x32_bf16 v[116:119], v[178:181], v[196:199], v[116:119]
	v_mfma_f32_16x16x32_bf16 v[108:111], v[188:191], v[196:199], v[108:111]
	v_mfma_f32_16x16x32_bf16 v[100:103], v[178:181], v[204:207], v[100:103]
	v_mfma_f32_16x16x32_bf16 v[92:95], v[188:191], v[204:207], v[92:95]
	v_mfma_f32_16x16x32_bf16 v[84:87], v[178:181], v[212:215], v[84:87]
	v_mfma_f32_16x16x32_bf16 v[76:79], v[188:191], v[212:215], v[76:79]
	v_mfma_f32_16x16x32_bf16 v[68:71], v[178:181], v[220:223], v[68:71]
	v_mfma_f32_16x16x32_bf16 v[64:67], v[188:191], v[220:223], v[64:67]
	v_mfma_f32_16x16x32_bf16 v[116:119], v[182:185], v[200:203], v[116:119]
	v_mfma_f32_16x16x32_bf16 v[108:111], v[192:195], v[200:203], v[108:111]
	v_mfma_f32_16x16x32_bf16 v[100:103], v[182:185], v[208:211], v[100:103]
	v_mfma_f32_16x16x32_bf16 v[92:95], v[192:195], v[208:211], v[92:95]
	v_mfma_f32_16x16x32_bf16 v[84:87], v[182:185], v[216:219], v[84:87]
	v_mfma_f32_16x16x32_bf16 v[76:79], v[192:195], v[216:219], v[76:79]
	v_mfma_f32_16x16x32_bf16 v[68:71], v[182:185], v[224:227], v[68:71]
	v_mfma_f32_16x16x32_bf16 v[64:67], v[192:195], v[224:227], v[64:67]
	s_barrier
	s_add_u32 s98, s52, 0x80
	s_addc_u32 s99, s53, 0
	s_add_u32 s100, s54, 0x80
	s_addc_u32 s101, s55, 0
	s_add_i32 s80, s72, s64
	s_mov_b32 m0, s80
	ds_read_b128 v[196:199], v149 offset:16384
	ds_read_b128 v[200:203], v149 offset:17408
	ds_read_b128 v[204:207], v149 offset:18432
	ds_read_b128 v[208:211], v149 offset:19456
	ds_read_b128 v[212:215], v149 offset:20480
	ds_read_b128 v[216:219], v149 offset:21504
	ds_read_b128 v[220:223], v149 offset:22528
	ds_read_b128 v[224:227], v149 offset:23552
	global_load_lds_dwordx4 v130, s[52:53]
	s_add_i32 m0, s80, 0x2000
	s_add_u32 s80, s52, 0x40000
	s_addc_u32 s81, s53, 0
	s_add_i32 s82, s73, s64
	global_load_lds_dwordx4 v134, s[52:53]
	s_mov_b32 m0, s82
	s_nop 0
	global_load_lds_dwordx4 v130, s[80:81]
	s_add_i32 m0, s82, 0x2000
	s_nop 0
	global_load_lds_dwordx4 v134, s[80:81]
	s_mov_b32 m0, s49
	s_nop 0
	global_load_lds_dwordx4 v128, s[54:55]
	s_mov_b32 m0, s65
	s_nop 0
	global_load_lds_dwordx4 v132, s[54:55]
	s_waitcnt vmcnt(8)
	s_waitcnt lgkmcnt(0)
	s_barrier
	s_waitcnt lgkmcnt(0)
	v_mfma_f32_16x16x32_bf16 v[60:63], v[150:153], v[196:199], v[60:63]
	v_mfma_f32_16x16x32_bf16 v[56:59], v[170:173], v[196:199], v[56:59]
	v_mfma_f32_16x16x32_bf16 v[52:55], v[150:153], v[204:207], v[52:55]
	v_mfma_f32_16x16x32_bf16 v[44:47], v[170:173], v[204:207], v[44:47]
	v_mfma_f32_16x16x32_bf16 v[36:39], v[150:153], v[212:215], v[36:39]
	v_mfma_f32_16x16x32_bf16 v[28:31], v[170:173], v[212:215], v[28:31]
	v_mfma_f32_16x16x32_bf16 v[20:23], v[150:153], v[220:223], v[20:23]
	v_mfma_f32_16x16x32_bf16 v[12:15], v[170:173], v[220:223], v[12:15]
	v_mfma_f32_16x16x32_bf16 v[60:63], v[166:169], v[200:203], v[60:63]
	v_mfma_f32_16x16x32_bf16 v[56:59], v[174:177], v[200:203], v[56:59]
	v_mfma_f32_16x16x32_bf16 v[52:55], v[166:169], v[208:211], v[52:55]
	v_mfma_f32_16x16x32_bf16 v[44:47], v[174:177], v[208:211], v[44:47]
	v_mfma_f32_16x16x32_bf16 v[36:39], v[166:169], v[216:219], v[36:39]
	v_mfma_f32_16x16x32_bf16 v[28:31], v[174:177], v[216:219], v[28:31]
	v_mfma_f32_16x16x32_bf16 v[20:23], v[166:169], v[224:227], v[20:23]
	v_mfma_f32_16x16x32_bf16 v[12:15], v[174:177], v[224:227], v[12:15]
	v_mfma_f32_16x16x32_bf16 v[48:51], v[178:181], v[196:199], v[48:51]
	v_mfma_f32_16x16x32_bf16 v[40:43], v[188:191], v[196:199], v[40:43]
	v_mfma_f32_16x16x32_bf16 v[32:35], v[178:181], v[204:207], v[32:35]
	v_mfma_f32_16x16x32_bf16 v[24:27], v[188:191], v[204:207], v[24:27]
	v_mfma_f32_16x16x32_bf16 v[16:19], v[178:181], v[212:215], v[16:19]
	v_mfma_f32_16x16x32_bf16 v[8:11], v[188:191], v[212:215], v[8:11]
	v_mfma_f32_16x16x32_bf16 v[4:7], v[178:181], v[220:223], v[4:7]
	v_mfma_f32_16x16x32_bf16 v[0:3], v[188:191], v[220:223], v[0:3]
	v_mfma_f32_16x16x32_bf16 v[48:51], v[182:185], v[200:203], v[48:51]
	v_mfma_f32_16x16x32_bf16 v[40:43], v[192:195], v[200:203], v[40:43]
	v_mfma_f32_16x16x32_bf16 v[32:35], v[182:185], v[208:211], v[32:35]
	v_mfma_f32_16x16x32_bf16 v[24:27], v[192:195], v[208:211], v[24:27]
	v_mfma_f32_16x16x32_bf16 v[16:19], v[182:185], v[216:219], v[16:19]
	v_mfma_f32_16x16x32_bf16 v[8:11], v[192:195], v[216:219], v[8:11]
	v_mfma_f32_16x16x32_bf16 v[4:7], v[182:185], v[224:227], v[4:7]
	v_mfma_f32_16x16x32_bf16 v[0:3], v[192:195], v[224:227], v[0:3]
	s_barrier
; #define PG8_STAGE(bufoff, gbase, voff) do { _Pragma("unroll") for (int _i = 0; _i < 2; ++_i) \
;         __builtin_amdgcn_global_load_lds((const unsigned*)((const char*)(gbase) + (voff)[_i]), (PG8_LAS unsigned*)(lds + (bufoff) + ldsw + _i * 8192), 16, 0, 0); } while (0)
; #define PG8_LDA(dst, b, h) do { _Pragma("unroll") for (int m = 0; m < 4; ++m) _Pragma("unroll") for (int k = 0; k < 2; ++k) dst[m][k] = *(const PG8_LAS bf16x8*)(lds + PG8_SA(b, h) + aoff + m * 2048 + k * 1024); } while (0)
; #define PG8_LDB(dst, b, h) do { _Pragma("unroll") for (int n = 0; n < 2; ++n) _Pragma("unroll") for (int k = 0; k < 2; ++k) dst[n][k] = *(const PG8_LAS bf16x8*)(lds + PG8_SB(b, h) + boff + n * 2048 + k * 1024); } while (0)
; #define PG8_MMA(ai, bj, At, Bt) do { __builtin_amdgcn_s_setprio(1); _Pragma("unroll") for (int m = 0; m < 4; ++m) _Pragma("unroll") for (int n = 0; n < 2; ++n) _Pragma("unroll") for (int k = 0; k < 2; ++k) \
;         acc[ai][bj][m][n] = __builtin_amdgcn_mfma_f32_16x16x32_bf16(Bt[n][k], At[m][k], acc[ai][bj][m][n], 0, 0, 0); __builtin_amdgcn_s_setprio(0); } while (0)
; #define PG8_WAIT_V(n) asm volatile("s_waitcnt vmcnt(" #n ")" ::: "memory")
; #define PG8_WAIT_L(n) asm volatile("s_waitcnt lgkmcnt(" #n ")" ::: "memory")
; #define PG8_BAR __builtin_amdgcn_s_barrier()
; template <class Epi, class Sched, bool ALIGN_EPI = false, bool SP2 = false>
; __device__ __forceinline__ void gemm_phase(PG8_LAS unsigned char* lds, const Gemm g, const Sched S, const Epi E, const int tid) {
;     ...
;         for (int t = 0; t < nt; t += 2) {
;             const bool last = (t == nt - 2);
;             const char* a1 = cA + (size_t)(t + 1) * kstep;
;             const char* a2 = last ? nA : cA + (size_t)(t + 2) * kstep; const char* b2 = last ? nB : cB + (size_t)(t + 2) * kstep;
;             const char* a3 = a2 + kstep; const char* b3 = b2 + kstep;
;     ...
;             PG8_LDB(B0, 1, 0); PG8_LDB(B1, 1, 1); PG8_SCHED; PG8_LDA(At, 1, 0); PG8_STAGE(PG8_SA(0, 1), a2 + hstepA, voffA);
;             PG8_WAIT_V(8); PG8_WAIT_L(0); PG8_BAR; PG8_MMA(0, 0, At, B0); PG8_MMA(0, 1, At, B1); PG8_BAR; PG8_SCHED;
;             PG8_LDA(At, 1, 1); PG8_STAGE(PG8_SB(1, 0), b3, voffB); PG8_STAGE(PG8_SB(1, 1), b3 + hstepB, voffB); PG8_STAGE(PG8_SA(1, 0), a3, voffA);
;             PG8_WAIT_V(8); PG8_WAIT_L(0); PG8_BAR; PG8_MMA(1, 0, At, B0); PG8_MMA(1, 1, At, B1); PG8_BAR; PG8_SCHED;
	s_add_i32 s80, 0, 0x18000
	v_add_u32_e32 v165, s80, v145
	s_add_i32 s81, 0, 0x1c000
	ds_read_b128 v[150:153], v165
	ds_read_b128 v[166:169], v165 offset:1024
	ds_read_b128 v[170:173], v165 offset:2048
	ds_read_b128 v[174:177], v165 offset:3072
	v_add_u32_e32 v165, s81, v145
	ds_read_b128 v[178:181], v165
	ds_read_b128 v[182:185], v165 offset:1024
	ds_read_b128 v[188:191], v165 offset:2048
	ds_read_b128 v[192:195], v165 offset:3072
	s_add_u32 s54, s54, 0x40000
	s_addc_u32 s55, s55, 0
	s_mov_b32 m0, s66
	ds_read_b128 v[196:199], v149 offset:32768
	ds_read_b128 v[200:203], v149 offset:33792
	ds_read_b128 v[204:207], v149 offset:34816
	ds_read_b128 v[208:211], v149 offset:35840
	ds_read_b128 v[212:215], v149 offset:36864
	ds_read_b128 v[216:219], v149 offset:37888
	ds_read_b128 v[220:223], v149 offset:38912
	ds_read_b128 v[224:227], v149 offset:39936
	global_load_lds_dwordx4 v128, s[54:55]
	s_mov_b32 m0, s67
	s_nop 0
	global_load_lds_dwordx4 v132, s[54:55]
	s_waitcnt vmcnt(8)
	s_waitcnt lgkmcnt(0)
	s_barrier
	s_waitcnt lgkmcnt(0)
	v_mfma_f32_16x16x32_bf16 v[124:127], v[150:153], v[196:199], v[124:127]
	v_mfma_f32_16x16x32_bf16 v[120:123], v[170:173], v[196:199], v[120:123]
	v_mfma_f32_16x16x32_bf16 v[112:115], v[150:153], v[204:207], v[112:115]
	v_mfma_f32_16x16x32_bf16 v[104:107], v[170:173], v[204:207], v[104:107]
	v_mfma_f32_16x16x32_bf16 v[96:99], v[150:153], v[212:215], v[96:99]
	v_mfma_f32_16x16x32_bf16 v[88:91], v[170:173], v[212:215], v[88:91]
	v_mfma_f32_16x16x32_bf16 v[80:83], v[150:153], v[220:223], v[80:83]
	v_mfma_f32_16x16x32_bf16 v[72:75], v[170:173], v[220:223], v[72:75]
	v_mfma_f32_16x16x32_bf16 v[124:127], v[166:169], v[200:203], v[124:127]
	v_mfma_f32_16x16x32_bf16 v[120:123], v[174:177], v[200:203], v[120:123]
	v_mfma_f32_16x16x32_bf16 v[112:115], v[166:169], v[208:211], v[112:115]
	v_mfma_f32_16x16x32_bf16 v[104:107], v[174:177], v[208:211], v[104:107]
	v_mfma_f32_16x16x32_bf16 v[96:99], v[166:169], v[216:219], v[96:99]
	v_mfma_f32_16x16x32_bf16 v[88:91], v[174:177], v[216:219], v[88:91]
	v_mfma_f32_16x16x32_bf16 v[80:83], v[166:169], v[224:227], v[80:83]
	v_mfma_f32_16x16x32_bf16 v[72:75], v[174:177], v[224:227], v[72:75]
	v_mfma_f32_16x16x32_bf16 v[116:119], v[178:181], v[196:199], v[116:119]
	v_mfma_f32_16x16x32_bf16 v[108:111], v[188:191], v[196:199], v[108:111]
	v_mfma_f32_16x16x32_bf16 v[100:103], v[178:181], v[204:207], v[100:103]
	v_mfma_f32_16x16x32_bf16 v[92:95], v[188:191], v[204:207], v[92:95]
	v_mfma_f32_16x16x32_bf16 v[84:87], v[178:181], v[212:215], v[84:87]
	v_mfma_f32_16x16x32_bf16 v[76:79], v[188:191], v[212:215], v[76:79]
	v_mfma_f32_16x16x32_bf16 v[68:71], v[178:181], v[220:223], v[68:71]
	v_mfma_f32_16x16x32_bf16 v[64:67], v[188:191], v[220:223], v[64:67]
	v_mfma_f32_16x16x32_bf16 v[116:119], v[182:185], v[200:203], v[116:119]
	v_mfma_f32_16x16x32_bf16 v[108:111], v[192:195], v[200:203], v[108:111]
	v_mfma_f32_16x16x32_bf16 v[100:103], v[182:185], v[208:211], v[100:103]
	v_mfma_f32_16x16x32_bf16 v[92:95], v[192:195], v[208:211], v[92:95]
	v_mfma_f32_16x16x32_bf16 v[84:87], v[182:185], v[216:219], v[84:87]
	v_mfma_f32_16x16x32_bf16 v[76:79], v[192:195], v[216:219], v[76:79]
	v_mfma_f32_16x16x32_bf16 v[68:71], v[182:185], v[224:227], v[68:71]
	v_mfma_f32_16x16x32_bf16 v[64:67], v[192:195], v[224:227], v[64:67]
	s_barrier
	s_add_i32 s54, s80, s64
	s_mov_b32 m0, s54
	ds_read_b128 v[196:199], v149 offset:49152
	ds_read_b128 v[200:203], v149 offset:50176
	ds_read_b128 v[204:207], v149 offset:51200
	ds_read_b128 v[208:211], v149 offset:52224
	ds_read_b128 v[212:215], v149 offset:53248
	ds_read_b128 v[216:219], v149 offset:54272
	ds_read_b128 v[220:223], v149 offset:55296
	ds_read_b128 v[224:227], v149 offset:56320
	global_load_lds_dwordx4 v130, s[98:99]
	s_add_i32 m0, s54, 0x2000
	s_add_u32 s52, s52, 0x40080
	s_addc_u32 s53, s53, 0
	s_add_i32 s54, s81, s64
	global_load_lds_dwordx4 v134, s[98:99]
	s_mov_b32 m0, s54
	s_nop 0
	global_load_lds_dwordx4 v130, s[52:53]
	s_add_i32 m0, s54, 0x2000
	s_nop 0
	global_load_lds_dwordx4 v134, s[52:53]
	s_mov_b32 m0, s70
	s_nop 0
	global_load_lds_dwordx4 v128, s[100:101]
	s_mov_b32 m0, s71
	s_nop 0
	global_load_lds_dwordx4 v132, s[100:101]
	s_waitcnt vmcnt(8)
	s_waitcnt lgkmcnt(0)
	s_barrier
	s_waitcnt lgkmcnt(0)
	v_mfma_f32_16x16x32_bf16 v[60:63], v[150:153], v[196:199], v[60:63]
	v_mfma_f32_16x16x32_bf16 v[56:59], v[170:173], v[196:199], v[56:59]
	v_mfma_f32_16x16x32_bf16 v[52:55], v[150:153], v[204:207], v[52:55]
	v_mfma_f32_16x16x32_bf16 v[44:47], v[170:173], v[204:207], v[44:47]
	v_mfma_f32_16x16x32_bf16 v[36:39], v[150:153], v[212:215], v[36:39]
	v_mfma_f32_16x16x32_bf16 v[28:31], v[170:173], v[212:215], v[28:31]
	v_mfma_f32_16x16x32_bf16 v[20:23], v[150:153], v[220:223], v[20:23]
	v_mfma_f32_16x16x32_bf16 v[12:15], v[170:173], v[220:223], v[12:15]
	v_mfma_f32_16x16x32_bf16 v[60:63], v[166:169], v[200:203], v[60:63]
	v_mfma_f32_16x16x32_bf16 v[56:59], v[174:177], v[200:203], v[56:59]
	v_mfma_f32_16x16x32_bf16 v[52:55], v[166:169], v[208:211], v[52:55]
	v_mfma_f32_16x16x32_bf16 v[44:47], v[174:177], v[208:211], v[44:47]
	v_mfma_f32_16x16x32_bf16 v[36:39], v[166:169], v[216:219], v[36:39]
	v_mfma_f32_16x16x32_bf16 v[28:31], v[174:177], v[216:219], v[28:31]
	v_mfma_f32_16x16x32_bf16 v[20:23], v[166:169], v[224:227], v[20:23]
	v_mfma_f32_16x16x32_bf16 v[12:15], v[174:177], v[224:227], v[12:15]
	v_mfma_f32_16x16x32_bf16 v[48:51], v[178:181], v[196:199], v[48:51]
	v_mfma_f32_16x16x32_bf16 v[40:43], v[188:191], v[196:199], v[40:43]
	v_mfma_f32_16x16x32_bf16 v[32:35], v[178:181], v[204:207], v[32:35]
	v_mfma_f32_16x16x32_bf16 v[24:27], v[188:191], v[204:207], v[24:27]
	v_mfma_f32_16x16x32_bf16 v[16:19], v[178:181], v[212:215], v[16:19]
	v_mfma_f32_16x16x32_bf16 v[8:11], v[188:191], v[212:215], v[8:11]
	v_mfma_f32_16x16x32_bf16 v[4:7], v[178:181], v[220:223], v[4:7]
	v_mfma_f32_16x16x32_bf16 v[0:3], v[188:191], v[220:223], v[0:3]
	v_mfma_f32_16x16x32_bf16 v[48:51], v[182:185], v[200:203], v[48:51]
	v_mfma_f32_16x16x32_bf16 v[40:43], v[192:195], v[200:203], v[40:43]
	v_mfma_f32_16x16x32_bf16 v[32:35], v[182:185], v[208:211], v[32:35]
	v_mfma_f32_16x16x32_bf16 v[24:27], v[192:195], v[208:211], v[24:27]
	v_mfma_f32_16x16x32_bf16 v[16:19], v[182:185], v[216:219], v[16:19]
	v_mfma_f32_16x16x32_bf16 v[8:11], v[192:195], v[216:219], v[8:11]
	v_mfma_f32_16x16x32_bf16 v[4:7], v[182:185], v[224:227], v[4:7]
	v_mfma_f32_16x16x32_bf16 v[0:3], v[192:195], v[224:227], v[0:3]
	s_barrier
	s_add_i32 s79, s79, 2
	s_add_u32 s50, s50, 0x100
	s_addc_u32 s51, s51, 0
	s_add_u32 s77, s77, 0x100
	s_addc_u32 s78, s78, 0
	s_cmp_gt_u32 s79, 13
	s_cbranch_scc0 .LBB0_1239
	s_setprio 0
	s_and_b64 vcc, exec, s[10:11]
	s_cbranch_vccz .LBB0_1242
	s_barrier

; #define PG8_STAGE(bufoff, gbase, voff) do { _Pragma("unroll") for (int _i = 0; _i < 2; ++_i) \
;         __builtin_amdgcn_global_load_lds((const unsigned*)((const char*)(gbase) + (voff)[_i]), (PG8_LAS unsigned*)(lds + (bufoff) + ldsw + _i * 8192), 16, 0, 0); } while (0)
; #define PG8_LDA(dst, b, h) do { _Pragma("unroll") for (int m = 0; m < 4; ++m) _Pragma("unroll") for (int k = 0; k < 2; ++k) dst[m][k] = *(const PG8_LAS bf16x8*)(lds + PG8_SA(b, h) + aoff + m * 2048 + k * 1024); } while (0)
; #define PG8_LDB(dst, b, h) do { _Pragma("unroll") for (int n = 0; n < 2; ++n) _Pragma("unroll") for (int k = 0; k < 2; ++k) dst[n][k] = *(const PG8_LAS bf16x8*)(lds + PG8_SB(b, h) + boff + n * 2048 + k * 1024); } while (0)
; #define PG8_WAIT_V(n) asm volatile("s_waitcnt vmcnt(" #n ")" ::: "memory")
; #define PG8_WAIT_L(n) asm volatile("s_waitcnt lgkmcnt(" #n ")" ::: "memory")
; #define PG8_BAR __builtin_amdgcn_s_barrier()
; template <class Epi, class Sched, bool ALIGN_EPI = false, bool SP2 = false>
; __device__ __forceinline__ void gemm_phase(PG8_LAS unsigned char* lds, const Gemm g, const Sched S, const Epi E, const int tid) {
;     ...
;         const bool has_next = S.next(ui + 1, nxt);
;         const char* nA = has_next ? (const char*)g.A + (size_t)nxt.pm * tstepA + (size_t)nxt.pn * apn : cA; const char* nB = has_next ? (const char*)g.Bt + (size_t)nxt.pn * bpn : cB;
;         for (int t = 0; t < nt; t += 2) {
;             const bool last = (t == nt - 2);
;             const char* a1 = cA + (size_t)(t + 1) * kstep;
;             const char* a2 = last ? nA : cA + (size_t)(t + 2) * kstep; const char* b2 = last ? nB : cB + (size_t)(t + 2) * kstep;
;             const char* a3 = a2 + kstep; const char* b3 = b2 + kstep;
;             if (last && has_next) S.a_ready(nxt);
;             if constexpr (SP2) {
;             PG8_LDB(B0, 0, 0); PG8_LDB(B1, 0, 1); PG8_SCHED; PG8_LDA(At, 0, 0); PG8_STAGE(PG8_SA(1, 1), a1 + hstepA, voffA);
;             PG8_WAIT_V(8); PG8_WAIT_L(0); PG8_BAR; PG8_MMA(0, 0, At, B0); PG8_MMA(0, 1, At, B1); PG8_BAR; PG8_SCHED;
;     ...
;         else {
; #pragma unroll
;         for (int a = 0; a < 2; ++a)
; #pragma unroll
;             for (int b = 0; b < 2; ++b)
; #pragma unroll
;                 for (int m = 0; m < 4; ++m)
; #pragma unroll
;                     for (int n = 0; n < 2; ++n) acc[a][b][m][n] = (f32x4){0.f, 0.f, 0.f, 0.f};
;         }
.LBB0_1254:
	s_ashr_i32 s37, s36, 31
	s_lshl_b64 s[40:41], s[36:37], 19
	s_add_u32 s40, s56, s40
	s_addc_u32 s41, s59, s41
	s_and_b64 s[46:47], s[38:39], exec
	s_cselect_b32 s37, s41, s51
	s_cselect_b32 s72, s40, s50
	s_ashr_i32 s35, s34, 31
	s_lshl_b64 s[46:47], s[34:35], 19
	s_add_u32 s46, s18, s46
	s_addc_u32 s47, s19, s47
	s_and_b64 s[54:55], s[38:39], exec
	s_cselect_b32 s35, s47, s53
	s_cselect_b32 s73, s46, s52
	s_add_u32 s50, s50, 0x40080
	s_addc_u32 s51, s51, 0
	s_add_u32 s74, s52, 0x100
	v_mov_b32_e32 v0, 0
	s_addc_u32 s75, s53, 0
	s_mov_b32 s76, -2
	v_mov_b32_e32 v1, v0
	v_mov_b32_e32 v2, v0
	v_mov_b32_e32 v3, v0
	v_mov_b32_e32 v4, v0
	v_mov_b32_e32 v5, v0
	v_mov_b32_e32 v6, v0
	v_mov_b32_e32 v7, v0
	v_mov_b32_e32 v8, v0
	v_mov_b32_e32 v9, v0
	v_mov_b32_e32 v10, v0
	v_mov_b32_e32 v11, v0
	v_mov_b32_e32 v16, v0
	v_mov_b32_e32 v17, v0
	v_mov_b32_e32 v18, v0
	v_mov_b32_e32 v19, v0
	v_mov_b32_e32 v24, v0
	v_mov_b32_e32 v25, v0
	v_mov_b32_e32 v26, v0
	v_mov_b32_e32 v27, v0
	v_mov_b32_e32 v32, v0
	v_mov_b32_e32 v33, v0
	v_mov_b32_e32 v34, v0
	v_mov_b32_e32 v35, v0
	v_mov_b32_e32 v40, v0
	v_mov_b32_e32 v41, v0
	v_mov_b32_e32 v42, v0
	v_mov_b32_e32 v43, v0
	v_mov_b32_e32 v48, v0
	v_mov_b32_e32 v49, v0
	v_mov_b32_e32 v50, v0
	v_mov_b32_e32 v51, v0
	v_mov_b32_e32 v12, v0
	v_mov_b32_e32 v13, v0
	v_mov_b32_e32 v14, v0
	v_mov_b32_e32 v15, v0
	v_mov_b32_e32 v20, v0
	v_mov_b32_e32 v21, v0
	v_mov_b32_e32 v22, v0
	v_mov_b32_e32 v23, v0
	v_mov_b32_e32 v28, v0
	v_mov_b32_e32 v29, v0
	v_mov_b32_e32 v30, v0
	v_mov_b32_e32 v31, v0
	v_mov_b32_e32 v36, v0
	v_mov_b32_e32 v37, v0
	v_mov_b32_e32 v38, v0
	v_mov_b32_e32 v39, v0
	v_mov_b32_e32 v44, v0
	v_mov_b32_e32 v45, v0
	v_mov_b32_e32 v46, v0
	v_mov_b32_e32 v47, v0
	v_mov_b32_e32 v52, v0
	v_mov_b32_e32 v53, v0
	v_mov_b32_e32 v54, v0
	v_mov_b32_e32 v55, v0
	v_mov_b32_e32 v56, v0
	v_mov_b32_e32 v57, v0
	v_mov_b32_e32 v58, v0
	v_mov_b32_e32 v59, v0
	v_mov_b32_e32 v60, v0
	v_mov_b32_e32 v61, v0
	v_mov_b32_e32 v62, v0
	v_mov_b32_e32 v63, v0
	v_mov_b32_e32 v64, v0
	v_mov_b32_e32 v65, v0
	v_mov_b32_e32 v66, v0
	v_mov_b32_e32 v67, v0
	v_mov_b32_e32 v68, v0
	v_mov_b32_e32 v69, v0
	v_mov_b32_e32 v70, v0
	v_mov_b32_e32 v71, v0
	v_mov_b32_e32 v76, v0
	v_mov_b32_e32 v77, v0
	v_mov_b32_e32 v78, v0
	v_mov_b32_e32 v79, v0
	v_mov_b32_e32 v84, v0
	v_mov_b32_e32 v85, v0
	v_mov_b32_e32 v86, v0
	v_mov_b32_e32 v87, v0
	v_mov_b32_e32 v92, v0
	v_mov_b32_e32 v93, v0
	v_mov_b32_e32 v94, v0
	v_mov_b32_e32 v95, v0
	v_mov_b32_e32 v100, v0
	v_mov_b32_e32 v101, v0
	v_mov_b32_e32 v102, v0
	v_mov_b32_e32 v103, v0
	v_mov_b32_e32 v108, v0
	v_mov_b32_e32 v109, v0
	v_mov_b32_e32 v110, v0
	v_mov_b32_e32 v111, v0
	v_mov_b32_e32 v116, v0
	v_mov_b32_e32 v117, v0
	v_mov_b32_e32 v118, v0
	v_mov_b32_e32 v119, v0
	v_mov_b32_e32 v72, v0
	v_mov_b32_e32 v73, v0
	v_mov_b32_e32 v74, v0
	v_mov_b32_e32 v75, v0
	v_mov_b32_e32 v80, v0
	v_mov_b32_e32 v81, v0
	v_mov_b32_e32 v82, v0
	v_mov_b32_e32 v83, v0
	v_mov_b32_e32 v88, v0
	v_mov_b32_e32 v89, v0
	v_mov_b32_e32 v90, v0
	v_mov_b32_e32 v91, v0
	v_mov_b32_e32 v96, v0
	v_mov_b32_e32 v97, v0
	v_mov_b32_e32 v98, v0
	v_mov_b32_e32 v99, v0
	v_mov_b32_e32 v104, v0
	v_mov_b32_e32 v105, v0
	v_mov_b32_e32 v106, v0
	v_mov_b32_e32 v107, v0
	v_mov_b32_e32 v112, v0
	v_mov_b32_e32 v113, v0
	v_mov_b32_e32 v114, v0
	v_mov_b32_e32 v115, v0
	v_mov_b32_e32 v120, v0
	v_mov_b32_e32 v121, v0
	v_mov_b32_e32 v122, v0
	v_mov_b32_e32 v123, v0
	v_mov_b32_e32 v124, v0
	v_mov_b32_e32 v125, v0
	v_mov_b32_e32 v126, v0
	v_mov_b32_e32 v127, v0
	v_readfirstlane_b32 s98, v186
	s_lshr_b32 s98, s98, 8
	s_cmp_eq_u32 s98, 0
	s_cbranch_scc1 .Lprio_skip_12
	s_setprio 1
.Lprio_skip_12:
.LBB0_1255:
	ds_read_b128 v[148:151], v145
	ds_read_b128 v[152:155], v145 offset:1024
	ds_read_b128 v[156:159], v145 offset:2048
	ds_read_b128 v[160:163], v145 offset:3072
	ds_read_b128 v[164:167], v146
	ds_read_b128 v[168:171], v146 offset:1024
	ds_read_b128 v[172:175], v146 offset:2048
	ds_read_b128 v[176:179], v146 offset:3072
	s_add_u32 s52, s50, 0xfffc0080
	s_addc_u32 s53, s51, -1
	s_cmp_eq_u32 s76, 12
	s_cselect_b32 s55, s37, s53
	s_cselect_b32 s54, s72, s52
	s_cselect_b32 s53, s35, s75
	s_cselect_b32 s52, s73, s74
	s_add_i32 m0, s49, 0xc000
	ds_read_b128 v[180:183], v147
	ds_read_b128 v[188:191], v147 offset:1024
	ds_read_b128 v[192:195], v147 offset:2048
	ds_read_b128 v[196:199], v147 offset:3072
	ds_read_b128 v[200:203], v147 offset:4096
	ds_read_b128 v[204:207], v147 offset:5120
	ds_read_b128 v[208:211], v147 offset:6144
	ds_read_b128 v[212:215], v147 offset:7168
	global_load_lds_dwordx4 v136, s[50:51]
	s_add_i32 m0, s49, 0xe000
	s_nop 0
	global_load_lds_dwordx4 v138, s[50:51]
	s_waitcnt vmcnt(8)
	s_waitcnt lgkmcnt(0)
	s_barrier
; #define PG8_STAGE(bufoff, gbase, voff) do { _Pragma("unroll") for (int _i = 0; _i < 2; ++_i) \
;         __builtin_amdgcn_global_load_lds((const unsigned*)((const char*)(gbase) + (voff)[_i]), (PG8_LAS unsigned*)(lds + (bufoff) + ldsw + _i * 8192), 16, 0, 0); } while (0)
; #define PG8_LDA(dst, b, h) do { _Pragma("unroll") for (int m = 0; m < 4; ++m) _Pragma("unroll") for (int k = 0; k < 2; ++k) dst[m][k] = *(const PG8_LAS bf16x8*)(lds + PG8_SA(b, h) + aoff + m * 2048 + k * 1024); } while (0)
; #define PG8_LDB(dst, b, h) do { _Pragma("unroll") for (int n = 0; n < 2; ++n) _Pragma("unroll") for (int k = 0; k < 2; ++k) dst[n][k] = *(const PG8_LAS bf16x8*)(lds + PG8_SB(b, h) + boff + n * 2048 + k * 1024); } while (0)
; #define PG8_MMA(ai, bj, At, Bt) do { __builtin_amdgcn_s_setprio(1); _Pragma("unroll") for (int m = 0; m < 4; ++m) _Pragma("unroll") for (int n = 0; n < 2; ++n) _Pragma("unroll") for (int k = 0; k < 2; ++k) \
;         acc[ai][bj][m][n] = __builtin_amdgcn_mfma_f32_16x16x32_bf16(Bt[n][k], At[m][k], acc[ai][bj][m][n], 0, 0, 0); __builtin_amdgcn_s_setprio(0); } while (0)
; #define PG8_WAIT_V(n) asm volatile("s_waitcnt vmcnt(" #n ")" ::: "memory")
; #define PG8_WAIT_L(n) asm volatile("s_waitcnt lgkmcnt(" #n ")" ::: "memory")
; #define PG8_BAR __builtin_amdgcn_s_barrier()
; #define PG8_SCHED __builtin_amdgcn_sched_barrier(0)
; template <class Epi, class Sched, bool ALIGN_EPI = false, bool SP2 = false>
; __device__ __forceinline__ void gemm_phase(PG8_LAS unsigned char* lds, const Gemm g, const Sched S, const Epi E, const int tid) {
;     ...
;             PG8_LDB(B0, 0, 0); PG8_LDB(B1, 0, 1); PG8_SCHED; PG8_LDA(At, 0, 0); PG8_STAGE(PG8_SA(1, 1), a1 + hstepA, voffA);
;             PG8_WAIT_V(8); PG8_WAIT_L(0); PG8_BAR; PG8_MMA(0, 0, At, B0); PG8_MMA(0, 1, At, B1); PG8_BAR; PG8_SCHED;
;             PG8_LDA(At, 0, 1); PG8_STAGE(PG8_SB(0, 0), b2, voffB); PG8_STAGE(PG8_SB(0, 1), b2 + hstepB, voffB); PG8_STAGE(PG8_SA(0, 0), a2, voffA);
;             PG8_WAIT_V(8); PG8_WAIT_L(0); PG8_BAR; PG8_MMA(1, 0, At, B0); PG8_MMA(1, 1, At, B1); PG8_BAR; PG8_SCHED;
	s_waitcnt lgkmcnt(0)
	v_mfma_f32_16x16x32_bf16 v[124:127], v[148:151], v[180:183], v[124:127]
	v_mfma_f32_16x16x32_bf16 v[120:123], v[156:159], v[180:183], v[120:123]
	v_mfma_f32_16x16x32_bf16 v[112:115], v[148:151], v[192:195], v[112:115]
	v_mfma_f32_16x16x32_bf16 v[104:107], v[156:159], v[192:195], v[104:107]
	v_mfma_f32_16x16x32_bf16 v[96:99], v[148:151], v[200:203], v[96:99]
	v_mfma_f32_16x16x32_bf16 v[88:91], v[156:159], v[200:203], v[88:91]
	v_mfma_f32_16x16x32_bf16 v[80:83], v[148:151], v[208:211], v[80:83]
	v_mfma_f32_16x16x32_bf16 v[72:75], v[156:159], v[208:211], v[72:75]
	v_mfma_f32_16x16x32_bf16 v[124:127], v[152:155], v[188:191], v[124:127]
	v_mfma_f32_16x16x32_bf16 v[120:123], v[160:163], v[188:191], v[120:123]
	v_mfma_f32_16x16x32_bf16 v[112:115], v[152:155], v[196:199], v[112:115]
	v_mfma_f32_16x16x32_bf16 v[104:107], v[160:163], v[196:199], v[104:107]
	v_mfma_f32_16x16x32_bf16 v[96:99], v[152:155], v[204:207], v[96:99]
	v_mfma_f32_16x16x32_bf16 v[88:91], v[160:163], v[204:207], v[88:91]
	v_mfma_f32_16x16x32_bf16 v[80:83], v[152:155], v[212:215], v[80:83]
	v_mfma_f32_16x16x32_bf16 v[72:75], v[160:163], v[212:215], v[72:75]
	v_mfma_f32_16x16x32_bf16 v[116:119], v[164:167], v[180:183], v[116:119]
	v_mfma_f32_16x16x32_bf16 v[108:111], v[172:175], v[180:183], v[108:111]
	v_mfma_f32_16x16x32_bf16 v[100:103], v[164:167], v[192:195], v[100:103]
	v_mfma_f32_16x16x32_bf16 v[92:95], v[172:175], v[192:195], v[92:95]
	v_mfma_f32_16x16x32_bf16 v[84:87], v[164:167], v[200:203], v[84:87]
	v_mfma_f32_16x16x32_bf16 v[76:79], v[172:175], v[200:203], v[76:79]
	v_mfma_f32_16x16x32_bf16 v[68:71], v[164:167], v[208:211], v[68:71]
	v_mfma_f32_16x16x32_bf16 v[64:67], v[172:175], v[208:211], v[64:67]
	v_mfma_f32_16x16x32_bf16 v[116:119], v[168:171], v[188:191], v[116:119]
	v_mfma_f32_16x16x32_bf16 v[108:111], v[176:179], v[188:191], v[108:111]
	v_mfma_f32_16x16x32_bf16 v[100:103], v[168:171], v[196:199], v[100:103]
	v_mfma_f32_16x16x32_bf16 v[92:95], v[176:179], v[196:199], v[92:95]
	v_mfma_f32_16x16x32_bf16 v[84:87], v[168:171], v[204:207], v[84:87]
	v_mfma_f32_16x16x32_bf16 v[76:79], v[176:179], v[204:207], v[76:79]
	v_mfma_f32_16x16x32_bf16 v[68:71], v[168:171], v[212:215], v[68:71]
	v_mfma_f32_16x16x32_bf16 v[64:67], v[176:179], v[212:215], v[64:67]
	s_barrier
	s_add_u32 s98, s52, 0x80
	s_addc_u32 s99, s53, 0
	s_add_u32 s100, s54, 0x80
	s_addc_u32 s101, s55, 0
	s_add_i32 s77, s69, s61
	s_mov_b32 m0, s77
	ds_read_b128 v[180:183], v147 offset:16384
	ds_read_b128 v[188:191], v147 offset:17408
	ds_read_b128 v[192:195], v147 offset:18432
	ds_read_b128 v[196:199], v147 offset:19456
	ds_read_b128 v[200:203], v147 offset:20480
	ds_read_b128 v[204:207], v147 offset:21504
	ds_read_b128 v[208:211], v147 offset:22528
	ds_read_b128 v[212:215], v147 offset:23552
	global_load_lds_dwordx4 v130, s[52:53]
	s_add_i32 m0, s77, 0x2000
	s_add_u32 s78, s52, 0x40000
	s_addc_u32 s79, s53, 0
	s_add_i32 s77, s70, s61
	global_load_lds_dwordx4 v134, s[52:53]
	s_mov_b32 m0, s77
	s_nop 0
	global_load_lds_dwordx4 v130, s[78:79]
	s_add_i32 m0, s77, 0x2000
	s_nop 0
	global_load_lds_dwordx4 v134, s[78:79]
	s_mov_b32 m0, s49
	s_nop 0
	global_load_lds_dwordx4 v128, s[54:55]
	s_mov_b32 m0, s62
	s_nop 0
	global_load_lds_dwordx4 v132, s[54:55]
	s_waitcnt vmcnt(8)
	s_waitcnt lgkmcnt(0)
	s_barrier
	s_waitcnt lgkmcnt(0)
	v_mfma_f32_16x16x32_bf16 v[60:63], v[148:151], v[180:183], v[60:63]
	v_mfma_f32_16x16x32_bf16 v[56:59], v[156:159], v[180:183], v[56:59]
	v_mfma_f32_16x16x32_bf16 v[52:55], v[148:151], v[192:195], v[52:55]
	v_mfma_f32_16x16x32_bf16 v[44:47], v[156:159], v[192:195], v[44:47]
	v_mfma_f32_16x16x32_bf16 v[36:39], v[148:151], v[200:203], v[36:39]
	v_mfma_f32_16x16x32_bf16 v[28:31], v[156:159], v[200:203], v[28:31]
	v_mfma_f32_16x16x32_bf16 v[20:23], v[148:151], v[208:211], v[20:23]
	v_mfma_f32_16x16x32_bf16 v[12:15], v[156:159], v[208:211], v[12:15]
	v_mfma_f32_16x16x32_bf16 v[60:63], v[152:155], v[188:191], v[60:63]
	v_mfma_f32_16x16x32_bf16 v[56:59], v[160:163], v[188:191], v[56:59]
	v_mfma_f32_16x16x32_bf16 v[52:55], v[152:155], v[196:199], v[52:55]
	v_mfma_f32_16x16x32_bf16 v[44:47], v[160:163], v[196:199], v[44:47]
	v_mfma_f32_16x16x32_bf16 v[36:39], v[152:155], v[204:207], v[36:39]
	v_mfma_f32_16x16x32_bf16 v[28:31], v[160:163], v[204:207], v[28:31]
	v_mfma_f32_16x16x32_bf16 v[20:23], v[152:155], v[212:215], v[20:23]
	v_mfma_f32_16x16x32_bf16 v[12:15], v[160:163], v[212:215], v[12:15]
	v_mfma_f32_16x16x32_bf16 v[48:51], v[164:167], v[180:183], v[48:51]
	v_mfma_f32_16x16x32_bf16 v[40:43], v[172:175], v[180:183], v[40:43]
	v_mfma_f32_16x16x32_bf16 v[32:35], v[164:167], v[192:195], v[32:35]
	v_mfma_f32_16x16x32_bf16 v[24:27], v[172:175], v[192:195], v[24:27]
	v_mfma_f32_16x16x32_bf16 v[16:19], v[164:167], v[200:203], v[16:19]
	v_mfma_f32_16x16x32_bf16 v[8:11], v[172:175], v[200:203], v[8:11]
	v_mfma_f32_16x16x32_bf16 v[4:7], v[164:167], v[208:211], v[4:7]
	v_mfma_f32_16x16x32_bf16 v[0:3], v[172:175], v[208:211], v[0:3]
	v_mfma_f32_16x16x32_bf16 v[48:51], v[168:171], v[188:191], v[48:51]
	v_mfma_f32_16x16x32_bf16 v[40:43], v[176:179], v[188:191], v[40:43]
	v_mfma_f32_16x16x32_bf16 v[32:35], v[168:171], v[196:199], v[32:35]
	v_mfma_f32_16x16x32_bf16 v[24:27], v[176:179], v[196:199], v[24:27]
	v_mfma_f32_16x16x32_bf16 v[16:19], v[168:171], v[204:207], v[16:19]
	v_mfma_f32_16x16x32_bf16 v[8:11], v[176:179], v[204:207], v[8:11]
	v_mfma_f32_16x16x32_bf16 v[4:7], v[168:171], v[212:215], v[4:7]
	v_mfma_f32_16x16x32_bf16 v[0:3], v[176:179], v[212:215], v[0:3]
	s_barrier
; #define PG8_STAGE(bufoff, gbase, voff) do { _Pragma("unroll") for (int _i = 0; _i < 2; ++_i) \
;         __builtin_amdgcn_global_load_lds((const unsigned*)((const char*)(gbase) + (voff)[_i]), (PG8_LAS unsigned*)(lds + (bufoff) + ldsw + _i * 8192), 16, 0, 0); } while (0)
; #define PG8_LDA(dst, b, h) do { _Pragma("unroll") for (int m = 0; m < 4; ++m) _Pragma("unroll") for (int k = 0; k < 2; ++k) dst[m][k] = *(const PG8_LAS bf16x8*)(lds + PG8_SA(b, h) + aoff + m * 2048 + k * 1024); } while (0)
; #define PG8_LDB(dst, b, h) do { _Pragma("unroll") for (int n = 0; n < 2; ++n) _Pragma("unroll") for (int k = 0; k < 2; ++k) dst[n][k] = *(const PG8_LAS bf16x8*)(lds + PG8_SB(b, h) + boff + n * 2048 + k * 1024); } while (0)
; #define PG8_MMA(ai, bj, At, Bt) do { __builtin_amdgcn_s_setprio(1); _Pragma("unroll") for (int m = 0; m < 4; ++m) _Pragma("unroll") for (int n = 0; n < 2; ++n) _Pragma("unroll") for (int k = 0; k < 2; ++k) \
;         acc[ai][bj][m][n] = __builtin_amdgcn_mfma_f32_16x16x32_bf16(Bt[n][k], At[m][k], acc[ai][bj][m][n], 0, 0, 0); __builtin_amdgcn_s_setprio(0); } while (0)
; #define PG8_WAIT_V(n) asm volatile("s_waitcnt vmcnt(" #n ")" ::: "memory")
; #define PG8_WAIT_L(n) asm volatile("s_waitcnt lgkmcnt(" #n ")" ::: "memory")
; #define PG8_BAR __builtin_amdgcn_s_barrier()
; template <class Epi, class Sched, bool ALIGN_EPI = false, bool SP2 = false>
; __device__ __forceinline__ void gemm_phase(PG8_LAS unsigned char* lds, const Gemm g, const Sched S, const Epi E, const int tid) {
;     ...
;         for (int t = 0; t < nt; t += 2) {
;             const bool last = (t == nt - 2);
;             const char* a1 = cA + (size_t)(t + 1) * kstep;
;             const char* a2 = last ? nA : cA + (size_t)(t + 2) * kstep; const char* b2 = last ? nB : cB + (size_t)(t + 2) * kstep;
;             const char* a3 = a2 + kstep; const char* b3 = b2 + kstep;
;     ...
;             PG8_LDB(B0, 1, 0); PG8_LDB(B1, 1, 1); PG8_SCHED; PG8_LDA(At, 1, 0); PG8_STAGE(PG8_SA(0, 1), a2 + hstepA, voffA);
;             PG8_WAIT_V(8); PG8_WAIT_L(0); PG8_BAR; PG8_MMA(0, 0, At, B0); PG8_MMA(0, 1, At, B1); PG8_BAR; PG8_SCHED;
;             PG8_LDA(At, 1, 1); PG8_STAGE(PG8_SB(1, 0), b3, voffB); PG8_STAGE(PG8_SB(1, 1), b3 + hstepB, voffB); PG8_STAGE(PG8_SA(1, 0), a3, voffA);
;             PG8_WAIT_V(8); PG8_WAIT_L(0); PG8_BAR; PG8_MMA(1, 0, At, B0); PG8_MMA(1, 1, At, B1); PG8_BAR; PG8_SCHED;
	s_add_i32 s77, 0, 0x18000
	s_add_i32 s78, 0, 0x1c000
	v_add_u32_e32 v160, s77, v143
	v_add_u32_e32 v176, s78, v143
	ds_read_b128 v[148:151], v160
	ds_read_b128 v[152:155], v160 offset:1024
	ds_read_b128 v[156:159], v160 offset:2048
	ds_read_b128 v[160:163], v160 offset:3072
	ds_read_b128 v[164:167], v176
	ds_read_b128 v[168:171], v176 offset:1024
	ds_read_b128 v[172:175], v176 offset:2048
	ds_read_b128 v[176:179], v176 offset:3072
	s_add_u32 s54, s54, 0x40000
	s_addc_u32 s55, s55, 0
	s_mov_b32 m0, s63
	ds_read_b128 v[180:183], v147 offset:32768
	ds_read_b128 v[188:191], v147 offset:33792
	ds_read_b128 v[192:195], v147 offset:34816
	ds_read_b128 v[196:199], v147 offset:35840
	ds_read_b128 v[200:203], v147 offset:36864
	ds_read_b128 v[204:207], v147 offset:37888
	ds_read_b128 v[208:211], v147 offset:38912
	ds_read_b128 v[212:215], v147 offset:39936
	global_load_lds_dwordx4 v128, s[54:55]
	s_mov_b32 m0, s64
	s_nop 0
	global_load_lds_dwordx4 v132, s[54:55]
	s_waitcnt vmcnt(8)
	s_waitcnt lgkmcnt(0)
	s_barrier
	s_waitcnt lgkmcnt(0)
	v_mfma_f32_16x16x32_bf16 v[124:127], v[148:151], v[180:183], v[124:127]
	v_mfma_f32_16x16x32_bf16 v[120:123], v[156:159], v[180:183], v[120:123]
	v_mfma_f32_16x16x32_bf16 v[112:115], v[148:151], v[192:195], v[112:115]
	v_mfma_f32_16x16x32_bf16 v[104:107], v[156:159], v[192:195], v[104:107]
	v_mfma_f32_16x16x32_bf16 v[96:99], v[148:151], v[200:203], v[96:99]
	v_mfma_f32_16x16x32_bf16 v[88:91], v[156:159], v[200:203], v[88:91]
	v_mfma_f32_16x16x32_bf16 v[80:83], v[148:151], v[208:211], v[80:83]
	v_mfma_f32_16x16x32_bf16 v[72:75], v[156:159], v[208:211], v[72:75]
	v_mfma_f32_16x16x32_bf16 v[124:127], v[152:155], v[188:191], v[124:127]
	v_mfma_f32_16x16x32_bf16 v[120:123], v[160:163], v[188:191], v[120:123]
	v_mfma_f32_16x16x32_bf16 v[112:115], v[152:155], v[196:199], v[112:115]
	v_mfma_f32_16x16x32_bf16 v[104:107], v[160:163], v[196:199], v[104:107]
	v_mfma_f32_16x16x32_bf16 v[96:99], v[152:155], v[204:207], v[96:99]
	v_mfma_f32_16x16x32_bf16 v[88:91], v[160:163], v[204:207], v[88:91]
	v_mfma_f32_16x16x32_bf16 v[80:83], v[152:155], v[212:215], v[80:83]
	v_mfma_f32_16x16x32_bf16 v[72:75], v[160:163], v[212:215], v[72:75]
	v_mfma_f32_16x16x32_bf16 v[116:119], v[164:167], v[180:183], v[116:119]
	v_mfma_f32_16x16x32_bf16 v[108:111], v[172:175], v[180:183], v[108:111]
	v_mfma_f32_16x16x32_bf16 v[100:103], v[164:167], v[192:195], v[100:103]
	v_mfma_f32_16x16x32_bf16 v[92:95], v[172:175], v[192:195], v[92:95]
	v_mfma_f32_16x16x32_bf16 v[84:87], v[164:167], v[200:203], v[84:87]
	v_mfma_f32_16x16x32_bf16 v[76:79], v[172:175], v[200:203], v[76:79]
	v_mfma_f32_16x16x32_bf16 v[68:71], v[164:167], v[208:211], v[68:71]
	v_mfma_f32_16x16x32_bf16 v[64:67], v[172:175], v[208:211], v[64:67]
	v_mfma_f32_16x16x32_bf16 v[116:119], v[168:171], v[188:191], v[116:119]
	v_mfma_f32_16x16x32_bf16 v[108:111], v[176:179], v[188:191], v[108:111]
	v_mfma_f32_16x16x32_bf16 v[100:103], v[168:171], v[196:199], v[100:103]
	v_mfma_f32_16x16x32_bf16 v[92:95], v[176:179], v[196:199], v[92:95]
	v_mfma_f32_16x16x32_bf16 v[84:87], v[168:171], v[204:207], v[84:87]
	v_mfma_f32_16x16x32_bf16 v[76:79], v[176:179], v[204:207], v[76:79]
	v_mfma_f32_16x16x32_bf16 v[68:71], v[168:171], v[212:215], v[68:71]
	v_mfma_f32_16x16x32_bf16 v[64:67], v[176:179], v[212:215], v[64:67]
	s_barrier
	s_add_i32 s54, s77, s61
	s_mov_b32 m0, s54
	ds_read_b128 v[180:183], v147 offset:49152
	ds_read_b128 v[188:191], v147 offset:50176
	ds_read_b128 v[192:195], v147 offset:51200
	ds_read_b128 v[196:199], v147 offset:52224
	ds_read_b128 v[200:203], v147 offset:53248
	ds_read_b128 v[204:207], v147 offset:54272
	ds_read_b128 v[208:211], v147 offset:55296
	ds_read_b128 v[212:215], v147 offset:56320
	global_load_lds_dwordx4 v130, s[98:99]
	s_add_i32 m0, s54, 0x2000
	s_add_u32 s52, s52, 0x40080
	s_addc_u32 s53, s53, 0
	s_add_i32 s54, s78, s61
	global_load_lds_dwordx4 v134, s[98:99]
	s_mov_b32 m0, s54
	s_nop 0
	global_load_lds_dwordx4 v130, s[52:53]
	s_add_i32 m0, s54, 0x2000
	s_nop 0
	global_load_lds_dwordx4 v134, s[52:53]
	s_mov_b32 m0, s66
	s_nop 0
	global_load_lds_dwordx4 v128, s[100:101]
	s_mov_b32 m0, s67
	s_nop 0
	global_load_lds_dwordx4 v132, s[100:101]
	s_waitcnt vmcnt(8)
	s_waitcnt lgkmcnt(0)
	s_barrier
	s_waitcnt lgkmcnt(0)
	v_mfma_f32_16x16x32_bf16 v[60:63], v[148:151], v[180:183], v[60:63]
	v_mfma_f32_16x16x32_bf16 v[56:59], v[156:159], v[180:183], v[56:59]
	v_mfma_f32_16x16x32_bf16 v[52:55], v[148:151], v[192:195], v[52:55]
	v_mfma_f32_16x16x32_bf16 v[44:47], v[156:159], v[192:195], v[44:47]
	v_mfma_f32_16x16x32_bf16 v[36:39], v[148:151], v[200:203], v[36:39]
	v_mfma_f32_16x16x32_bf16 v[28:31], v[156:159], v[200:203], v[28:31]
	v_mfma_f32_16x16x32_bf16 v[20:23], v[148:151], v[208:211], v[20:23]
	v_mfma_f32_16x16x32_bf16 v[12:15], v[156:159], v[208:211], v[12:15]
	v_mfma_f32_16x16x32_bf16 v[60:63], v[152:155], v[188:191], v[60:63]
	v_mfma_f32_16x16x32_bf16 v[56:59], v[160:163], v[188:191], v[56:59]
	v_mfma_f32_16x16x32_bf16 v[52:55], v[152:155], v[196:199], v[52:55]
	v_mfma_f32_16x16x32_bf16 v[44:47], v[160:163], v[196:199], v[44:47]
	v_mfma_f32_16x16x32_bf16 v[36:39], v[152:155], v[204:207], v[36:39]
	v_mfma_f32_16x16x32_bf16 v[28:31], v[160:163], v[204:207], v[28:31]
	v_mfma_f32_16x16x32_bf16 v[20:23], v[152:155], v[212:215], v[20:23]
	v_mfma_f32_16x16x32_bf16 v[12:15], v[160:163], v[212:215], v[12:15]
	v_mfma_f32_16x16x32_bf16 v[48:51], v[164:167], v[180:183], v[48:51]
	v_mfma_f32_16x16x32_bf16 v[40:43], v[172:175], v[180:183], v[40:43]
	v_mfma_f32_16x16x32_bf16 v[32:35], v[164:167], v[192:195], v[32:35]
	v_mfma_f32_16x16x32_bf16 v[24:27], v[172:175], v[192:195], v[24:27]
	v_mfma_f32_16x16x32_bf16 v[16:19], v[164:167], v[200:203], v[16:19]
	v_mfma_f32_16x16x32_bf16 v[8:11], v[172:175], v[200:203], v[8:11]
	v_mfma_f32_16x16x32_bf16 v[4:7], v[164:167], v[208:211], v[4:7]
	v_mfma_f32_16x16x32_bf16 v[0:3], v[172:175], v[208:211], v[0:3]
	v_mfma_f32_16x16x32_bf16 v[48:51], v[168:171], v[188:191], v[48:51]
	v_mfma_f32_16x16x32_bf16 v[40:43], v[176:179], v[188:191], v[40:43]
	v_mfma_f32_16x16x32_bf16 v[32:35], v[168:171], v[196:199], v[32:35]
	v_mfma_f32_16x16x32_bf16 v[24:27], v[176:179], v[196:199], v[24:27]
	v_mfma_f32_16x16x32_bf16 v[16:19], v[168:171], v[204:207], v[16:19]
	v_mfma_f32_16x16x32_bf16 v[8:11], v[176:179], v[204:207], v[8:11]
	v_mfma_f32_16x16x32_bf16 v[4:7], v[168:171], v[212:215], v[4:7]
	v_mfma_f32_16x16x32_bf16 v[0:3], v[176:179], v[212:215], v[0:3]
	s_barrier
	s_add_i32 s76, s76, 2
	s_add_u32 s50, s50, 0x100
	s_addc_u32 s51, s51, 0
	s_add_u32 s74, s74, 0x100
	s_addc_u32 s75, s75, 0
	s_cmp_gt_u32 s76, 13
	s_cbranch_scc0 .LBB0_1255
	s_setprio 0
	s_and_b64 vcc, exec, s[8:9]
	s_cbranch_vccz .LBB0_1258
	s_barrier
